# pool rewrite + GEMM K-loops: per-cluster s_setprio flips deleted, one static s_setprio 1 for waves 4-7 before each K-loop
# speedup vs baseline: 1.0171x; 1.0078x over previous
; #define PG8_STAGE(bufoff, gbase, voff) do { _Pragma("unroll") for (int _i = 0; _i < 2; ++_i) \
;         __builtin_amdgcn_global_load_lds((const unsigned*)((const char*)(gbase) + (voff)[_i]), (LAS unsigned*)(lds + (bufoff) + ldsw + _i * 8192), 16, 0, 0); } while (0)
; #define PG8_LDA(dst, b, h) do { _Pragma("unroll") for (int m = 0; m < 4; ++m) _Pragma("unroll") for (int k = 0; k < 2; ++k) dst[m][k] = *(const LAS bf16x8*)(lds + PG8_SA(b, h) + aoff + m * 2048 + k * 1024); } while (0)
; #define PG8_LDB(dst, b, h) do { _Pragma("unroll") for (int n = 0; n < 2; ++n) _Pragma("unroll") for (int k = 0; k < 2; ++k) dst[n][k] = *(const LAS bf16x8*)(lds + PG8_SB(b, h) + boff + n * 2048 + k * 1024); } while (0)
; #define PG8_MMA(ai, bj, At, Bt) do { __builtin_amdgcn_s_setprio(1); _Pragma("unroll") for (int m = 0; m < 4; ++m) _Pragma("unroll") for (int n = 0; n < 2; ++n) _Pragma("unroll") for (int k = 0; k < 2; ++k) \
;         acc[ai][bj][m][n] = __builtin_amdgcn_mfma_f32_16x16x32_bf16(Bt[n][k], At[m][k], acc[ai][bj][m][n], 0, 0, 0); __builtin_amdgcn_s_setprio(0); } while (0)
; #define PG8_WAIT_L(n) asm volatile("s_waitcnt lgkmcnt(" #n ")" ::: "memory")
; #define PG8_BAR __builtin_amdgcn_s_barrier()
; #define PG8_SCHED __builtin_amdgcn_sched_barrier(0)
; template <class Epi>
; __device__ __forceinline__ void gemm_phase(LAS unsigned char* lds, const Gemm g, const StaticOrder& S, const Epi& E) {
;     ...
;             PG8_LDB(B0, 0, 0); PG8_SCHED; PG8_LDA(At, 0, 0); PG8_STAGE(PG8_SA(1, 1), a1 + hstepA, voffA);
;             PG8_WAIT_L(8); PG8_BAR; PG8_WAIT_L(0); PG8_MMA(0, 0, At, B0); PG8_BAR; PG8_SCHED;
;     ...
; #pragma unroll
;         for (int a = 0; a < 2; ++a)
; #pragma unroll
;             for (int b = 0; b < 2; ++b)
; #pragma unroll
;                 for (int m = 0; m < 4; ++m)
; #pragma unroll
;                     for (int n = 0; n < 2; ++n) acc[a][b][m][n] = (f32x4){0.f, 0.f, 0.f, 0.f};
;         cur = nxt; cA = nA; cB = nB; ++ui;
.LBB0_157:
	s_ashr_i32 s23, s22, 31
	s_lshl_b64 s[24:25], s[22:23], 20
	s_add_u32 s26, s10, s24
	s_addc_u32 s27, s11, s25
	s_and_b64 s[24:25], s[40:41], exec
	s_cselect_b32 s23, s27, s39
	s_cselect_b32 s55, s26, s38
	s_ashr_i32 s21, s20, 31
	s_lshl_b64 s[24:25], s[20:21], 20
	s_add_u32 s36, s35, s24
	s_addc_u32 s37, s44, s25
	s_and_b64 s[24:25], s[40:41], exec
	s_cselect_b32 s21, s37, s5
	s_cselect_b32 s56, s36, s4
	s_add_u32 s57, s4, 0x100
	v_mov_b32_e32 v2, 0
	s_addc_u32 s58, s5, 0
	s_mov_b32 s59, -2
	v_mov_b32_e32 v3, v2
	v_mov_b32_e32 v4, v2
	v_mov_b32_e32 v5, v2
	v_mov_b32_e32 v6, v2
	v_mov_b32_e32 v7, v2
	v_mov_b32_e32 v8, v2
	v_mov_b32_e32 v9, v2
	v_mov_b32_e32 v18, v2
	v_mov_b32_e32 v19, v2
	v_mov_b32_e32 v20, v2
	v_mov_b32_e32 v21, v2
	v_mov_b32_e32 v22, v2
	v_mov_b32_e32 v23, v2
	v_mov_b32_e32 v24, v2
	v_mov_b32_e32 v25, v2
	v_mov_b32_e32 v34, v2
	v_mov_b32_e32 v35, v2
	v_mov_b32_e32 v36, v2
	v_mov_b32_e32 v37, v2
	v_mov_b32_e32 v38, v2
	v_mov_b32_e32 v39, v2
	v_mov_b32_e32 v40, v2
	v_mov_b32_e32 v41, v2
	v_mov_b32_e32 v50, v2
	v_mov_b32_e32 v51, v2
	v_mov_b32_e32 v52, v2
	v_mov_b32_e32 v53, v2
	v_mov_b32_e32 v54, v2
	v_mov_b32_e32 v55, v2
	v_mov_b32_e32 v56, v2
	v_mov_b32_e32 v57, v2
	v_mov_b32_e32 v10, v2
	v_mov_b32_e32 v11, v2
	v_mov_b32_e32 v12, v2
	v_mov_b32_e32 v13, v2
	v_mov_b32_e32 v14, v2
	v_mov_b32_e32 v15, v2
	v_mov_b32_e32 v16, v2
	v_mov_b32_e32 v17, v2
	s_waitcnt vmcnt(0)
	v_mov_b32_e32 v26, v2
	v_mov_b32_e32 v27, v2
	v_mov_b32_e32 v28, v2
	v_mov_b32_e32 v29, v2
	v_mov_b32_e32 v30, v2
	v_mov_b32_e32 v31, v2
	v_mov_b32_e32 v32, v2
	v_mov_b32_e32 v33, v2
	v_mov_b32_e32 v42, v2
	v_mov_b32_e32 v43, v2
	v_mov_b32_e32 v44, v2
	v_mov_b32_e32 v45, v2
	v_mov_b32_e32 v46, v2
	v_mov_b32_e32 v47, v2
	v_mov_b32_e32 v48, v2
	v_mov_b32_e32 v49, v2
	v_mov_b32_e32 v58, v2
	v_mov_b32_e32 v59, v2
	v_mov_b32_e32 v60, v2
	v_mov_b32_e32 v61, v2
	v_mov_b32_e32 v62, v2
	v_mov_b32_e32 v63, v2
	v_mov_b32_e32 v64, v2
	v_mov_b32_e32 v65, v2
	v_mov_b32_e32 v66, v2
	v_mov_b32_e32 v67, v2
	v_mov_b32_e32 v68, v2
	v_mov_b32_e32 v69, v2
	v_mov_b32_e32 v70, v2
	v_mov_b32_e32 v71, v2
	v_mov_b32_e32 v72, v2
	v_mov_b32_e32 v73, v2
	v_mov_b32_e32 v82, v2
	v_mov_b32_e32 v83, v2
	v_mov_b32_e32 v84, v2
	v_mov_b32_e32 v85, v2
	v_mov_b32_e32 v86, v2
	v_mov_b32_e32 v87, v2
	v_mov_b32_e32 v88, v2
	v_mov_b32_e32 v89, v2
	v_mov_b32_e32 v98, v2
	v_mov_b32_e32 v99, v2
	v_mov_b32_e32 v100, v2
	v_mov_b32_e32 v101, v2
	v_mov_b32_e32 v102, v2
	v_mov_b32_e32 v103, v2
	v_mov_b32_e32 v104, v2
	v_mov_b32_e32 v105, v2
	v_mov_b32_e32 v114, v2
	v_mov_b32_e32 v115, v2
	v_mov_b32_e32 v116, v2
	v_mov_b32_e32 v117, v2
	v_mov_b32_e32 v118, v2
	v_mov_b32_e32 v119, v2
	v_mov_b32_e32 v120, v2
	v_mov_b32_e32 v121, v2
	v_mov_b32_e32 v74, v2
	v_mov_b32_e32 v75, v2
	v_mov_b32_e32 v76, v2
	v_mov_b32_e32 v77, v2
	v_mov_b32_e32 v78, v2
	v_mov_b32_e32 v79, v2
	v_mov_b32_e32 v80, v2
	v_mov_b32_e32 v81, v2
	v_mov_b32_e32 v90, v2
	v_mov_b32_e32 v91, v2
	v_mov_b32_e32 v92, v2
	v_mov_b32_e32 v93, v2
	v_mov_b32_e32 v94, v2
	v_mov_b32_e32 v95, v2
	v_mov_b32_e32 v96, v2
	v_mov_b32_e32 v97, v2
	v_mov_b32_e32 v106, v2
	v_mov_b32_e32 v107, v2
	v_mov_b32_e32 v108, v2
	v_mov_b32_e32 v109, v2
	v_mov_b32_e32 v110, v2
	v_mov_b32_e32 v111, v2
	v_mov_b32_e32 v112, v2
	v_mov_b32_e32 v113, v2
	v_mov_b32_e32 v122, v2
	v_mov_b32_e32 v123, v2
	v_mov_b32_e32 v124, v2
	v_mov_b32_e32 v125, v2
	v_mov_b32_e32 v126, v2
	v_mov_b32_e32 v127, v2
	v_mov_b32_e32 v128, v2
	v_mov_b32_e32 v129, v2
	v_readfirstlane_b32 s100, v232
	s_nop 3
	s_cmp_ge_u32 s100, 0x100
	s_cbranch_scc0 .Lprio_skip_0
	s_setprio 1
.Lprio_skip_0:
.LBB0_158:
	s_add_u32 s42, s38, 0x100
	s_addc_u32 s43, s39, 0
	s_add_i32 s60, 0, 0x10000
	v_add_u32_e32 v0, s60, v152
	ds_read_b128 v[146:149], v0
	ds_read_b128 v[162:165], v0 offset:1024
	ds_read_b128 v[166:169], v0 offset:2048
	ds_read_b128 v[170:173], v0 offset:3072
	s_cmp_eq_u32 s59, 28
	s_cselect_b32 s25, s23, s43
	s_cselect_b32 s24, s55, s42
	s_cselect_b32 s5, s21, s58
	s_cselect_b32 s4, s56, s57
	v_lshl_add_u64 v[150:151], s[38:39], 0, v[140:141]
	s_add_i32 m0, s46, 0xc000
	ds_read_b128 v[174:177], v154
	ds_read_b128 v[188:191], v154 offset:1024
	ds_read_b128 v[192:195], v154 offset:2048
	ds_read_b128 v[196:199], v154 offset:3072
	ds_read_b128 v[200:203], v154 offset:4096
	ds_read_b128 v[204:207], v154 offset:5120
	ds_read_b128 v[208:211], v154 offset:6144
	ds_read_b128 v[212:215], v154 offset:7168
	global_load_lds_dwordx4 v[150:151], off
	v_lshl_add_u64 v[150:151], s[38:39], 0, v[142:143]
	s_add_i32 m0, s46, 0xe000
	s_nop 0
	global_load_lds_dwordx4 v[150:151], off
	s_waitcnt lgkmcnt(8)
	s_barrier
	s_waitcnt lgkmcnt(0)
	s_waitcnt lgkmcnt(0)
	v_mfma_f32_16x16x32_bf16 v[126:129], v[146:149], v[174:177], v[126:129]
	v_mfma_f32_16x16x32_bf16 v[122:125], v[166:169], v[174:177], v[122:125]
	v_mfma_f32_16x16x32_bf16 v[110:113], v[146:149], v[192:195], v[110:113]
	v_mfma_f32_16x16x32_bf16 v[106:109], v[166:169], v[192:195], v[106:109]
	v_mfma_f32_16x16x32_bf16 v[94:97], v[146:149], v[200:203], v[94:97]
	v_mfma_f32_16x16x32_bf16 v[90:93], v[166:169], v[200:203], v[90:93]
	v_mfma_f32_16x16x32_bf16 v[78:81], v[146:149], v[208:211], v[78:81]
	v_mfma_f32_16x16x32_bf16 v[74:77], v[166:169], v[208:211], v[74:77]
	v_mfma_f32_16x16x32_bf16 v[126:129], v[162:165], v[188:191], v[126:129]
	v_mfma_f32_16x16x32_bf16 v[122:125], v[170:173], v[188:191], v[122:125]
	v_mfma_f32_16x16x32_bf16 v[110:113], v[162:165], v[196:199], v[110:113]
	v_mfma_f32_16x16x32_bf16 v[106:109], v[170:173], v[196:199], v[106:109]
	v_mfma_f32_16x16x32_bf16 v[94:97], v[162:165], v[204:207], v[94:97]
	v_mfma_f32_16x16x32_bf16 v[90:93], v[170:173], v[204:207], v[90:93]
	v_mfma_f32_16x16x32_bf16 v[78:81], v[162:165], v[212:215], v[78:81]
	v_mfma_f32_16x16x32_bf16 v[74:77], v[170:173], v[212:215], v[74:77]
	s_barrier
; #define PG8_STAGE(bufoff, gbase, voff) do { _Pragma("unroll") for (int _i = 0; _i < 2; ++_i) \
;         __builtin_amdgcn_global_load_lds((const unsigned*)((const char*)(gbase) + (voff)[_i]), (LAS unsigned*)(lds + (bufoff) + ldsw + _i * 8192), 16, 0, 0); } while (0)
; #define PG8_LDA(dst, b, h) do { _Pragma("unroll") for (int m = 0; m < 4; ++m) _Pragma("unroll") for (int k = 0; k < 2; ++k) dst[m][k] = *(const LAS bf16x8*)(lds + PG8_SA(b, h) + aoff + m * 2048 + k * 1024); } while (0)
; #define PG8_LDB(dst, b, h) do { _Pragma("unroll") for (int n = 0; n < 2; ++n) _Pragma("unroll") for (int k = 0; k < 2; ++k) dst[n][k] = *(const LAS bf16x8*)(lds + PG8_SB(b, h) + boff + n * 2048 + k * 1024); } while (0)
; #define PG8_MMA(ai, bj, At, Bt) do { __builtin_amdgcn_s_setprio(1); _Pragma("unroll") for (int m = 0; m < 4; ++m) _Pragma("unroll") for (int n = 0; n < 2; ++n) _Pragma("unroll") for (int k = 0; k < 2; ++k) \
;         acc[ai][bj][m][n] = __builtin_amdgcn_mfma_f32_16x16x32_bf16(Bt[n][k], At[m][k], acc[ai][bj][m][n], 0, 0, 0); __builtin_amdgcn_s_setprio(0); } while (0)
; #define PG8_WAIT_V(n) asm volatile("s_waitcnt vmcnt(" #n ")" ::: "memory")
; #define PG8_WAIT_L(n) asm volatile("s_waitcnt lgkmcnt(" #n ")" ::: "memory")
; #define PG8_BAR __builtin_amdgcn_s_barrier()
; #define PG8_SCHED __builtin_amdgcn_sched_barrier(0)
; template <class Epi>
; __device__ __forceinline__ void gemm_phase(LAS unsigned char* lds, const Gemm g, const StaticOrder& S, const Epi& E) {
;     ...
;             PG8_LDB(B1, 0, 1); PG8_STAGE(PG8_SB(0, 0), b2, voffB);
;             PG8_BAR; PG8_WAIT_L(0); PG8_MMA(0, 1, At, B1); PG8_BAR;
;             PG8_LDA(At, 0, 1); PG8_STAGE(PG8_SA(0, 0), a2, voffA);
;             PG8_BAR; PG8_WAIT_L(0); PG8_MMA(1, 0, At, B0); PG8_BAR; PG8_SCHED;
;             PG8_STAGE(PG8_SB(0, 1), b2 + hstepB, voffB);
;             PG8_WAIT_V(6); PG8_BAR; PG8_MMA(1, 1, At, B1); PG8_BAR;
;             PG8_LDB(B0, 1, 0); PG8_SCHED; PG8_LDA(At, 1, 0); PG8_STAGE(PG8_SA(0, 1), a2 + hstepA, voffA);
;             PG8_WAIT_L(8); PG8_BAR; PG8_WAIT_L(0); PG8_MMA(0, 0, At, B0); PG8_BAR; PG8_SCHED;
	s_add_i32 s61, 0, 0x14000
	s_add_i32 s38, s60, s45
	v_add_u32_e32 v0, s61, v152
	v_lshl_add_u64 v[150:151], s[4:5], 0, v[134:135]
	s_mov_b32 m0, s38
	ds_read_b128 v[216:219], v0
	ds_read_b128 v[220:223], v0 offset:1024
	ds_read_b128 v[224:227], v0 offset:2048
	ds_read_b128 v[228:231], v0 offset:3072
	global_load_lds_dwordx4 v[150:151], off
	v_lshl_add_u64 v[184:185], s[4:5], 0, v[130:131]
	s_add_i32 m0, s38, 0x2000
	s_nop 0
	global_load_lds_dwordx4 v[184:185], off
	s_barrier
	s_waitcnt lgkmcnt(0)
	s_waitcnt lgkmcnt(0)
	v_mfma_f32_16x16x32_bf16 v[118:121], v[216:219], v[174:177], v[118:121]
	v_mfma_f32_16x16x32_bf16 v[114:117], v[224:227], v[174:177], v[114:117]
	v_mfma_f32_16x16x32_bf16 v[102:105], v[216:219], v[192:195], v[102:105]
	v_mfma_f32_16x16x32_bf16 v[98:101], v[224:227], v[192:195], v[98:101]
	v_mfma_f32_16x16x32_bf16 v[86:89], v[216:219], v[200:203], v[86:89]
	v_mfma_f32_16x16x32_bf16 v[82:85], v[224:227], v[200:203], v[82:85]
	v_mfma_f32_16x16x32_bf16 v[70:73], v[216:219], v[208:211], v[70:73]
	v_mfma_f32_16x16x32_bf16 v[66:69], v[224:227], v[208:211], v[66:69]
	v_mfma_f32_16x16x32_bf16 v[118:121], v[220:223], v[188:191], v[118:121]
	v_mfma_f32_16x16x32_bf16 v[114:117], v[228:231], v[188:191], v[114:117]
	v_mfma_f32_16x16x32_bf16 v[102:105], v[220:223], v[196:199], v[102:105]
	v_mfma_f32_16x16x32_bf16 v[98:101], v[228:231], v[196:199], v[98:101]
	v_mfma_f32_16x16x32_bf16 v[86:89], v[220:223], v[204:207], v[86:89]
	v_mfma_f32_16x16x32_bf16 v[82:85], v[228:231], v[204:207], v[82:85]
	v_mfma_f32_16x16x32_bf16 v[70:73], v[220:223], v[212:215], v[70:73]
	v_mfma_f32_16x16x32_bf16 v[66:69], v[228:231], v[212:215], v[66:69]
	s_mov_b32 m0, s46
	v_lshl_add_u64 v[186:187], s[24:25], 0, v[136:137]
	s_barrier
	ds_read_b128 v[174:177], v154 offset:16384
	ds_read_b128 v[188:191], v154 offset:17408
	ds_read_b128 v[192:195], v154 offset:18432
	ds_read_b128 v[196:199], v154 offset:19456
	ds_read_b128 v[200:203], v154 offset:20480
	ds_read_b128 v[204:207], v154 offset:21504
	ds_read_b128 v[208:211], v154 offset:22528
	ds_read_b128 v[212:215], v154 offset:23552
	global_load_lds_dwordx4 v[186:187], off
	v_lshl_add_u64 v[244:245], s[24:25], 0, v[132:133]
	s_mov_b32 m0, s47
	s_nop 0
	global_load_lds_dwordx4 v[244:245], off
	s_barrier
	s_waitcnt lgkmcnt(0)
	s_waitcnt lgkmcnt(0)
	v_mfma_f32_16x16x32_bf16 v[62:65], v[146:149], v[174:177], v[62:65]
	v_mfma_f32_16x16x32_bf16 v[58:61], v[166:169], v[174:177], v[58:61]
	v_mfma_f32_16x16x32_bf16 v[46:49], v[146:149], v[192:195], v[46:49]
	v_mfma_f32_16x16x32_bf16 v[42:45], v[166:169], v[192:195], v[42:45]
	v_mfma_f32_16x16x32_bf16 v[30:33], v[146:149], v[200:203], v[30:33]
	v_mfma_f32_16x16x32_bf16 v[26:29], v[166:169], v[200:203], v[26:29]
	v_mfma_f32_16x16x32_bf16 v[14:17], v[146:149], v[208:211], v[14:17]
	v_mfma_f32_16x16x32_bf16 v[10:13], v[166:169], v[208:211], v[10:13]
	v_mfma_f32_16x16x32_bf16 v[62:65], v[162:165], v[188:191], v[62:65]
	v_mfma_f32_16x16x32_bf16 v[58:61], v[170:173], v[188:191], v[58:61]
	v_mfma_f32_16x16x32_bf16 v[46:49], v[162:165], v[196:199], v[46:49]
	v_mfma_f32_16x16x32_bf16 v[42:45], v[170:173], v[196:199], v[42:45]
	v_mfma_f32_16x16x32_bf16 v[30:33], v[162:165], v[204:207], v[30:33]
	v_mfma_f32_16x16x32_bf16 v[26:29], v[170:173], v[204:207], v[26:29]
	v_mfma_f32_16x16x32_bf16 v[14:17], v[162:165], v[212:215], v[14:17]
	v_mfma_f32_16x16x32_bf16 v[10:13], v[170:173], v[212:215], v[10:13]
	s_barrier
	s_add_u32 s38, s4, 0x80000
	s_addc_u32 s39, s5, 0
	s_add_i32 s60, s61, s45
	v_lshl_add_u64 v[146:147], s[38:39], 0, v[134:135]
	s_mov_b32 m0, s60
	s_nop 0
	global_load_lds_dwordx4 v[146:147], off
	v_lshl_add_u64 v[146:147], s[38:39], 0, v[130:131]
	s_add_i32 m0, s60, 0x2000
	s_nop 0
	global_load_lds_dwordx4 v[146:147], off
	s_waitcnt vmcnt(6)
	s_barrier
	v_mfma_f32_16x16x32_bf16 v[54:57], v[216:219], v[174:177], v[54:57]
	v_mfma_f32_16x16x32_bf16 v[50:53], v[224:227], v[174:177], v[50:53]
	v_mfma_f32_16x16x32_bf16 v[38:41], v[216:219], v[192:195], v[38:41]
	v_mfma_f32_16x16x32_bf16 v[34:37], v[224:227], v[192:195], v[34:37]
	v_mfma_f32_16x16x32_bf16 v[22:25], v[216:219], v[200:203], v[22:25]
	v_mfma_f32_16x16x32_bf16 v[18:21], v[224:227], v[200:203], v[18:21]
	v_mfma_f32_16x16x32_bf16 v[6:9], v[216:219], v[208:211], v[6:9]
	v_mfma_f32_16x16x32_bf16 v[2:5], v[224:227], v[208:211], v[2:5]
	v_mfma_f32_16x16x32_bf16 v[54:57], v[220:223], v[188:191], v[54:57]
	v_mfma_f32_16x16x32_bf16 v[50:53], v[228:231], v[188:191], v[50:53]
	v_mfma_f32_16x16x32_bf16 v[38:41], v[220:223], v[196:199], v[38:41]
	v_mfma_f32_16x16x32_bf16 v[34:37], v[228:231], v[196:199], v[34:37]
	v_mfma_f32_16x16x32_bf16 v[22:25], v[220:223], v[204:207], v[22:25]
	v_mfma_f32_16x16x32_bf16 v[18:21], v[228:231], v[204:207], v[18:21]
	v_mfma_f32_16x16x32_bf16 v[6:9], v[220:223], v[212:215], v[6:9]
	v_mfma_f32_16x16x32_bf16 v[2:5], v[228:231], v[212:215], v[2:5]
	s_add_i32 s38, 0, 0x18000
	v_add_u32_e32 v0, s38, v152
	s_barrier
	ds_read_b128 v[146:149], v0
	ds_read_b128 v[162:165], v0 offset:1024
	ds_read_b128 v[166:169], v0 offset:2048
	ds_read_b128 v[170:173], v0 offset:3072
	s_add_u32 s24, s24, 0x80000
	s_addc_u32 s25, s25, 0
	s_mov_b32 m0, s48
	v_lshl_add_u64 v[216:217], s[24:25], 0, v[136:137]
	ds_read_b128 v[174:177], v154 offset:32768
	ds_read_b128 v[188:191], v154 offset:33792
	ds_read_b128 v[192:195], v154 offset:34816
	ds_read_b128 v[196:199], v154 offset:35840
	ds_read_b128 v[200:203], v154 offset:36864
	ds_read_b128 v[204:207], v154 offset:37888
	ds_read_b128 v[208:211], v154 offset:38912
	ds_read_b128 v[212:215], v154 offset:39936
	global_load_lds_dwordx4 v[216:217], off
	v_lshl_add_u64 v[216:217], s[24:25], 0, v[132:133]
	s_mov_b32 m0, s49
	s_nop 0
	global_load_lds_dwordx4 v[216:217], off
	s_waitcnt lgkmcnt(8)
	s_barrier
; #define PG8_STAGE(bufoff, gbase, voff) do { _Pragma("unroll") for (int _i = 0; _i < 2; ++_i) \
;         __builtin_amdgcn_global_load_lds((const unsigned*)((const char*)(gbase) + (voff)[_i]), (LAS unsigned*)(lds + (bufoff) + ldsw + _i * 8192), 16, 0, 0); } while (0)
; #define PG8_LDA(dst, b, h) do { _Pragma("unroll") for (int m = 0; m < 4; ++m) _Pragma("unroll") for (int k = 0; k < 2; ++k) dst[m][k] = *(const LAS bf16x8*)(lds + PG8_SA(b, h) + aoff + m * 2048 + k * 1024); } while (0)
; #define PG8_LDB(dst, b, h) do { _Pragma("unroll") for (int n = 0; n < 2; ++n) _Pragma("unroll") for (int k = 0; k < 2; ++k) dst[n][k] = *(const LAS bf16x8*)(lds + PG8_SB(b, h) + boff + n * 2048 + k * 1024); } while (0)
; #define PG8_MMA(ai, bj, At, Bt) do { __builtin_amdgcn_s_setprio(1); _Pragma("unroll") for (int m = 0; m < 4; ++m) _Pragma("unroll") for (int n = 0; n < 2; ++n) _Pragma("unroll") for (int k = 0; k < 2; ++k) \
;         acc[ai][bj][m][n] = __builtin_amdgcn_mfma_f32_16x16x32_bf16(Bt[n][k], At[m][k], acc[ai][bj][m][n], 0, 0, 0); __builtin_amdgcn_s_setprio(0); } while (0)
; #define PG8_WAIT_L(n) asm volatile("s_waitcnt lgkmcnt(" #n ")" ::: "memory")
; #define PG8_BAR __builtin_amdgcn_s_barrier()
; #define PG8_SCHED __builtin_amdgcn_sched_barrier(0)
; template <class Epi>
; __device__ __forceinline__ void gemm_phase(LAS unsigned char* lds, const Gemm g, const StaticOrder& S, const Epi& E) {
;     ...
;             PG8_WAIT_L(8); PG8_BAR; PG8_WAIT_L(0); PG8_MMA(0, 0, At, B0); PG8_BAR; PG8_SCHED;
;             PG8_LDB(B1, 1, 1); PG8_STAGE(PG8_SB(1, 0), b3, voffB);
;             PG8_BAR; PG8_WAIT_L(0); PG8_MMA(0, 1, At, B1); PG8_BAR;
;             PG8_LDA(At, 1, 1); PG8_STAGE(PG8_SA(1, 0), a3, voffA);
	s_waitcnt lgkmcnt(0)
	s_waitcnt lgkmcnt(0)
	v_mfma_f32_16x16x32_bf16 v[126:129], v[146:149], v[174:177], v[126:129]
	v_mfma_f32_16x16x32_bf16 v[122:125], v[166:169], v[174:177], v[122:125]
	v_mfma_f32_16x16x32_bf16 v[110:113], v[146:149], v[192:195], v[110:113]
	v_mfma_f32_16x16x32_bf16 v[106:109], v[166:169], v[192:195], v[106:109]
	v_mfma_f32_16x16x32_bf16 v[94:97], v[146:149], v[200:203], v[94:97]
	v_mfma_f32_16x16x32_bf16 v[90:93], v[166:169], v[200:203], v[90:93]
	v_mfma_f32_16x16x32_bf16 v[78:81], v[146:149], v[208:211], v[78:81]
	v_mfma_f32_16x16x32_bf16 v[74:77], v[166:169], v[208:211], v[74:77]
	v_mfma_f32_16x16x32_bf16 v[126:129], v[162:165], v[188:191], v[126:129]
	v_mfma_f32_16x16x32_bf16 v[122:125], v[170:173], v[188:191], v[122:125]
	v_mfma_f32_16x16x32_bf16 v[110:113], v[162:165], v[196:199], v[110:113]
	v_mfma_f32_16x16x32_bf16 v[106:109], v[170:173], v[196:199], v[106:109]
	v_mfma_f32_16x16x32_bf16 v[94:97], v[162:165], v[204:207], v[94:97]
	v_mfma_f32_16x16x32_bf16 v[90:93], v[170:173], v[204:207], v[90:93]
	v_mfma_f32_16x16x32_bf16 v[78:81], v[162:165], v[212:215], v[78:81]
	v_mfma_f32_16x16x32_bf16 v[74:77], v[170:173], v[212:215], v[74:77]
	s_barrier
	s_add_i32 s24, 0, 0x1c000
	s_add_i32 s25, s38, s45
	v_add_u32_e32 v0, s24, v152
	v_lshl_add_u64 v[150:151], v[150:151], 0, s[6:7]
	s_mov_b32 m0, s25
	ds_read_b128 v[216:219], v0
	ds_read_b128 v[220:223], v0 offset:1024
	ds_read_b128 v[224:227], v0 offset:2048
	ds_read_b128 v[228:231], v0 offset:3072
	global_load_lds_dwordx4 v[150:151], off
	v_lshl_add_u64 v[150:151], v[184:185], 0, s[6:7]
	s_add_i32 m0, s25, 0x2000
	s_nop 0
	global_load_lds_dwordx4 v[150:151], off
	s_barrier
	s_waitcnt lgkmcnt(0)
	s_waitcnt lgkmcnt(0)
	v_mfma_f32_16x16x32_bf16 v[118:121], v[216:219], v[174:177], v[118:121]
	v_mfma_f32_16x16x32_bf16 v[114:117], v[224:227], v[174:177], v[114:117]
	v_mfma_f32_16x16x32_bf16 v[102:105], v[216:219], v[192:195], v[102:105]
	v_mfma_f32_16x16x32_bf16 v[98:101], v[224:227], v[192:195], v[98:101]
	v_mfma_f32_16x16x32_bf16 v[86:89], v[216:219], v[200:203], v[86:89]
	v_mfma_f32_16x16x32_bf16 v[82:85], v[224:227], v[200:203], v[82:85]
	v_mfma_f32_16x16x32_bf16 v[70:73], v[216:219], v[208:211], v[70:73]
	v_mfma_f32_16x16x32_bf16 v[66:69], v[224:227], v[208:211], v[66:69]
	v_mfma_f32_16x16x32_bf16 v[118:121], v[220:223], v[188:191], v[118:121]
	v_mfma_f32_16x16x32_bf16 v[114:117], v[228:231], v[188:191], v[114:117]
	v_mfma_f32_16x16x32_bf16 v[102:105], v[220:223], v[196:199], v[102:105]
	v_mfma_f32_16x16x32_bf16 v[98:101], v[228:231], v[196:199], v[98:101]
	v_mfma_f32_16x16x32_bf16 v[86:89], v[220:223], v[204:207], v[86:89]
	v_mfma_f32_16x16x32_bf16 v[82:85], v[228:231], v[204:207], v[82:85]
	v_mfma_f32_16x16x32_bf16 v[70:73], v[220:223], v[212:215], v[70:73]
	v_mfma_f32_16x16x32_bf16 v[66:69], v[228:231], v[212:215], v[66:69]
	s_mov_b32 m0, s50
	v_lshl_add_u64 v[150:151], v[186:187], 0, s[6:7]
	s_barrier
	ds_read_b128 v[174:177], v154 offset:49152
	ds_read_b128 v[188:191], v154 offset:50176
	ds_read_b128 v[192:195], v154 offset:51200
	ds_read_b128 v[196:199], v154 offset:52224
	ds_read_b128 v[200:203], v154 offset:53248
	ds_read_b128 v[204:207], v154 offset:54272
	ds_read_b128 v[208:211], v154 offset:55296
	ds_read_b128 v[212:215], v154 offset:56320
	global_load_lds_dwordx4 v[150:151], off
	v_lshl_add_u64 v[150:151], v[244:245], 0, s[6:7]
	s_mov_b32 m0, s51
	s_nop 0
	global_load_lds_dwordx4 v[150:151], off
	s_barrier
; __device__ __forceinline__ unsigned cvt_pk_bf16(float lo, float hi) { unsigned r; asm volatile("v_cvt_pk_bf16_f32 %0, %1, %2" : "=v"(r) : "v"(lo), "v"(hi)); return r; }
; #define PG8_STAGE(bufoff, gbase, voff) do { _Pragma("unroll") for (int _i = 0; _i < 2; ++_i) \
;         __builtin_amdgcn_global_load_lds((const unsigned*)((const char*)(gbase) + (voff)[_i]), (LAS unsigned*)(lds + (bufoff) + ldsw + _i * 8192), 16, 0, 0); } while (0)
; #define PG8_MMA(ai, bj, At, Bt) do { __builtin_amdgcn_s_setprio(1); _Pragma("unroll") for (int m = 0; m < 4; ++m) _Pragma("unroll") for (int n = 0; n < 2; ++n) _Pragma("unroll") for (int k = 0; k < 2; ++k) \
;         acc[ai][bj][m][n] = __builtin_amdgcn_mfma_f32_16x16x32_bf16(Bt[n][k], At[m][k], acc[ai][bj][m][n], 0, 0, 0); __builtin_amdgcn_s_setprio(0); } while (0)
; #define PG8_WAIT_V(n) asm volatile("s_waitcnt vmcnt(" #n ")" ::: "memory")
; #define PG8_WAIT_L(n) asm volatile("s_waitcnt lgkmcnt(" #n ")" ::: "memory")
; template <class Epi>
; __device__ __forceinline__ void gemm_phase(LAS unsigned char* lds, const Gemm g, const StaticOrder& S, const Epi& E) {
;     ...
;             PG8_BAR; PG8_WAIT_L(0); PG8_MMA(1, 0, At, B0); PG8_BAR; PG8_SCHED;
;             PG8_STAGE(PG8_SB(1, 1), b3 + hstepB, voffB);
;             PG8_WAIT_V(6); PG8_BAR; PG8_MMA(1, 1, At, B1); PG8_BAR;
;     __device__ __forceinline__ void operator()(const f32x4 (&acc)[2][2][4][2], const Unit& u, int wr, int wc, int fr, int fq, const Pre& pp) const {
;         const int row0 = u.pm * BM + wr * 64 + fr, col0 = u.pn * BM + wc * 32 + 8 * fq;
;         const bool gm = (UG != nullptr) && (u.pn < DE / BM);
;         const float (&rs)[8] = pp.rs;
; #pragma unroll
;         for (int ai = 0; ai < 2; ++ai)
; #pragma unroll
;             for (int m = 0; m < 4; ++m) { const int r = row0 + ai * HALF + m * 16; const float inv = rsqrtf(rs[ai * 4 + m] * (1.0f / DM) + EPS);
; #pragma unroll
;                 for (int bj = 0; bj < 2; ++bj) { const f32x4 v0 = acc[ai][bj][m][0] * inv, v1 = acc[ai][bj][m][1] * inv; const int c = col0 + bj * HALF;
;                     u32x4 w; w.x = cvt_pk_bf16(v0[0], v0[1]); w.y = cvt_pk_bf16(v0[2], v0[3]); w.z = cvt_pk_bf16(v1[0], v1[1]); w.w = cvt_pk_bf16(v1[2], v1[3]);
;                     bf16_t* dst = gm ? UG + (size_t)(c >> 4) * GSTR + r * 16 + (c & 15) : O + (size_t)r * DE2 + c;
;                     *(u32x4*)dst = w; } }
	s_waitcnt lgkmcnt(0)
	s_waitcnt lgkmcnt(0)
	v_mfma_f32_16x16x32_bf16 v[62:65], v[146:149], v[174:177], v[62:65]
	v_mfma_f32_16x16x32_bf16 v[58:61], v[166:169], v[174:177], v[58:61]
	v_mfma_f32_16x16x32_bf16 v[46:49], v[146:149], v[192:195], v[46:49]
	v_mfma_f32_16x16x32_bf16 v[42:45], v[166:169], v[192:195], v[42:45]
	v_mfma_f32_16x16x32_bf16 v[30:33], v[146:149], v[200:203], v[30:33]
	v_mfma_f32_16x16x32_bf16 v[26:29], v[166:169], v[200:203], v[26:29]
	v_mfma_f32_16x16x32_bf16 v[14:17], v[146:149], v[208:211], v[14:17]
	v_mfma_f32_16x16x32_bf16 v[10:13], v[166:169], v[208:211], v[10:13]
	v_mfma_f32_16x16x32_bf16 v[62:65], v[162:165], v[188:191], v[62:65]
	v_mfma_f32_16x16x32_bf16 v[58:61], v[170:173], v[188:191], v[58:61]
	v_mfma_f32_16x16x32_bf16 v[46:49], v[162:165], v[196:199], v[46:49]
	v_mfma_f32_16x16x32_bf16 v[42:45], v[170:173], v[196:199], v[42:45]
	v_mfma_f32_16x16x32_bf16 v[30:33], v[162:165], v[204:207], v[30:33]
	v_mfma_f32_16x16x32_bf16 v[26:29], v[170:173], v[204:207], v[26:29]
	v_mfma_f32_16x16x32_bf16 v[14:17], v[162:165], v[212:215], v[14:17]
	v_mfma_f32_16x16x32_bf16 v[10:13], v[170:173], v[212:215], v[10:13]
	s_barrier
	s_add_u32 s4, s4, 0x80080
	s_addc_u32 s5, s5, 0
	s_add_i32 s24, s24, s45
	v_lshl_add_u64 v[146:147], s[4:5], 0, v[134:135]
	s_mov_b32 m0, s24
	s_nop 0
	global_load_lds_dwordx4 v[146:147], off
	v_lshl_add_u64 v[146:147], s[4:5], 0, v[130:131]
	s_add_i32 m0, s24, 0x2000
	s_nop 0
	global_load_lds_dwordx4 v[146:147], off
	s_waitcnt vmcnt(6)
	s_barrier
	v_mfma_f32_16x16x32_bf16 v[54:57], v[216:219], v[174:177], v[54:57]
	v_mfma_f32_16x16x32_bf16 v[50:53], v[224:227], v[174:177], v[50:53]
	v_mfma_f32_16x16x32_bf16 v[38:41], v[216:219], v[192:195], v[38:41]
	v_mfma_f32_16x16x32_bf16 v[34:37], v[224:227], v[192:195], v[34:37]
	v_mfma_f32_16x16x32_bf16 v[22:25], v[216:219], v[200:203], v[22:25]
	v_mfma_f32_16x16x32_bf16 v[18:21], v[224:227], v[200:203], v[18:21]
	v_mfma_f32_16x16x32_bf16 v[6:9], v[216:219], v[208:211], v[6:9]
	v_mfma_f32_16x16x32_bf16 v[2:5], v[224:227], v[208:211], v[2:5]
	v_mfma_f32_16x16x32_bf16 v[54:57], v[220:223], v[188:191], v[54:57]
	v_mfma_f32_16x16x32_bf16 v[50:53], v[228:231], v[188:191], v[50:53]
	v_mfma_f32_16x16x32_bf16 v[38:41], v[220:223], v[196:199], v[38:41]
	v_mfma_f32_16x16x32_bf16 v[34:37], v[228:231], v[196:199], v[34:37]
	v_mfma_f32_16x16x32_bf16 v[22:25], v[220:223], v[204:207], v[22:25]
	v_mfma_f32_16x16x32_bf16 v[18:21], v[228:231], v[204:207], v[18:21]
	v_mfma_f32_16x16x32_bf16 v[6:9], v[220:223], v[212:215], v[6:9]
	v_mfma_f32_16x16x32_bf16 v[2:5], v[228:231], v[212:215], v[2:5]
	s_add_i32 s59, s59, 2
	s_add_u32 s57, s57, 0x100
	s_addc_u32 s58, s58, 0
	s_cmp_gt_u32 s59, 29
	s_mov_b64 s[38:39], s[42:43]
	s_barrier
	s_cbranch_scc0 .LBB0_158
	s_setprio 0
	v_fmamk_f32 v0, v145, 0x3a000000, v233
	v_cmp_gt_f32_e32 vcc, s66, v0
	v_mul_f32_e32 v145, 0x4b800000, v0
	v_readlane_b32 s38, v254, 47
	v_cndmask_b32_e32 v0, v0, v145, vcc
	v_rsq_f32_e32 v0, v0
	v_lshl_add_u32 v146, s54, 8, v139
	s_cmp_gt_i32 s53, 15
	v_readlane_b32 s39, v254, 48
	v_mul_f32_e32 v145, 0x45800000, v0
	s_cselect_b64 s[4:5], -1, 0
	s_xor_b64 s[38:39], s[38:39], -1
	v_cndmask_b32_e32 v148, v0, v145, vcc
	v_ashrrev_i32_e32 v147, 31, v146
	s_or_b64 s[4:5], s[38:39], s[4:5]
	v_lshl_or_b32 v144, s53, 8, v153
	v_lshlrev_b64 v[150:151], 14, v[146:147]
	v_pk_mul_f32 v[128:129], v[148:149], v[128:129] op_sel_hi:[0,1]
	s_mov_b64 s[24:25], -1
	v_pk_mul_f32 v[126:127], v[148:149], v[126:127] op_sel_hi:[0,1]
	v_pk_mul_f32 v[162:163], v[148:149], v[124:125] op_sel_hi:[0,1]
	v_pk_mul_f32 v[124:125], v[148:149], v[122:123] op_sel_hi:[0,1]
	v_cvt_pk_bf16_f32 v122, v126, v127
	v_cvt_pk_bf16_f32 v123, v128, v129
	s_and_b64 vcc, exec, s[4:5]
	v_lshl_add_u64 v[128:129], s[16:17], 0, v[150:151]
	v_ashrrev_i32_e32 v145, 31, v144
	v_cvt_pk_bf16_f32 v124, v124, v125
	v_cvt_pk_bf16_f32 v125, v162, v163
	s_cbranch_vccz .LBB0_161
	v_lshl_add_u64 v[150:151], v[144:145], 1, v[128:129]
	s_mov_b64 s[24:25], 0

; #define PG8_STAGE(bufoff, gbase, voff) do { _Pragma("unroll") for (int _i = 0; _i < 2; ++_i) \
;         __builtin_amdgcn_global_load_lds((const unsigned*)((const char*)(gbase) + (voff)[_i]), (LAS unsigned*)(lds + (bufoff) + ldsw + _i * 8192), 16, 0, 0); } while (0)
; #define PG8_LDA(dst, b, h) do { _Pragma("unroll") for (int m = 0; m < 4; ++m) _Pragma("unroll") for (int k = 0; k < 2; ++k) dst[m][k] = *(const LAS bf16x8*)(lds + PG8_SA(b, h) + aoff + m * 2048 + k * 1024); } while (0)
; #define PG8_LDB(dst, b, h) do { _Pragma("unroll") for (int n = 0; n < 2; ++n) _Pragma("unroll") for (int k = 0; k < 2; ++k) dst[n][k] = *(const LAS bf16x8*)(lds + PG8_SB(b, h) + boff + n * 2048 + k * 1024); } while (0)
; #define PG8_MMA(ai, bj, At, Bt) do { __builtin_amdgcn_s_setprio(1); _Pragma("unroll") for (int m = 0; m < 4; ++m) _Pragma("unroll") for (int n = 0; n < 2; ++n) _Pragma("unroll") for (int k = 0; k < 2; ++k) \
;         acc[ai][bj][m][n] = __builtin_amdgcn_mfma_f32_16x16x32_bf16(Bt[n][k], At[m][k], acc[ai][bj][m][n], 0, 0, 0); __builtin_amdgcn_s_setprio(0); } while (0)
; #define PG8_WAIT_L(n) asm volatile("s_waitcnt lgkmcnt(" #n ")" ::: "memory")
; template <class Epi>
; __device__ __forceinline__ void gemm_phase(LAS unsigned char* lds, const Gemm g, const StaticOrder& S, const Epi& E) {
;     ...
;         const bool has_next = S.next(ui + 1, nxt);
;         const char* nA = has_next ? (const char*)g.A + (size_t)nxt.pm * tstepA + (size_t)(nxt.pn >> 2) * gstepA : cA; const char* nB = has_next ? (const char*)g.Bt + (size_t)nxt.pn * tstepB : cB;
;         for (int t = 0; t < nt; t += 2) {
;             const bool last = (t == nt - 2);
;             const char* a1 = cA + (size_t)(t + 1) * kstepA;
;             const char* a2 = last ? nA : cA + (size_t)(t + 2) * kstepA; const char* b2 = last ? nB : cB + (size_t)(t + 2) * kstep;
;             const char* a3 = a2 + kstepA; const char* b3 = b2 + kstep;
;             PG8_LDB(B0, 0, 0); PG8_SCHED; PG8_LDA(At, 0, 0); PG8_STAGE(PG8_SA(1, 1), a1 + hstepA, voffA);
;             PG8_WAIT_L(8); PG8_BAR; PG8_WAIT_L(0); PG8_MMA(0, 0, At, B0); PG8_BAR; PG8_SCHED;
;     ...
;         for (int a = 0; a < 2; ++a)
; #pragma unroll
;             for (int b = 0; b < 2; ++b)
; #pragma unroll
;                 for (int m = 0; m < 4; ++m)
; #pragma unroll
;                     for (int n = 0; n < 2; ++n) acc[a][b][m][n] = (f32x4){0.f, 0.f, 0.f, 0.f};
.LBB0_358:
	v_mov_b64_e32 v[2:3], 0x100
	s_ashr_i32 s17, s16, 31
	v_cmp_lt_i64_e32 vcc, s[18:19], v[2:3]
	s_lshl_b64 s[18:19], s[16:17], 21
	s_add_u32 s18, s38, s18
	s_addc_u32 s19, s39, s19
	s_and_b64 s[20:21], vcc, exec
	s_cselect_b32 s17, s19, s23
	s_cselect_b32 s60, s18, s22
	s_ashr_i32 s15, s14, 31
	s_lshl_b64 s[20:21], s[14:15], 21
	s_add_u32 s20, s46, s20
	s_addc_u32 s21, s47, s21
	s_and_b64 s[24:25], vcc, exec
	s_cselect_b32 s15, s21, s27
	s_cselect_b32 s61, s20, s26
	s_add_u32 s62, s26, 0x100
	v_mov_b32_e32 v2, 0
	s_addc_u32 s63, s27, 0
	s_mov_b32 s64, -2
	v_mov_b32_e32 v3, v2
	v_mov_b32_e32 v4, v2
	v_mov_b32_e32 v5, v2
	v_mov_b32_e32 v6, v2
	v_mov_b32_e32 v7, v2
	v_mov_b32_e32 v8, v2
	v_mov_b32_e32 v9, v2
	v_mov_b32_e32 v18, v2
	v_mov_b32_e32 v19, v2
	v_mov_b32_e32 v20, v2
	v_mov_b32_e32 v21, v2
	v_mov_b32_e32 v22, v2
	v_mov_b32_e32 v23, v2
	v_mov_b32_e32 v24, v2
	v_mov_b32_e32 v25, v2
	v_mov_b32_e32 v34, v2
	v_mov_b32_e32 v35, v2
	v_mov_b32_e32 v36, v2
	v_mov_b32_e32 v37, v2
	v_mov_b32_e32 v38, v2
	v_mov_b32_e32 v39, v2
	v_mov_b32_e32 v40, v2
	v_mov_b32_e32 v41, v2
	v_mov_b32_e32 v50, v2
	v_mov_b32_e32 v51, v2
	v_mov_b32_e32 v52, v2
	v_mov_b32_e32 v53, v2
	v_mov_b32_e32 v54, v2
	v_mov_b32_e32 v55, v2
	v_mov_b32_e32 v56, v2
	v_mov_b32_e32 v57, v2
	v_mov_b32_e32 v10, v2
	v_mov_b32_e32 v11, v2
	v_mov_b32_e32 v12, v2
	v_mov_b32_e32 v13, v2
	v_mov_b32_e32 v14, v2
	v_mov_b32_e32 v15, v2
	v_mov_b32_e32 v16, v2
	v_mov_b32_e32 v17, v2
	v_mov_b32_e32 v26, v2
	v_mov_b32_e32 v27, v2
	v_mov_b32_e32 v28, v2
	v_mov_b32_e32 v29, v2
	v_mov_b32_e32 v30, v2
	v_mov_b32_e32 v31, v2
	v_mov_b32_e32 v32, v2
	v_mov_b32_e32 v33, v2
	v_mov_b32_e32 v42, v2
	v_mov_b32_e32 v43, v2
	v_mov_b32_e32 v44, v2
	v_mov_b32_e32 v45, v2
	v_mov_b32_e32 v46, v2
	v_mov_b32_e32 v47, v2
	v_mov_b32_e32 v48, v2
	v_mov_b32_e32 v49, v2
	v_mov_b32_e32 v58, v2
	v_mov_b32_e32 v59, v2
	v_mov_b32_e32 v60, v2
	v_mov_b32_e32 v61, v2
	v_mov_b32_e32 v62, v2
	v_mov_b32_e32 v63, v2
	v_mov_b32_e32 v64, v2
	v_mov_b32_e32 v65, v2
	v_mov_b32_e32 v66, v2
	v_mov_b32_e32 v67, v2
	v_mov_b32_e32 v68, v2
	v_mov_b32_e32 v69, v2
	v_mov_b32_e32 v78, v2
	v_mov_b32_e32 v79, v2
	v_mov_b32_e32 v80, v2
	v_mov_b32_e32 v81, v2
	v_mov_b32_e32 v98, v2
	v_mov_b32_e32 v99, v2
	v_mov_b32_e32 v100, v2
	v_mov_b32_e32 v101, v2
	v_mov_b32_e32 v102, v2
	v_mov_b32_e32 v103, v2
	v_mov_b32_e32 v104, v2
	v_mov_b32_e32 v105, v2
	v_mov_b32_e32 v114, v2
	v_mov_b32_e32 v115, v2
	v_mov_b32_e32 v116, v2
	v_mov_b32_e32 v117, v2
	v_mov_b32_e32 v118, v2
	v_mov_b32_e32 v119, v2
	v_mov_b32_e32 v120, v2
	v_mov_b32_e32 v121, v2
	v_mov_b32_e32 v130, v2
	v_mov_b32_e32 v131, v2
	v_mov_b32_e32 v132, v2
	v_mov_b32_e32 v133, v2
	v_mov_b32_e32 v134, v2
	v_mov_b32_e32 v135, v2
	v_mov_b32_e32 v136, v2
	v_mov_b32_e32 v137, v2
	v_mov_b32_e32 v90, v2
	v_mov_b32_e32 v91, v2
	v_mov_b32_e32 v92, v2
	v_mov_b32_e32 v93, v2
	v_mov_b32_e32 v94, v2
	v_mov_b32_e32 v95, v2
	v_mov_b32_e32 v96, v2
	v_mov_b32_e32 v97, v2
	v_mov_b32_e32 v106, v2
	v_mov_b32_e32 v107, v2
	v_mov_b32_e32 v108, v2
	v_mov_b32_e32 v109, v2
	v_mov_b32_e32 v110, v2
	v_mov_b32_e32 v111, v2
	v_mov_b32_e32 v112, v2
	v_mov_b32_e32 v113, v2
	v_mov_b32_e32 v122, v2
	v_mov_b32_e32 v123, v2
	v_mov_b32_e32 v124, v2
	v_mov_b32_e32 v125, v2
	v_mov_b32_e32 v126, v2
	v_mov_b32_e32 v127, v2
	v_mov_b32_e32 v128, v2
	v_mov_b32_e32 v129, v2
	v_mov_b32_e32 v138, v2
	v_mov_b32_e32 v139, v2
	v_mov_b32_e32 v140, v2
	v_mov_b32_e32 v141, v2
	v_mov_b32_e32 v142, v2
	v_mov_b32_e32 v143, v2
	v_mov_b32_e32 v144, v2
	v_mov_b32_e32 v145, v2
	v_readfirstlane_b32 s100, v232
	s_nop 3
	s_cmp_ge_u32 s100, 0x100
	s_cbranch_scc0 .Lprio_skip_1
	s_setprio 1
.Lprio_skip_1:
.LBB0_359:
	s_add_u32 s26, s22, 0x100
	s_addc_u32 s27, s23, 0
	s_add_i32 s65, 0, 0x10000
	v_add_u32_e32 v86, s65, v209
	ds_read_b128 v[70:73], v86
	ds_read_b128 v[74:77], v86 offset:1024
	ds_read_b128 v[82:85], v86 offset:2048
	ds_read_b128 v[86:89], v86 offset:3072
	s_cmp_eq_u32 s64, 60
	s_cselect_b32 s25, s17, s27
	s_cselect_b32 s24, s60, s26
	s_cselect_b32 s37, s15, s63
	s_cselect_b32 s36, s61, s62
	v_lshl_add_u64 v[194:195], s[22:23], 0, v[190:191]
	s_add_i32 m0, s53, 0xc000
	ds_read_b128 v[146:149], v211
	ds_read_b128 v[150:153], v211 offset:1024
	ds_read_b128 v[154:157], v211 offset:2048
	ds_read_b128 v[158:161], v211 offset:3072
	ds_read_b128 v[162:165], v211 offset:4096
	ds_read_b128 v[166:169], v211 offset:5120
	ds_read_b128 v[170:173], v211 offset:6144
	ds_read_b128 v[184:187], v211 offset:7168
	global_load_lds_dwordx4 v[194:195], off
	v_lshl_add_u64 v[194:195], s[22:23], 0, v[192:193]
	s_add_i32 m0, s53, 0xe000
	s_nop 0
	global_load_lds_dwordx4 v[194:195], off
	s_waitcnt lgkmcnt(8)
	s_barrier
	s_waitcnt lgkmcnt(0)
	s_waitcnt lgkmcnt(0)
	v_mfma_f32_16x16x32_bf16 v[142:145], v[70:73], v[146:149], v[142:145]
	v_mfma_f32_16x16x32_bf16 v[138:141], v[82:85], v[146:149], v[138:141]
	v_mfma_f32_16x16x32_bf16 v[126:129], v[70:73], v[154:157], v[126:129]
	v_mfma_f32_16x16x32_bf16 v[122:125], v[82:85], v[154:157], v[122:125]
	v_mfma_f32_16x16x32_bf16 v[110:113], v[70:73], v[162:165], v[110:113]
	v_mfma_f32_16x16x32_bf16 v[106:109], v[82:85], v[162:165], v[106:109]
	v_mfma_f32_16x16x32_bf16 v[94:97], v[70:73], v[170:173], v[94:97]
	v_mfma_f32_16x16x32_bf16 v[90:93], v[82:85], v[170:173], v[90:93]
	v_mfma_f32_16x16x32_bf16 v[142:145], v[74:77], v[150:153], v[142:145]
	v_mfma_f32_16x16x32_bf16 v[138:141], v[86:89], v[150:153], v[138:141]
	v_mfma_f32_16x16x32_bf16 v[126:129], v[74:77], v[158:161], v[126:129]
	v_mfma_f32_16x16x32_bf16 v[122:125], v[86:89], v[158:161], v[122:125]
	v_mfma_f32_16x16x32_bf16 v[110:113], v[74:77], v[166:169], v[110:113]
	v_mfma_f32_16x16x32_bf16 v[106:109], v[86:89], v[166:169], v[106:109]
	v_mfma_f32_16x16x32_bf16 v[94:97], v[74:77], v[184:187], v[94:97]
	v_mfma_f32_16x16x32_bf16 v[90:93], v[86:89], v[184:187], v[90:93]
	s_barrier
; #define PG8_STAGE(bufoff, gbase, voff) do { _Pragma("unroll") for (int _i = 0; _i < 2; ++_i) \
;         __builtin_amdgcn_global_load_lds((const unsigned*)((const char*)(gbase) + (voff)[_i]), (LAS unsigned*)(lds + (bufoff) + ldsw + _i * 8192), 16, 0, 0); } while (0)
; #define PG8_LDA(dst, b, h) do { _Pragma("unroll") for (int m = 0; m < 4; ++m) _Pragma("unroll") for (int k = 0; k < 2; ++k) dst[m][k] = *(const LAS bf16x8*)(lds + PG8_SA(b, h) + aoff + m * 2048 + k * 1024); } while (0)
; #define PG8_LDB(dst, b, h) do { _Pragma("unroll") for (int n = 0; n < 2; ++n) _Pragma("unroll") for (int k = 0; k < 2; ++k) dst[n][k] = *(const LAS bf16x8*)(lds + PG8_SB(b, h) + boff + n * 2048 + k * 1024); } while (0)
; #define PG8_MMA(ai, bj, At, Bt) do { __builtin_amdgcn_s_setprio(1); _Pragma("unroll") for (int m = 0; m < 4; ++m) _Pragma("unroll") for (int n = 0; n < 2; ++n) _Pragma("unroll") for (int k = 0; k < 2; ++k) \
;         acc[ai][bj][m][n] = __builtin_amdgcn_mfma_f32_16x16x32_bf16(Bt[n][k], At[m][k], acc[ai][bj][m][n], 0, 0, 0); __builtin_amdgcn_s_setprio(0); } while (0)
; #define PG8_WAIT_V(n) asm volatile("s_waitcnt vmcnt(" #n ")" ::: "memory")
; #define PG8_WAIT_L(n) asm volatile("s_waitcnt lgkmcnt(" #n ")" ::: "memory")
; #define PG8_BAR __builtin_amdgcn_s_barrier()
; #define PG8_SCHED __builtin_amdgcn_sched_barrier(0)
; template <class Epi>
; __device__ __forceinline__ void gemm_phase(LAS unsigned char* lds, const Gemm g, const StaticOrder& S, const Epi& E) {
;     ...
;             PG8_LDB(B1, 0, 1); PG8_STAGE(PG8_SB(0, 0), b2, voffB);
;             PG8_BAR; PG8_WAIT_L(0); PG8_MMA(0, 1, At, B1); PG8_BAR;
;             PG8_LDA(At, 0, 1); PG8_STAGE(PG8_SA(0, 0), a2, voffA);
;             PG8_BAR; PG8_WAIT_L(0); PG8_MMA(1, 0, At, B0); PG8_BAR; PG8_SCHED;
;             PG8_STAGE(PG8_SB(0, 1), b2 + hstepB, voffB);
;             PG8_WAIT_V(6); PG8_BAR; PG8_MMA(1, 1, At, B1); PG8_BAR;
;             PG8_LDB(B0, 1, 0); PG8_SCHED; PG8_LDA(At, 1, 0); PG8_STAGE(PG8_SA(0, 1), a2 + hstepA, voffA);
;             PG8_WAIT_L(8); PG8_BAR; PG8_WAIT_L(0); PG8_MMA(0, 0, At, B0); PG8_BAR; PG8_SCHED;
	s_add_i32 s66, 0, 0x14000
	v_add_u32_e32 v206, s66, v209
	s_add_i32 s22, s65, s52
	ds_read_b128 v[194:197], v206
	ds_read_b128 v[198:201], v206 offset:1024
	ds_read_b128 v[202:205], v206 offset:2048
	ds_read_b128 v[212:215], v206 offset:3072
	v_lshl_add_u64 v[206:207], s[36:37], 0, v[0:1]
	s_mov_b32 m0, s22
	v_lshl_add_u64 v[216:217], s[36:37], 0, v[174:175]
	global_load_lds_dwordx4 v[206:207], off
	s_add_i32 m0, s22, 0x2000
	s_nop 0
	global_load_lds_dwordx4 v[216:217], off
	s_barrier
	s_waitcnt lgkmcnt(0)
	s_waitcnt lgkmcnt(0)
	v_mfma_f32_16x16x32_bf16 v[134:137], v[194:197], v[146:149], v[134:137]
	v_mfma_f32_16x16x32_bf16 v[130:133], v[202:205], v[146:149], v[130:133]
	v_mfma_f32_16x16x32_bf16 v[118:121], v[194:197], v[154:157], v[118:121]
	v_mfma_f32_16x16x32_bf16 v[114:117], v[202:205], v[154:157], v[114:117]
	v_mfma_f32_16x16x32_bf16 v[102:105], v[194:197], v[162:165], v[102:105]
	v_mfma_f32_16x16x32_bf16 v[98:101], v[202:205], v[162:165], v[98:101]
	v_mfma_f32_16x16x32_bf16 v[78:81], v[194:197], v[170:173], v[78:81]
	v_mfma_f32_16x16x32_bf16 v[66:69], v[202:205], v[170:173], v[66:69]
	v_mfma_f32_16x16x32_bf16 v[134:137], v[198:201], v[150:153], v[134:137]
	v_mfma_f32_16x16x32_bf16 v[130:133], v[212:215], v[150:153], v[130:133]
	v_mfma_f32_16x16x32_bf16 v[118:121], v[198:201], v[158:161], v[118:121]
	v_mfma_f32_16x16x32_bf16 v[114:117], v[212:215], v[158:161], v[114:117]
	v_mfma_f32_16x16x32_bf16 v[102:105], v[198:201], v[166:169], v[102:105]
	v_mfma_f32_16x16x32_bf16 v[98:101], v[212:215], v[166:169], v[98:101]
	v_mfma_f32_16x16x32_bf16 v[78:81], v[198:201], v[184:187], v[78:81]
	v_mfma_f32_16x16x32_bf16 v[66:69], v[212:215], v[184:187], v[66:69]
	s_mov_b32 m0, s53
	v_lshl_add_u64 v[218:219], s[24:25], 0, v[188:189]
	s_barrier
	ds_read_b128 v[146:149], v211 offset:16384
	ds_read_b128 v[150:153], v211 offset:17408
	ds_read_b128 v[154:157], v211 offset:18432
	ds_read_b128 v[158:161], v211 offset:19456
	ds_read_b128 v[162:165], v211 offset:20480
	ds_read_b128 v[166:169], v211 offset:21504
	ds_read_b128 v[170:173], v211 offset:22528
	ds_read_b128 v[184:187], v211 offset:23552
	global_load_lds_dwordx4 v[218:219], off
	v_lshl_add_u64 v[220:221], s[24:25], 0, v[176:177]
	s_mov_b32 m0, s54
	s_nop 0
	global_load_lds_dwordx4 v[220:221], off
	s_barrier
	s_waitcnt lgkmcnt(0)
	s_waitcnt lgkmcnt(0)
	v_mfma_f32_16x16x32_bf16 v[62:65], v[70:73], v[146:149], v[62:65]
	v_mfma_f32_16x16x32_bf16 v[58:61], v[82:85], v[146:149], v[58:61]
	v_mfma_f32_16x16x32_bf16 v[46:49], v[70:73], v[154:157], v[46:49]
	v_mfma_f32_16x16x32_bf16 v[42:45], v[82:85], v[154:157], v[42:45]
	v_mfma_f32_16x16x32_bf16 v[30:33], v[70:73], v[162:165], v[30:33]
	v_mfma_f32_16x16x32_bf16 v[26:29], v[82:85], v[162:165], v[26:29]
	v_mfma_f32_16x16x32_bf16 v[14:17], v[70:73], v[170:173], v[14:17]
	v_mfma_f32_16x16x32_bf16 v[10:13], v[82:85], v[170:173], v[10:13]
	v_mfma_f32_16x16x32_bf16 v[62:65], v[74:77], v[150:153], v[62:65]
	v_mfma_f32_16x16x32_bf16 v[58:61], v[86:89], v[150:153], v[58:61]
	v_mfma_f32_16x16x32_bf16 v[46:49], v[74:77], v[158:161], v[46:49]
	v_mfma_f32_16x16x32_bf16 v[42:45], v[86:89], v[158:161], v[42:45]
	v_mfma_f32_16x16x32_bf16 v[30:33], v[74:77], v[166:169], v[30:33]
	v_mfma_f32_16x16x32_bf16 v[26:29], v[86:89], v[166:169], v[26:29]
	v_mfma_f32_16x16x32_bf16 v[14:17], v[74:77], v[184:187], v[14:17]
	v_mfma_f32_16x16x32_bf16 v[10:13], v[86:89], v[184:187], v[10:13]
	s_barrier
	s_add_u32 s22, s36, 0x100000
	s_addc_u32 s23, s37, 0
	s_add_i32 s65, s66, s52
	v_lshl_add_u64 v[70:71], s[22:23], 0, v[0:1]
	s_mov_b32 m0, s65
	s_nop 0
	global_load_lds_dwordx4 v[70:71], off
	v_lshl_add_u64 v[70:71], s[22:23], 0, v[174:175]
	s_add_i32 m0, s65, 0x2000
	s_nop 0
	global_load_lds_dwordx4 v[70:71], off
	s_waitcnt vmcnt(6)
	s_barrier
	v_mfma_f32_16x16x32_bf16 v[54:57], v[194:197], v[146:149], v[54:57]
	v_mfma_f32_16x16x32_bf16 v[50:53], v[202:205], v[146:149], v[50:53]
	v_mfma_f32_16x16x32_bf16 v[38:41], v[194:197], v[154:157], v[38:41]
	v_mfma_f32_16x16x32_bf16 v[34:37], v[202:205], v[154:157], v[34:37]
	v_mfma_f32_16x16x32_bf16 v[22:25], v[194:197], v[162:165], v[22:25]
	v_mfma_f32_16x16x32_bf16 v[18:21], v[202:205], v[162:165], v[18:21]
	v_mfma_f32_16x16x32_bf16 v[6:9], v[194:197], v[170:173], v[6:9]
	v_mfma_f32_16x16x32_bf16 v[2:5], v[202:205], v[170:173], v[2:5]
	v_mfma_f32_16x16x32_bf16 v[54:57], v[198:201], v[150:153], v[54:57]
	v_mfma_f32_16x16x32_bf16 v[50:53], v[212:215], v[150:153], v[50:53]
	v_mfma_f32_16x16x32_bf16 v[38:41], v[198:201], v[158:161], v[38:41]
	v_mfma_f32_16x16x32_bf16 v[34:37], v[212:215], v[158:161], v[34:37]
	v_mfma_f32_16x16x32_bf16 v[22:25], v[198:201], v[166:169], v[22:25]
	v_mfma_f32_16x16x32_bf16 v[18:21], v[212:215], v[166:169], v[18:21]
	v_mfma_f32_16x16x32_bf16 v[6:9], v[198:201], v[184:187], v[6:9]
	v_mfma_f32_16x16x32_bf16 v[2:5], v[212:215], v[184:187], v[2:5]
	s_add_i32 s65, 0, 0x18000
	v_add_u32_e32 v86, s65, v209
	s_barrier
	ds_read_b128 v[70:73], v86
	ds_read_b128 v[74:77], v86 offset:1024
	ds_read_b128 v[82:85], v86 offset:2048
	ds_read_b128 v[86:89], v86 offset:3072
	s_add_u32 s22, s24, 0x100000
	s_addc_u32 s23, s25, 0
	s_mov_b32 m0, s55
	v_lshl_add_u64 v[194:195], s[22:23], 0, v[188:189]
	ds_read_b128 v[146:149], v211 offset:32768
	ds_read_b128 v[150:153], v211 offset:33792
	ds_read_b128 v[154:157], v211 offset:34816
	ds_read_b128 v[158:161], v211 offset:35840
	ds_read_b128 v[162:165], v211 offset:36864
	ds_read_b128 v[166:169], v211 offset:37888
	ds_read_b128 v[170:173], v211 offset:38912
	ds_read_b128 v[184:187], v211 offset:39936
	global_load_lds_dwordx4 v[194:195], off
	v_lshl_add_u64 v[194:195], s[22:23], 0, v[176:177]
	s_mov_b32 m0, s56
	s_nop 0
	global_load_lds_dwordx4 v[194:195], off
	s_waitcnt lgkmcnt(8)
	s_barrier
; #define PG8_STAGE(bufoff, gbase, voff) do { _Pragma("unroll") for (int _i = 0; _i < 2; ++_i) \
;         __builtin_amdgcn_global_load_lds((const unsigned*)((const char*)(gbase) + (voff)[_i]), (LAS unsigned*)(lds + (bufoff) + ldsw + _i * 8192), 16, 0, 0); } while (0)
; #define PG8_LDA(dst, b, h) do { _Pragma("unroll") for (int m = 0; m < 4; ++m) _Pragma("unroll") for (int k = 0; k < 2; ++k) dst[m][k] = *(const LAS bf16x8*)(lds + PG8_SA(b, h) + aoff + m * 2048 + k * 1024); } while (0)
; #define PG8_LDB(dst, b, h) do { _Pragma("unroll") for (int n = 0; n < 2; ++n) _Pragma("unroll") for (int k = 0; k < 2; ++k) dst[n][k] = *(const LAS bf16x8*)(lds + PG8_SB(b, h) + boff + n * 2048 + k * 1024); } while (0)
; #define PG8_MMA(ai, bj, At, Bt) do { __builtin_amdgcn_s_setprio(1); _Pragma("unroll") for (int m = 0; m < 4; ++m) _Pragma("unroll") for (int n = 0; n < 2; ++n) _Pragma("unroll") for (int k = 0; k < 2; ++k) \
;         acc[ai][bj][m][n] = __builtin_amdgcn_mfma_f32_16x16x32_bf16(Bt[n][k], At[m][k], acc[ai][bj][m][n], 0, 0, 0); __builtin_amdgcn_s_setprio(0); } while (0)
; #define PG8_WAIT_L(n) asm volatile("s_waitcnt lgkmcnt(" #n ")" ::: "memory")
; #define PG8_BAR __builtin_amdgcn_s_barrier()
; #define PG8_SCHED __builtin_amdgcn_sched_barrier(0)
; template <class Epi>
; __device__ __forceinline__ void gemm_phase(LAS unsigned char* lds, const Gemm g, const StaticOrder& S, const Epi& E) {
;     ...
;             PG8_WAIT_L(8); PG8_BAR; PG8_WAIT_L(0); PG8_MMA(0, 0, At, B0); PG8_BAR; PG8_SCHED;
;             PG8_LDB(B1, 1, 1); PG8_STAGE(PG8_SB(1, 0), b3, voffB);
;             PG8_BAR; PG8_WAIT_L(0); PG8_MMA(0, 1, At, B1); PG8_BAR;
;             PG8_LDA(At, 1, 1); PG8_STAGE(PG8_SA(1, 0), a3, voffA);
;             PG8_BAR; PG8_WAIT_L(0); PG8_MMA(1, 0, At, B0); PG8_BAR; PG8_SCHED;
	s_waitcnt lgkmcnt(0)
	s_waitcnt lgkmcnt(0)
	v_mfma_f32_16x16x32_bf16 v[142:145], v[70:73], v[146:149], v[142:145]
	v_mfma_f32_16x16x32_bf16 v[138:141], v[82:85], v[146:149], v[138:141]
	v_mfma_f32_16x16x32_bf16 v[126:129], v[70:73], v[154:157], v[126:129]
	v_mfma_f32_16x16x32_bf16 v[122:125], v[82:85], v[154:157], v[122:125]
	v_mfma_f32_16x16x32_bf16 v[110:113], v[70:73], v[162:165], v[110:113]
	v_mfma_f32_16x16x32_bf16 v[106:109], v[82:85], v[162:165], v[106:109]
	v_mfma_f32_16x16x32_bf16 v[94:97], v[70:73], v[170:173], v[94:97]
	v_mfma_f32_16x16x32_bf16 v[90:93], v[82:85], v[170:173], v[90:93]
	v_mfma_f32_16x16x32_bf16 v[142:145], v[74:77], v[150:153], v[142:145]
	v_mfma_f32_16x16x32_bf16 v[138:141], v[86:89], v[150:153], v[138:141]
	v_mfma_f32_16x16x32_bf16 v[126:129], v[74:77], v[158:161], v[126:129]
	v_mfma_f32_16x16x32_bf16 v[122:125], v[86:89], v[158:161], v[122:125]
	v_mfma_f32_16x16x32_bf16 v[110:113], v[74:77], v[166:169], v[110:113]
	v_mfma_f32_16x16x32_bf16 v[106:109], v[86:89], v[166:169], v[106:109]
	v_mfma_f32_16x16x32_bf16 v[94:97], v[74:77], v[184:187], v[94:97]
	v_mfma_f32_16x16x32_bf16 v[90:93], v[86:89], v[184:187], v[90:93]
	s_barrier
	s_add_i32 s24, 0, 0x1c000
	s_add_i32 s22, s65, s52
	v_add_u32_e32 v212, s24, v209
	v_lshl_add_u64 v[206:207], v[206:207], 0, s[6:7]
	s_mov_b32 m0, s22
	ds_read_b128 v[194:197], v212
	ds_read_b128 v[198:201], v212 offset:1024
	ds_read_b128 v[202:205], v212 offset:2048
	ds_read_b128 v[212:215], v212 offset:3072
	global_load_lds_dwordx4 v[206:207], off
	v_lshl_add_u64 v[206:207], v[216:217], 0, s[6:7]
	s_add_i32 m0, s22, 0x2000
	s_nop 0
	global_load_lds_dwordx4 v[206:207], off
	s_barrier
	s_waitcnt lgkmcnt(0)
	s_waitcnt lgkmcnt(0)
	v_mfma_f32_16x16x32_bf16 v[134:137], v[194:197], v[146:149], v[134:137]
	v_mfma_f32_16x16x32_bf16 v[130:133], v[202:205], v[146:149], v[130:133]
	v_mfma_f32_16x16x32_bf16 v[118:121], v[194:197], v[154:157], v[118:121]
	v_mfma_f32_16x16x32_bf16 v[114:117], v[202:205], v[154:157], v[114:117]
	v_mfma_f32_16x16x32_bf16 v[102:105], v[194:197], v[162:165], v[102:105]
	v_mfma_f32_16x16x32_bf16 v[98:101], v[202:205], v[162:165], v[98:101]
	v_mfma_f32_16x16x32_bf16 v[78:81], v[194:197], v[170:173], v[78:81]
	v_mfma_f32_16x16x32_bf16 v[66:69], v[202:205], v[170:173], v[66:69]
	v_mfma_f32_16x16x32_bf16 v[134:137], v[198:201], v[150:153], v[134:137]
	v_mfma_f32_16x16x32_bf16 v[130:133], v[212:215], v[150:153], v[130:133]
	v_mfma_f32_16x16x32_bf16 v[118:121], v[198:201], v[158:161], v[118:121]
	v_mfma_f32_16x16x32_bf16 v[114:117], v[212:215], v[158:161], v[114:117]
	v_mfma_f32_16x16x32_bf16 v[102:105], v[198:201], v[166:169], v[102:105]
	v_mfma_f32_16x16x32_bf16 v[98:101], v[212:215], v[166:169], v[98:101]
	v_mfma_f32_16x16x32_bf16 v[78:81], v[198:201], v[184:187], v[78:81]
	v_mfma_f32_16x16x32_bf16 v[66:69], v[212:215], v[184:187], v[66:69]
	s_mov_b32 m0, s58
	v_lshl_add_u64 v[206:207], v[218:219], 0, s[6:7]
	s_barrier
	ds_read_b128 v[146:149], v211 offset:49152
	ds_read_b128 v[150:153], v211 offset:50176
	ds_read_b128 v[154:157], v211 offset:51200
	ds_read_b128 v[158:161], v211 offset:52224
	ds_read_b128 v[162:165], v211 offset:53248
	ds_read_b128 v[166:169], v211 offset:54272
	ds_read_b128 v[170:173], v211 offset:55296
	ds_read_b128 v[184:187], v211 offset:56320
	global_load_lds_dwordx4 v[206:207], off
	v_lshl_add_u64 v[206:207], v[220:221], 0, s[6:7]
	s_mov_b32 m0, s59
	s_nop 0
	global_load_lds_dwordx4 v[206:207], off
	s_barrier
	s_waitcnt lgkmcnt(0)
	s_waitcnt lgkmcnt(0)
	v_mfma_f32_16x16x32_bf16 v[62:65], v[70:73], v[146:149], v[62:65]
	v_mfma_f32_16x16x32_bf16 v[58:61], v[82:85], v[146:149], v[58:61]
	v_mfma_f32_16x16x32_bf16 v[46:49], v[70:73], v[154:157], v[46:49]
	v_mfma_f32_16x16x32_bf16 v[42:45], v[82:85], v[154:157], v[42:45]
	v_mfma_f32_16x16x32_bf16 v[30:33], v[70:73], v[162:165], v[30:33]
	v_mfma_f32_16x16x32_bf16 v[26:29], v[82:85], v[162:165], v[26:29]
	v_mfma_f32_16x16x32_bf16 v[14:17], v[70:73], v[170:173], v[14:17]
	v_mfma_f32_16x16x32_bf16 v[10:13], v[82:85], v[170:173], v[10:13]
	v_mfma_f32_16x16x32_bf16 v[62:65], v[74:77], v[150:153], v[62:65]
	v_mfma_f32_16x16x32_bf16 v[58:61], v[86:89], v[150:153], v[58:61]
	v_mfma_f32_16x16x32_bf16 v[46:49], v[74:77], v[158:161], v[46:49]
	v_mfma_f32_16x16x32_bf16 v[42:45], v[86:89], v[158:161], v[42:45]
	v_mfma_f32_16x16x32_bf16 v[30:33], v[74:77], v[166:169], v[30:33]
	v_mfma_f32_16x16x32_bf16 v[26:29], v[86:89], v[166:169], v[26:29]
	v_mfma_f32_16x16x32_bf16 v[14:17], v[74:77], v[184:187], v[14:17]
	v_mfma_f32_16x16x32_bf16 v[10:13], v[86:89], v[184:187], v[10:13]
	s_barrier
; __device__ __forceinline__ unsigned cvt_pk_bf16(float lo, float hi) { unsigned r; asm volatile("v_cvt_pk_bf16_f32 %0, %1, %2" : "=v"(r) : "v"(lo), "v"(hi)); return r; }
; #define PG8_WAIT_V(n) asm volatile("s_waitcnt vmcnt(" #n ")" ::: "memory")
; #define PG8_BAR __builtin_amdgcn_s_barrier()
; template <class Epi>
; __device__ __forceinline__ void gemm_phase(LAS unsigned char* lds, const Gemm g, const StaticOrder& S, const Epi& E) {
;     ...
;             PG8_STAGE(PG8_SB(1, 1), b3 + hstepB, voffB);
;             PG8_WAIT_V(6); PG8_BAR; PG8_MMA(1, 1, At, B1); PG8_BAR;
;     __device__ __forceinline__ void operator()(const f32x4 (&acc)[2][2][4][2], const Unit& u, int wr, int wc, int fr, int fq, const Pre&) const {
;         const int row0 = u.pm * BM + wr * 64 + fr, col0 = u.pn * BM + wc * 32 + 4 * fq;
;         f32x4 gv[2][2];
; #pragma unroll
;         for (int bj = 0; bj < 2; ++bj)
; #pragma unroll
;             for (int n = 0; n < 2; ++n) gv[bj][n] = *(const f32x4*)(gnext + col0 + bj * HALF + n * 16);
;         f32x4 xb[2][2][2];
; #pragma unroll
;         for (int bj = 0; bj < 2; ++bj)
; #pragma unroll
;             for (int n = 0; n < 2; ++n) xb[0][bj][n] = *(const f32x4*)(Xin + (size_t)row0 * DM + col0 + bj * HALF + n * 16);
; #pragma unroll
;         for (int grp = 0; grp < 8; ++grp) { const int ai = grp >> 2, m = grp & 3, cur = grp & 1; const int r = row0 + ai * HALF + m * 16; float ss = 0.f;
;             if (grp < 7) { const int rn = row0 + ((grp + 1) >> 2) * HALF + ((grp + 1) & 3) * 16;
; #pragma unroll
;                 for (int bj = 0; bj < 2; ++bj)
; #pragma unroll
;                     for (int n = 0; n < 2; ++n) xb[cur ^ 1][bj][n] = *(const f32x4*)(Xin + (size_t)rn * DM + col0 + bj * HALF + n * 16); }
; #pragma unroll
;             for (int bj = 0; bj < 2; ++bj)
; #pragma unroll
;                 for (int n = 0; n < 2; ++n) { const int c = col0 + bj * HALF + n * 16;
;                     const f32x4 xv = xb[cur][bj][n] + acc[ai][bj][m][n]; *(f32x4*)(X + (size_t)r * DM + c) = xv;
;                     ss += (xv[0] * xv[0] + xv[1] * xv[1]) + (xv[2] * xv[2] + xv[3] * xv[3]);
;                     if (H) { const f32x4 hv = xv * gv[bj][n]; u32x2 w; w.x = cvt_pk_bf16(hv[0], hv[1]); w.y = cvt_pk_bf16(hv[2], hv[3]);
;                         *(u32x2*)(H + (size_t)r * DM + c) = w; } }
	s_add_u32 s22, s36, 0x100080
	s_addc_u32 s23, s37, 0
	s_add_i32 s24, s24, s52
	v_lshl_add_u64 v[70:71], s[22:23], 0, v[0:1]
	s_mov_b32 m0, s24
	s_nop 0
	global_load_lds_dwordx4 v[70:71], off
	v_lshl_add_u64 v[70:71], s[22:23], 0, v[174:175]
	s_add_i32 m0, s24, 0x2000
	s_nop 0
	global_load_lds_dwordx4 v[70:71], off
	s_waitcnt vmcnt(6)
	s_barrier
	v_mfma_f32_16x16x32_bf16 v[54:57], v[194:197], v[146:149], v[54:57]
	v_mfma_f32_16x16x32_bf16 v[50:53], v[202:205], v[146:149], v[50:53]
	v_mfma_f32_16x16x32_bf16 v[38:41], v[194:197], v[154:157], v[38:41]
	v_mfma_f32_16x16x32_bf16 v[34:37], v[202:205], v[154:157], v[34:37]
	v_mfma_f32_16x16x32_bf16 v[22:25], v[194:197], v[162:165], v[22:25]
	v_mfma_f32_16x16x32_bf16 v[18:21], v[202:205], v[162:165], v[18:21]
	v_mfma_f32_16x16x32_bf16 v[6:9], v[194:197], v[170:173], v[6:9]
	v_mfma_f32_16x16x32_bf16 v[2:5], v[202:205], v[170:173], v[2:5]
	v_mfma_f32_16x16x32_bf16 v[54:57], v[198:201], v[150:153], v[54:57]
	v_mfma_f32_16x16x32_bf16 v[50:53], v[212:215], v[150:153], v[50:53]
	v_mfma_f32_16x16x32_bf16 v[38:41], v[198:201], v[158:161], v[38:41]
	v_mfma_f32_16x16x32_bf16 v[34:37], v[212:215], v[158:161], v[34:37]
	v_mfma_f32_16x16x32_bf16 v[22:25], v[198:201], v[166:169], v[22:25]
	v_mfma_f32_16x16x32_bf16 v[18:21], v[212:215], v[166:169], v[18:21]
	v_mfma_f32_16x16x32_bf16 v[6:9], v[198:201], v[184:187], v[6:9]
	v_mfma_f32_16x16x32_bf16 v[2:5], v[212:215], v[184:187], v[2:5]
	s_add_i32 s64, s64, 2
	s_add_u32 s62, s62, 0x100
	s_addc_u32 s63, s63, 0
	s_cmp_gt_u32 s64, 61
	s_mov_b64 s[22:23], s[26:27]
	s_barrier
	s_cbranch_scc0 .LBB0_359
	s_setprio 0
	v_lshl_add_u32 v198, s44, 8, v208
	v_lshl_or_b32 v194, s45, 8, v210
	v_ashrrev_i32_e32 v199, 31, v198
	v_ashrrev_i32_e32 v195, 31, v194
	v_lshlrev_b64 v[204:205], 13, v[198:199]
	v_or_b32_e32 v202, 16, v198
	v_lshlrev_b64 v[196:197], 2, v[194:195]
	v_lshl_add_u64 v[146:147], s[0:1], 0, v[204:205]
	v_ashrrev_i32_e32 v203, 31, v202
	v_lshl_add_u64 v[70:71], s[4:5], 0, v[196:197]
	v_lshl_add_u64 v[146:147], v[146:147], 0, v[196:197]
	v_lshlrev_b64 v[200:201], 13, v[202:203]
	global_load_dwordx4 v[86:89], v[70:71], off
	global_load_dwordx4 v[82:85], v[70:71], off offset:64
	global_load_dwordx4 v[74:77], v[70:71], off offset:512
	s_nop 0
	global_load_dwordx4 v[70:73], v[70:71], off offset:576
	s_nop 0
	global_load_dwordx4 v[184:187], v[146:147], off
	global_load_dwordx4 v[170:173], v[146:147], off offset:64
	global_load_dwordx4 v[166:169], v[146:147], off offset:512
	global_load_dwordx4 v[162:165], v[146:147], off offset:576
	v_lshl_add_u64 v[146:147], s[0:1], 0, v[200:201]
	v_lshl_add_u64 v[146:147], v[146:147], 0, v[196:197]
	global_load_dwordx4 v[158:161], v[146:147], off
	global_load_dwordx4 v[154:157], v[146:147], off offset:64
	global_load_dwordx4 v[150:153], v[146:147], off offset:512
	s_nop 0
	global_load_dwordx4 v[146:149], v[146:147], off offset:576
	v_cndmask_b32_e64 v206, 0, 1, s[10:11]
	v_lshlrev_b64 v[212:213], 11, v[198:199]
	v_lshl_add_u64 v[204:205], s[48:49], 0, v[204:205]
	v_cmp_ne_u32_e64 s[44:45], 1, v206
	s_andn2_b64 vcc, exec, s[10:11]
	v_lshl_add_u64 v[206:207], v[204:205], 0, v[196:197]
	v_lshl_add_u64 v[204:205], v[212:213], 1, s[50:51]
	s_waitcnt vmcnt(0)
	v_pk_add_f32 v[144:145], v[144:145], v[186:187]
	v_pk_add_f32 v[142:143], v[142:143], v[184:185]
	global_store_dwordx4 v[206:207], v[142:145], off
	s_cbranch_vccnz .LBB0_362
	v_pk_mul_f32 v[184:185], v[88:89], v[144:145]
	v_pk_mul_f32 v[186:187], v[86:87], v[142:143]
	s_nop 0
	v_cvt_pk_bf16_f32 v186, v186, v187
	v_cvt_pk_bf16_f32 v187, v184, v185
	v_lshl_add_u64 v[184:185], v[194:195], 1, v[204:205]
	global_store_dwordx2 v[184:185], v[186:187], off

; #define PG8_STAGE(bufoff, gbase, voff) do { _Pragma("unroll") for (int _i = 0; _i < 2; ++_i) \
;         __builtin_amdgcn_global_load_lds((const unsigned*)((const char*)(gbase) + (voff)[_i]), (LAS unsigned*)(lds + (bufoff) + ldsw + _i * 8192), 16, 0, 0); } while (0)
; #define PG8_LDA(dst, b, h) do { _Pragma("unroll") for (int m = 0; m < 4; ++m) _Pragma("unroll") for (int k = 0; k < 2; ++k) dst[m][k] = *(const LAS bf16x8*)(lds + PG8_SA(b, h) + aoff + m * 2048 + k * 1024); } while (0)
; #define PG8_LDB(dst, b, h) do { _Pragma("unroll") for (int n = 0; n < 2; ++n) _Pragma("unroll") for (int k = 0; k < 2; ++k) dst[n][k] = *(const LAS bf16x8*)(lds + PG8_SB(b, h) + boff + n * 2048 + k * 1024); } while (0)
; #define PG8_MMA(ai, bj, At, Bt) do { __builtin_amdgcn_s_setprio(1); _Pragma("unroll") for (int m = 0; m < 4; ++m) _Pragma("unroll") for (int n = 0; n < 2; ++n) _Pragma("unroll") for (int k = 0; k < 2; ++k) \
;         acc[ai][bj][m][n] = __builtin_amdgcn_mfma_f32_16x16x32_bf16(Bt[n][k], At[m][k], acc[ai][bj][m][n], 0, 0, 0); __builtin_amdgcn_s_setprio(0); } while (0)
; #define PG8_WAIT_L(n) asm volatile("s_waitcnt lgkmcnt(" #n ")" ::: "memory")
; #define PG8_BAR __builtin_amdgcn_s_barrier()
; #define PG8_SCHED __builtin_amdgcn_sched_barrier(0)
; template <class Epi>
; __device__ __forceinline__ void gemm_phase(LAS unsigned char* lds, const Gemm g, const StaticOrder& S, const Epi& E) {
;     ...
;         const bool has_next = S.next(ui + 1, nxt);
;         const char* nA = has_next ? (const char*)g.A + (size_t)nxt.pm * tstepA + (size_t)(nxt.pn >> 2) * gstepA : cA; const char* nB = has_next ? (const char*)g.Bt + (size_t)nxt.pn * tstepB : cB;
;         for (int t = 0; t < nt; t += 2) {
;             const bool last = (t == nt - 2);
;             const char* a1 = cA + (size_t)(t + 1) * kstepA;
;             const char* a2 = last ? nA : cA + (size_t)(t + 2) * kstepA; const char* b2 = last ? nB : cB + (size_t)(t + 2) * kstep;
;             const char* a3 = a2 + kstepA; const char* b3 = b2 + kstep;
;             PG8_LDB(B0, 0, 0); PG8_SCHED; PG8_LDA(At, 0, 0); PG8_STAGE(PG8_SA(1, 1), a1 + hstepA, voffA);
;             PG8_WAIT_L(8); PG8_BAR; PG8_WAIT_L(0); PG8_MMA(0, 0, At, B0); PG8_BAR; PG8_SCHED;
;             PG8_LDB(B1, 0, 1); PG8_STAGE(PG8_SB(0, 0), b2, voffB);
;             PG8_BAR; PG8_WAIT_L(0); PG8_MMA(0, 1, At, B1); PG8_BAR;
.LBB0_471:
	s_add_u32 s17, s20, 0x100
	s_addc_u32 s58, s21, 0
	s_ashr_i32 s11, s10, 31
	s_lshl_b64 s[14:15], s[10:11], 21
	s_add_u32 s18, s35, s14
	s_addc_u32 s19, s36, s15
	s_and_b64 s[14:15], s[42:43], exec
	s_cselect_b32 s11, s19, s5
	s_cselect_b32 s59, s18, s4
	s_ashr_i32 s9, s8, 31
	s_lshl_b64 s[14:15], s[8:9], 21
	s_add_u32 s14, s37, s14
	s_addc_u32 s15, s38, s15
	s_and_b64 s[22:23], s[42:43], exec
	s_cselect_b32 s9, s15, s21
	s_cselect_b32 s60, s14, s20
	s_add_u32 s20, s4, 0x100080
	s_addc_u32 s21, s5, 0
	v_lshl_add_u64 v[140:141], s[20:21], 0, v[136:137]
	v_lshl_add_u64 v[142:143], s[20:21], 0, v[138:139]
	s_mov_b32 s61, -2
	s_mov_b64 s[20:21], 0
	v_readfirstlane_b32 s100, v232
	s_nop 3
	s_cmp_ge_u32 s100, 0x100
	s_cbranch_scc0 .Lprio_skip_2
	s_setprio 1
.Lprio_skip_2:
.LBB0_472:
	s_add_u32 s22, s4, s20
	s_addc_u32 s23, s5, s21
	s_add_u32 s22, s22, 0x100
	s_addc_u32 s23, s23, 0
	s_add_u32 s62, s17, s20
	s_addc_u32 s63, s58, s21
	s_add_i32 s64, 0, 0x10000
	v_add_u32_e32 v160, s64, v146
	ds_read_b128 v[148:151], v160
	ds_read_b128 v[152:155], v160 offset:1024
	ds_read_b128 v[156:159], v160 offset:2048
	ds_read_b128 v[160:163], v160 offset:3072
	s_cmpk_eq_i32 s20, 0x1f00
	s_cselect_b32 s25, s11, s23
	s_cselect_b32 s24, s59, s22
	s_cselect_b32 s23, s9, s63
	s_cselect_b32 s22, s60, s62
	v_lshl_add_u64 v[176:177], v[140:141], 0, s[20:21]
	s_add_i32 m0, s48, 0xc000
	ds_read_b128 v[164:167], v147
	ds_read_b128 v[168:171], v147 offset:1024
	ds_read_b128 v[172:175], v147 offset:2048
	ds_read_b128 v[184:187], v147 offset:3072
	ds_read_b128 v[188:191], v147 offset:4096
	ds_read_b128 v[192:195], v147 offset:5120
	ds_read_b128 v[196:199], v147 offset:6144
	ds_read_b128 v[200:203], v147 offset:7168
	global_load_lds_dwordx4 v[176:177], off
	v_lshl_add_u64 v[176:177], v[142:143], 0, s[20:21]
	s_add_i32 m0, s48, 0xe000
	s_nop 0
	global_load_lds_dwordx4 v[176:177], off
	s_waitcnt lgkmcnt(8)
	s_barrier
	s_waitcnt lgkmcnt(0)
	s_waitcnt lgkmcnt(0)
	v_mfma_f32_16x16x32_bf16 v[126:129], v[148:151], v[164:167], v[126:129]
	v_mfma_f32_16x16x32_bf16 v[122:125], v[156:159], v[164:167], v[122:125]
	v_mfma_f32_16x16x32_bf16 v[110:113], v[148:151], v[172:175], v[110:113]
	v_mfma_f32_16x16x32_bf16 v[106:109], v[156:159], v[172:175], v[106:109]
	v_mfma_f32_16x16x32_bf16 v[94:97], v[148:151], v[188:191], v[94:97]
	v_mfma_f32_16x16x32_bf16 v[90:93], v[156:159], v[188:191], v[90:93]
	v_mfma_f32_16x16x32_bf16 v[78:81], v[148:151], v[196:199], v[78:81]
	v_mfma_f32_16x16x32_bf16 v[74:77], v[156:159], v[196:199], v[74:77]
	v_mfma_f32_16x16x32_bf16 v[126:129], v[152:155], v[168:171], v[126:129]
	v_mfma_f32_16x16x32_bf16 v[122:125], v[160:163], v[168:171], v[122:125]
	v_mfma_f32_16x16x32_bf16 v[110:113], v[152:155], v[184:187], v[110:113]
	v_mfma_f32_16x16x32_bf16 v[106:109], v[160:163], v[184:187], v[106:109]
	v_mfma_f32_16x16x32_bf16 v[94:97], v[152:155], v[192:195], v[94:97]
	v_mfma_f32_16x16x32_bf16 v[90:93], v[160:163], v[192:195], v[90:93]
	v_mfma_f32_16x16x32_bf16 v[78:81], v[152:155], v[200:203], v[78:81]
	v_mfma_f32_16x16x32_bf16 v[74:77], v[160:163], v[200:203], v[74:77]
	s_barrier
	s_add_i32 s65, 0, 0x14000
	v_add_u32_e32 v176, s65, v146
	s_add_i32 s62, s64, s39
	ds_read_b128 v[204:207], v176
	ds_read_b128 v[208:211], v176 offset:1024
	ds_read_b128 v[212:215], v176 offset:2048
	ds_read_b128 v[216:219], v176 offset:3072
	v_lshl_add_u64 v[176:177], s[22:23], 0, v[0:1]
	s_mov_b32 m0, s62
	v_lshl_add_u64 v[220:221], s[22:23], 0, v[130:131]
	global_load_lds_dwordx4 v[176:177], off
	s_add_i32 m0, s62, 0x2000
	s_nop 0
	global_load_lds_dwordx4 v[220:221], off
	s_barrier
	s_waitcnt lgkmcnt(0)
	s_waitcnt lgkmcnt(0)
	v_mfma_f32_16x16x32_bf16 v[118:121], v[204:207], v[164:167], v[118:121]
	v_mfma_f32_16x16x32_bf16 v[114:117], v[212:215], v[164:167], v[114:117]
	v_mfma_f32_16x16x32_bf16 v[102:105], v[204:207], v[172:175], v[102:105]
	v_mfma_f32_16x16x32_bf16 v[98:101], v[212:215], v[172:175], v[98:101]
	v_mfma_f32_16x16x32_bf16 v[86:89], v[204:207], v[188:191], v[86:89]
	v_mfma_f32_16x16x32_bf16 v[82:85], v[212:215], v[188:191], v[82:85]
	v_mfma_f32_16x16x32_bf16 v[70:73], v[204:207], v[196:199], v[70:73]
	v_mfma_f32_16x16x32_bf16 v[66:69], v[212:215], v[196:199], v[66:69]
	v_mfma_f32_16x16x32_bf16 v[118:121], v[208:211], v[168:171], v[118:121]
	v_mfma_f32_16x16x32_bf16 v[114:117], v[216:219], v[168:171], v[114:117]
	v_mfma_f32_16x16x32_bf16 v[102:105], v[208:211], v[184:187], v[102:105]
	v_mfma_f32_16x16x32_bf16 v[98:101], v[216:219], v[184:187], v[98:101]
	v_mfma_f32_16x16x32_bf16 v[86:89], v[208:211], v[192:195], v[86:89]
	v_mfma_f32_16x16x32_bf16 v[82:85], v[216:219], v[192:195], v[82:85]
	v_mfma_f32_16x16x32_bf16 v[70:73], v[208:211], v[200:203], v[70:73]
	v_mfma_f32_16x16x32_bf16 v[66:69], v[216:219], v[200:203], v[66:69]
	s_mov_b32 m0, s48
	v_lshl_add_u64 v[222:223], s[24:25], 0, v[134:135]
	s_barrier
	ds_read_b128 v[164:167], v147 offset:16384
	ds_read_b128 v[168:171], v147 offset:17408
	ds_read_b128 v[172:175], v147 offset:18432
	ds_read_b128 v[184:187], v147 offset:19456
	ds_read_b128 v[188:191], v147 offset:20480
	ds_read_b128 v[192:195], v147 offset:21504
	ds_read_b128 v[196:199], v147 offset:22528
	ds_read_b128 v[200:203], v147 offset:23552
	global_load_lds_dwordx4 v[222:223], off
	v_lshl_add_u64 v[224:225], s[24:25], 0, v[132:133]
	s_mov_b32 m0, s49
	s_nop 0
	global_load_lds_dwordx4 v[224:225], off
	s_barrier
; #define PG8_STAGE(bufoff, gbase, voff) do { _Pragma("unroll") for (int _i = 0; _i < 2; ++_i) \
;         __builtin_amdgcn_global_load_lds((const unsigned*)((const char*)(gbase) + (voff)[_i]), (LAS unsigned*)(lds + (bufoff) + ldsw + _i * 8192), 16, 0, 0); } while (0)
; #define PG8_LDA(dst, b, h) do { _Pragma("unroll") for (int m = 0; m < 4; ++m) _Pragma("unroll") for (int k = 0; k < 2; ++k) dst[m][k] = *(const LAS bf16x8*)(lds + PG8_SA(b, h) + aoff + m * 2048 + k * 1024); } while (0)
; #define PG8_LDB(dst, b, h) do { _Pragma("unroll") for (int n = 0; n < 2; ++n) _Pragma("unroll") for (int k = 0; k < 2; ++k) dst[n][k] = *(const LAS bf16x8*)(lds + PG8_SB(b, h) + boff + n * 2048 + k * 1024); } while (0)
; #define PG8_MMA(ai, bj, At, Bt) do { __builtin_amdgcn_s_setprio(1); _Pragma("unroll") for (int m = 0; m < 4; ++m) _Pragma("unroll") for (int n = 0; n < 2; ++n) _Pragma("unroll") for (int k = 0; k < 2; ++k) \
;         acc[ai][bj][m][n] = __builtin_amdgcn_mfma_f32_16x16x32_bf16(Bt[n][k], At[m][k], acc[ai][bj][m][n], 0, 0, 0); __builtin_amdgcn_s_setprio(0); } while (0)
; #define PG8_WAIT_V(n) asm volatile("s_waitcnt vmcnt(" #n ")" ::: "memory")
; #define PG8_WAIT_L(n) asm volatile("s_waitcnt lgkmcnt(" #n ")" ::: "memory")
; #define PG8_BAR __builtin_amdgcn_s_barrier()
; #define PG8_SCHED __builtin_amdgcn_sched_barrier(0)
; template <class Epi>
; __device__ __forceinline__ void gemm_phase(LAS unsigned char* lds, const Gemm g, const StaticOrder& S, const Epi& E) {
;     ...
;             PG8_BAR; PG8_WAIT_L(0); PG8_MMA(0, 1, At, B1); PG8_BAR;
;             PG8_LDA(At, 0, 1); PG8_STAGE(PG8_SA(0, 0), a2, voffA);
;             PG8_BAR; PG8_WAIT_L(0); PG8_MMA(1, 0, At, B0); PG8_BAR; PG8_SCHED;
;             PG8_STAGE(PG8_SB(0, 1), b2 + hstepB, voffB);
;             PG8_WAIT_V(6); PG8_BAR; PG8_MMA(1, 1, At, B1); PG8_BAR;
;             PG8_LDB(B0, 1, 0); PG8_SCHED; PG8_LDA(At, 1, 0); PG8_STAGE(PG8_SA(0, 1), a2 + hstepA, voffA);
;             PG8_WAIT_L(8); PG8_BAR; PG8_WAIT_L(0); PG8_MMA(0, 0, At, B0); PG8_BAR; PG8_SCHED;
	s_waitcnt lgkmcnt(0)
	s_waitcnt lgkmcnt(0)
	v_mfma_f32_16x16x32_bf16 v[62:65], v[148:151], v[164:167], v[62:65]
	v_mfma_f32_16x16x32_bf16 v[58:61], v[156:159], v[164:167], v[58:61]
	v_mfma_f32_16x16x32_bf16 v[46:49], v[148:151], v[172:175], v[46:49]
	v_mfma_f32_16x16x32_bf16 v[42:45], v[156:159], v[172:175], v[42:45]
	v_mfma_f32_16x16x32_bf16 v[30:33], v[148:151], v[188:191], v[30:33]
	v_mfma_f32_16x16x32_bf16 v[26:29], v[156:159], v[188:191], v[26:29]
	v_mfma_f32_16x16x32_bf16 v[18:21], v[148:151], v[196:199], v[18:21]
	v_mfma_f32_16x16x32_bf16 v[10:13], v[156:159], v[196:199], v[10:13]
	v_mfma_f32_16x16x32_bf16 v[62:65], v[152:155], v[168:171], v[62:65]
	v_mfma_f32_16x16x32_bf16 v[58:61], v[160:163], v[168:171], v[58:61]
	v_mfma_f32_16x16x32_bf16 v[46:49], v[152:155], v[184:187], v[46:49]
	v_mfma_f32_16x16x32_bf16 v[42:45], v[160:163], v[184:187], v[42:45]
	v_mfma_f32_16x16x32_bf16 v[30:33], v[152:155], v[192:195], v[30:33]
	v_mfma_f32_16x16x32_bf16 v[26:29], v[160:163], v[192:195], v[26:29]
	v_mfma_f32_16x16x32_bf16 v[18:21], v[152:155], v[200:203], v[18:21]
	v_mfma_f32_16x16x32_bf16 v[10:13], v[160:163], v[200:203], v[10:13]
	s_barrier
	s_add_u32 s62, s22, 0x100000
	s_addc_u32 s63, s23, 0
	s_add_i32 s64, s65, s39
	v_lshl_add_u64 v[148:149], s[62:63], 0, v[0:1]
	s_mov_b32 m0, s64
	s_nop 0
	global_load_lds_dwordx4 v[148:149], off
	v_lshl_add_u64 v[148:149], s[62:63], 0, v[130:131]
	s_add_i32 m0, s64, 0x2000
	s_nop 0
	global_load_lds_dwordx4 v[148:149], off
	s_waitcnt vmcnt(6)
	s_barrier
	v_mfma_f32_16x16x32_bf16 v[54:57], v[204:207], v[164:167], v[54:57]
	v_mfma_f32_16x16x32_bf16 v[50:53], v[212:215], v[164:167], v[50:53]
	v_mfma_f32_16x16x32_bf16 v[38:41], v[204:207], v[172:175], v[38:41]
	v_mfma_f32_16x16x32_bf16 v[34:37], v[212:215], v[172:175], v[34:37]
	v_mfma_f32_16x16x32_bf16 v[22:25], v[204:207], v[188:191], v[22:25]
	v_mfma_f32_16x16x32_bf16 v[14:17], v[212:215], v[188:191], v[14:17]
	v_mfma_f32_16x16x32_bf16 v[6:9], v[204:207], v[196:199], v[6:9]
	v_mfma_f32_16x16x32_bf16 v[2:5], v[212:215], v[196:199], v[2:5]
	v_mfma_f32_16x16x32_bf16 v[54:57], v[208:211], v[168:171], v[54:57]
	v_mfma_f32_16x16x32_bf16 v[50:53], v[216:219], v[168:171], v[50:53]
	v_mfma_f32_16x16x32_bf16 v[38:41], v[208:211], v[184:187], v[38:41]
	v_mfma_f32_16x16x32_bf16 v[34:37], v[216:219], v[184:187], v[34:37]
	v_mfma_f32_16x16x32_bf16 v[22:25], v[208:211], v[192:195], v[22:25]
	v_mfma_f32_16x16x32_bf16 v[14:17], v[216:219], v[192:195], v[14:17]
	v_mfma_f32_16x16x32_bf16 v[6:9], v[208:211], v[200:203], v[6:9]
	v_mfma_f32_16x16x32_bf16 v[2:5], v[216:219], v[200:203], v[2:5]
	s_add_i32 s62, 0, 0x18000
	v_add_u32_e32 v160, s62, v146
	s_barrier
	ds_read_b128 v[148:151], v160
	ds_read_b128 v[152:155], v160 offset:1024
	ds_read_b128 v[156:159], v160 offset:2048
	ds_read_b128 v[160:163], v160 offset:3072
	s_add_u32 s24, s24, 0x100000
	s_addc_u32 s25, s25, 0
	s_mov_b32 m0, s50
	v_lshl_add_u64 v[204:205], s[24:25], 0, v[134:135]
	ds_read_b128 v[164:167], v147 offset:32768
	ds_read_b128 v[168:171], v147 offset:33792
	ds_read_b128 v[172:175], v147 offset:34816
	ds_read_b128 v[184:187], v147 offset:35840
	ds_read_b128 v[188:191], v147 offset:36864
	ds_read_b128 v[192:195], v147 offset:37888
	ds_read_b128 v[196:199], v147 offset:38912
	ds_read_b128 v[200:203], v147 offset:39936
	global_load_lds_dwordx4 v[204:205], off
	v_lshl_add_u64 v[204:205], s[24:25], 0, v[132:133]
	s_mov_b32 m0, s51
	s_nop 0
	global_load_lds_dwordx4 v[204:205], off
	s_waitcnt lgkmcnt(8)
	s_barrier
	s_waitcnt lgkmcnt(0)
	s_waitcnt lgkmcnt(0)
	v_mfma_f32_16x16x32_bf16 v[126:129], v[148:151], v[164:167], v[126:129]
	v_mfma_f32_16x16x32_bf16 v[122:125], v[156:159], v[164:167], v[122:125]
	v_mfma_f32_16x16x32_bf16 v[110:113], v[148:151], v[172:175], v[110:113]
	v_mfma_f32_16x16x32_bf16 v[106:109], v[156:159], v[172:175], v[106:109]
	v_mfma_f32_16x16x32_bf16 v[94:97], v[148:151], v[188:191], v[94:97]
	v_mfma_f32_16x16x32_bf16 v[90:93], v[156:159], v[188:191], v[90:93]
	v_mfma_f32_16x16x32_bf16 v[78:81], v[148:151], v[196:199], v[78:81]
	v_mfma_f32_16x16x32_bf16 v[74:77], v[156:159], v[196:199], v[74:77]
	v_mfma_f32_16x16x32_bf16 v[126:129], v[152:155], v[168:171], v[126:129]
	v_mfma_f32_16x16x32_bf16 v[122:125], v[160:163], v[168:171], v[122:125]
	v_mfma_f32_16x16x32_bf16 v[110:113], v[152:155], v[184:187], v[110:113]
	v_mfma_f32_16x16x32_bf16 v[106:109], v[160:163], v[184:187], v[106:109]
	v_mfma_f32_16x16x32_bf16 v[94:97], v[152:155], v[192:195], v[94:97]
	v_mfma_f32_16x16x32_bf16 v[90:93], v[160:163], v[192:195], v[90:93]
	v_mfma_f32_16x16x32_bf16 v[78:81], v[152:155], v[200:203], v[78:81]
	v_mfma_f32_16x16x32_bf16 v[74:77], v[160:163], v[200:203], v[74:77]
	s_barrier
	s_add_i32 s24, 0, 0x1c000
	s_add_i32 s25, s62, s39
	v_add_u32_e32 v216, s24, v146
	v_lshl_add_u64 v[176:177], v[176:177], 0, s[6:7]
	s_mov_b32 m0, s25
	ds_read_b128 v[204:207], v216
	ds_read_b128 v[208:211], v216 offset:1024
	ds_read_b128 v[212:215], v216 offset:2048
	ds_read_b128 v[216:219], v216 offset:3072
	global_load_lds_dwordx4 v[176:177], off
	v_lshl_add_u64 v[176:177], v[220:221], 0, s[6:7]
	s_add_i32 m0, s25, 0x2000
	s_nop 0
	global_load_lds_dwordx4 v[176:177], off
	s_barrier
; #define PG8_STAGE(bufoff, gbase, voff) do { _Pragma("unroll") for (int _i = 0; _i < 2; ++_i) \
;         __builtin_amdgcn_global_load_lds((const unsigned*)((const char*)(gbase) + (voff)[_i]), (LAS unsigned*)(lds + (bufoff) + ldsw + _i * 8192), 16, 0, 0); } while (0)
; #define PG8_LDA(dst, b, h) do { _Pragma("unroll") for (int m = 0; m < 4; ++m) _Pragma("unroll") for (int k = 0; k < 2; ++k) dst[m][k] = *(const LAS bf16x8*)(lds + PG8_SA(b, h) + aoff + m * 2048 + k * 1024); } while (0)
; #define PG8_LDB(dst, b, h) do { _Pragma("unroll") for (int n = 0; n < 2; ++n) _Pragma("unroll") for (int k = 0; k < 2; ++k) dst[n][k] = *(const LAS bf16x8*)(lds + PG8_SB(b, h) + boff + n * 2048 + k * 1024); } while (0)
; #define PG8_MMA(ai, bj, At, Bt) do { __builtin_amdgcn_s_setprio(1); _Pragma("unroll") for (int m = 0; m < 4; ++m) _Pragma("unroll") for (int n = 0; n < 2; ++n) _Pragma("unroll") for (int k = 0; k < 2; ++k) \
;         acc[ai][bj][m][n] = __builtin_amdgcn_mfma_f32_16x16x32_bf16(Bt[n][k], At[m][k], acc[ai][bj][m][n], 0, 0, 0); __builtin_amdgcn_s_setprio(0); } while (0)
; #define PG8_WAIT_L(n) asm volatile("s_waitcnt lgkmcnt(" #n ")" ::: "memory")
; #define PG8_BAR __builtin_amdgcn_s_barrier()
; #define PG8_SCHED __builtin_amdgcn_sched_barrier(0)
; template <class Epi>
; __device__ __forceinline__ void gemm_phase(LAS unsigned char* lds, const Gemm g, const StaticOrder& S, const Epi& E) {
;     ...
;             PG8_LDB(B1, 1, 1); PG8_STAGE(PG8_SB(1, 0), b3, voffB);
;             PG8_BAR; PG8_WAIT_L(0); PG8_MMA(0, 1, At, B1); PG8_BAR;
;             PG8_LDA(At, 1, 1); PG8_STAGE(PG8_SA(1, 0), a3, voffA);
;             PG8_BAR; PG8_WAIT_L(0); PG8_MMA(1, 0, At, B0); PG8_BAR; PG8_SCHED;
;             PG8_STAGE(PG8_SB(1, 1), b3 + hstepB, voffB);
	s_waitcnt lgkmcnt(0)
	s_waitcnt lgkmcnt(0)
	v_mfma_f32_16x16x32_bf16 v[118:121], v[204:207], v[164:167], v[118:121]
	v_mfma_f32_16x16x32_bf16 v[114:117], v[212:215], v[164:167], v[114:117]
	v_mfma_f32_16x16x32_bf16 v[102:105], v[204:207], v[172:175], v[102:105]
	v_mfma_f32_16x16x32_bf16 v[98:101], v[212:215], v[172:175], v[98:101]
	v_mfma_f32_16x16x32_bf16 v[86:89], v[204:207], v[188:191], v[86:89]
	v_mfma_f32_16x16x32_bf16 v[82:85], v[212:215], v[188:191], v[82:85]
	v_mfma_f32_16x16x32_bf16 v[70:73], v[204:207], v[196:199], v[70:73]
	v_mfma_f32_16x16x32_bf16 v[66:69], v[212:215], v[196:199], v[66:69]
	v_mfma_f32_16x16x32_bf16 v[118:121], v[208:211], v[168:171], v[118:121]
	v_mfma_f32_16x16x32_bf16 v[114:117], v[216:219], v[168:171], v[114:117]
	v_mfma_f32_16x16x32_bf16 v[102:105], v[208:211], v[184:187], v[102:105]
	v_mfma_f32_16x16x32_bf16 v[98:101], v[216:219], v[184:187], v[98:101]
	v_mfma_f32_16x16x32_bf16 v[86:89], v[208:211], v[192:195], v[86:89]
	v_mfma_f32_16x16x32_bf16 v[82:85], v[216:219], v[192:195], v[82:85]
	v_mfma_f32_16x16x32_bf16 v[70:73], v[208:211], v[200:203], v[70:73]
	v_mfma_f32_16x16x32_bf16 v[66:69], v[216:219], v[200:203], v[66:69]
	s_mov_b32 m0, s54
	v_lshl_add_u64 v[176:177], v[222:223], 0, s[6:7]
	s_barrier
	ds_read_b128 v[164:167], v147 offset:49152
	ds_read_b128 v[168:171], v147 offset:50176
	ds_read_b128 v[172:175], v147 offset:51200
	ds_read_b128 v[184:187], v147 offset:52224
	ds_read_b128 v[188:191], v147 offset:53248
	ds_read_b128 v[192:195], v147 offset:54272
	ds_read_b128 v[196:199], v147 offset:55296
	ds_read_b128 v[200:203], v147 offset:56320
	global_load_lds_dwordx4 v[176:177], off
	v_lshl_add_u64 v[176:177], v[224:225], 0, s[6:7]
	s_mov_b32 m0, s55
	s_nop 0
	global_load_lds_dwordx4 v[176:177], off
	s_barrier
	s_waitcnt lgkmcnt(0)
	s_waitcnt lgkmcnt(0)
	v_mfma_f32_16x16x32_bf16 v[62:65], v[148:151], v[164:167], v[62:65]
	v_mfma_f32_16x16x32_bf16 v[58:61], v[156:159], v[164:167], v[58:61]
	v_mfma_f32_16x16x32_bf16 v[46:49], v[148:151], v[172:175], v[46:49]
	v_mfma_f32_16x16x32_bf16 v[42:45], v[156:159], v[172:175], v[42:45]
	v_mfma_f32_16x16x32_bf16 v[30:33], v[148:151], v[188:191], v[30:33]
	v_mfma_f32_16x16x32_bf16 v[26:29], v[156:159], v[188:191], v[26:29]
	v_mfma_f32_16x16x32_bf16 v[18:21], v[148:151], v[196:199], v[18:21]
	v_mfma_f32_16x16x32_bf16 v[10:13], v[156:159], v[196:199], v[10:13]
	v_mfma_f32_16x16x32_bf16 v[62:65], v[152:155], v[168:171], v[62:65]
	v_mfma_f32_16x16x32_bf16 v[58:61], v[160:163], v[168:171], v[58:61]
	v_mfma_f32_16x16x32_bf16 v[46:49], v[152:155], v[184:187], v[46:49]
	v_mfma_f32_16x16x32_bf16 v[42:45], v[160:163], v[184:187], v[42:45]
	v_mfma_f32_16x16x32_bf16 v[30:33], v[152:155], v[192:195], v[30:33]
	v_mfma_f32_16x16x32_bf16 v[26:29], v[160:163], v[192:195], v[26:29]
	v_mfma_f32_16x16x32_bf16 v[18:21], v[152:155], v[200:203], v[18:21]
	v_mfma_f32_16x16x32_bf16 v[10:13], v[160:163], v[200:203], v[10:13]
	s_barrier
	s_add_u32 s22, s22, 0x100080
	s_addc_u32 s23, s23, 0
	s_add_i32 s24, s24, s39
	v_lshl_add_u64 v[148:149], s[22:23], 0, v[0:1]
	s_mov_b32 m0, s24
	s_nop 0
	global_load_lds_dwordx4 v[148:149], off
	v_lshl_add_u64 v[148:149], s[22:23], 0, v[130:131]
	s_add_i32 m0, s24, 0x2000
	s_nop 0
	global_load_lds_dwordx4 v[148:149], off
	s_waitcnt vmcnt(6)
	s_barrier
; #define PG8_MMA(ai, bj, At, Bt) do { __builtin_amdgcn_s_setprio(1); _Pragma("unroll") for (int m = 0; m < 4; ++m) _Pragma("unroll") for (int n = 0; n < 2; ++n) _Pragma("unroll") for (int k = 0; k < 2; ++k) \
;         acc[ai][bj][m][n] = __builtin_amdgcn_mfma_f32_16x16x32_bf16(Bt[n][k], At[m][k], acc[ai][bj][m][n], 0, 0, 0); __builtin_amdgcn_s_setprio(0); } while (0)
; #define PG8_WAIT_V(n) asm volatile("s_waitcnt vmcnt(" #n ")" ::: "memory")
; #define PG8_BAR __builtin_amdgcn_s_barrier()
; template <class Epi>
; __device__ __forceinline__ void gemm_phase(LAS unsigned char* lds, const Gemm g, const StaticOrder& S, const Epi& E) {
;     ...
;             PG8_WAIT_V(6); PG8_BAR; PG8_MMA(1, 1, At, B1); PG8_BAR;
;         }
;         if constexpr (!Epi::AFTER_DRAIN) E(acc, cur, wr, wc, fr, fq, pre);
;         if (!has_next) break;
; #pragma unroll
;         for (int a = 0; a < 2; ++a)
; #pragma unroll
;             for (int b = 0; b < 2; ++b)
; #pragma unroll
;                 for (int m = 0; m < 4; ++m)
; #pragma unroll
;                     for (int n = 0; n < 2; ++n) acc[a][b][m][n] = (f32x4){0.f, 0.f, 0.f, 0.f};
;         cur = nxt; cA = nA; cB = nB; ++ui;
	v_mfma_f32_16x16x32_bf16 v[54:57], v[204:207], v[164:167], v[54:57]
	v_mfma_f32_16x16x32_bf16 v[50:53], v[212:215], v[164:167], v[50:53]
	v_mfma_f32_16x16x32_bf16 v[38:41], v[204:207], v[172:175], v[38:41]
	v_mfma_f32_16x16x32_bf16 v[34:37], v[212:215], v[172:175], v[34:37]
	v_mfma_f32_16x16x32_bf16 v[22:25], v[204:207], v[188:191], v[22:25]
	v_mfma_f32_16x16x32_bf16 v[14:17], v[212:215], v[188:191], v[14:17]
	v_mfma_f32_16x16x32_bf16 v[6:9], v[204:207], v[196:199], v[6:9]
	v_mfma_f32_16x16x32_bf16 v[2:5], v[212:215], v[196:199], v[2:5]
	v_mfma_f32_16x16x32_bf16 v[54:57], v[208:211], v[168:171], v[54:57]
	v_mfma_f32_16x16x32_bf16 v[50:53], v[216:219], v[168:171], v[50:53]
	v_mfma_f32_16x16x32_bf16 v[38:41], v[208:211], v[184:187], v[38:41]
	v_mfma_f32_16x16x32_bf16 v[34:37], v[216:219], v[184:187], v[34:37]
	v_mfma_f32_16x16x32_bf16 v[22:25], v[208:211], v[192:195], v[22:25]
	v_mfma_f32_16x16x32_bf16 v[14:17], v[216:219], v[192:195], v[14:17]
	v_mfma_f32_16x16x32_bf16 v[6:9], v[208:211], v[200:203], v[6:9]
	v_mfma_f32_16x16x32_bf16 v[2:5], v[216:219], v[200:203], v[2:5]
	s_add_i32 s61, s61, 2
	s_add_u32 s20, s20, 0x100
	s_addc_u32 s21, s21, 0
	s_cmp_gt_u32 s61, 61
	s_barrier
	s_cbranch_scc0 .LBB0_472
	s_setprio 0
	s_add_u32 s20, s17, 0xffffff00
	s_addc_u32 s21, s58, -1
	s_andn2_b64 vcc, exec, s[42:43]
	s_cbranch_vccnz .LBB0_463
	v_mov_b32_e32 v2, 0
	s_mov_b32 s57, s8
	s_mov_b32 s26, s10
	s_mov_b64 s[4:5], s[18:19]
	s_mov_b32 s56, s16
	v_mov_b32_e32 v3, v2
	v_mov_b32_e32 v4, v2
	v_mov_b32_e32 v5, v2
	v_mov_b32_e32 v6, v2
	v_mov_b32_e32 v7, v2
	v_mov_b32_e32 v8, v2
	v_mov_b32_e32 v9, v2
	v_mov_b32_e32 v14, v2
	v_mov_b32_e32 v15, v2
	v_mov_b32_e32 v16, v2
	v_mov_b32_e32 v17, v2
	v_mov_b32_e32 v22, v2
	v_mov_b32_e32 v23, v2
	v_mov_b32_e32 v24, v2
	v_mov_b32_e32 v25, v2
	v_mov_b32_e32 v34, v2
	v_mov_b32_e32 v35, v2
	v_mov_b32_e32 v36, v2
	v_mov_b32_e32 v37, v2
	v_mov_b32_e32 v38, v2
	v_mov_b32_e32 v39, v2
	v_mov_b32_e32 v40, v2
	v_mov_b32_e32 v41, v2
	v_mov_b32_e32 v50, v2
	v_mov_b32_e32 v51, v2
	v_mov_b32_e32 v52, v2
	v_mov_b32_e32 v53, v2
	v_mov_b32_e32 v54, v2
	v_mov_b32_e32 v55, v2
	v_mov_b32_e32 v56, v2
	v_mov_b32_e32 v57, v2
	v_mov_b32_e32 v10, v2
	v_mov_b32_e32 v11, v2
	v_mov_b32_e32 v12, v2
	v_mov_b32_e32 v13, v2
	v_mov_b32_e32 v18, v2
	v_mov_b32_e32 v19, v2
	v_mov_b32_e32 v20, v2
	v_mov_b32_e32 v21, v2
	v_mov_b32_e32 v26, v2
	v_mov_b32_e32 v27, v2
	v_mov_b32_e32 v28, v2
	v_mov_b32_e32 v29, v2
	v_mov_b32_e32 v30, v2
	v_mov_b32_e32 v31, v2
	v_mov_b32_e32 v32, v2
	v_mov_b32_e32 v33, v2
	v_mov_b32_e32 v42, v2
	v_mov_b32_e32 v43, v2
	v_mov_b32_e32 v44, v2
	v_mov_b32_e32 v45, v2
	v_mov_b32_e32 v46, v2
	v_mov_b32_e32 v47, v2
	v_mov_b32_e32 v48, v2
	v_mov_b32_e32 v49, v2
	v_mov_b32_e32 v58, v2
	v_mov_b32_e32 v59, v2
	v_mov_b32_e32 v60, v2
	v_mov_b32_e32 v61, v2
	v_mov_b32_e32 v62, v2
	v_mov_b32_e32 v63, v2
	v_mov_b32_e32 v64, v2
	v_mov_b32_e32 v65, v2
	v_mov_b32_e32 v66, v2
	v_mov_b32_e32 v67, v2
	v_mov_b32_e32 v68, v2
	v_mov_b32_e32 v69, v2
	v_mov_b32_e32 v70, v2
	v_mov_b32_e32 v71, v2
	v_mov_b32_e32 v72, v2
	v_mov_b32_e32 v73, v2
	v_mov_b32_e32 v82, v2
	v_mov_b32_e32 v83, v2
	v_mov_b32_e32 v84, v2
	v_mov_b32_e32 v85, v2
	v_mov_b32_e32 v86, v2
	v_mov_b32_e32 v87, v2
	v_mov_b32_e32 v88, v2
	v_mov_b32_e32 v89, v2
	v_mov_b32_e32 v98, v2
	v_mov_b32_e32 v99, v2
	v_mov_b32_e32 v100, v2
	v_mov_b32_e32 v101, v2
	v_mov_b32_e32 v102, v2
	v_mov_b32_e32 v103, v2
	v_mov_b32_e32 v104, v2
	v_mov_b32_e32 v105, v2
	v_mov_b32_e32 v114, v2
	v_mov_b32_e32 v115, v2
	v_mov_b32_e32 v116, v2
	v_mov_b32_e32 v117, v2
	v_mov_b32_e32 v118, v2
	v_mov_b32_e32 v119, v2
	v_mov_b32_e32 v120, v2
	v_mov_b32_e32 v121, v2
	v_mov_b32_e32 v74, v2
	v_mov_b32_e32 v75, v2
	v_mov_b32_e32 v76, v2
	v_mov_b32_e32 v77, v2
	v_mov_b32_e32 v78, v2
	v_mov_b32_e32 v79, v2
	v_mov_b32_e32 v80, v2
	v_mov_b32_e32 v81, v2
	v_mov_b32_e32 v90, v2
	v_mov_b32_e32 v91, v2
	v_mov_b32_e32 v92, v2
	v_mov_b32_e32 v93, v2
	v_mov_b32_e32 v94, v2
	v_mov_b32_e32 v95, v2
	v_mov_b32_e32 v96, v2
	v_mov_b32_e32 v97, v2
	v_mov_b32_e32 v106, v2
	v_mov_b32_e32 v107, v2
	v_mov_b32_e32 v108, v2
	v_mov_b32_e32 v109, v2
	v_mov_b32_e32 v110, v2
	v_mov_b32_e32 v111, v2
	v_mov_b32_e32 v112, v2
	v_mov_b32_e32 v113, v2
	v_mov_b32_e32 v122, v2
	v_mov_b32_e32 v123, v2
	v_mov_b32_e32 v124, v2
	v_mov_b32_e32 v125, v2
	v_mov_b32_e32 v126, v2
	v_mov_b32_e32 v127, v2
	v_mov_b32_e32 v128, v2
	v_mov_b32_e32 v129, v2
	s_andn2_b64 vcc, exec, s[40:41]
	s_cbranch_vccnz .LBB0_464

; #define PG8_STAGE(bufoff, gbase, voff) do { _Pragma("unroll") for (int _i = 0; _i < 2; ++_i) \
;         __builtin_amdgcn_global_load_lds((const unsigned*)((const char*)(gbase) + (voff)[_i]), (LAS unsigned*)(lds + (bufoff) + ldsw + _i * 8192), 16, 0, 0); } while (0)
; #define PG8_LDA(dst, b, h) do { _Pragma("unroll") for (int m = 0; m < 4; ++m) _Pragma("unroll") for (int k = 0; k < 2; ++k) dst[m][k] = *(const LAS bf16x8*)(lds + PG8_SA(b, h) + aoff + m * 2048 + k * 1024); } while (0)
; #define PG8_LDB(dst, b, h) do { _Pragma("unroll") for (int n = 0; n < 2; ++n) _Pragma("unroll") for (int k = 0; k < 2; ++k) dst[n][k] = *(const LAS bf16x8*)(lds + PG8_SB(b, h) + boff + n * 2048 + k * 1024); } while (0)
; #define PG8_MMA(ai, bj, At, Bt) do { __builtin_amdgcn_s_setprio(1); _Pragma("unroll") for (int m = 0; m < 4; ++m) _Pragma("unroll") for (int n = 0; n < 2; ++n) _Pragma("unroll") for (int k = 0; k < 2; ++k) \
;         acc[ai][bj][m][n] = __builtin_amdgcn_mfma_f32_16x16x32_bf16(Bt[n][k], At[m][k], acc[ai][bj][m][n], 0, 0, 0); __builtin_amdgcn_s_setprio(0); } while (0)
; #define PG8_WAIT_L(n) asm volatile("s_waitcnt lgkmcnt(" #n ")" ::: "memory")
; template <class Epi>
; __device__ __forceinline__ void gemm_phase(LAS unsigned char* lds, const Gemm g, const StaticOrder& S, const Epi& E) {
;     ...
;         const bool has_next = S.next(ui + 1, nxt);
;         const char* nA = has_next ? (const char*)g.A + (size_t)nxt.pm * tstepA + (size_t)(nxt.pn >> 2) * gstepA : cA; const char* nB = has_next ? (const char*)g.Bt + (size_t)nxt.pn * tstepB : cB;
;         for (int t = 0; t < nt; t += 2) {
;             const bool last = (t == nt - 2);
;             const char* a1 = cA + (size_t)(t + 1) * kstepA;
;             const char* a2 = last ? nA : cA + (size_t)(t + 2) * kstepA; const char* b2 = last ? nB : cB + (size_t)(t + 2) * kstep;
;             const char* a3 = a2 + kstepA; const char* b3 = b2 + kstep;
;             PG8_LDB(B0, 0, 0); PG8_SCHED; PG8_LDA(At, 0, 0); PG8_STAGE(PG8_SA(1, 1), a1 + hstepA, voffA);
;             PG8_WAIT_L(8); PG8_BAR; PG8_WAIT_L(0); PG8_MMA(0, 0, At, B0); PG8_BAR; PG8_SCHED;
;     ...
;         for (int a = 0; a < 2; ++a)
; #pragma unroll
;             for (int b = 0; b < 2; ++b)
; #pragma unroll
;                 for (int m = 0; m < 4; ++m)
; #pragma unroll
;                     for (int n = 0; n < 2; ++n) acc[a][b][m][n] = (f32x4){0.f, 0.f, 0.f, 0.f};
.LBB0_602:
	s_ashr_i32 s53, s52, 31
	v_cmp_lt_i64_e32 vcc, s[4:5], v[182:183]
	s_lshl_b64 s[4:5], s[52:53], 21
	s_add_u32 s10, s15, s4
	s_addc_u32 s11, s16, s5
	s_ashr_i32 s4, s50, 2
	s_ashr_i32 s5, s4, 31
	s_lshl_b64 s[4:5], s[4:5], 11
	s_add_u32 s54, s10, s4
	s_addc_u32 s55, s11, s5
	s_and_b64 s[4:5], vcc, exec
	s_cselect_b32 s35, s55, s1
	s_cselect_b32 s36, s54, s0
	s_ashr_i32 s51, s50, 31
	s_lshl_b64 s[4:5], s[50:51], 19
	s_add_u32 s56, s17, s4
	s_addc_u32 s57, s18, s5
	s_and_b64 s[4:5], vcc, exec
	s_cselect_b32 s37, s57, s9
	s_cselect_b32 s51, s56, s8
	s_add_u32 s53, s8, 0x100
	v_mov_b32_e32 v2, 0
	s_addc_u32 s58, s9, 0
	s_mov_b32 s59, -2
	v_mov_b32_e32 v3, v2
	v_mov_b32_e32 v4, v2
	v_mov_b32_e32 v5, v2
	v_mov_b32_e32 v6, v2
	v_mov_b32_e32 v7, v2
	v_mov_b32_e32 v8, v2
	v_mov_b32_e32 v9, v2
	v_mov_b32_e32 v10, v2
	v_mov_b32_e32 v11, v2
	v_mov_b32_e32 v12, v2
	v_mov_b32_e32 v13, v2
	v_mov_b32_e32 v14, v2
	v_mov_b32_e32 v15, v2
	v_mov_b32_e32 v16, v2
	v_mov_b32_e32 v17, v2
	v_mov_b32_e32 v18, v2
	v_mov_b32_e32 v19, v2
	v_mov_b32_e32 v20, v2
	v_mov_b32_e32 v21, v2
	v_mov_b32_e32 v22, v2
	v_mov_b32_e32 v23, v2
	v_mov_b32_e32 v24, v2
	v_mov_b32_e32 v25, v2
	v_mov_b32_e32 v26, v2
	v_mov_b32_e32 v27, v2
	v_mov_b32_e32 v28, v2
	v_mov_b32_e32 v29, v2
	v_mov_b32_e32 v30, v2
	v_mov_b32_e32 v31, v2
	v_mov_b32_e32 v32, v2
	v_mov_b32_e32 v33, v2
	v_mov_b32_e32 v74, v2
	v_mov_b32_e32 v75, v2
	v_mov_b32_e32 v76, v2
	v_mov_b32_e32 v77, v2
	v_mov_b32_e32 v78, v2
	v_mov_b32_e32 v79, v2
	v_mov_b32_e32 v80, v2
	v_mov_b32_e32 v81, v2
	v_mov_b32_e32 v82, v2
	v_mov_b32_e32 v83, v2
	v_mov_b32_e32 v84, v2
	v_mov_b32_e32 v85, v2
	v_mov_b32_e32 v86, v2
	v_mov_b32_e32 v87, v2
	v_mov_b32_e32 v88, v2
	v_mov_b32_e32 v89, v2
	v_mov_b32_e32 v90, v2
	v_mov_b32_e32 v91, v2
	v_mov_b32_e32 v92, v2
	v_mov_b32_e32 v93, v2
	v_mov_b32_e32 v94, v2
	v_mov_b32_e32 v95, v2
	v_mov_b32_e32 v96, v2
	v_mov_b32_e32 v97, v2
	v_mov_b32_e32 v110, v2
	v_mov_b32_e32 v111, v2
	v_mov_b32_e32 v112, v2
	v_mov_b32_e32 v113, v2
	v_mov_b32_e32 v114, v2
	v_mov_b32_e32 v115, v2
	v_mov_b32_e32 v116, v2
	v_mov_b32_e32 v117, v2
	v_mov_b32_e32 v42, v2
	v_mov_b32_e32 v43, v2
	v_mov_b32_e32 v44, v2
	v_mov_b32_e32 v45, v2
	v_mov_b32_e32 v46, v2
	v_mov_b32_e32 v47, v2
	v_mov_b32_e32 v48, v2
	v_mov_b32_e32 v49, v2
	v_mov_b32_e32 v50, v2
	v_mov_b32_e32 v51, v2
	v_mov_b32_e32 v52, v2
	v_mov_b32_e32 v53, v2
	v_mov_b32_e32 v54, v2
	v_mov_b32_e32 v55, v2
	v_mov_b32_e32 v56, v2
	v_mov_b32_e32 v57, v2
	v_mov_b32_e32 v58, v2
	v_mov_b32_e32 v59, v2
	v_mov_b32_e32 v60, v2
	v_mov_b32_e32 v61, v2
	v_mov_b32_e32 v62, v2
	v_mov_b32_e32 v63, v2
	v_mov_b32_e32 v64, v2
	v_mov_b32_e32 v65, v2
	v_mov_b32_e32 v66, v2
	v_mov_b32_e32 v67, v2
	v_mov_b32_e32 v68, v2
	v_mov_b32_e32 v69, v2
	v_mov_b32_e32 v70, v2
	v_mov_b32_e32 v71, v2
	v_mov_b32_e32 v72, v2
	v_mov_b32_e32 v73, v2
	v_mov_b32_e32 v122, v2
	v_mov_b32_e32 v123, v2
	v_mov_b32_e32 v124, v2
	v_mov_b32_e32 v125, v2
	v_mov_b32_e32 v126, v2
	v_mov_b32_e32 v127, v2
	v_mov_b32_e32 v128, v2
	v_mov_b32_e32 v129, v2
	v_mov_b32_e32 v134, v2
	v_mov_b32_e32 v135, v2
	v_mov_b32_e32 v136, v2
	v_mov_b32_e32 v137, v2
	v_mov_b32_e32 v138, v2
	v_mov_b32_e32 v139, v2
	v_mov_b32_e32 v140, v2
	v_mov_b32_e32 v141, v2
	v_mov_b32_e32 v146, v2
	v_mov_b32_e32 v147, v2
	v_mov_b32_e32 v148, v2
	v_mov_b32_e32 v149, v2
	v_mov_b32_e32 v150, v2
	v_mov_b32_e32 v151, v2
	v_mov_b32_e32 v152, v2
	v_mov_b32_e32 v153, v2
	v_mov_b32_e32 v162, v2
	v_mov_b32_e32 v163, v2
	v_mov_b32_e32 v164, v2
	v_mov_b32_e32 v165, v2
	v_mov_b32_e32 v166, v2
	v_mov_b32_e32 v167, v2
	v_mov_b32_e32 v168, v2
	v_mov_b32_e32 v169, v2
	v_readfirstlane_b32 s100, v232
	s_nop 3
	s_cmp_ge_u32 s100, 0x100
	s_cbranch_scc0 .Lprio_skip_3
	s_setprio 1
.Lprio_skip_3:
.LBB0_603:
	s_add_u32 s8, s0, 0x100
	s_addc_u32 s9, s1, 0
	s_add_i32 s60, 0, 0x10000
	v_add_u32_e32 v102, s60, v229
	ds_read_b128 v[34:37], v102
	ds_read_b128 v[38:41], v102 offset:1024
	ds_read_b128 v[98:101], v102 offset:2048
	ds_read_b128 v[102:105], v102 offset:3072
	s_cmp_eq_u32 s59, 12
	s_cselect_b32 s11, s35, s9
	s_cselect_b32 s10, s36, s8
	s_cselect_b32 s5, s37, s58
	s_cselect_b32 s4, s51, s53
	v_lshl_add_u64 v[184:185], s[0:1], 0, v[194:195]
	s_add_i32 m0, s20, 0xc000
	ds_read_b128 v[106:109], v231
	ds_read_b128 v[118:121], v231 offset:1024
	ds_read_b128 v[130:133], v231 offset:2048
	ds_read_b128 v[142:145], v231 offset:3072
	ds_read_b128 v[154:157], v231 offset:4096
	ds_read_b128 v[158:161], v231 offset:5120
	ds_read_b128 v[170:173], v231 offset:6144
	ds_read_b128 v[174:177], v231 offset:7168
	global_load_lds_dwordx4 v[184:185], off
	v_lshl_add_u64 v[184:185], s[0:1], 0, v[196:197]
	s_add_i32 m0, s20, 0xe000
	s_nop 0
	global_load_lds_dwordx4 v[184:185], off
	s_waitcnt lgkmcnt(8)
	s_barrier
	s_waitcnt lgkmcnt(0)
	s_waitcnt lgkmcnt(0)
	v_mfma_f32_16x16x32_bf16 v[166:169], v[34:37], v[106:109], v[166:169]
	v_mfma_f32_16x16x32_bf16 v[162:165], v[98:101], v[106:109], v[162:165]
	v_mfma_f32_16x16x32_bf16 v[150:153], v[34:37], v[130:133], v[150:153]
	v_mfma_f32_16x16x32_bf16 v[146:149], v[98:101], v[130:133], v[146:149]
	v_mfma_f32_16x16x32_bf16 v[138:141], v[34:37], v[154:157], v[138:141]
	v_mfma_f32_16x16x32_bf16 v[134:137], v[98:101], v[154:157], v[134:137]
	v_mfma_f32_16x16x32_bf16 v[126:129], v[34:37], v[170:173], v[126:129]
	v_mfma_f32_16x16x32_bf16 v[122:125], v[98:101], v[170:173], v[122:125]
	v_mfma_f32_16x16x32_bf16 v[166:169], v[38:41], v[118:121], v[166:169]
	v_mfma_f32_16x16x32_bf16 v[162:165], v[102:105], v[118:121], v[162:165]
	v_mfma_f32_16x16x32_bf16 v[150:153], v[38:41], v[142:145], v[150:153]
	v_mfma_f32_16x16x32_bf16 v[146:149], v[102:105], v[142:145], v[146:149]
	v_mfma_f32_16x16x32_bf16 v[138:141], v[38:41], v[158:161], v[138:141]
	v_mfma_f32_16x16x32_bf16 v[134:137], v[102:105], v[158:161], v[134:137]
	v_mfma_f32_16x16x32_bf16 v[126:129], v[38:41], v[174:177], v[126:129]
	v_mfma_f32_16x16x32_bf16 v[122:125], v[102:105], v[174:177], v[122:125]
	s_barrier
; #define PG8_STAGE(bufoff, gbase, voff) do { _Pragma("unroll") for (int _i = 0; _i < 2; ++_i) \
;         __builtin_amdgcn_global_load_lds((const unsigned*)((const char*)(gbase) + (voff)[_i]), (LAS unsigned*)(lds + (bufoff) + ldsw + _i * 8192), 16, 0, 0); } while (0)
; #define PG8_LDA(dst, b, h) do { _Pragma("unroll") for (int m = 0; m < 4; ++m) _Pragma("unroll") for (int k = 0; k < 2; ++k) dst[m][k] = *(const LAS bf16x8*)(lds + PG8_SA(b, h) + aoff + m * 2048 + k * 1024); } while (0)
; #define PG8_LDB(dst, b, h) do { _Pragma("unroll") for (int n = 0; n < 2; ++n) _Pragma("unroll") for (int k = 0; k < 2; ++k) dst[n][k] = *(const LAS bf16x8*)(lds + PG8_SB(b, h) + boff + n * 2048 + k * 1024); } while (0)
; #define PG8_MMA(ai, bj, At, Bt) do { __builtin_amdgcn_s_setprio(1); _Pragma("unroll") for (int m = 0; m < 4; ++m) _Pragma("unroll") for (int n = 0; n < 2; ++n) _Pragma("unroll") for (int k = 0; k < 2; ++k) \
;         acc[ai][bj][m][n] = __builtin_amdgcn_mfma_f32_16x16x32_bf16(Bt[n][k], At[m][k], acc[ai][bj][m][n], 0, 0, 0); __builtin_amdgcn_s_setprio(0); } while (0)
; #define PG8_WAIT_V(n) asm volatile("s_waitcnt vmcnt(" #n ")" ::: "memory")
; #define PG8_WAIT_L(n) asm volatile("s_waitcnt lgkmcnt(" #n ")" ::: "memory")
; #define PG8_BAR __builtin_amdgcn_s_barrier()
; #define PG8_SCHED __builtin_amdgcn_sched_barrier(0)
; template <class Epi>
; __device__ __forceinline__ void gemm_phase(LAS unsigned char* lds, const Gemm g, const StaticOrder& S, const Epi& E) {
;     ...
;             PG8_LDB(B1, 0, 1); PG8_STAGE(PG8_SB(0, 0), b2, voffB);
;             PG8_BAR; PG8_WAIT_L(0); PG8_MMA(0, 1, At, B1); PG8_BAR;
;             PG8_LDA(At, 0, 1); PG8_STAGE(PG8_SA(0, 0), a2, voffA);
;             PG8_BAR; PG8_WAIT_L(0); PG8_MMA(1, 0, At, B0); PG8_BAR; PG8_SCHED;
;             PG8_STAGE(PG8_SB(0, 1), b2 + hstepB, voffB);
;             PG8_WAIT_V(6); PG8_BAR; PG8_MMA(1, 1, At, B1); PG8_BAR;
;             PG8_LDB(B0, 1, 0); PG8_SCHED; PG8_LDA(At, 1, 0); PG8_STAGE(PG8_SA(0, 1), a2 + hstepA, voffA);
;             PG8_WAIT_L(8); PG8_BAR; PG8_WAIT_L(0); PG8_MMA(0, 0, At, B0); PG8_BAR; PG8_SCHED;
	s_add_i32 s61, 0, 0x14000
	v_add_u32_e32 v184, s61, v229
	s_add_i32 s0, s60, s19
	ds_read_b128 v[198:201], v184
	ds_read_b128 v[202:205], v184 offset:1024
	ds_read_b128 v[206:209], v184 offset:2048
	ds_read_b128 v[210:213], v184 offset:3072
	v_lshl_add_u64 v[184:185], s[4:5], 0, v[0:1]
	s_mov_b32 m0, s0
	v_lshl_add_u64 v[186:187], s[4:5], 0, v[188:189]
	global_load_lds_dwordx4 v[184:185], off
	s_add_i32 m0, s0, 0x2000
	s_nop 0
	global_load_lds_dwordx4 v[186:187], off
	s_barrier
	s_waitcnt lgkmcnt(0)
	s_waitcnt lgkmcnt(0)
	v_mfma_f32_16x16x32_bf16 v[70:73], v[198:201], v[106:109], v[70:73]
	v_mfma_f32_16x16x32_bf16 v[66:69], v[206:209], v[106:109], v[66:69]
	v_mfma_f32_16x16x32_bf16 v[62:65], v[198:201], v[130:133], v[62:65]
	v_mfma_f32_16x16x32_bf16 v[58:61], v[206:209], v[130:133], v[58:61]
	v_mfma_f32_16x16x32_bf16 v[54:57], v[198:201], v[154:157], v[54:57]
	v_mfma_f32_16x16x32_bf16 v[50:53], v[206:209], v[154:157], v[50:53]
	v_mfma_f32_16x16x32_bf16 v[46:49], v[198:201], v[170:173], v[46:49]
	v_mfma_f32_16x16x32_bf16 v[42:45], v[206:209], v[170:173], v[42:45]
	v_mfma_f32_16x16x32_bf16 v[70:73], v[202:205], v[118:121], v[70:73]
	v_mfma_f32_16x16x32_bf16 v[66:69], v[210:213], v[118:121], v[66:69]
	v_mfma_f32_16x16x32_bf16 v[62:65], v[202:205], v[142:145], v[62:65]
	v_mfma_f32_16x16x32_bf16 v[58:61], v[210:213], v[142:145], v[58:61]
	v_mfma_f32_16x16x32_bf16 v[54:57], v[202:205], v[158:161], v[54:57]
	v_mfma_f32_16x16x32_bf16 v[50:53], v[210:213], v[158:161], v[50:53]
	v_mfma_f32_16x16x32_bf16 v[46:49], v[202:205], v[174:177], v[46:49]
	v_mfma_f32_16x16x32_bf16 v[42:45], v[210:213], v[174:177], v[42:45]
	s_mov_b32 m0, s20
	v_lshl_add_u64 v[214:215], s[10:11], 0, v[192:193]
	s_barrier
	ds_read_b128 v[106:109], v231 offset:16384
	ds_read_b128 v[118:121], v231 offset:17408
	ds_read_b128 v[130:133], v231 offset:18432
	ds_read_b128 v[142:145], v231 offset:19456
	ds_read_b128 v[154:157], v231 offset:20480
	ds_read_b128 v[158:161], v231 offset:21504
	ds_read_b128 v[170:173], v231 offset:22528
	ds_read_b128 v[174:177], v231 offset:23552
	global_load_lds_dwordx4 v[214:215], off
	v_lshl_add_u64 v[216:217], s[10:11], 0, v[190:191]
	s_mov_b32 m0, s21
	s_nop 0
	global_load_lds_dwordx4 v[216:217], off
	s_barrier
	s_waitcnt lgkmcnt(0)
	s_waitcnt lgkmcnt(0)
	v_mfma_f32_16x16x32_bf16 v[114:117], v[34:37], v[106:109], v[114:117]
	v_mfma_f32_16x16x32_bf16 v[110:113], v[98:101], v[106:109], v[110:113]
	v_mfma_f32_16x16x32_bf16 v[94:97], v[34:37], v[130:133], v[94:97]
	v_mfma_f32_16x16x32_bf16 v[90:93], v[98:101], v[130:133], v[90:93]
	v_mfma_f32_16x16x32_bf16 v[86:89], v[34:37], v[154:157], v[86:89]
	v_mfma_f32_16x16x32_bf16 v[82:85], v[98:101], v[154:157], v[82:85]
	v_mfma_f32_16x16x32_bf16 v[34:37], v[34:37], v[170:173], v[78:81]
	v_mfma_f32_16x16x32_bf16 v[114:117], v[38:41], v[118:121], v[114:117]
	v_mfma_f32_16x16x32_bf16 v[110:113], v[102:105], v[118:121], v[110:113]
	v_mfma_f32_16x16x32_bf16 v[94:97], v[38:41], v[142:145], v[94:97]
	v_mfma_f32_16x16x32_bf16 v[90:93], v[102:105], v[142:145], v[90:93]
	v_mfma_f32_16x16x32_bf16 v[86:89], v[38:41], v[158:161], v[86:89]
	v_mfma_f32_16x16x32_bf16 v[82:85], v[102:105], v[158:161], v[82:85]
	v_mfma_f32_16x16x32_bf16 v[34:37], v[38:41], v[174:177], v[34:37]
	v_mfma_f32_16x16x32_bf16 v[38:41], v[98:101], v[170:173], v[74:77]
	v_mfma_f32_16x16x32_bf16 v[38:41], v[102:105], v[174:177], v[38:41]
	s_barrier
	s_add_u32 s0, s4, 0x40000
	s_addc_u32 s1, s5, 0
	s_add_i32 s60, s61, s19
	v_lshl_add_u64 v[74:75], s[0:1], 0, v[0:1]
	s_mov_b32 m0, s60
	s_nop 0
	global_load_lds_dwordx4 v[74:75], off
	v_lshl_add_u64 v[74:75], s[0:1], 0, v[188:189]
	s_add_i32 m0, s60, 0x2000
	s_nop 0
	global_load_lds_dwordx4 v[74:75], off
	s_waitcnt vmcnt(6)
	s_barrier
	v_mfma_f32_16x16x32_bf16 v[30:33], v[198:201], v[106:109], v[30:33]
	v_mfma_f32_16x16x32_bf16 v[26:29], v[206:209], v[106:109], v[26:29]
	v_mfma_f32_16x16x32_bf16 v[22:25], v[198:201], v[130:133], v[22:25]
	v_mfma_f32_16x16x32_bf16 v[18:21], v[206:209], v[130:133], v[18:21]
	v_mfma_f32_16x16x32_bf16 v[14:17], v[198:201], v[154:157], v[14:17]
	v_mfma_f32_16x16x32_bf16 v[10:13], v[206:209], v[154:157], v[10:13]
	v_mfma_f32_16x16x32_bf16 v[6:9], v[198:201], v[170:173], v[6:9]
	v_mfma_f32_16x16x32_bf16 v[2:5], v[206:209], v[170:173], v[2:5]
	v_mfma_f32_16x16x32_bf16 v[30:33], v[202:205], v[118:121], v[30:33]
	v_mfma_f32_16x16x32_bf16 v[26:29], v[210:213], v[118:121], v[26:29]
	v_mfma_f32_16x16x32_bf16 v[22:25], v[202:205], v[142:145], v[22:25]
	v_mfma_f32_16x16x32_bf16 v[18:21], v[210:213], v[142:145], v[18:21]
	v_mfma_f32_16x16x32_bf16 v[14:17], v[202:205], v[158:161], v[14:17]
	v_mfma_f32_16x16x32_bf16 v[10:13], v[210:213], v[158:161], v[10:13]
	v_mfma_f32_16x16x32_bf16 v[6:9], v[202:205], v[174:177], v[6:9]
	v_mfma_f32_16x16x32_bf16 v[2:5], v[210:213], v[174:177], v[2:5]
	s_add_i32 s60, 0, 0x18000
	v_add_u32_e32 v102, s60, v229
	s_barrier
	ds_read_b128 v[74:77], v102
	ds_read_b128 v[78:81], v102 offset:1024
	ds_read_b128 v[98:101], v102 offset:2048
	ds_read_b128 v[102:105], v102 offset:3072
	s_add_u32 s0, s10, 0x100000
	s_addc_u32 s1, s11, 0
	s_mov_b32 m0, s22
	v_lshl_add_u64 v[198:199], s[0:1], 0, v[192:193]
	ds_read_b128 v[106:109], v231 offset:32768
	ds_read_b128 v[118:121], v231 offset:33792
	ds_read_b128 v[130:133], v231 offset:34816
	ds_read_b128 v[142:145], v231 offset:35840
	ds_read_b128 v[154:157], v231 offset:36864
	ds_read_b128 v[158:161], v231 offset:37888
	ds_read_b128 v[170:173], v231 offset:38912
	ds_read_b128 v[174:177], v231 offset:39936
	global_load_lds_dwordx4 v[198:199], off
	v_lshl_add_u64 v[198:199], s[0:1], 0, v[190:191]
	s_mov_b32 m0, s23
	s_nop 0
	global_load_lds_dwordx4 v[198:199], off
	s_waitcnt lgkmcnt(8)
	s_barrier
; #define PG8_STAGE(bufoff, gbase, voff) do { _Pragma("unroll") for (int _i = 0; _i < 2; ++_i) \
;         __builtin_amdgcn_global_load_lds((const unsigned*)((const char*)(gbase) + (voff)[_i]), (LAS unsigned*)(lds + (bufoff) + ldsw + _i * 8192), 16, 0, 0); } while (0)
; #define PG8_LDA(dst, b, h) do { _Pragma("unroll") for (int m = 0; m < 4; ++m) _Pragma("unroll") for (int k = 0; k < 2; ++k) dst[m][k] = *(const LAS bf16x8*)(lds + PG8_SA(b, h) + aoff + m * 2048 + k * 1024); } while (0)
; #define PG8_LDB(dst, b, h) do { _Pragma("unroll") for (int n = 0; n < 2; ++n) _Pragma("unroll") for (int k = 0; k < 2; ++k) dst[n][k] = *(const LAS bf16x8*)(lds + PG8_SB(b, h) + boff + n * 2048 + k * 1024); } while (0)
; #define PG8_MMA(ai, bj, At, Bt) do { __builtin_amdgcn_s_setprio(1); _Pragma("unroll") for (int m = 0; m < 4; ++m) _Pragma("unroll") for (int n = 0; n < 2; ++n) _Pragma("unroll") for (int k = 0; k < 2; ++k) \
;         acc[ai][bj][m][n] = __builtin_amdgcn_mfma_f32_16x16x32_bf16(Bt[n][k], At[m][k], acc[ai][bj][m][n], 0, 0, 0); __builtin_amdgcn_s_setprio(0); } while (0)
; #define PG8_WAIT_V(n) asm volatile("s_waitcnt vmcnt(" #n ")" ::: "memory")
; #define PG8_WAIT_L(n) asm volatile("s_waitcnt lgkmcnt(" #n ")" ::: "memory")
; #define PG8_BAR __builtin_amdgcn_s_barrier()
; #define PG8_SCHED __builtin_amdgcn_sched_barrier(0)
; template <class Epi>
; __device__ __forceinline__ void gemm_phase(LAS unsigned char* lds, const Gemm g, const StaticOrder& S, const Epi& E) {
;     ...
;             PG8_WAIT_L(8); PG8_BAR; PG8_WAIT_L(0); PG8_MMA(0, 0, At, B0); PG8_BAR; PG8_SCHED;
;             PG8_LDB(B1, 1, 1); PG8_STAGE(PG8_SB(1, 0), b3, voffB);
;             PG8_BAR; PG8_WAIT_L(0); PG8_MMA(0, 1, At, B1); PG8_BAR;
;             PG8_LDA(At, 1, 1); PG8_STAGE(PG8_SA(1, 0), a3, voffA);
;             PG8_BAR; PG8_WAIT_L(0); PG8_MMA(1, 0, At, B0); PG8_BAR; PG8_SCHED;
;             PG8_STAGE(PG8_SB(1, 1), b3 + hstepB, voffB);
;             PG8_WAIT_V(6); PG8_BAR; PG8_MMA(1, 1, At, B1); PG8_BAR;
	s_waitcnt lgkmcnt(0)
	s_waitcnt lgkmcnt(0)
	v_mfma_f32_16x16x32_bf16 v[166:169], v[74:77], v[106:109], v[166:169]
	v_mfma_f32_16x16x32_bf16 v[162:165], v[98:101], v[106:109], v[162:165]
	v_mfma_f32_16x16x32_bf16 v[150:153], v[74:77], v[130:133], v[150:153]
	v_mfma_f32_16x16x32_bf16 v[146:149], v[98:101], v[130:133], v[146:149]
	v_mfma_f32_16x16x32_bf16 v[138:141], v[74:77], v[154:157], v[138:141]
	v_mfma_f32_16x16x32_bf16 v[134:137], v[98:101], v[154:157], v[134:137]
	v_mfma_f32_16x16x32_bf16 v[126:129], v[74:77], v[170:173], v[126:129]
	v_mfma_f32_16x16x32_bf16 v[122:125], v[98:101], v[170:173], v[122:125]
	v_mfma_f32_16x16x32_bf16 v[166:169], v[78:81], v[118:121], v[166:169]
	v_mfma_f32_16x16x32_bf16 v[162:165], v[102:105], v[118:121], v[162:165]
	v_mfma_f32_16x16x32_bf16 v[150:153], v[78:81], v[142:145], v[150:153]
	v_mfma_f32_16x16x32_bf16 v[146:149], v[102:105], v[142:145], v[146:149]
	v_mfma_f32_16x16x32_bf16 v[138:141], v[78:81], v[158:161], v[138:141]
	v_mfma_f32_16x16x32_bf16 v[134:137], v[102:105], v[158:161], v[134:137]
	v_mfma_f32_16x16x32_bf16 v[126:129], v[78:81], v[174:177], v[126:129]
	v_mfma_f32_16x16x32_bf16 v[122:125], v[102:105], v[174:177], v[122:125]
	s_barrier
	s_add_i32 s10, 0, 0x1c000
	s_add_i32 s0, s60, s19
	v_add_u32_e32 v210, s10, v229
	v_lshl_add_u64 v[184:185], v[184:185], 0, s[6:7]
	s_mov_b32 m0, s0
	ds_read_b128 v[198:201], v210
	ds_read_b128 v[202:205], v210 offset:1024
	ds_read_b128 v[206:209], v210 offset:2048
	ds_read_b128 v[210:213], v210 offset:3072
	global_load_lds_dwordx4 v[184:185], off
	v_lshl_add_u64 v[184:185], v[186:187], 0, s[6:7]
	s_add_i32 m0, s0, 0x2000
	s_nop 0
	global_load_lds_dwordx4 v[184:185], off
	s_barrier
	s_waitcnt lgkmcnt(0)
	s_waitcnt lgkmcnt(0)
	v_mfma_f32_16x16x32_bf16 v[70:73], v[198:201], v[106:109], v[70:73]
	v_mfma_f32_16x16x32_bf16 v[66:69], v[206:209], v[106:109], v[66:69]
	v_mfma_f32_16x16x32_bf16 v[62:65], v[198:201], v[130:133], v[62:65]
	v_mfma_f32_16x16x32_bf16 v[58:61], v[206:209], v[130:133], v[58:61]
	v_mfma_f32_16x16x32_bf16 v[54:57], v[198:201], v[154:157], v[54:57]
	v_mfma_f32_16x16x32_bf16 v[50:53], v[206:209], v[154:157], v[50:53]
	v_mfma_f32_16x16x32_bf16 v[46:49], v[198:201], v[170:173], v[46:49]
	v_mfma_f32_16x16x32_bf16 v[42:45], v[206:209], v[170:173], v[42:45]
	v_mfma_f32_16x16x32_bf16 v[70:73], v[202:205], v[118:121], v[70:73]
	v_mfma_f32_16x16x32_bf16 v[66:69], v[210:213], v[118:121], v[66:69]
	v_mfma_f32_16x16x32_bf16 v[62:65], v[202:205], v[142:145], v[62:65]
	v_mfma_f32_16x16x32_bf16 v[58:61], v[210:213], v[142:145], v[58:61]
	v_mfma_f32_16x16x32_bf16 v[54:57], v[202:205], v[158:161], v[54:57]
	v_mfma_f32_16x16x32_bf16 v[50:53], v[210:213], v[158:161], v[50:53]
	v_mfma_f32_16x16x32_bf16 v[46:49], v[202:205], v[174:177], v[46:49]
	v_mfma_f32_16x16x32_bf16 v[42:45], v[210:213], v[174:177], v[42:45]
	s_mov_b32 m0, s24
	v_lshl_add_u64 v[184:185], v[214:215], 0, s[6:7]
	s_barrier
	ds_read_b128 v[106:109], v231 offset:49152
	ds_read_b128 v[118:121], v231 offset:50176
	ds_read_b128 v[130:133], v231 offset:51200
	ds_read_b128 v[142:145], v231 offset:52224
	ds_read_b128 v[154:157], v231 offset:53248
	ds_read_b128 v[158:161], v231 offset:54272
	ds_read_b128 v[170:173], v231 offset:55296
	ds_read_b128 v[174:177], v231 offset:56320
	global_load_lds_dwordx4 v[184:185], off
	v_lshl_add_u64 v[184:185], v[216:217], 0, s[6:7]
	s_mov_b32 m0, s25
	s_nop 0
	global_load_lds_dwordx4 v[184:185], off
	s_barrier
	s_waitcnt lgkmcnt(0)
	s_waitcnt lgkmcnt(0)
	v_mfma_f32_16x16x32_bf16 v[114:117], v[74:77], v[106:109], v[114:117]
	v_mfma_f32_16x16x32_bf16 v[94:97], v[74:77], v[130:133], v[94:97]
	v_mfma_f32_16x16x32_bf16 v[86:89], v[74:77], v[154:157], v[86:89]
	v_mfma_f32_16x16x32_bf16 v[34:37], v[74:77], v[170:173], v[34:37]
	v_mfma_f32_16x16x32_bf16 v[114:117], v[78:81], v[118:121], v[114:117]
	v_mfma_f32_16x16x32_bf16 v[110:113], v[98:101], v[106:109], v[110:113]
	v_mfma_f32_16x16x32_bf16 v[94:97], v[78:81], v[142:145], v[94:97]
	v_mfma_f32_16x16x32_bf16 v[90:93], v[98:101], v[130:133], v[90:93]
	v_mfma_f32_16x16x32_bf16 v[86:89], v[78:81], v[158:161], v[86:89]
	v_mfma_f32_16x16x32_bf16 v[82:85], v[98:101], v[154:157], v[82:85]
	v_mfma_f32_16x16x32_bf16 v[78:81], v[78:81], v[174:177], v[34:37]
	v_mfma_f32_16x16x32_bf16 v[34:37], v[98:101], v[170:173], v[38:41]
	v_mfma_f32_16x16x32_bf16 v[110:113], v[102:105], v[118:121], v[110:113]
	v_mfma_f32_16x16x32_bf16 v[90:93], v[102:105], v[142:145], v[90:93]
	v_mfma_f32_16x16x32_bf16 v[82:85], v[102:105], v[158:161], v[82:85]
	v_mfma_f32_16x16x32_bf16 v[74:77], v[102:105], v[174:177], v[34:37]
	s_barrier
	s_add_u32 s0, s4, 0x40080
	s_addc_u32 s1, s5, 0
	s_add_i32 s4, s10, s19
	v_lshl_add_u64 v[34:35], s[0:1], 0, v[0:1]
	s_mov_b32 m0, s4
	s_nop 0
	global_load_lds_dwordx4 v[34:35], off
	v_lshl_add_u64 v[34:35], s[0:1], 0, v[188:189]
	s_add_i32 m0, s4, 0x2000
	s_nop 0
	global_load_lds_dwordx4 v[34:35], off
	s_waitcnt vmcnt(6)
	s_barrier
	v_mfma_f32_16x16x32_bf16 v[30:33], v[198:201], v[106:109], v[30:33]
	v_mfma_f32_16x16x32_bf16 v[26:29], v[206:209], v[106:109], v[26:29]
	v_mfma_f32_16x16x32_bf16 v[22:25], v[198:201], v[130:133], v[22:25]
	v_mfma_f32_16x16x32_bf16 v[18:21], v[206:209], v[130:133], v[18:21]
	v_mfma_f32_16x16x32_bf16 v[14:17], v[198:201], v[154:157], v[14:17]
	v_mfma_f32_16x16x32_bf16 v[10:13], v[206:209], v[154:157], v[10:13]
	v_mfma_f32_16x16x32_bf16 v[6:9], v[198:201], v[170:173], v[6:9]
	v_mfma_f32_16x16x32_bf16 v[2:5], v[206:209], v[170:173], v[2:5]
	v_mfma_f32_16x16x32_bf16 v[30:33], v[202:205], v[118:121], v[30:33]
	v_mfma_f32_16x16x32_bf16 v[26:29], v[210:213], v[118:121], v[26:29]
	v_mfma_f32_16x16x32_bf16 v[22:25], v[202:205], v[142:145], v[22:25]
	v_mfma_f32_16x16x32_bf16 v[18:21], v[210:213], v[142:145], v[18:21]
	v_mfma_f32_16x16x32_bf16 v[14:17], v[202:205], v[158:161], v[14:17]
	v_mfma_f32_16x16x32_bf16 v[10:13], v[210:213], v[158:161], v[10:13]
	v_mfma_f32_16x16x32_bf16 v[6:9], v[202:205], v[174:177], v[6:9]
	v_mfma_f32_16x16x32_bf16 v[2:5], v[210:213], v[174:177], v[2:5]
	s_add_i32 s59, s59, 2
	s_add_u32 s53, s53, 0x100
	s_addc_u32 s58, s58, 0
	s_cmp_gt_u32 s59, 13
	s_mov_b64 s[0:1], s[8:9]
	s_barrier
; __device__ __forceinline__ unsigned cvt_pk_bf16(float lo, float hi) { unsigned r; asm volatile("v_cvt_pk_bf16_f32 %0, %1, %2" : "=v"(r) : "v"(lo), "v"(hi)); return r; }
; __device__ __forceinline__ float bf_lo(unsigned w) { return __uint_as_float(w << 16); }
; __device__ __forceinline__ float bf_hi(unsigned w) { return __uint_as_float(w & 0xffff0000u); }
; __device__ __forceinline__ float silu_f(float z) { return z * fast_rcp(1.0f + __builtin_amdgcn_exp2f(z * -1.44269504f)); }
; #define PG8_WAIT_V(n) asm volatile("s_waitcnt vmcnt(" #n ")" ::: "memory")
; #define PG8_BAR __builtin_amdgcn_s_barrier()
; template <class Epi>
; __device__ __forceinline__ void gemm_phase(LAS unsigned char* lds, const Gemm g, const StaticOrder& S, const Epi& E) {
;     ...
;             PG8_WAIT_V(6); PG8_BAR; PG8_MMA(1, 1, At, B1); PG8_BAR;
;         }
;     __device__ __forceinline__ void operator()(const f32x4 (&acc)[2][2][4][2], const Unit& u, int wr, int wc, int fr, int fq, const Pre&) const {
;         const int row0 = u.pm * BM + wr * 64 + fr, col0 = u.pn * BM + wc * 32 + 8 * fq;
;         f32x4 sc[2][2];
; #pragma unroll
;         for (int bj = 0; bj < 2; ++bj) { sc[bj][0] = *(const f32x4*)(scale + col0 + bj * HALF); sc[bj][1] = *(const f32x4*)(scale + col0 + bj * HALF + 4); }
; #pragma unroll
;         for (int bj = 0; bj < 2; ++bj) { const int c = col0 + bj * HALF;
;             u32x4 zv[8];
; #pragma unroll
;             for (int g8 = 0; g8 < 8; ++g8) zv[g8] = *(const u32x4*)(Z + (size_t)(row0 + (g8 >> 2) * HALF + (g8 & 3) * 16) * DE2 + c);
; #pragma unroll
;             for (int ai = 0; ai < 2; ++ai)
; #pragma unroll
;                 for (int m = 0; m < 4; ++m) { const int r = row0 + ai * HALF + m * 16;
;                     const u32x4 zw = zv[ai * 4 + m];
;                     const f32x4 a0 = acc[ai][bj][m][0] * sc[bj][0], a1 = acc[ai][bj][m][1] * sc[bj][1];
;                     u32x4 w;
;                     w.x = cvt_pk_bf16(a0[0] * silu_f(bf_lo(zw.x)), a0[1] * silu_f(bf_hi(zw.x)));
;                     w.y = cvt_pk_bf16(a0[2] * silu_f(bf_lo(zw.y)), a0[3] * silu_f(bf_hi(zw.y)));
;                     w.z = cvt_pk_bf16(a1[0] * silu_f(bf_lo(zw.z)), a1[1] * silu_f(bf_hi(zw.z)));
;                     w.w = cvt_pk_bf16(a1[2] * silu_f(bf_lo(zw.w)), a1[3] * silu_f(bf_hi(zw.w)));
;                     *(u32x4*)(O + (size_t)r * DE + c) = w; } }
	s_cbranch_scc0 .LBB0_603
	s_setprio 0
	v_lshl_or_b32 v200, s34, 8, v230
	v_ashrrev_i32_e32 v201, 31, v200
	v_lshl_add_u32 v226, s27, 8, v228
	v_lshlrev_b64 v[216:217], 1, v[200:201]
	v_ashrrev_i32_e32 v227, 31, v226
	v_lshl_add_u64 v[106:107], s[46:47], 0, v[216:217]
	v_lshlrev_b64 v[204:205], 14, v[226:227]
	v_lshl_add_u64 v[38:39], v[200:201], 2, s[48:49]
	v_lshl_add_u64 v[108:109], v[106:107], 0, v[204:205]
	global_load_dwordx4 v[98:101], v[38:39], off offset:16
	global_load_dwordx4 v[102:105], v[38:39], off
	global_load_dwordx4 v[34:37], v[38:39], off offset:528
	s_nop 0
	global_load_dwordx4 v[38:41], v[38:39], off offset:512
	v_or_b32_e32 v224, 16, v226
	global_load_dwordx4 v[174:177], v[108:109], off
	v_ashrrev_i32_e32 v225, 31, v224
	v_or_b32_e32 v222, 32, v226
	v_lshlrev_b64 v[198:199], 14, v[224:225]
	v_ashrrev_i32_e32 v223, 31, v222
	v_or_b32_e32 v220, 48, v226
	v_lshl_add_u64 v[108:109], v[106:107], 0, v[198:199]
	v_lshlrev_b64 v[202:203], 14, v[222:223]
	v_ashrrev_i32_e32 v221, 31, v220
	v_add_u32_e32 v218, 0x80, v226
	global_load_dwordx4 v[170:173], v[108:109], off
	v_lshl_add_u64 v[108:109], v[106:107], 0, v[202:203]
	v_lshlrev_b64 v[206:207], 14, v[220:221]
	v_ashrrev_i32_e32 v219, 31, v218
	global_load_dwordx4 v[158:161], v[108:109], off
	v_lshl_add_u64 v[108:109], v[106:107], 0, v[206:207]
	v_lshlrev_b64 v[208:209], 14, v[218:219]
	global_load_dwordx4 v[154:157], v[108:109], off
	v_lshl_add_u64 v[108:109], v[106:107], 0, v[208:209]
	global_load_dwordx4 v[142:145], v[108:109], off
	v_add_u32_e32 v108, 0x90, v226
	v_ashrrev_i32_e32 v109, 31, v108
	v_lshlrev_b64 v[210:211], 14, v[108:109]
	v_lshl_add_u64 v[108:109], v[106:107], 0, v[210:211]
	global_load_dwordx4 v[130:133], v[108:109], off
	v_add_u32_e32 v108, 0xa0, v226
	v_ashrrev_i32_e32 v109, 31, v108
	v_lshlrev_b64 v[212:213], 14, v[108:109]
	v_lshl_add_u64 v[108:109], v[106:107], 0, v[212:213]
	global_load_dwordx4 v[118:121], v[108:109], off
	v_add_u32_e32 v108, 0xb0, v226
	v_ashrrev_i32_e32 v109, 31, v108
	v_lshlrev_b64 v[214:215], 14, v[108:109]
	v_lshl_add_u64 v[106:107], v[106:107], 0, v[214:215]
	global_load_dwordx4 v[106:109], v[106:107], off
	s_mov_b64 s[0:1], 0x120000
	s_mov_b32 s27, s52
	s_mov_b32 s34, s50
	s_mov_b64 s[8:9], s[56:57]
	s_waitcnt vmcnt(0)
	v_pk_mul_f32 v[146:147], v[146:147], v[98:99]
	v_pk_mul_f32 v[184:185], v[166:167], v[102:103]
	v_pk_mul_f32 v[166:167], v[164:165], v[100:101]
	v_pk_mul_f32 v[164:165], v[162:163], v[98:99]
	v_pk_mul_f32 v[168:169], v[168:169], v[104:105]
	v_lshlrev_b32_e32 v162, 16, v174
	v_mul_f32_e32 v163, 0xbfb8aa3b, v162
	v_exp_f32_e32 v163, v163
	v_pk_mul_f32 v[150:151], v[150:151], v[102:103]
	v_pk_mul_f32 v[152:153], v[152:153], v[104:105]
	v_pk_mul_f32 v[148:149], v[148:149], v[100:101]
	v_add_f32_e32 v163, 1.0, v163
	v_rcp_f32_e32 v163, v163
	v_pk_mul_f32 v[138:139], v[138:139], v[102:103]
	v_pk_mul_f32 v[140:141], v[140:141], v[104:105]
	v_pk_mul_f32 v[134:135], v[134:135], v[98:99]
	v_mul_f32_e32 v162, v163, v162
	v_and_b32_e32 v163, 0xffff0000, v174
	v_mul_f32_e32 v174, 0xbfb8aa3b, v163
	v_exp_f32_e32 v174, v174
	v_mul_f32_e32 v162, v184, v162
	v_pk_mul_f32 v[136:137], v[136:137], v[100:101]
	v_pk_mul_f32 v[126:127], v[126:127], v[102:103]
	v_add_f32_e32 v174, 1.0, v174
	v_rcp_f32_e32 v174, v174
	v_pk_mul_f32 v[128:129], v[128:129], v[104:105]
	v_pk_mul_f32 v[122:123], v[122:123], v[98:99]
	v_pk_mul_f32 v[124:125], v[124:125], v[100:101]
	v_mul_f32_e32 v163, v174, v163
	v_mul_f32_e32 v163, v185, v163
	v_cvt_pk_bf16_f32 v162, v162, v163
	v_lshlrev_b32_e32 v163, 16, v175
	v_mul_f32_e32 v174, 0xbfb8aa3b, v163
	v_exp_f32_e32 v174, v174
	v_pk_mul_f32 v[114:115], v[114:115], v[102:103]
	v_pk_mul_f32 v[116:117], v[116:117], v[104:105]
	v_pk_mul_f32 v[110:111], v[110:111], v[98:99]
	v_add_f32_e32 v174, 1.0, v174
	v_rcp_f32_e32 v174, v174
	v_pk_mul_f32 v[112:113], v[112:113], v[100:101]
	v_pk_mul_f32 v[94:95], v[94:95], v[102:103]
	v_pk_mul_f32 v[96:97], v[96:97], v[104:105]
	v_mul_f32_e32 v163, v174, v163
	v_mul_f32_e32 v163, v168, v163
	v_and_b32_e32 v168, 0xffff0000, v175
	v_mul_f32_e32 v174, 0xbfb8aa3b, v168
	v_exp_f32_e32 v174, v174
	v_pk_mul_f32 v[90:91], v[90:91], v[98:99]
	v_pk_mul_f32 v[92:93], v[92:93], v[100:101]
	v_pk_mul_f32 v[86:87], v[86:87], v[102:103]
	v_add_f32_e32 v174, 1.0, v174
	v_rcp_f32_e32 v174, v174
	v_pk_mul_f32 v[88:89], v[88:89], v[104:105]
	v_pk_mul_f32 v[82:83], v[82:83], v[98:99]
	v_pk_mul_f32 v[84:85], v[84:85], v[100:101]
	v_mul_f32_e32 v168, v174, v168
	v_mul_f32_e32 v168, v169, v168
	v_cvt_pk_bf16_f32 v163, v163, v168
	v_lshlrev_b32_e32 v168, 16, v176
	v_mul_f32_e32 v169, 0xbfb8aa3b, v168
	v_exp_f32_e32 v169, v169
	v_pk_mul_f32 v[78:79], v[78:79], v[102:103]
	v_pk_mul_f32 v[80:81], v[80:81], v[104:105]
	v_pk_mul_f32 v[74:75], v[74:75], v[98:99]
	v_add_f32_e32 v169, 1.0, v169
	v_rcp_f32_e32 v169, v169
	v_pk_mul_f32 v[76:77], v[76:77], v[100:101]
	v_pk_mul_f32 v[70:71], v[70:71], v[38:39]
	v_pk_mul_f32 v[72:73], v[72:73], v[40:41]
	v_mul_f32_e32 v168, v169, v168
	v_mul_f32_e32 v164, v164, v168
	v_and_b32_e32 v168, 0xffff0000, v176
	v_mul_f32_e32 v169, 0xbfb8aa3b, v168
	v_exp_f32_e32 v169, v169
	v_pk_mul_f32 v[66:67], v[66:67], v[34:35]
	v_pk_mul_f32 v[68:69], v[68:69], v[36:37]
	v_pk_mul_f32 v[62:63], v[62:63], v[38:39]
	v_add_f32_e32 v169, 1.0, v169
	v_rcp_f32_e32 v169, v169
	v_pk_mul_f32 v[64:65], v[64:65], v[40:41]
	v_pk_mul_f32 v[58:59], v[58:59], v[34:35]
	v_pk_mul_f32 v[60:61], v[60:61], v[36:37]
	v_mul_f32_e32 v168, v169, v168
	v_mul_f32_e32 v165, v165, v168
	v_cvt_pk_bf16_f32 v164, v164, v165
	v_lshlrev_b32_e32 v165, 16, v177
	v_mul_f32_e32 v168, 0xbfb8aa3b, v165
	v_exp_f32_e32 v168, v168
; __device__ __forceinline__ unsigned cvt_pk_bf16(float lo, float hi) { unsigned r; asm volatile("v_cvt_pk_bf16_f32 %0, %1, %2" : "=v"(r) : "v"(lo), "v"(hi)); return r; }
; __device__ __forceinline__ float bf_lo(unsigned w) { return __uint_as_float(w << 16); }
; __device__ __forceinline__ float bf_hi(unsigned w) { return __uint_as_float(w & 0xffff0000u); }
; __device__ __forceinline__ float silu_f(float z) { return z * fast_rcp(1.0f + __builtin_amdgcn_exp2f(z * -1.44269504f)); }
;     __device__ __forceinline__ void operator()(const f32x4 (&acc)[2][2][4][2], const Unit& u, int wr, int wc, int fr, int fq, const Pre&) const {
;     ...
;             for (int ai = 0; ai < 2; ++ai)
; #pragma unroll
;                 for (int m = 0; m < 4; ++m) { const int r = row0 + ai * HALF + m * 16;
;                     const u32x4 zw = zv[ai * 4 + m];
;                     const f32x4 a0 = acc[ai][bj][m][0] * sc[bj][0], a1 = acc[ai][bj][m][1] * sc[bj][1];
;                     u32x4 w;
;                     w.x = cvt_pk_bf16(a0[0] * silu_f(bf_lo(zw.x)), a0[1] * silu_f(bf_hi(zw.x)));
;                     w.y = cvt_pk_bf16(a0[2] * silu_f(bf_lo(zw.y)), a0[3] * silu_f(bf_hi(zw.y)));
;                     w.z = cvt_pk_bf16(a1[0] * silu_f(bf_lo(zw.z)), a1[1] * silu_f(bf_hi(zw.z)));
;                     w.w = cvt_pk_bf16(a1[2] * silu_f(bf_lo(zw.w)), a1[3] * silu_f(bf_hi(zw.w)));
;                     *(u32x4*)(O + (size_t)r * DE + c) = w; } }
	v_pk_mul_f32 v[54:55], v[54:55], v[38:39]
	v_pk_mul_f32 v[56:57], v[56:57], v[40:41]
	v_pk_mul_f32 v[50:51], v[50:51], v[34:35]
	v_add_f32_e32 v168, 1.0, v168
	v_rcp_f32_e32 v168, v168
	v_pk_mul_f32 v[52:53], v[52:53], v[36:37]
	v_pk_mul_f32 v[46:47], v[46:47], v[38:39]
	v_pk_mul_f32 v[48:49], v[48:49], v[40:41]
	v_mul_f32_e32 v165, v168, v165
	v_mul_f32_e32 v165, v166, v165
	v_and_b32_e32 v166, 0xffff0000, v177
	v_mul_f32_e32 v168, 0xbfb8aa3b, v166
	v_exp_f32_e32 v168, v168
	v_pk_mul_f32 v[42:43], v[42:43], v[34:35]
	v_pk_mul_f32 v[44:45], v[44:45], v[36:37]
	v_pk_mul_f32 v[30:31], v[30:31], v[38:39]
	v_add_f32_e32 v168, 1.0, v168
	v_rcp_f32_e32 v168, v168
	v_pk_mul_f32 v[32:33], v[32:33], v[40:41]
	v_pk_mul_f32 v[26:27], v[26:27], v[34:35]
	v_pk_mul_f32 v[28:29], v[28:29], v[36:37]
	v_mul_f32_e32 v166, v168, v166
	v_mul_f32_e32 v166, v167, v166
	v_cvt_pk_bf16_f32 v165, v165, v166
	v_lshlrev_b64 v[166:167], 13, v[226:227]
	v_lshl_add_u64 v[166:167], s[44:45], 0, v[166:167]
	v_lshl_add_u64 v[166:167], v[166:167], 0, v[216:217]
	global_store_dwordx4 v[166:167], v[162:165], off
	v_pk_mul_f32 v[22:23], v[22:23], v[38:39]
	v_pk_mul_f32 v[24:25], v[24:25], v[40:41]
	v_lshlrev_b32_e32 v162, 16, v170
	v_mul_f32_e32 v163, 0xbfb8aa3b, v162
	v_exp_f32_e32 v163, v163
	v_pk_mul_f32 v[18:19], v[18:19], v[34:35]
	v_pk_mul_f32 v[20:21], v[20:21], v[36:37]
	v_pk_mul_f32 v[14:15], v[14:15], v[38:39]
	v_add_f32_e32 v163, 1.0, v163
	v_rcp_f32_e32 v163, v163
	v_pk_mul_f32 v[16:17], v[16:17], v[40:41]
	v_pk_mul_f32 v[10:11], v[10:11], v[34:35]
	v_pk_mul_f32 v[12:13], v[12:13], v[36:37]
	v_mul_f32_e32 v162, v163, v162
	v_mul_f32_e32 v150, v150, v162
	v_and_b32_e32 v162, 0xffff0000, v170
	v_mul_f32_e32 v163, 0xbfb8aa3b, v162
	v_exp_f32_e32 v163, v163
	v_pk_mul_f32 v[6:7], v[6:7], v[38:39]
	v_pk_mul_f32 v[8:9], v[8:9], v[40:41]
	v_pk_mul_f32 v[2:3], v[2:3], v[34:35]
	v_add_f32_e32 v163, 1.0, v163
	v_rcp_f32_e32 v163, v163
	v_pk_mul_f32 v[4:5], v[4:5], v[36:37]
	v_mul_f32_e32 v162, v163, v162
	v_mul_f32_e32 v151, v151, v162
	v_cvt_pk_bf16_f32 v150, v150, v151
	v_lshlrev_b32_e32 v151, 16, v171
	v_mul_f32_e32 v162, 0xbfb8aa3b, v151
	v_exp_f32_e32 v162, v162
	s_nop 0
	v_add_f32_e32 v162, 1.0, v162
	v_rcp_f32_e32 v162, v162
	s_nop 0
	v_mul_f32_e32 v151, v162, v151
	v_mul_f32_e32 v151, v152, v151
	v_and_b32_e32 v152, 0xffff0000, v171
	v_mul_f32_e32 v162, 0xbfb8aa3b, v152
	v_exp_f32_e32 v162, v162
	s_nop 0
	v_add_f32_e32 v162, 1.0, v162
	v_rcp_f32_e32 v162, v162
	s_nop 0
	v_mul_f32_e32 v152, v162, v152
	v_mul_f32_e32 v152, v153, v152
	v_cvt_pk_bf16_f32 v151, v151, v152
	v_lshlrev_b32_e32 v152, 16, v172
	v_mul_f32_e32 v153, 0xbfb8aa3b, v152
	v_exp_f32_e32 v153, v153
	s_nop 0
	v_add_f32_e32 v153, 1.0, v153
	v_rcp_f32_e32 v153, v153
	s_nop 0
	v_mul_f32_e32 v152, v153, v152
	v_mul_f32_e32 v146, v146, v152
	v_and_b32_e32 v152, 0xffff0000, v172
	v_mul_f32_e32 v153, 0xbfb8aa3b, v152
	v_exp_f32_e32 v153, v153
	s_nop 0
	v_add_f32_e32 v153, 1.0, v153
	v_rcp_f32_e32 v153, v153
	s_nop 0
	v_mul_f32_e32 v152, v153, v152
	v_mul_f32_e32 v147, v147, v152
	v_cvt_pk_bf16_f32 v152, v146, v147
	v_lshlrev_b32_e32 v146, 16, v173
	v_mul_f32_e32 v147, 0xbfb8aa3b, v146
	v_exp_f32_e32 v147, v147
	s_nop 0
	v_add_f32_e32 v147, 1.0, v147
	v_rcp_f32_e32 v147, v147
	s_nop 0
	v_mul_f32_e32 v146, v147, v146
	v_and_b32_e32 v147, 0xffff0000, v173
	v_mul_f32_e32 v146, v148, v146
	v_mul_f32_e32 v148, 0xbfb8aa3b, v147
	v_exp_f32_e32 v148, v148
	s_nop 0
	v_add_f32_e32 v148, 1.0, v148
	v_rcp_f32_e32 v148, v148
	s_nop 0
	v_mul_f32_e32 v147, v148, v147
	v_lshlrev_b32_e32 v148, 16, v158
	v_mul_f32_e32 v147, v149, v147
	v_mul_f32_e32 v149, 0xbfb8aa3b, v148
	v_exp_f32_e32 v149, v149
	v_cvt_pk_bf16_f32 v153, v146, v147
	v_lshlrev_b64 v[146:147], 13, v[224:225]
	v_lshl_add_u64 v[146:147], s[44:45], 0, v[146:147]
	v_add_f32_e32 v149, 1.0, v149
	v_rcp_f32_e32 v149, v149
	v_lshl_add_u64 v[146:147], v[146:147], 0, v[216:217]
	global_store_dwordx4 v[146:147], v[150:153], off
	v_mul_f32_e32 v148, v149, v148
	v_mul_f32_e32 v138, v138, v148
	v_and_b32_e32 v148, 0xffff0000, v158
	v_mul_f32_e32 v149, 0xbfb8aa3b, v148
	v_exp_f32_e32 v149, v149
	s_nop 0
	v_add_f32_e32 v149, 1.0, v149
	v_rcp_f32_e32 v149, v149
	s_nop 0
	v_mul_f32_e32 v148, v149, v148
	v_mul_f32_e32 v139, v139, v148
	v_cvt_pk_bf16_f32 v138, v138, v139
	v_lshlrev_b32_e32 v139, 16, v159
	v_mul_f32_e32 v148, 0xbfb8aa3b, v139
	v_exp_f32_e32 v148, v148
	s_nop 0
	v_add_f32_e32 v148, 1.0, v148
	v_rcp_f32_e32 v148, v148
	s_nop 0
	v_mul_f32_e32 v139, v148, v139
	v_mul_f32_e32 v139, v140, v139
	v_and_b32_e32 v140, 0xffff0000, v159
	v_mul_f32_e32 v148, 0xbfb8aa3b, v140
	v_exp_f32_e32 v148, v148
	s_nop 0
	v_add_f32_e32 v148, 1.0, v148
	v_rcp_f32_e32 v148, v148
	s_nop 0
	v_mul_f32_e32 v140, v148, v140
	v_mul_f32_e32 v140, v141, v140
	v_cvt_pk_bf16_f32 v139, v139, v140
	v_lshlrev_b32_e32 v140, 16, v160
	v_mul_f32_e32 v141, 0xbfb8aa3b, v140
	v_exp_f32_e32 v141, v141
	s_nop 0
	v_add_f32_e32 v141, 1.0, v141
	v_rcp_f32_e32 v141, v141
	s_nop 0
	v_mul_f32_e32 v140, v141, v140
	v_mul_f32_e32 v134, v134, v140
	v_and_b32_e32 v140, 0xffff0000, v160
	v_mul_f32_e32 v141, 0xbfb8aa3b, v140
	v_exp_f32_e32 v141, v141
	s_nop 0
	v_add_f32_e32 v141, 1.0, v141
	v_rcp_f32_e32 v141, v141
	s_nop 0
	v_mul_f32_e32 v140, v141, v140
	v_mul_f32_e32 v135, v135, v140
	v_cvt_pk_bf16_f32 v140, v134, v135
	v_lshlrev_b32_e32 v134, 16, v161
	v_mul_f32_e32 v135, 0xbfb8aa3b, v134
	v_exp_f32_e32 v135, v135
	s_nop 0
	v_add_f32_e32 v135, 1.0, v135
	v_rcp_f32_e32 v135, v135
	s_nop 0
	v_mul_f32_e32 v134, v135, v134
	v_and_b32_e32 v135, 0xffff0000, v161
	v_mul_f32_e32 v134, v136, v134
	v_mul_f32_e32 v136, 0xbfb8aa3b, v135
; __device__ __forceinline__ unsigned cvt_pk_bf16(float lo, float hi) { unsigned r; asm volatile("v_cvt_pk_bf16_f32 %0, %1, %2" : "=v"(r) : "v"(lo), "v"(hi)); return r; }
; __device__ __forceinline__ float bf_lo(unsigned w) { return __uint_as_float(w << 16); }
; __device__ __forceinline__ float bf_hi(unsigned w) { return __uint_as_float(w & 0xffff0000u); }
; __device__ __forceinline__ float silu_f(float z) { return z * fast_rcp(1.0f + __builtin_amdgcn_exp2f(z * -1.44269504f)); }
;     __device__ __forceinline__ void operator()(const f32x4 (&acc)[2][2][4][2], const Unit& u, int wr, int wc, int fr, int fq, const Pre&) const {
;     ...
;             for (int ai = 0; ai < 2; ++ai)
; #pragma unroll
;                 for (int m = 0; m < 4; ++m) { const int r = row0 + ai * HALF + m * 16;
;                     const u32x4 zw = zv[ai * 4 + m];
;                     const f32x4 a0 = acc[ai][bj][m][0] * sc[bj][0], a1 = acc[ai][bj][m][1] * sc[bj][1];
;                     u32x4 w;
;                     w.x = cvt_pk_bf16(a0[0] * silu_f(bf_lo(zw.x)), a0[1] * silu_f(bf_hi(zw.x)));
;                     w.y = cvt_pk_bf16(a0[2] * silu_f(bf_lo(zw.y)), a0[3] * silu_f(bf_hi(zw.y)));
;                     w.z = cvt_pk_bf16(a1[0] * silu_f(bf_lo(zw.z)), a1[1] * silu_f(bf_hi(zw.z)));
;                     w.w = cvt_pk_bf16(a1[2] * silu_f(bf_lo(zw.w)), a1[3] * silu_f(bf_hi(zw.w)));
;                     *(u32x4*)(O + (size_t)r * DE + c) = w; } }
	v_exp_f32_e32 v136, v136
	s_nop 0
	v_add_f32_e32 v136, 1.0, v136
	v_rcp_f32_e32 v136, v136
	s_nop 0
	v_mul_f32_e32 v135, v136, v135
	v_lshlrev_b32_e32 v136, 16, v154
	v_mul_f32_e32 v135, v137, v135
	v_mul_f32_e32 v137, 0xbfb8aa3b, v136
	v_exp_f32_e32 v137, v137
	v_cvt_pk_bf16_f32 v141, v134, v135
	v_lshlrev_b64 v[134:135], 13, v[222:223]
	v_lshl_add_u64 v[134:135], s[44:45], 0, v[134:135]
	v_add_f32_e32 v137, 1.0, v137
	v_rcp_f32_e32 v137, v137
	v_lshl_add_u64 v[134:135], v[134:135], 0, v[216:217]
	global_store_dwordx4 v[134:135], v[138:141], off
	v_mul_f32_e32 v136, v137, v136
	v_mul_f32_e32 v126, v126, v136
	v_and_b32_e32 v136, 0xffff0000, v154
	v_mul_f32_e32 v137, 0xbfb8aa3b, v136
	v_exp_f32_e32 v137, v137
	s_nop 0
	v_add_f32_e32 v137, 1.0, v137
	v_rcp_f32_e32 v137, v137
	s_nop 0
	v_mul_f32_e32 v136, v137, v136
	v_mul_f32_e32 v127, v127, v136
	v_cvt_pk_bf16_f32 v126, v126, v127
	v_lshlrev_b32_e32 v127, 16, v155
	v_mul_f32_e32 v136, 0xbfb8aa3b, v127
	v_exp_f32_e32 v136, v136
	s_nop 0
	v_add_f32_e32 v136, 1.0, v136
	v_rcp_f32_e32 v136, v136
	s_nop 0
	v_mul_f32_e32 v127, v136, v127
	v_mul_f32_e32 v127, v128, v127
	v_and_b32_e32 v128, 0xffff0000, v155
	v_mul_f32_e32 v136, 0xbfb8aa3b, v128
	v_exp_f32_e32 v136, v136
	s_nop 0
	v_add_f32_e32 v136, 1.0, v136
	v_rcp_f32_e32 v136, v136
	s_nop 0
	v_mul_f32_e32 v128, v136, v128
	v_mul_f32_e32 v128, v129, v128
	v_cvt_pk_bf16_f32 v127, v127, v128
	v_lshlrev_b32_e32 v128, 16, v156
	v_mul_f32_e32 v129, 0xbfb8aa3b, v128
	v_exp_f32_e32 v129, v129
	s_nop 0
	v_add_f32_e32 v129, 1.0, v129
	v_rcp_f32_e32 v129, v129
	s_nop 0
	v_mul_f32_e32 v128, v129, v128
	v_mul_f32_e32 v122, v122, v128
	v_and_b32_e32 v128, 0xffff0000, v156
	v_mul_f32_e32 v129, 0xbfb8aa3b, v128
	v_exp_f32_e32 v129, v129
	s_nop 0
	v_add_f32_e32 v129, 1.0, v129
	v_rcp_f32_e32 v129, v129
	s_nop 0
	v_mul_f32_e32 v128, v129, v128
	v_mul_f32_e32 v123, v123, v128
	v_cvt_pk_bf16_f32 v128, v122, v123
	v_lshlrev_b32_e32 v122, 16, v157
	v_mul_f32_e32 v123, 0xbfb8aa3b, v122
	v_exp_f32_e32 v123, v123
	s_nop 0
	v_add_f32_e32 v123, 1.0, v123
	v_rcp_f32_e32 v123, v123
	s_nop 0
	v_mul_f32_e32 v122, v123, v122
	v_and_b32_e32 v123, 0xffff0000, v157
	v_mul_f32_e32 v122, v124, v122
	v_mul_f32_e32 v124, 0xbfb8aa3b, v123
	v_exp_f32_e32 v124, v124
	s_nop 0
	v_add_f32_e32 v124, 1.0, v124
	v_rcp_f32_e32 v124, v124
	s_nop 0
	v_mul_f32_e32 v123, v124, v123
	v_lshlrev_b32_e32 v124, 16, v142
	v_mul_f32_e32 v123, v125, v123
	v_mul_f32_e32 v125, 0xbfb8aa3b, v124
	v_exp_f32_e32 v125, v125
	v_cvt_pk_bf16_f32 v129, v122, v123
	v_lshlrev_b64 v[122:123], 13, v[220:221]
	v_lshl_add_u64 v[122:123], s[44:45], 0, v[122:123]
	v_add_f32_e32 v125, 1.0, v125
	v_rcp_f32_e32 v125, v125
	v_lshl_add_u64 v[122:123], v[122:123], 0, v[216:217]
	global_store_dwordx4 v[122:123], v[126:129], off
	v_mul_f32_e32 v124, v125, v124
	v_mul_f32_e32 v114, v114, v124
	v_and_b32_e32 v124, 0xffff0000, v142
	v_mul_f32_e32 v125, 0xbfb8aa3b, v124
	v_exp_f32_e32 v125, v125
	s_nop 0
	v_add_f32_e32 v125, 1.0, v125
	v_rcp_f32_e32 v125, v125
	s_nop 0
	v_mul_f32_e32 v124, v125, v124
	v_mul_f32_e32 v115, v115, v124
	v_cvt_pk_bf16_f32 v114, v114, v115
	v_lshlrev_b32_e32 v115, 16, v143
	v_mul_f32_e32 v124, 0xbfb8aa3b, v115
	v_exp_f32_e32 v124, v124
	s_nop 0
	v_add_f32_e32 v124, 1.0, v124
	v_rcp_f32_e32 v124, v124
	s_nop 0
	v_mul_f32_e32 v115, v124, v115
	v_mul_f32_e32 v115, v116, v115
	v_and_b32_e32 v116, 0xffff0000, v143
	v_mul_f32_e32 v124, 0xbfb8aa3b, v116
	v_exp_f32_e32 v124, v124
	s_nop 0
	v_add_f32_e32 v124, 1.0, v124
	v_rcp_f32_e32 v124, v124
	s_nop 0
	v_mul_f32_e32 v116, v124, v116
	v_mul_f32_e32 v116, v117, v116
	v_cvt_pk_bf16_f32 v115, v115, v116
	v_lshlrev_b32_e32 v116, 16, v144
	v_mul_f32_e32 v117, 0xbfb8aa3b, v116
	v_exp_f32_e32 v117, v117
	s_nop 0
	v_add_f32_e32 v117, 1.0, v117
	v_rcp_f32_e32 v117, v117
	s_nop 0
	v_mul_f32_e32 v116, v117, v116
	v_mul_f32_e32 v110, v110, v116
	v_and_b32_e32 v116, 0xffff0000, v144
	v_mul_f32_e32 v117, 0xbfb8aa3b, v116
	v_exp_f32_e32 v117, v117
	s_nop 0
	v_add_f32_e32 v117, 1.0, v117
	v_rcp_f32_e32 v117, v117
	s_nop 0
	v_mul_f32_e32 v116, v117, v116
	v_mul_f32_e32 v111, v111, v116
	v_cvt_pk_bf16_f32 v116, v110, v111
	v_lshlrev_b32_e32 v110, 16, v145
	v_mul_f32_e32 v111, 0xbfb8aa3b, v110
	v_exp_f32_e32 v111, v111
	s_nop 0
	v_add_f32_e32 v111, 1.0, v111
	v_rcp_f32_e32 v111, v111
	s_nop 0
	v_mul_f32_e32 v110, v111, v110
	v_and_b32_e32 v111, 0xffff0000, v145
	v_mul_f32_e32 v110, v112, v110
	v_mul_f32_e32 v112, 0xbfb8aa3b, v111
	v_exp_f32_e32 v112, v112
	s_nop 0
	v_add_f32_e32 v112, 1.0, v112
	v_rcp_f32_e32 v112, v112
	s_nop 0
	v_mul_f32_e32 v111, v112, v111
	v_mul_f32_e32 v111, v113, v111
	v_cvt_pk_bf16_f32 v117, v110, v111
	v_lshlrev_b64 v[110:111], 13, v[218:219]
	v_lshl_add_u64 v[110:111], s[44:45], 0, v[110:111]
	v_lshl_add_u64 v[112:113], v[110:111], 0, v[216:217]
	v_lshlrev_b32_e32 v110, 16, v130
	v_mul_f32_e32 v111, 0xbfb8aa3b, v110
	v_exp_f32_e32 v111, v111
	global_store_dwordx4 v[112:113], v[114:117], off
	v_add_f32_e32 v111, 1.0, v111
	v_rcp_f32_e32 v111, v111
	s_nop 0
	v_mul_f32_e32 v110, v111, v110
	v_mul_f32_e32 v94, v94, v110
	v_and_b32_e32 v110, 0xffff0000, v130
	v_mul_f32_e32 v111, 0xbfb8aa3b, v110
	v_exp_f32_e32 v111, v111
	s_nop 0
	v_add_f32_e32 v111, 1.0, v111
	v_rcp_f32_e32 v111, v111
	s_nop 0
	v_mul_f32_e32 v110, v111, v110
	v_mul_f32_e32 v95, v95, v110
	v_cvt_pk_bf16_f32 v94, v94, v95
	v_lshlrev_b32_e32 v95, 16, v131
	v_mul_f32_e32 v110, 0xbfb8aa3b, v95
	v_exp_f32_e32 v110, v110
	s_nop 0
	v_add_f32_e32 v110, 1.0, v110
	v_rcp_f32_e32 v110, v110
	s_nop 0
	v_mul_f32_e32 v95, v110, v95
	v_mul_f32_e32 v95, v96, v95
	v_and_b32_e32 v96, 0xffff0000, v131
; __device__ __forceinline__ unsigned cvt_pk_bf16(float lo, float hi) { unsigned r; asm volatile("v_cvt_pk_bf16_f32 %0, %1, %2" : "=v"(r) : "v"(lo), "v"(hi)); return r; }
; __device__ __forceinline__ float bf_lo(unsigned w) { return __uint_as_float(w << 16); }
; __device__ __forceinline__ float bf_hi(unsigned w) { return __uint_as_float(w & 0xffff0000u); }
; __device__ __forceinline__ float silu_f(float z) { return z * fast_rcp(1.0f + __builtin_amdgcn_exp2f(z * -1.44269504f)); }
;     __device__ __forceinline__ void operator()(const f32x4 (&acc)[2][2][4][2], const Unit& u, int wr, int wc, int fr, int fq, const Pre&) const {
;     ...
;             for (int g8 = 0; g8 < 8; ++g8) zv[g8] = *(const u32x4*)(Z + (size_t)(row0 + (g8 >> 2) * HALF + (g8 & 3) * 16) * DE2 + c);
; #pragma unroll
;             for (int ai = 0; ai < 2; ++ai)
; #pragma unroll
;                 for (int m = 0; m < 4; ++m) { const int r = row0 + ai * HALF + m * 16;
;                     const u32x4 zw = zv[ai * 4 + m];
;                     const f32x4 a0 = acc[ai][bj][m][0] * sc[bj][0], a1 = acc[ai][bj][m][1] * sc[bj][1];
;                     u32x4 w;
;                     w.x = cvt_pk_bf16(a0[0] * silu_f(bf_lo(zw.x)), a0[1] * silu_f(bf_hi(zw.x)));
;                     w.y = cvt_pk_bf16(a0[2] * silu_f(bf_lo(zw.y)), a0[3] * silu_f(bf_hi(zw.y)));
;                     w.z = cvt_pk_bf16(a1[0] * silu_f(bf_lo(zw.z)), a1[1] * silu_f(bf_hi(zw.z)));
;                     w.w = cvt_pk_bf16(a1[2] * silu_f(bf_lo(zw.w)), a1[3] * silu_f(bf_hi(zw.w)));
;                     *(u32x4*)(O + (size_t)r * DE + c) = w; } }
	v_mul_f32_e32 v110, 0xbfb8aa3b, v96
	v_exp_f32_e32 v110, v110
	s_nop 0
	v_add_f32_e32 v110, 1.0, v110
	v_rcp_f32_e32 v110, v110
	s_nop 0
	v_mul_f32_e32 v96, v110, v96
	v_mul_f32_e32 v96, v97, v96
	v_cvt_pk_bf16_f32 v95, v95, v96
	v_lshlrev_b32_e32 v96, 16, v132
	v_mul_f32_e32 v97, 0xbfb8aa3b, v96
	v_exp_f32_e32 v97, v97
	v_lshl_add_u64 v[110:111], v[166:167], 0, s[0:1]
	s_mov_b64 s[0:1], 0x140000
	v_lshl_add_u64 v[114:115], v[166:167], 0, s[0:1]
	v_add_f32_e32 v97, 1.0, v97
	v_rcp_f32_e32 v97, v97
	s_mov_b64 s[0:1], 0x160000
	v_mul_f32_e32 v96, v97, v96
	v_mul_f32_e32 v90, v90, v96
	v_and_b32_e32 v96, 0xffff0000, v132
	v_mul_f32_e32 v97, 0xbfb8aa3b, v96
	v_exp_f32_e32 v97, v97
	s_nop 0
	v_add_f32_e32 v97, 1.0, v97
	v_rcp_f32_e32 v97, v97
	s_nop 0
	v_mul_f32_e32 v96, v97, v96
	v_mul_f32_e32 v91, v91, v96
	v_cvt_pk_bf16_f32 v96, v90, v91
	v_lshlrev_b32_e32 v90, 16, v133
	v_mul_f32_e32 v91, 0xbfb8aa3b, v90
	v_exp_f32_e32 v91, v91
	s_nop 0
	v_add_f32_e32 v91, 1.0, v91
	v_rcp_f32_e32 v91, v91
	s_nop 0
	v_mul_f32_e32 v90, v91, v90
	v_and_b32_e32 v91, 0xffff0000, v133
	v_mul_f32_e32 v90, v92, v90
	v_mul_f32_e32 v92, 0xbfb8aa3b, v91
	v_exp_f32_e32 v92, v92
	s_nop 0
	v_add_f32_e32 v92, 1.0, v92
	v_rcp_f32_e32 v92, v92
	s_nop 0
	v_mul_f32_e32 v91, v92, v91
	v_mul_f32_e32 v91, v93, v91
	v_cvt_pk_bf16_f32 v97, v90, v91
	v_add_co_u32_e32 v90, vcc, s41, v166
	s_nop 1
	v_addc_co_u32_e32 v91, vcc, 0, v167, vcc
	global_store_dwordx4 v[90:91], v[94:97], off
	v_lshlrev_b32_e32 v90, 16, v118
	v_mul_f32_e32 v91, 0xbfb8aa3b, v90
	v_exp_f32_e32 v91, v91
	s_nop 0
	v_add_f32_e32 v91, 1.0, v91
	v_rcp_f32_e32 v91, v91
	s_nop 0
	v_mul_f32_e32 v90, v91, v90
	v_mul_f32_e32 v86, v86, v90
	v_and_b32_e32 v90, 0xffff0000, v118
	v_mul_f32_e32 v91, 0xbfb8aa3b, v90
	v_exp_f32_e32 v91, v91
	s_nop 0
	v_add_f32_e32 v91, 1.0, v91
	v_rcp_f32_e32 v91, v91
	s_nop 0
	v_mul_f32_e32 v90, v91, v90
	v_mul_f32_e32 v87, v87, v90
	v_cvt_pk_bf16_f32 v86, v86, v87
	v_lshlrev_b32_e32 v87, 16, v119
	v_mul_f32_e32 v90, 0xbfb8aa3b, v87
	v_exp_f32_e32 v90, v90
	s_nop 0
	v_add_f32_e32 v90, 1.0, v90
	v_rcp_f32_e32 v90, v90
	s_nop 0
	v_mul_f32_e32 v87, v90, v87
	v_mul_f32_e32 v87, v88, v87
	v_and_b32_e32 v88, 0xffff0000, v119
	v_mul_f32_e32 v90, 0xbfb8aa3b, v88
	v_exp_f32_e32 v90, v90
	s_nop 0
	v_add_f32_e32 v90, 1.0, v90
	v_rcp_f32_e32 v90, v90
	s_nop 0
	v_mul_f32_e32 v88, v90, v88
	v_mul_f32_e32 v88, v89, v88
	v_cvt_pk_bf16_f32 v87, v87, v88
	v_lshlrev_b32_e32 v88, 16, v120
	v_mul_f32_e32 v89, 0xbfb8aa3b, v88
	v_exp_f32_e32 v89, v89
	s_nop 0
	v_add_f32_e32 v89, 1.0, v89
	v_rcp_f32_e32 v89, v89
	s_nop 0
	v_mul_f32_e32 v88, v89, v88
	v_mul_f32_e32 v82, v82, v88
	v_and_b32_e32 v88, 0xffff0000, v120
	v_mul_f32_e32 v89, 0xbfb8aa3b, v88
	v_exp_f32_e32 v89, v89
	s_nop 0
	v_add_f32_e32 v89, 1.0, v89
	v_rcp_f32_e32 v89, v89
	s_nop 0
	v_mul_f32_e32 v88, v89, v88
	v_mul_f32_e32 v83, v83, v88
	v_cvt_pk_bf16_f32 v88, v82, v83
	v_lshlrev_b32_e32 v82, 16, v121
	v_mul_f32_e32 v83, 0xbfb8aa3b, v82
	v_exp_f32_e32 v83, v83
	s_nop 0
	v_add_f32_e32 v83, 1.0, v83
	v_rcp_f32_e32 v83, v83
	s_nop 0
	v_mul_f32_e32 v82, v83, v82
	v_and_b32_e32 v83, 0xffff0000, v121
	v_mul_f32_e32 v82, v84, v82
	v_mul_f32_e32 v84, 0xbfb8aa3b, v83
	v_exp_f32_e32 v84, v84
	s_nop 0
	v_add_f32_e32 v84, 1.0, v84
	v_rcp_f32_e32 v84, v84
	s_nop 0
	v_mul_f32_e32 v83, v84, v83
	v_mul_f32_e32 v83, v85, v83
	v_cvt_pk_bf16_f32 v89, v82, v83
	v_add_co_u32_e32 v82, vcc, s65, v166
	s_nop 1
	v_addc_co_u32_e32 v83, vcc, 0, v167, vcc
	global_store_dwordx4 v[82:83], v[86:89], off
	v_lshlrev_b32_e32 v82, 16, v106
	v_mul_f32_e32 v83, 0xbfb8aa3b, v82
	v_exp_f32_e32 v83, v83
	s_nop 0
	v_add_f32_e32 v83, 1.0, v83
	v_rcp_f32_e32 v83, v83
	s_nop 0
	v_mul_f32_e32 v82, v83, v82
	v_mul_f32_e32 v78, v78, v82
	v_and_b32_e32 v82, 0xffff0000, v106
	v_mul_f32_e32 v83, 0xbfb8aa3b, v82
	v_exp_f32_e32 v83, v83
	s_nop 0
	v_add_f32_e32 v83, 1.0, v83
	v_rcp_f32_e32 v83, v83
	s_nop 0
	v_mul_f32_e32 v82, v83, v82
	v_mul_f32_e32 v79, v79, v82
	v_cvt_pk_bf16_f32 v78, v78, v79
	v_lshlrev_b32_e32 v79, 16, v107
	v_mul_f32_e32 v82, 0xbfb8aa3b, v79
	v_exp_f32_e32 v82, v82
	s_nop 0
	v_add_f32_e32 v82, 1.0, v82
	v_rcp_f32_e32 v82, v82
	s_nop 0
	v_mul_f32_e32 v79, v82, v79
	v_mul_f32_e32 v79, v80, v79
	v_and_b32_e32 v80, 0xffff0000, v107
	v_mul_f32_e32 v82, 0xbfb8aa3b, v80
	v_exp_f32_e32 v82, v82
	v_lshl_add_u64 v[106:107], v[166:167], 0, s[0:1]
	s_mov_b64 s[0:1], s[54:55]
	v_add_f32_e32 v82, 1.0, v82
	v_rcp_f32_e32 v82, v82
	s_nop 0
	v_mul_f32_e32 v80, v82, v80
	v_mul_f32_e32 v80, v81, v80
	v_cvt_pk_bf16_f32 v79, v79, v80
	v_lshlrev_b32_e32 v80, 16, v108
	v_mul_f32_e32 v81, 0xbfb8aa3b, v80
	v_exp_f32_e32 v81, v81
	s_nop 0
	v_add_f32_e32 v81, 1.0, v81
	v_rcp_f32_e32 v81, v81
	s_nop 0
	v_mul_f32_e32 v80, v81, v80
	v_mul_f32_e32 v74, v74, v80
	v_and_b32_e32 v80, 0xffff0000, v108
	v_mul_f32_e32 v81, 0xbfb8aa3b, v80
	v_exp_f32_e32 v81, v81
	s_nop 0
	v_add_f32_e32 v81, 1.0, v81
	v_rcp_f32_e32 v81, v81
	s_nop 0
	v_mul_f32_e32 v80, v81, v80
	v_mul_f32_e32 v75, v75, v80
	v_cvt_pk_bf16_f32 v80, v74, v75
	v_lshlrev_b32_e32 v74, 16, v109
	v_mul_f32_e32 v75, 0xbfb8aa3b, v74
	v_exp_f32_e32 v75, v75
	s_nop 0
	v_add_f32_e32 v75, 1.0, v75
	v_rcp_f32_e32 v75, v75
	s_nop 0
	v_mul_f32_e32 v74, v75, v74
	v_and_b32_e32 v75, 0xffff0000, v109
	v_mul_f32_e32 v74, v76, v74
	v_mul_f32_e32 v76, 0xbfb8aa3b, v75
	v_exp_f32_e32 v76, v76
	s_nop 0
	v_add_f32_e32 v76, 1.0, v76
	v_rcp_f32_e32 v76, v76
	s_nop 0
	v_mul_f32_e32 v75, v76, v75
	v_mul_f32_e32 v75, v77, v75
	v_cvt_pk_bf16_f32 v81, v74, v75
	v_add_co_u32_e32 v74, vcc, s70, v166
	v_lshl_add_u64 v[76:77], s[46:47], 0, v[204:205]
	s_nop 0
	v_addc_co_u32_e32 v75, vcc, 0, v167, vcc
	global_store_dwordx4 v[74:75], v[78:81], off
	v_or_b32_e32 v74, 0x80, v200
	v_ashrrev_i32_e32 v75, 31, v74
	v_lshlrev_b64 v[74:75], 1, v[74:75]
	v_lshl_add_u64 v[76:77], v[76:77], 0, v[74:75]
	global_load_dwordx4 v[102:105], v[76:77], off
	v_lshl_add_u64 v[76:77], s[46:47], 0, v[198:199]
	v_lshl_add_u64 v[76:77], v[76:77], 0, v[74:75]
	global_load_dwordx4 v[98:101], v[76:77], off
	v_lshl_add_u64 v[76:77], s[46:47], 0, v[202:203]
	v_lshl_add_u64 v[76:77], v[76:77], 0, v[74:75]
	global_load_dwordx4 v[94:97], v[76:77], off
	v_lshl_add_u64 v[76:77], s[46:47], 0, v[206:207]
	v_lshl_add_u64 v[76:77], v[76:77], 0, v[74:75]
	global_load_dwordx4 v[90:93], v[76:77], off
	v_lshl_add_u64 v[76:77], s[46:47], 0, v[208:209]
	v_lshl_add_u64 v[76:77], v[76:77], 0, v[74:75]
	global_load_dwordx4 v[86:89], v[76:77], off
	v_lshl_add_u64 v[76:77], s[46:47], 0, v[210:211]
	v_lshl_add_u64 v[76:77], v[76:77], 0, v[74:75]
	global_load_dwordx4 v[82:85], v[76:77], off
	v_lshl_add_u64 v[76:77], s[46:47], 0, v[212:213]
	v_lshl_add_u64 v[76:77], v[76:77], 0, v[74:75]
	global_load_dwordx4 v[78:81], v[76:77], off
	v_lshl_add_u64 v[76:77], s[46:47], 0, v[214:215]
	v_lshl_add_u64 v[74:75], v[76:77], 0, v[74:75]
	global_load_dwordx4 v[74:77], v[74:75], off
	s_and_b64 vcc, exec, s[42:43]
	s_waitcnt vmcnt(0)
; __device__ __forceinline__ unsigned cvt_pk_bf16(float lo, float hi) { unsigned r; asm volatile("v_cvt_pk_bf16_f32 %0, %1, %2" : "=v"(r) : "v"(lo), "v"(hi)); return r; }
; __device__ __forceinline__ float bf_lo(unsigned w) { return __uint_as_float(w << 16); }
; __device__ __forceinline__ float bf_hi(unsigned w) { return __uint_as_float(w & 0xffff0000u); }
; __device__ __forceinline__ float silu_f(float z) { return z * fast_rcp(1.0f + __builtin_amdgcn_exp2f(z * -1.44269504f)); }
;     __device__ __forceinline__ void operator()(const f32x4 (&acc)[2][2][4][2], const Unit& u, int wr, int wc, int fr, int fq, const Pre&) const {
;     ...
;                 for (int m = 0; m < 4; ++m) { const int r = row0 + ai * HALF + m * 16;
;                     const u32x4 zw = zv[ai * 4 + m];
;                     const f32x4 a0 = acc[ai][bj][m][0] * sc[bj][0], a1 = acc[ai][bj][m][1] * sc[bj][1];
;                     u32x4 w;
;                     w.x = cvt_pk_bf16(a0[0] * silu_f(bf_lo(zw.x)), a0[1] * silu_f(bf_hi(zw.x)));
;                     w.y = cvt_pk_bf16(a0[2] * silu_f(bf_lo(zw.y)), a0[3] * silu_f(bf_hi(zw.y)));
;                     w.z = cvt_pk_bf16(a1[0] * silu_f(bf_lo(zw.z)), a1[1] * silu_f(bf_hi(zw.z)));
;                     w.w = cvt_pk_bf16(a1[2] * silu_f(bf_lo(zw.w)), a1[3] * silu_f(bf_hi(zw.w)));
;                     *(u32x4*)(O + (size_t)r * DE + c) = w; } }
	v_lshlrev_b32_e32 v108, 16, v102
	v_mul_f32_e32 v109, 0xbfb8aa3b, v108
	v_exp_f32_e32 v109, v109
	v_and_b32_e32 v102, 0xffff0000, v102
	v_add_f32_e32 v109, 1.0, v109
	v_rcp_f32_e32 v109, v109
	s_nop 0
	v_mul_f32_e32 v108, v109, v108
	v_mul_f32_e32 v70, v70, v108
	v_mul_f32_e32 v108, 0xbfb8aa3b, v102
	v_exp_f32_e32 v108, v108
	s_nop 0
	v_add_f32_e32 v108, 1.0, v108
	v_rcp_f32_e32 v108, v108
	s_nop 0
	v_mul_f32_e32 v102, v108, v102
	v_mul_f32_e32 v71, v71, v102
	v_cvt_pk_bf16_f32 v70, v70, v71
	v_lshlrev_b32_e32 v71, 16, v103
	v_mul_f32_e32 v102, 0xbfb8aa3b, v71
	v_exp_f32_e32 v102, v102
	s_nop 0
	v_add_f32_e32 v102, 1.0, v102
	v_rcp_f32_e32 v102, v102
	s_nop 0
	v_mul_f32_e32 v71, v102, v71
	v_mul_f32_e32 v71, v72, v71
	v_and_b32_e32 v72, 0xffff0000, v103
	v_mul_f32_e32 v102, 0xbfb8aa3b, v72
	v_exp_f32_e32 v102, v102
	s_nop 0
	v_add_f32_e32 v102, 1.0, v102
	v_rcp_f32_e32 v102, v102
	s_nop 0
	v_mul_f32_e32 v72, v102, v72
	v_mul_f32_e32 v72, v73, v72
	v_cvt_pk_bf16_f32 v71, v71, v72
	v_lshlrev_b32_e32 v72, 16, v104
	v_mul_f32_e32 v73, 0xbfb8aa3b, v72
	v_exp_f32_e32 v73, v73
	s_nop 0
	v_add_f32_e32 v73, 1.0, v73
	v_rcp_f32_e32 v73, v73
	s_nop 0
	v_mul_f32_e32 v72, v73, v72
	v_mul_f32_e32 v66, v66, v72
	v_and_b32_e32 v72, 0xffff0000, v104
	v_mul_f32_e32 v73, 0xbfb8aa3b, v72
	v_exp_f32_e32 v73, v73
	s_nop 0
	v_add_f32_e32 v73, 1.0, v73
	v_rcp_f32_e32 v73, v73
	s_nop 0
	v_mul_f32_e32 v72, v73, v72
	v_mul_f32_e32 v67, v67, v72
	v_cvt_pk_bf16_f32 v72, v66, v67
	v_lshlrev_b32_e32 v66, 16, v105
	v_mul_f32_e32 v67, 0xbfb8aa3b, v66
	v_exp_f32_e32 v67, v67
	s_nop 0
	v_add_f32_e32 v67, 1.0, v67
	v_rcp_f32_e32 v67, v67
	s_nop 0
	v_mul_f32_e32 v66, v67, v66
	v_and_b32_e32 v67, 0xffff0000, v105
	v_mul_f32_e32 v66, v68, v66
	v_mul_f32_e32 v68, 0xbfb8aa3b, v67
	v_exp_f32_e32 v68, v68
	s_nop 0
	v_add_f32_e32 v68, 1.0, v68
	v_rcp_f32_e32 v68, v68
	s_nop 0
	v_mul_f32_e32 v67, v68, v67
	v_mul_f32_e32 v67, v69, v67
	v_cvt_pk_bf16_f32 v73, v66, v67
	v_lshlrev_b32_e32 v66, 16, v98
	v_mul_f32_e32 v67, 0xbfb8aa3b, v66
	v_exp_f32_e32 v67, v67
	global_store_dwordx4 v[166:167], v[70:73], off offset:256
	v_add_f32_e32 v67, 1.0, v67
	v_rcp_f32_e32 v67, v67
	s_nop 0
	v_mul_f32_e32 v66, v67, v66
	v_mul_f32_e32 v62, v62, v66
	v_and_b32_e32 v66, 0xffff0000, v98
	v_mul_f32_e32 v67, 0xbfb8aa3b, v66
	v_exp_f32_e32 v67, v67
	s_nop 0
	v_add_f32_e32 v67, 1.0, v67
	v_rcp_f32_e32 v67, v67
	s_nop 0
	v_mul_f32_e32 v66, v67, v66
	v_mul_f32_e32 v63, v63, v66
	v_cvt_pk_bf16_f32 v62, v62, v63
	v_lshlrev_b32_e32 v63, 16, v99
	v_mul_f32_e32 v66, 0xbfb8aa3b, v63
	v_exp_f32_e32 v66, v66
	s_nop 0
	v_add_f32_e32 v66, 1.0, v66
	v_rcp_f32_e32 v66, v66
	s_nop 0
	v_mul_f32_e32 v63, v66, v63
	v_mul_f32_e32 v63, v64, v63
	v_and_b32_e32 v64, 0xffff0000, v99
	v_mul_f32_e32 v66, 0xbfb8aa3b, v64
	v_exp_f32_e32 v66, v66
	s_nop 0
	v_add_f32_e32 v66, 1.0, v66
	v_rcp_f32_e32 v66, v66
	s_nop 0
	v_mul_f32_e32 v64, v66, v64
	v_mul_f32_e32 v64, v65, v64
	v_cvt_pk_bf16_f32 v63, v63, v64
	v_lshlrev_b32_e32 v64, 16, v100
	v_mul_f32_e32 v65, 0xbfb8aa3b, v64
	v_exp_f32_e32 v65, v65
	s_nop 0
	v_add_f32_e32 v65, 1.0, v65
	v_rcp_f32_e32 v65, v65
	s_nop 0
	v_mul_f32_e32 v64, v65, v64
	v_mul_f32_e32 v58, v58, v64
	v_and_b32_e32 v64, 0xffff0000, v100
	v_mul_f32_e32 v65, 0xbfb8aa3b, v64
	v_exp_f32_e32 v65, v65
	s_nop 0
	v_add_f32_e32 v65, 1.0, v65
	v_rcp_f32_e32 v65, v65
	s_nop 0
	v_mul_f32_e32 v64, v65, v64
	v_mul_f32_e32 v59, v59, v64
	v_cvt_pk_bf16_f32 v64, v58, v59
	v_lshlrev_b32_e32 v58, 16, v101
	v_mul_f32_e32 v59, 0xbfb8aa3b, v58
	v_exp_f32_e32 v59, v59
	s_nop 0
	v_add_f32_e32 v59, 1.0, v59
	v_rcp_f32_e32 v59, v59
	s_nop 0
	v_mul_f32_e32 v58, v59, v58
	v_and_b32_e32 v59, 0xffff0000, v101
	v_mul_f32_e32 v58, v60, v58
	v_mul_f32_e32 v60, 0xbfb8aa3b, v59
	v_exp_f32_e32 v60, v60
	s_nop 0
	v_add_f32_e32 v60, 1.0, v60
	v_rcp_f32_e32 v60, v60
	s_nop 0
	v_mul_f32_e32 v59, v60, v59
	v_mul_f32_e32 v59, v61, v59
	v_cvt_pk_bf16_f32 v65, v58, v59
	v_lshlrev_b32_e32 v58, 16, v94
	v_mul_f32_e32 v59, 0xbfb8aa3b, v58
	v_exp_f32_e32 v59, v59
	global_store_dwordx4 v[146:147], v[62:65], off offset:256
	v_add_f32_e32 v59, 1.0, v59
	v_rcp_f32_e32 v59, v59
	s_nop 0
	v_mul_f32_e32 v58, v59, v58
	v_mul_f32_e32 v54, v54, v58
	v_and_b32_e32 v58, 0xffff0000, v94
	v_mul_f32_e32 v59, 0xbfb8aa3b, v58
	v_exp_f32_e32 v59, v59
	s_nop 0
	v_add_f32_e32 v59, 1.0, v59
	v_rcp_f32_e32 v59, v59
	s_nop 0
	v_mul_f32_e32 v58, v59, v58
	v_mul_f32_e32 v55, v55, v58
	v_cvt_pk_bf16_f32 v54, v54, v55
	v_lshlrev_b32_e32 v55, 16, v95
	v_mul_f32_e32 v58, 0xbfb8aa3b, v55
	v_exp_f32_e32 v58, v58
	s_nop 0
	v_add_f32_e32 v58, 1.0, v58
	v_rcp_f32_e32 v58, v58
	s_nop 0
	v_mul_f32_e32 v55, v58, v55
	v_mul_f32_e32 v55, v56, v55
	v_and_b32_e32 v56, 0xffff0000, v95
	v_mul_f32_e32 v58, 0xbfb8aa3b, v56
	v_exp_f32_e32 v58, v58
	s_nop 0
	v_add_f32_e32 v58, 1.0, v58
	v_rcp_f32_e32 v58, v58
	s_nop 0
	v_mul_f32_e32 v56, v58, v56
	v_mul_f32_e32 v56, v57, v56
	v_cvt_pk_bf16_f32 v55, v55, v56
	v_lshlrev_b32_e32 v56, 16, v96
	v_mul_f32_e32 v57, 0xbfb8aa3b, v56
	v_exp_f32_e32 v57, v57
	s_nop 0
	v_add_f32_e32 v57, 1.0, v57
	v_rcp_f32_e32 v57, v57
	s_nop 0
	v_mul_f32_e32 v56, v57, v56
	v_mul_f32_e32 v50, v50, v56
	v_and_b32_e32 v56, 0xffff0000, v96
	v_mul_f32_e32 v57, 0xbfb8aa3b, v56
	v_exp_f32_e32 v57, v57
	s_nop 0
	v_add_f32_e32 v57, 1.0, v57
	v_rcp_f32_e32 v57, v57
	s_nop 0
	v_mul_f32_e32 v56, v57, v56
	v_mul_f32_e32 v51, v51, v56
	v_cvt_pk_bf16_f32 v56, v50, v51
	v_lshlrev_b32_e32 v50, 16, v97
	v_mul_f32_e32 v51, 0xbfb8aa3b, v50
	v_exp_f32_e32 v51, v51
	s_nop 0
	v_add_f32_e32 v51, 1.0, v51
	v_rcp_f32_e32 v51, v51
	s_nop 0
	v_mul_f32_e32 v50, v51, v50
	v_and_b32_e32 v51, 0xffff0000, v97
; __device__ __forceinline__ unsigned cvt_pk_bf16(float lo, float hi) { unsigned r; asm volatile("v_cvt_pk_bf16_f32 %0, %1, %2" : "=v"(r) : "v"(lo), "v"(hi)); return r; }
; __device__ __forceinline__ float bf_lo(unsigned w) { return __uint_as_float(w << 16); }
; __device__ __forceinline__ float bf_hi(unsigned w) { return __uint_as_float(w & 0xffff0000u); }
; __device__ __forceinline__ float silu_f(float z) { return z * fast_rcp(1.0f + __builtin_amdgcn_exp2f(z * -1.44269504f)); }
;     __device__ __forceinline__ void operator()(const f32x4 (&acc)[2][2][4][2], const Unit& u, int wr, int wc, int fr, int fq, const Pre&) const {
;     ...
;                 for (int m = 0; m < 4; ++m) { const int r = row0 + ai * HALF + m * 16;
;                     const u32x4 zw = zv[ai * 4 + m];
;                     const f32x4 a0 = acc[ai][bj][m][0] * sc[bj][0], a1 = acc[ai][bj][m][1] * sc[bj][1];
;                     u32x4 w;
;                     w.x = cvt_pk_bf16(a0[0] * silu_f(bf_lo(zw.x)), a0[1] * silu_f(bf_hi(zw.x)));
;                     w.y = cvt_pk_bf16(a0[2] * silu_f(bf_lo(zw.y)), a0[3] * silu_f(bf_hi(zw.y)));
;                     w.z = cvt_pk_bf16(a1[0] * silu_f(bf_lo(zw.z)), a1[1] * silu_f(bf_hi(zw.z)));
;                     w.w = cvt_pk_bf16(a1[2] * silu_f(bf_lo(zw.w)), a1[3] * silu_f(bf_hi(zw.w)));
;                     *(u32x4*)(O + (size_t)r * DE + c) = w; } }
	v_mul_f32_e32 v50, v52, v50
	v_mul_f32_e32 v52, 0xbfb8aa3b, v51
	v_exp_f32_e32 v52, v52
	s_nop 0
	v_add_f32_e32 v52, 1.0, v52
	v_rcp_f32_e32 v52, v52
	s_nop 0
	v_mul_f32_e32 v51, v52, v51
	v_mul_f32_e32 v51, v53, v51
	v_cvt_pk_bf16_f32 v57, v50, v51
	v_lshlrev_b32_e32 v50, 16, v90
	v_mul_f32_e32 v51, 0xbfb8aa3b, v50
	v_exp_f32_e32 v51, v51
	global_store_dwordx4 v[134:135], v[54:57], off offset:256
	v_add_f32_e32 v51, 1.0, v51
	v_rcp_f32_e32 v51, v51
	s_nop 0
	v_mul_f32_e32 v50, v51, v50
	v_mul_f32_e32 v46, v46, v50
	v_and_b32_e32 v50, 0xffff0000, v90
	v_mul_f32_e32 v51, 0xbfb8aa3b, v50
	v_exp_f32_e32 v51, v51
	s_nop 0
	v_add_f32_e32 v51, 1.0, v51
	v_rcp_f32_e32 v51, v51
	s_nop 0
	v_mul_f32_e32 v50, v51, v50
	v_mul_f32_e32 v47, v47, v50
	v_cvt_pk_bf16_f32 v46, v46, v47
	v_lshlrev_b32_e32 v47, 16, v91
	v_mul_f32_e32 v50, 0xbfb8aa3b, v47
	v_exp_f32_e32 v50, v50
	s_nop 0
	v_add_f32_e32 v50, 1.0, v50
	v_rcp_f32_e32 v50, v50
	s_nop 0
	v_mul_f32_e32 v47, v50, v47
	v_mul_f32_e32 v47, v48, v47
	v_and_b32_e32 v48, 0xffff0000, v91
	v_mul_f32_e32 v50, 0xbfb8aa3b, v48
	v_exp_f32_e32 v50, v50
	s_nop 0
	v_add_f32_e32 v50, 1.0, v50
	v_rcp_f32_e32 v50, v50
	s_nop 0
	v_mul_f32_e32 v48, v50, v48
	v_mul_f32_e32 v48, v49, v48
	v_cvt_pk_bf16_f32 v47, v47, v48
	v_lshlrev_b32_e32 v48, 16, v92
	v_mul_f32_e32 v49, 0xbfb8aa3b, v48
	v_exp_f32_e32 v49, v49
	s_nop 0
	v_add_f32_e32 v49, 1.0, v49
	v_rcp_f32_e32 v49, v49
	s_nop 0
	v_mul_f32_e32 v48, v49, v48
	v_mul_f32_e32 v42, v42, v48
	v_and_b32_e32 v48, 0xffff0000, v92
	v_mul_f32_e32 v49, 0xbfb8aa3b, v48
	v_exp_f32_e32 v49, v49
	s_nop 0
	v_add_f32_e32 v49, 1.0, v49
	v_rcp_f32_e32 v49, v49
	s_nop 0
	v_mul_f32_e32 v48, v49, v48
	v_mul_f32_e32 v43, v43, v48
	v_cvt_pk_bf16_f32 v48, v42, v43
	v_lshlrev_b32_e32 v42, 16, v93
	v_mul_f32_e32 v43, 0xbfb8aa3b, v42
	v_exp_f32_e32 v43, v43
	s_nop 0
	v_add_f32_e32 v43, 1.0, v43
	v_rcp_f32_e32 v43, v43
	s_nop 0
	v_mul_f32_e32 v42, v43, v42
	v_and_b32_e32 v43, 0xffff0000, v93
	v_mul_f32_e32 v42, v44, v42
	v_mul_f32_e32 v44, 0xbfb8aa3b, v43
	v_exp_f32_e32 v44, v44
	s_nop 0
	v_add_f32_e32 v44, 1.0, v44
	v_rcp_f32_e32 v44, v44
	s_nop 0
	v_mul_f32_e32 v43, v44, v43
	v_mul_f32_e32 v43, v45, v43
	v_cvt_pk_bf16_f32 v49, v42, v43
	v_lshlrev_b32_e32 v42, 16, v86
	v_mul_f32_e32 v43, 0xbfb8aa3b, v42
	v_exp_f32_e32 v43, v43
	global_store_dwordx4 v[122:123], v[46:49], off offset:256
	v_add_f32_e32 v43, 1.0, v43
	v_rcp_f32_e32 v43, v43
	s_nop 0
	v_mul_f32_e32 v42, v43, v42
	v_mul_f32_e32 v30, v30, v42
	v_and_b32_e32 v42, 0xffff0000, v86
	v_mul_f32_e32 v43, 0xbfb8aa3b, v42
	v_exp_f32_e32 v43, v43
	s_nop 0
	v_add_f32_e32 v43, 1.0, v43
	v_rcp_f32_e32 v43, v43
	s_nop 0
	v_mul_f32_e32 v42, v43, v42
	v_mul_f32_e32 v31, v31, v42
	v_cvt_pk_bf16_f32 v30, v30, v31
	v_lshlrev_b32_e32 v31, 16, v87
	v_mul_f32_e32 v42, 0xbfb8aa3b, v31
	v_exp_f32_e32 v42, v42
	s_nop 0
	v_add_f32_e32 v42, 1.0, v42
	v_rcp_f32_e32 v42, v42
	s_nop 0
	v_mul_f32_e32 v31, v42, v31
	v_mul_f32_e32 v31, v32, v31
	v_and_b32_e32 v32, 0xffff0000, v87
	v_mul_f32_e32 v42, 0xbfb8aa3b, v32
	v_exp_f32_e32 v42, v42
	s_nop 0
	v_add_f32_e32 v42, 1.0, v42
	v_rcp_f32_e32 v42, v42
	s_nop 0
	v_mul_f32_e32 v32, v42, v32
	v_mul_f32_e32 v32, v33, v32
	v_cvt_pk_bf16_f32 v31, v31, v32
	v_lshlrev_b32_e32 v32, 16, v88
	v_mul_f32_e32 v33, 0xbfb8aa3b, v32
	v_exp_f32_e32 v33, v33
	s_nop 0
	v_add_f32_e32 v33, 1.0, v33
	v_rcp_f32_e32 v33, v33
	s_nop 0
	v_mul_f32_e32 v32, v33, v32
	v_mul_f32_e32 v26, v26, v32
	v_and_b32_e32 v32, 0xffff0000, v88
	v_mul_f32_e32 v33, 0xbfb8aa3b, v32
	v_exp_f32_e32 v33, v33
	s_nop 0
	v_add_f32_e32 v33, 1.0, v33
	v_rcp_f32_e32 v33, v33
	s_nop 0
	v_mul_f32_e32 v32, v33, v32
	v_mul_f32_e32 v27, v27, v32
	v_cvt_pk_bf16_f32 v32, v26, v27
	v_lshlrev_b32_e32 v26, 16, v89
	v_mul_f32_e32 v27, 0xbfb8aa3b, v26
	v_exp_f32_e32 v27, v27
	s_nop 0
	v_add_f32_e32 v27, 1.0, v27
	v_rcp_f32_e32 v27, v27
	s_nop 0
	v_mul_f32_e32 v26, v27, v26
	v_and_b32_e32 v27, 0xffff0000, v89
	v_mul_f32_e32 v26, v28, v26
	v_mul_f32_e32 v28, 0xbfb8aa3b, v27
	v_exp_f32_e32 v28, v28
	s_nop 0
	v_add_f32_e32 v28, 1.0, v28
	v_rcp_f32_e32 v28, v28
	s_nop 0
	v_mul_f32_e32 v27, v28, v27
	v_mul_f32_e32 v27, v29, v27
	v_cvt_pk_bf16_f32 v33, v26, v27
	v_lshlrev_b32_e32 v26, 16, v82
	v_mul_f32_e32 v27, 0xbfb8aa3b, v26
	v_exp_f32_e32 v27, v27
	global_store_dwordx4 v[112:113], v[30:33], off offset:256
	v_add_f32_e32 v27, 1.0, v27
	v_rcp_f32_e32 v27, v27
	s_nop 0
	v_mul_f32_e32 v26, v27, v26
	v_mul_f32_e32 v22, v22, v26
	v_and_b32_e32 v26, 0xffff0000, v82
	v_mul_f32_e32 v27, 0xbfb8aa3b, v26
	v_exp_f32_e32 v27, v27
	s_nop 0
	v_add_f32_e32 v27, 1.0, v27
	v_rcp_f32_e32 v27, v27
	s_nop 0
	v_mul_f32_e32 v26, v27, v26
	v_mul_f32_e32 v23, v23, v26
	v_cvt_pk_bf16_f32 v22, v22, v23
	v_lshlrev_b32_e32 v23, 16, v83
	v_mul_f32_e32 v26, 0xbfb8aa3b, v23
	v_exp_f32_e32 v26, v26
	s_nop 0
	v_add_f32_e32 v26, 1.0, v26
	v_rcp_f32_e32 v26, v26
	s_nop 0
	v_mul_f32_e32 v23, v26, v23
	v_mul_f32_e32 v23, v24, v23
	v_and_b32_e32 v24, 0xffff0000, v83
	v_mul_f32_e32 v26, 0xbfb8aa3b, v24
	v_exp_f32_e32 v26, v26
	s_nop 0
	v_add_f32_e32 v26, 1.0, v26
	v_rcp_f32_e32 v26, v26
; __device__ __forceinline__ unsigned cvt_pk_bf16(float lo, float hi) { unsigned r; asm volatile("v_cvt_pk_bf16_f32 %0, %1, %2" : "=v"(r) : "v"(lo), "v"(hi)); return r; }
; __device__ __forceinline__ float bf_lo(unsigned w) { return __uint_as_float(w << 16); }
; __device__ __forceinline__ float bf_hi(unsigned w) { return __uint_as_float(w & 0xffff0000u); }
; __device__ __forceinline__ float silu_f(float z) { return z * fast_rcp(1.0f + __builtin_amdgcn_exp2f(z * -1.44269504f)); }
; #define PG8_WAIT_V(n) asm volatile("s_waitcnt vmcnt(" #n ")" ::: "memory")
; #define PG8_BAR __builtin_amdgcn_s_barrier()
; template <class Epi>
; __device__ __forceinline__ void gemm_phase(LAS unsigned char* lds, const Gemm g, const StaticOrder& S, const Epi& E) {
;     ...
;     PG8_WAIT_V(0);
;     if (wr == 0) PG8_BAR;
;     PG8_BAR;
;     __device__ __forceinline__ void operator()(const f32x4 (&acc)[2][2][4][2], const Unit& u, int wr, int wc, int fr, int fq, const Pre&) const {
;     ...
;                 for (int m = 0; m < 4; ++m) { const int r = row0 + ai * HALF + m * 16;
;                     const u32x4 zw = zv[ai * 4 + m];
;                     const f32x4 a0 = acc[ai][bj][m][0] * sc[bj][0], a1 = acc[ai][bj][m][1] * sc[bj][1];
;                     u32x4 w;
;                     w.x = cvt_pk_bf16(a0[0] * silu_f(bf_lo(zw.x)), a0[1] * silu_f(bf_hi(zw.x)));
;                     w.y = cvt_pk_bf16(a0[2] * silu_f(bf_lo(zw.y)), a0[3] * silu_f(bf_hi(zw.y)));
;                     w.z = cvt_pk_bf16(a1[0] * silu_f(bf_lo(zw.z)), a1[1] * silu_f(bf_hi(zw.z)));
;                     w.w = cvt_pk_bf16(a1[2] * silu_f(bf_lo(zw.w)), a1[3] * silu_f(bf_hi(zw.w)));
;                     *(u32x4*)(O + (size_t)r * DE + c) = w; } }
	s_nop 0
	v_mul_f32_e32 v24, v26, v24
	v_mul_f32_e32 v24, v25, v24
	v_cvt_pk_bf16_f32 v23, v23, v24
	v_lshlrev_b32_e32 v24, 16, v84
	v_mul_f32_e32 v25, 0xbfb8aa3b, v24
	v_exp_f32_e32 v25, v25
	s_nop 0
	v_add_f32_e32 v25, 1.0, v25
	v_rcp_f32_e32 v25, v25
	s_nop 0
	v_mul_f32_e32 v24, v25, v24
	v_mul_f32_e32 v18, v18, v24
	v_and_b32_e32 v24, 0xffff0000, v84
	v_mul_f32_e32 v25, 0xbfb8aa3b, v24
	v_exp_f32_e32 v25, v25
	s_nop 0
	v_add_f32_e32 v25, 1.0, v25
	v_rcp_f32_e32 v25, v25
	s_nop 0
	v_mul_f32_e32 v24, v25, v24
	v_mul_f32_e32 v19, v19, v24
	v_cvt_pk_bf16_f32 v24, v18, v19
	v_lshlrev_b32_e32 v18, 16, v85
	v_mul_f32_e32 v19, 0xbfb8aa3b, v18
	v_exp_f32_e32 v19, v19
	s_nop 0
	v_add_f32_e32 v19, 1.0, v19
	v_rcp_f32_e32 v19, v19
	s_nop 0
	v_mul_f32_e32 v18, v19, v18
	v_and_b32_e32 v19, 0xffff0000, v85
	v_mul_f32_e32 v18, v20, v18
	v_mul_f32_e32 v20, 0xbfb8aa3b, v19
	v_exp_f32_e32 v20, v20
	s_nop 0
	v_add_f32_e32 v20, 1.0, v20
	v_rcp_f32_e32 v20, v20
	s_nop 0
	v_mul_f32_e32 v19, v20, v19
	v_mul_f32_e32 v19, v21, v19
	v_cvt_pk_bf16_f32 v25, v18, v19
	v_lshlrev_b32_e32 v18, 16, v78
	v_mul_f32_e32 v19, 0xbfb8aa3b, v18
	v_exp_f32_e32 v19, v19
	global_store_dwordx4 v[110:111], v[22:25], off offset:256
	v_add_f32_e32 v19, 1.0, v19
	v_rcp_f32_e32 v19, v19
	s_nop 0
	v_mul_f32_e32 v18, v19, v18
	v_mul_f32_e32 v14, v14, v18
	v_and_b32_e32 v18, 0xffff0000, v78
	v_mul_f32_e32 v19, 0xbfb8aa3b, v18
	v_exp_f32_e32 v19, v19
	s_nop 0
	v_add_f32_e32 v19, 1.0, v19
	v_rcp_f32_e32 v19, v19
	s_nop 0
	v_mul_f32_e32 v18, v19, v18
	v_mul_f32_e32 v15, v15, v18
	v_cvt_pk_bf16_f32 v14, v14, v15
	v_lshlrev_b32_e32 v15, 16, v79
	v_mul_f32_e32 v18, 0xbfb8aa3b, v15
	v_exp_f32_e32 v18, v18
	s_nop 0
	v_add_f32_e32 v18, 1.0, v18
	v_rcp_f32_e32 v18, v18
	s_nop 0
	v_mul_f32_e32 v15, v18, v15
	v_mul_f32_e32 v15, v16, v15
	v_and_b32_e32 v16, 0xffff0000, v79
	v_mul_f32_e32 v18, 0xbfb8aa3b, v16
	v_exp_f32_e32 v18, v18
	s_nop 0
	v_add_f32_e32 v18, 1.0, v18
	v_rcp_f32_e32 v18, v18
	s_nop 0
	v_mul_f32_e32 v16, v18, v16
	v_mul_f32_e32 v16, v17, v16
	v_cvt_pk_bf16_f32 v15, v15, v16
	v_lshlrev_b32_e32 v16, 16, v80
	v_mul_f32_e32 v17, 0xbfb8aa3b, v16
	v_exp_f32_e32 v17, v17
	s_nop 0
	v_add_f32_e32 v17, 1.0, v17
	v_rcp_f32_e32 v17, v17
	s_nop 0
	v_mul_f32_e32 v16, v17, v16
	v_mul_f32_e32 v10, v10, v16
	v_and_b32_e32 v16, 0xffff0000, v80
	v_mul_f32_e32 v17, 0xbfb8aa3b, v16
	v_exp_f32_e32 v17, v17
	s_nop 0
	v_add_f32_e32 v17, 1.0, v17
	v_rcp_f32_e32 v17, v17
	s_nop 0
	v_mul_f32_e32 v16, v17, v16
	v_mul_f32_e32 v11, v11, v16
	v_cvt_pk_bf16_f32 v16, v10, v11
	v_lshlrev_b32_e32 v10, 16, v81
	v_mul_f32_e32 v11, 0xbfb8aa3b, v10
	v_exp_f32_e32 v11, v11
	s_nop 0
	v_add_f32_e32 v11, 1.0, v11
	v_rcp_f32_e32 v11, v11
	s_nop 0
	v_mul_f32_e32 v10, v11, v10
	v_and_b32_e32 v11, 0xffff0000, v81
	v_mul_f32_e32 v10, v12, v10
	v_mul_f32_e32 v12, 0xbfb8aa3b, v11
	v_exp_f32_e32 v12, v12
	s_nop 0
	v_add_f32_e32 v12, 1.0, v12
	v_rcp_f32_e32 v12, v12
	s_nop 0
	v_mul_f32_e32 v11, v12, v11
	v_mul_f32_e32 v11, v13, v11
	v_cvt_pk_bf16_f32 v17, v10, v11
	v_lshlrev_b32_e32 v10, 16, v74
	v_mul_f32_e32 v11, 0xbfb8aa3b, v10
	v_exp_f32_e32 v11, v11
	global_store_dwordx4 v[114:115], v[14:17], off offset:256
	v_add_f32_e32 v11, 1.0, v11
	v_rcp_f32_e32 v11, v11
	s_nop 0
	v_mul_f32_e32 v10, v11, v10
	v_mul_f32_e32 v6, v6, v10
	v_and_b32_e32 v10, 0xffff0000, v74
	v_mul_f32_e32 v11, 0xbfb8aa3b, v10
	v_exp_f32_e32 v11, v11
	s_nop 0
	v_add_f32_e32 v11, 1.0, v11
	v_rcp_f32_e32 v11, v11
	s_nop 0
	v_mul_f32_e32 v10, v11, v10
	v_mul_f32_e32 v7, v7, v10
	v_cvt_pk_bf16_f32 v6, v6, v7
	v_lshlrev_b32_e32 v7, 16, v75
	v_mul_f32_e32 v10, 0xbfb8aa3b, v7
	v_exp_f32_e32 v10, v10
	s_nop 0
	v_add_f32_e32 v10, 1.0, v10
	v_rcp_f32_e32 v10, v10
	s_nop 0
	v_mul_f32_e32 v7, v10, v7
	v_mul_f32_e32 v7, v8, v7
	v_and_b32_e32 v8, 0xffff0000, v75
	v_mul_f32_e32 v10, 0xbfb8aa3b, v8
	v_exp_f32_e32 v10, v10
	s_nop 0
	v_add_f32_e32 v10, 1.0, v10
	v_rcp_f32_e32 v10, v10
	s_nop 0
	v_mul_f32_e32 v8, v10, v8
	v_mul_f32_e32 v8, v9, v8
	v_cvt_pk_bf16_f32 v7, v7, v8
	v_lshlrev_b32_e32 v8, 16, v76
	v_mul_f32_e32 v9, 0xbfb8aa3b, v8
	v_exp_f32_e32 v9, v9
	s_nop 0
	v_add_f32_e32 v9, 1.0, v9
	v_rcp_f32_e32 v9, v9
	s_nop 0
	v_mul_f32_e32 v8, v9, v8
	v_mul_f32_e32 v2, v2, v8
	v_and_b32_e32 v8, 0xffff0000, v76
	v_mul_f32_e32 v9, 0xbfb8aa3b, v8
	v_exp_f32_e32 v9, v9
	s_nop 0
	v_add_f32_e32 v9, 1.0, v9
	v_rcp_f32_e32 v9, v9
	s_nop 0
	v_mul_f32_e32 v8, v9, v8
	v_mul_f32_e32 v3, v3, v8
	v_cvt_pk_bf16_f32 v8, v2, v3
	v_lshlrev_b32_e32 v2, 16, v77
	v_mul_f32_e32 v3, 0xbfb8aa3b, v2
	v_exp_f32_e32 v3, v3
	s_nop 0
	v_add_f32_e32 v3, 1.0, v3
	v_rcp_f32_e32 v3, v3
	s_nop 0
	v_mul_f32_e32 v2, v3, v2
	v_and_b32_e32 v3, 0xffff0000, v77
	v_mul_f32_e32 v2, v4, v2
	v_mul_f32_e32 v4, 0xbfb8aa3b, v3
	v_exp_f32_e32 v4, v4
	s_nop 0
	v_add_f32_e32 v4, 1.0, v4
	v_rcp_f32_e32 v4, v4
	s_nop 0
	v_mul_f32_e32 v3, v4, v3
	v_mul_f32_e32 v3, v5, v3
	v_cvt_pk_bf16_f32 v9, v2, v3
	global_store_dwordx4 v[106:107], v[6:9], off offset:256
	s_cbranch_vccz .LBB0_596
	s_waitcnt vmcnt(0)
	s_cmpk_gt_u32 s14, 0xff
	s_mov_b64 s[36:37], s[96:97]
	s_cbranch_scc1 .LBB0_607
	s_barrier

; #define PG8_STAGE(bufoff, gbase, voff) do { _Pragma("unroll") for (int _i = 0; _i < 2; ++_i) \
;         __builtin_amdgcn_global_load_lds((const unsigned*)((const char*)(gbase) + (voff)[_i]), (LAS unsigned*)(lds + (bufoff) + ldsw + _i * 8192), 16, 0, 0); } while (0)
; #define PG8_LDA(dst, b, h) do { _Pragma("unroll") for (int m = 0; m < 4; ++m) _Pragma("unroll") for (int k = 0; k < 2; ++k) dst[m][k] = *(const LAS bf16x8*)(lds + PG8_SA(b, h) + aoff + m * 2048 + k * 1024); } while (0)
; #define PG8_LDB(dst, b, h) do { _Pragma("unroll") for (int n = 0; n < 2; ++n) _Pragma("unroll") for (int k = 0; k < 2; ++k) dst[n][k] = *(const LAS bf16x8*)(lds + PG8_SB(b, h) + boff + n * 2048 + k * 1024); } while (0)
; #define PG8_MMA(ai, bj, At, Bt) do { __builtin_amdgcn_s_setprio(1); _Pragma("unroll") for (int m = 0; m < 4; ++m) _Pragma("unroll") for (int n = 0; n < 2; ++n) _Pragma("unroll") for (int k = 0; k < 2; ++k) \
;         acc[ai][bj][m][n] = __builtin_amdgcn_mfma_f32_16x16x32_bf16(Bt[n][k], At[m][k], acc[ai][bj][m][n], 0, 0, 0); __builtin_amdgcn_s_setprio(0); } while (0)
; #define PG8_WAIT_L(n) asm volatile("s_waitcnt lgkmcnt(" #n ")" ::: "memory")
; template <class Epi>
; __device__ __forceinline__ void gemm_phase(LAS unsigned char* lds, const Gemm g, const StaticOrder& S, const Epi& E) {
;     ...
;         const bool has_next = S.next(ui + 1, nxt);
;         const char* nA = has_next ? (const char*)g.A + (size_t)nxt.pm * tstepA + (size_t)(nxt.pn >> 2) * gstepA : cA; const char* nB = has_next ? (const char*)g.Bt + (size_t)nxt.pn * tstepB : cB;
;         for (int t = 0; t < nt; t += 2) {
;             const bool last = (t == nt - 2);
;             const char* a1 = cA + (size_t)(t + 1) * kstepA;
;             const char* a2 = last ? nA : cA + (size_t)(t + 2) * kstepA; const char* b2 = last ? nB : cB + (size_t)(t + 2) * kstep;
;             const char* a3 = a2 + kstepA; const char* b3 = b2 + kstep;
;             PG8_LDB(B0, 0, 0); PG8_SCHED; PG8_LDA(At, 0, 0); PG8_STAGE(PG8_SA(1, 1), a1 + hstepA, voffA);
;             PG8_WAIT_L(8); PG8_BAR; PG8_WAIT_L(0); PG8_MMA(0, 0, At, B0); PG8_BAR; PG8_SCHED;
;     ...
;         for (int a = 0; a < 2; ++a)
; #pragma unroll
;             for (int b = 0; b < 2; ++b)
; #pragma unroll
;                 for (int m = 0; m < 4; ++m)
; #pragma unroll
;                     for (int n = 0; n < 2; ++n) acc[a][b][m][n] = (f32x4){0.f, 0.f, 0.f, 0.f};
.LBB0_795:
	s_ashr_i32 s51, s50, 31
	v_cmp_lt_i64_e32 vcc, s[4:5], v[182:183]
	s_lshl_b64 s[4:5], s[50:51], 13
	s_add_u32 s52, s42, s4
	s_addc_u32 s53, s43, s5
	s_and_b64 s[4:5], vcc, exec
	s_cselect_b32 s37, s53, s15
	s_cselect_b32 s38, s52, s14
	s_ashr_i32 s49, s48, 31
	s_lshl_b64 s[4:5], s[48:49], 21
	s_add_u32 s54, s19, s4
	s_addc_u32 s55, s20, s5
	s_and_b64 s[4:5], vcc, exec
	s_cselect_b32 s39, s55, s9
	s_cselect_b32 s49, s54, s8
	s_add_u32 s51, s8, 0x100
	s_addc_u32 s56, s9, 0
	s_add_u32 s8, s14, 0x105400
	v_mov_b32_e32 v2, 0
	s_addc_u32 s9, s15, 0
	s_mov_b32 s57, -2
	v_mov_b32_e32 v3, v2
	v_mov_b32_e32 v4, v2
	v_mov_b32_e32 v5, v2
	v_mov_b32_e32 v6, v2
	v_mov_b32_e32 v7, v2
	v_mov_b32_e32 v8, v2
	v_mov_b32_e32 v9, v2
	v_mov_b32_e32 v10, v2
	v_mov_b32_e32 v11, v2
	v_mov_b32_e32 v12, v2
	v_mov_b32_e32 v13, v2
	v_mov_b32_e32 v14, v2
	v_mov_b32_e32 v15, v2
	v_mov_b32_e32 v16, v2
	v_mov_b32_e32 v17, v2
	v_mov_b32_e32 v18, v2
	v_mov_b32_e32 v19, v2
	v_mov_b32_e32 v20, v2
	v_mov_b32_e32 v21, v2
	v_mov_b32_e32 v22, v2
	v_mov_b32_e32 v23, v2
	v_mov_b32_e32 v24, v2
	v_mov_b32_e32 v25, v2
	v_mov_b32_e32 v34, v2
	v_mov_b32_e32 v35, v2
	v_mov_b32_e32 v36, v2
	v_mov_b32_e32 v37, v2
	v_mov_b32_e32 v38, v2
	v_mov_b32_e32 v39, v2
	v_mov_b32_e32 v40, v2
	v_mov_b32_e32 v41, v2
	v_mov_b32_e32 v74, v2
	v_mov_b32_e32 v75, v2
	v_mov_b32_e32 v76, v2
	v_mov_b32_e32 v77, v2
	v_mov_b32_e32 v78, v2
	v_mov_b32_e32 v79, v2
	v_mov_b32_e32 v80, v2
	v_mov_b32_e32 v81, v2
	v_mov_b32_e32 v82, v2
	v_mov_b32_e32 v83, v2
	v_mov_b32_e32 v84, v2
	v_mov_b32_e32 v85, v2
	v_mov_b32_e32 v86, v2
	v_mov_b32_e32 v87, v2
	v_mov_b32_e32 v88, v2
	v_mov_b32_e32 v89, v2
	v_mov_b32_e32 v90, v2
	v_mov_b32_e32 v91, v2
	v_mov_b32_e32 v92, v2
	v_mov_b32_e32 v93, v2
	v_mov_b32_e32 v94, v2
	v_mov_b32_e32 v95, v2
	v_mov_b32_e32 v96, v2
	v_mov_b32_e32 v97, v2
	v_mov_b32_e32 v106, v2
	v_mov_b32_e32 v107, v2
	v_mov_b32_e32 v108, v2
	v_mov_b32_e32 v109, v2
	v_mov_b32_e32 v110, v2
	v_mov_b32_e32 v111, v2
	v_mov_b32_e32 v112, v2
	v_mov_b32_e32 v113, v2
	v_mov_b32_e32 v42, v2
	v_mov_b32_e32 v43, v2
	v_mov_b32_e32 v44, v2
	v_mov_b32_e32 v45, v2
	v_mov_b32_e32 v46, v2
	v_mov_b32_e32 v47, v2
	v_mov_b32_e32 v48, v2
	v_mov_b32_e32 v49, v2
	v_mov_b32_e32 v50, v2
	v_mov_b32_e32 v51, v2
	v_mov_b32_e32 v52, v2
	v_mov_b32_e32 v53, v2
	v_mov_b32_e32 v54, v2
	v_mov_b32_e32 v55, v2
	v_mov_b32_e32 v56, v2
	v_mov_b32_e32 v57, v2
	v_mov_b32_e32 v58, v2
	v_mov_b32_e32 v59, v2
	v_mov_b32_e32 v60, v2
	v_mov_b32_e32 v61, v2
	v_mov_b32_e32 v62, v2
	v_mov_b32_e32 v63, v2
	v_mov_b32_e32 v64, v2
	v_mov_b32_e32 v65, v2
	v_mov_b32_e32 v66, v2
	v_mov_b32_e32 v67, v2
	v_mov_b32_e32 v68, v2
	v_mov_b32_e32 v69, v2
	v_mov_b32_e32 v70, v2
	v_mov_b32_e32 v71, v2
	v_mov_b32_e32 v72, v2
	v_mov_b32_e32 v73, v2
	v_mov_b32_e32 v114, v2
	v_mov_b32_e32 v115, v2
	v_mov_b32_e32 v116, v2
	v_mov_b32_e32 v117, v2
	v_mov_b32_e32 v118, v2
	v_mov_b32_e32 v119, v2
	v_mov_b32_e32 v120, v2
	v_mov_b32_e32 v121, v2
	v_mov_b32_e32 v122, v2
	v_mov_b32_e32 v123, v2
	v_mov_b32_e32 v124, v2
	v_mov_b32_e32 v125, v2
	v_mov_b32_e32 v126, v2
	v_mov_b32_e32 v127, v2
	v_mov_b32_e32 v128, v2
	v_mov_b32_e32 v129, v2
	v_mov_b32_e32 v134, v2
	v_mov_b32_e32 v135, v2
	v_mov_b32_e32 v136, v2
	v_mov_b32_e32 v137, v2
	v_mov_b32_e32 v138, v2
	v_mov_b32_e32 v139, v2
	v_mov_b32_e32 v140, v2
	v_mov_b32_e32 v141, v2
	v_mov_b32_e32 v158, v2
	v_mov_b32_e32 v159, v2
	v_mov_b32_e32 v160, v2
	v_mov_b32_e32 v161, v2
	v_mov_b32_e32 v162, v2
	v_mov_b32_e32 v163, v2
	v_mov_b32_e32 v164, v2
	v_mov_b32_e32 v165, v2
	v_readfirstlane_b32 s100, v232
	s_nop 3
	s_cmp_ge_u32 s100, 0x100
	s_cbranch_scc0 .Lprio_skip_4
	s_setprio 1
.Lprio_skip_4:
.LBB0_796:
	s_add_u32 s4, s8, 0x103400
	s_addc_u32 s5, s9, 0
	s_cmp_eq_u32 s57, 60
	s_cselect_b32 s16, s38, s4
	s_cselect_b32 s17, s37, s5
	s_cselect_b32 s4, s49, s51
	s_cselect_b32 s5, s39, s56
	s_add_u32 s14, s16, 0x104400
	s_addc_u32 s15, s17, 0
	s_add_i32 s58, 0, 0x10000
	v_add_u32_e32 v102, s58, v245
	ds_read_b128 v[26:29], v102
	ds_read_b128 v[30:33], v102 offset:1024
	ds_read_b128 v[98:101], v102 offset:2048
	ds_read_b128 v[102:105], v102 offset:3072
	v_lshl_add_u64 v[184:185], s[8:9], 0, v[196:197]
	s_add_i32 m0, s22, 0xc000
	ds_read_b128 v[130:133], v247
	ds_read_b128 v[142:145], v247 offset:1024
	ds_read_b128 v[146:149], v247 offset:2048
	ds_read_b128 v[150:153], v247 offset:3072
	ds_read_b128 v[154:157], v247 offset:4096
	ds_read_b128 v[166:169], v247 offset:5120
	ds_read_b128 v[170:173], v247 offset:6144
	ds_read_b128 v[174:177], v247 offset:7168
	global_load_lds_dwordx4 v[184:185], off
	v_lshl_add_u64 v[184:185], s[8:9], 0, v[198:199]
	s_add_i32 m0, s22, 0xe000
	s_nop 0
	global_load_lds_dwordx4 v[184:185], off
	s_waitcnt lgkmcnt(8)
	s_barrier
	s_waitcnt lgkmcnt(0)
	s_waitcnt lgkmcnt(0)
	v_mfma_f32_16x16x32_bf16 v[162:165], v[26:29], v[130:133], v[162:165]
	v_mfma_f32_16x16x32_bf16 v[158:161], v[98:101], v[130:133], v[158:161]
	v_mfma_f32_16x16x32_bf16 v[138:141], v[26:29], v[146:149], v[138:141]
	v_mfma_f32_16x16x32_bf16 v[134:137], v[98:101], v[146:149], v[134:137]
	v_mfma_f32_16x16x32_bf16 v[126:129], v[26:29], v[154:157], v[126:129]
	v_mfma_f32_16x16x32_bf16 v[122:125], v[98:101], v[154:157], v[122:125]
	v_mfma_f32_16x16x32_bf16 v[118:121], v[26:29], v[170:173], v[118:121]
	v_mfma_f32_16x16x32_bf16 v[114:117], v[98:101], v[170:173], v[114:117]
	v_mfma_f32_16x16x32_bf16 v[162:165], v[30:33], v[142:145], v[162:165]
	v_mfma_f32_16x16x32_bf16 v[158:161], v[102:105], v[142:145], v[158:161]
	v_mfma_f32_16x16x32_bf16 v[138:141], v[30:33], v[150:153], v[138:141]
	v_mfma_f32_16x16x32_bf16 v[134:137], v[102:105], v[150:153], v[134:137]
	v_mfma_f32_16x16x32_bf16 v[126:129], v[30:33], v[166:169], v[126:129]
	v_mfma_f32_16x16x32_bf16 v[122:125], v[102:105], v[166:169], v[122:125]
	v_mfma_f32_16x16x32_bf16 v[118:121], v[30:33], v[174:177], v[118:121]
	v_mfma_f32_16x16x32_bf16 v[114:117], v[102:105], v[174:177], v[114:117]
	s_barrier
; #define PG8_STAGE(bufoff, gbase, voff) do { _Pragma("unroll") for (int _i = 0; _i < 2; ++_i) \
;         __builtin_amdgcn_global_load_lds((const unsigned*)((const char*)(gbase) + (voff)[_i]), (LAS unsigned*)(lds + (bufoff) + ldsw + _i * 8192), 16, 0, 0); } while (0)
; #define PG8_LDA(dst, b, h) do { _Pragma("unroll") for (int m = 0; m < 4; ++m) _Pragma("unroll") for (int k = 0; k < 2; ++k) dst[m][k] = *(const LAS bf16x8*)(lds + PG8_SA(b, h) + aoff + m * 2048 + k * 1024); } while (0)
; #define PG8_LDB(dst, b, h) do { _Pragma("unroll") for (int n = 0; n < 2; ++n) _Pragma("unroll") for (int k = 0; k < 2; ++k) dst[n][k] = *(const LAS bf16x8*)(lds + PG8_SB(b, h) + boff + n * 2048 + k * 1024); } while (0)
; #define PG8_MMA(ai, bj, At, Bt) do { __builtin_amdgcn_s_setprio(1); _Pragma("unroll") for (int m = 0; m < 4; ++m) _Pragma("unroll") for (int n = 0; n < 2; ++n) _Pragma("unroll") for (int k = 0; k < 2; ++k) \
;         acc[ai][bj][m][n] = __builtin_amdgcn_mfma_f32_16x16x32_bf16(Bt[n][k], At[m][k], acc[ai][bj][m][n], 0, 0, 0); __builtin_amdgcn_s_setprio(0); } while (0)
; #define PG8_WAIT_V(n) asm volatile("s_waitcnt vmcnt(" #n ")" ::: "memory")
; #define PG8_WAIT_L(n) asm volatile("s_waitcnt lgkmcnt(" #n ")" ::: "memory")
; #define PG8_BAR __builtin_amdgcn_s_barrier()
; #define PG8_SCHED __builtin_amdgcn_sched_barrier(0)
; template <class Epi>
; __device__ __forceinline__ void gemm_phase(LAS unsigned char* lds, const Gemm g, const StaticOrder& S, const Epi& E) {
;     ...
;             PG8_LDB(B1, 0, 1); PG8_STAGE(PG8_SB(0, 0), b2, voffB);
;             PG8_BAR; PG8_WAIT_L(0); PG8_MMA(0, 1, At, B1); PG8_BAR;
;             PG8_LDA(At, 0, 1); PG8_STAGE(PG8_SA(0, 0), a2, voffA);
;             PG8_BAR; PG8_WAIT_L(0); PG8_MMA(1, 0, At, B0); PG8_BAR; PG8_SCHED;
;             PG8_STAGE(PG8_SB(0, 1), b2 + hstepB, voffB);
;             PG8_WAIT_V(6); PG8_BAR; PG8_MMA(1, 1, At, B1); PG8_BAR;
;             PG8_LDB(B0, 1, 0); PG8_SCHED; PG8_LDA(At, 1, 0); PG8_STAGE(PG8_SA(0, 1), a2 + hstepA, voffA);
;             PG8_WAIT_L(8); PG8_BAR; PG8_WAIT_L(0); PG8_MMA(0, 0, At, B0); PG8_BAR; PG8_SCHED;
	s_add_i32 s60, 0, 0x14000
	s_add_i32 s58, s58, s21
	v_add_u32_e32 v208, s60, v245
	v_lshl_add_u64 v[212:213], s[4:5], 0, v[0:1]
	s_mov_b32 m0, s58
	ds_read_b128 v[184:187], v208
	ds_read_b128 v[200:203], v208 offset:1024
	ds_read_b128 v[204:207], v208 offset:2048
	ds_read_b128 v[208:211], v208 offset:3072
	global_load_lds_dwordx4 v[212:213], off
	v_lshl_add_u64 v[214:215], s[4:5], 0, v[188:189]
	s_add_i32 m0, s58, 0x2000
	s_nop 0
	global_load_lds_dwordx4 v[214:215], off
	s_barrier
	s_waitcnt lgkmcnt(0)
	s_waitcnt lgkmcnt(0)
	v_mfma_f32_16x16x32_bf16 v[70:73], v[184:187], v[130:133], v[70:73]
	v_mfma_f32_16x16x32_bf16 v[66:69], v[204:207], v[130:133], v[66:69]
	v_mfma_f32_16x16x32_bf16 v[62:65], v[184:187], v[146:149], v[62:65]
	v_mfma_f32_16x16x32_bf16 v[58:61], v[204:207], v[146:149], v[58:61]
	v_mfma_f32_16x16x32_bf16 v[54:57], v[184:187], v[154:157], v[54:57]
	v_mfma_f32_16x16x32_bf16 v[50:53], v[204:207], v[154:157], v[50:53]
	v_mfma_f32_16x16x32_bf16 v[46:49], v[184:187], v[170:173], v[46:49]
	v_mfma_f32_16x16x32_bf16 v[42:45], v[204:207], v[170:173], v[42:45]
	v_mfma_f32_16x16x32_bf16 v[70:73], v[200:203], v[142:145], v[70:73]
	v_mfma_f32_16x16x32_bf16 v[66:69], v[208:211], v[142:145], v[66:69]
	v_mfma_f32_16x16x32_bf16 v[62:65], v[200:203], v[150:153], v[62:65]
	v_mfma_f32_16x16x32_bf16 v[58:61], v[208:211], v[150:153], v[58:61]
	v_mfma_f32_16x16x32_bf16 v[54:57], v[200:203], v[166:169], v[54:57]
	v_mfma_f32_16x16x32_bf16 v[50:53], v[208:211], v[166:169], v[50:53]
	v_mfma_f32_16x16x32_bf16 v[46:49], v[200:203], v[174:177], v[46:49]
	v_mfma_f32_16x16x32_bf16 v[42:45], v[208:211], v[174:177], v[42:45]
	s_mov_b32 m0, s22
	v_lshl_add_u64 v[216:217], s[16:17], 0, v[192:193]
	s_barrier
	ds_read_b128 v[130:133], v247 offset:16384
	ds_read_b128 v[142:145], v247 offset:17408
	ds_read_b128 v[146:149], v247 offset:18432
	ds_read_b128 v[150:153], v247 offset:19456
	ds_read_b128 v[154:157], v247 offset:20480
	ds_read_b128 v[166:169], v247 offset:21504
	ds_read_b128 v[170:173], v247 offset:22528
	ds_read_b128 v[174:177], v247 offset:23552
	global_load_lds_dwordx4 v[216:217], off
	v_lshl_add_u64 v[216:217], s[16:17], 0, v[190:191]
	s_mov_b32 m0, s23
	s_nop 0
	global_load_lds_dwordx4 v[216:217], off
	s_barrier
	s_waitcnt lgkmcnt(0)
	s_waitcnt lgkmcnt(0)
	v_mfma_f32_16x16x32_bf16 v[110:113], v[26:29], v[130:133], v[110:113]
	v_mfma_f32_16x16x32_bf16 v[106:109], v[98:101], v[130:133], v[106:109]
	v_mfma_f32_16x16x32_bf16 v[94:97], v[26:29], v[146:149], v[94:97]
	v_mfma_f32_16x16x32_bf16 v[90:93], v[98:101], v[146:149], v[90:93]
	v_mfma_f32_16x16x32_bf16 v[86:89], v[26:29], v[154:157], v[86:89]
	v_mfma_f32_16x16x32_bf16 v[82:85], v[98:101], v[154:157], v[82:85]
	v_mfma_f32_16x16x32_bf16 v[26:29], v[26:29], v[170:173], v[78:81]
	v_mfma_f32_16x16x32_bf16 v[110:113], v[30:33], v[142:145], v[110:113]
	v_mfma_f32_16x16x32_bf16 v[106:109], v[102:105], v[142:145], v[106:109]
	v_mfma_f32_16x16x32_bf16 v[94:97], v[30:33], v[150:153], v[94:97]
	v_mfma_f32_16x16x32_bf16 v[90:93], v[102:105], v[150:153], v[90:93]
	v_mfma_f32_16x16x32_bf16 v[86:89], v[30:33], v[166:169], v[86:89]
	v_mfma_f32_16x16x32_bf16 v[82:85], v[102:105], v[166:169], v[82:85]
	v_mfma_f32_16x16x32_bf16 v[26:29], v[30:33], v[174:177], v[26:29]
	v_mfma_f32_16x16x32_bf16 v[30:33], v[98:101], v[170:173], v[74:77]
	v_mfma_f32_16x16x32_bf16 v[30:33], v[102:105], v[174:177], v[30:33]
	s_barrier
	s_add_u32 s58, s4, 0x100000
	s_addc_u32 s59, s5, 0
	s_add_i32 s60, s60, s21
	v_lshl_add_u64 v[74:75], s[58:59], 0, v[0:1]
	s_mov_b32 m0, s60
	s_nop 0
	global_load_lds_dwordx4 v[74:75], off
	v_lshl_add_u64 v[74:75], s[58:59], 0, v[188:189]
	s_add_i32 m0, s60, 0x2000
	s_nop 0
	global_load_lds_dwordx4 v[74:75], off
	s_waitcnt vmcnt(6)
	s_barrier
	v_mfma_f32_16x16x32_bf16 v[38:41], v[184:187], v[130:133], v[38:41]
	v_mfma_f32_16x16x32_bf16 v[34:37], v[204:207], v[130:133], v[34:37]
	v_mfma_f32_16x16x32_bf16 v[22:25], v[184:187], v[146:149], v[22:25]
	v_mfma_f32_16x16x32_bf16 v[18:21], v[204:207], v[146:149], v[18:21]
	v_mfma_f32_16x16x32_bf16 v[14:17], v[184:187], v[154:157], v[14:17]
	v_mfma_f32_16x16x32_bf16 v[10:13], v[204:207], v[154:157], v[10:13]
	v_mfma_f32_16x16x32_bf16 v[6:9], v[184:187], v[170:173], v[6:9]
	v_mfma_f32_16x16x32_bf16 v[2:5], v[204:207], v[170:173], v[2:5]
	v_mfma_f32_16x16x32_bf16 v[38:41], v[200:203], v[142:145], v[38:41]
	v_mfma_f32_16x16x32_bf16 v[34:37], v[208:211], v[142:145], v[34:37]
	v_mfma_f32_16x16x32_bf16 v[22:25], v[200:203], v[150:153], v[22:25]
	v_mfma_f32_16x16x32_bf16 v[18:21], v[208:211], v[150:153], v[18:21]
	v_mfma_f32_16x16x32_bf16 v[14:17], v[200:203], v[166:169], v[14:17]
	v_mfma_f32_16x16x32_bf16 v[10:13], v[208:211], v[166:169], v[10:13]
	v_mfma_f32_16x16x32_bf16 v[6:9], v[200:203], v[174:177], v[6:9]
	v_mfma_f32_16x16x32_bf16 v[2:5], v[208:211], v[174:177], v[2:5]
	s_add_i32 s58, 0, 0x18000
	v_add_u32_e32 v102, s58, v245
	s_barrier
	ds_read_b128 v[74:77], v102
	ds_read_b128 v[78:81], v102 offset:1024
	ds_read_b128 v[98:101], v102 offset:2048
	ds_read_b128 v[102:105], v102 offset:3072
	s_add_u32 s16, s16, 0x1000
	s_addc_u32 s17, s17, 0
	s_mov_b32 m0, s24
	v_lshl_add_u64 v[184:185], s[16:17], 0, v[192:193]
	ds_read_b128 v[130:133], v247 offset:32768
	ds_read_b128 v[142:145], v247 offset:33792
	ds_read_b128 v[146:149], v247 offset:34816
	ds_read_b128 v[150:153], v247 offset:35840
	ds_read_b128 v[154:157], v247 offset:36864
	ds_read_b128 v[166:169], v247 offset:37888
	ds_read_b128 v[170:173], v247 offset:38912
	ds_read_b128 v[174:177], v247 offset:39936
	global_load_lds_dwordx4 v[184:185], off
	v_lshl_add_u64 v[184:185], s[16:17], 0, v[190:191]
	s_mov_b32 m0, s25
	s_nop 0
	global_load_lds_dwordx4 v[184:185], off
	s_waitcnt lgkmcnt(8)
	s_barrier
; #define PG8_STAGE(bufoff, gbase, voff) do { _Pragma("unroll") for (int _i = 0; _i < 2; ++_i) \
;         __builtin_amdgcn_global_load_lds((const unsigned*)((const char*)(gbase) + (voff)[_i]), (LAS unsigned*)(lds + (bufoff) + ldsw + _i * 8192), 16, 0, 0); } while (0)
; #define PG8_LDA(dst, b, h) do { _Pragma("unroll") for (int m = 0; m < 4; ++m) _Pragma("unroll") for (int k = 0; k < 2; ++k) dst[m][k] = *(const LAS bf16x8*)(lds + PG8_SA(b, h) + aoff + m * 2048 + k * 1024); } while (0)
; #define PG8_LDB(dst, b, h) do { _Pragma("unroll") for (int n = 0; n < 2; ++n) _Pragma("unroll") for (int k = 0; k < 2; ++k) dst[n][k] = *(const LAS bf16x8*)(lds + PG8_SB(b, h) + boff + n * 2048 + k * 1024); } while (0)
; #define PG8_MMA(ai, bj, At, Bt) do { __builtin_amdgcn_s_setprio(1); _Pragma("unroll") for (int m = 0; m < 4; ++m) _Pragma("unroll") for (int n = 0; n < 2; ++n) _Pragma("unroll") for (int k = 0; k < 2; ++k) \
;         acc[ai][bj][m][n] = __builtin_amdgcn_mfma_f32_16x16x32_bf16(Bt[n][k], At[m][k], acc[ai][bj][m][n], 0, 0, 0); __builtin_amdgcn_s_setprio(0); } while (0)
; #define PG8_WAIT_V(n) asm volatile("s_waitcnt vmcnt(" #n ")" ::: "memory")
; #define PG8_WAIT_L(n) asm volatile("s_waitcnt lgkmcnt(" #n ")" ::: "memory")
; #define PG8_BAR __builtin_amdgcn_s_barrier()
; #define PG8_SCHED __builtin_amdgcn_sched_barrier(0)
; template <class Epi>
; __device__ __forceinline__ void gemm_phase(LAS unsigned char* lds, const Gemm g, const StaticOrder& S, const Epi& E) {
;     ...
;             PG8_WAIT_L(8); PG8_BAR; PG8_WAIT_L(0); PG8_MMA(0, 0, At, B0); PG8_BAR; PG8_SCHED;
;             PG8_LDB(B1, 1, 1); PG8_STAGE(PG8_SB(1, 0), b3, voffB);
;             PG8_BAR; PG8_WAIT_L(0); PG8_MMA(0, 1, At, B1); PG8_BAR;
;             PG8_LDA(At, 1, 1); PG8_STAGE(PG8_SA(1, 0), a3, voffA);
;             PG8_BAR; PG8_WAIT_L(0); PG8_MMA(1, 0, At, B0); PG8_BAR; PG8_SCHED;
;             PG8_STAGE(PG8_SB(1, 1), b3 + hstepB, voffB);
;             PG8_WAIT_V(6); PG8_BAR; PG8_MMA(1, 1, At, B1); PG8_BAR;
	s_waitcnt lgkmcnt(0)
	s_waitcnt lgkmcnt(0)
	v_mfma_f32_16x16x32_bf16 v[162:165], v[74:77], v[130:133], v[162:165]
	v_mfma_f32_16x16x32_bf16 v[158:161], v[98:101], v[130:133], v[158:161]
	v_mfma_f32_16x16x32_bf16 v[138:141], v[74:77], v[146:149], v[138:141]
	v_mfma_f32_16x16x32_bf16 v[134:137], v[98:101], v[146:149], v[134:137]
	v_mfma_f32_16x16x32_bf16 v[126:129], v[74:77], v[154:157], v[126:129]
	v_mfma_f32_16x16x32_bf16 v[122:125], v[98:101], v[154:157], v[122:125]
	v_mfma_f32_16x16x32_bf16 v[118:121], v[74:77], v[170:173], v[118:121]
	v_mfma_f32_16x16x32_bf16 v[114:117], v[98:101], v[170:173], v[114:117]
	v_mfma_f32_16x16x32_bf16 v[162:165], v[78:81], v[142:145], v[162:165]
	v_mfma_f32_16x16x32_bf16 v[158:161], v[102:105], v[142:145], v[158:161]
	v_mfma_f32_16x16x32_bf16 v[138:141], v[78:81], v[150:153], v[138:141]
	v_mfma_f32_16x16x32_bf16 v[134:137], v[102:105], v[150:153], v[134:137]
	v_mfma_f32_16x16x32_bf16 v[126:129], v[78:81], v[166:169], v[126:129]
	v_mfma_f32_16x16x32_bf16 v[122:125], v[102:105], v[166:169], v[122:125]
	v_mfma_f32_16x16x32_bf16 v[118:121], v[78:81], v[174:177], v[118:121]
	v_mfma_f32_16x16x32_bf16 v[114:117], v[102:105], v[174:177], v[114:117]
	s_barrier
	s_add_i32 s16, 0, 0x1c000
	s_add_i32 s17, s58, s21
	v_add_u32_e32 v208, s16, v245
	v_lshl_add_u64 v[212:213], v[212:213], 0, s[6:7]
	s_mov_b32 m0, s17
	ds_read_b128 v[184:187], v208
	ds_read_b128 v[200:203], v208 offset:1024
	ds_read_b128 v[204:207], v208 offset:2048
	ds_read_b128 v[208:211], v208 offset:3072
	global_load_lds_dwordx4 v[212:213], off
	v_lshl_add_u64 v[212:213], v[214:215], 0, s[6:7]
	s_add_i32 m0, s17, 0x2000
	s_nop 0
	global_load_lds_dwordx4 v[212:213], off
	s_barrier
	s_waitcnt lgkmcnt(0)
	s_waitcnt lgkmcnt(0)
	v_mfma_f32_16x16x32_bf16 v[70:73], v[184:187], v[130:133], v[70:73]
	v_mfma_f32_16x16x32_bf16 v[66:69], v[204:207], v[130:133], v[66:69]
	v_mfma_f32_16x16x32_bf16 v[62:65], v[184:187], v[146:149], v[62:65]
	v_mfma_f32_16x16x32_bf16 v[58:61], v[204:207], v[146:149], v[58:61]
	v_mfma_f32_16x16x32_bf16 v[54:57], v[184:187], v[154:157], v[54:57]
	v_mfma_f32_16x16x32_bf16 v[50:53], v[204:207], v[154:157], v[50:53]
	v_mfma_f32_16x16x32_bf16 v[46:49], v[184:187], v[170:173], v[46:49]
	v_mfma_f32_16x16x32_bf16 v[42:45], v[204:207], v[170:173], v[42:45]
	v_mfma_f32_16x16x32_bf16 v[70:73], v[200:203], v[142:145], v[70:73]
	v_mfma_f32_16x16x32_bf16 v[66:69], v[208:211], v[142:145], v[66:69]
	v_mfma_f32_16x16x32_bf16 v[62:65], v[200:203], v[150:153], v[62:65]
	v_mfma_f32_16x16x32_bf16 v[58:61], v[208:211], v[150:153], v[58:61]
	v_mfma_f32_16x16x32_bf16 v[54:57], v[200:203], v[166:169], v[54:57]
	v_mfma_f32_16x16x32_bf16 v[50:53], v[208:211], v[166:169], v[50:53]
	v_mfma_f32_16x16x32_bf16 v[46:49], v[200:203], v[174:177], v[46:49]
	v_mfma_f32_16x16x32_bf16 v[42:45], v[208:211], v[174:177], v[42:45]
	s_mov_b32 m0, s26
	v_lshl_add_u64 v[212:213], s[14:15], 0, v[192:193]
	s_barrier
	ds_read_b128 v[130:133], v247 offset:49152
	ds_read_b128 v[142:145], v247 offset:50176
	ds_read_b128 v[146:149], v247 offset:51200
	ds_read_b128 v[150:153], v247 offset:52224
	ds_read_b128 v[154:157], v247 offset:53248
	ds_read_b128 v[166:169], v247 offset:54272
	ds_read_b128 v[170:173], v247 offset:55296
	ds_read_b128 v[174:177], v247 offset:56320
	global_load_lds_dwordx4 v[212:213], off
	v_lshl_add_u64 v[212:213], s[14:15], 0, v[190:191]
	s_mov_b32 m0, s27
	s_nop 0
	global_load_lds_dwordx4 v[212:213], off
	s_barrier
	s_waitcnt lgkmcnt(0)
	s_waitcnt lgkmcnt(0)
	v_mfma_f32_16x16x32_bf16 v[110:113], v[74:77], v[130:133], v[110:113]
	v_mfma_f32_16x16x32_bf16 v[94:97], v[74:77], v[146:149], v[94:97]
	v_mfma_f32_16x16x32_bf16 v[86:89], v[74:77], v[154:157], v[86:89]
	v_mfma_f32_16x16x32_bf16 v[26:29], v[74:77], v[170:173], v[26:29]
	v_mfma_f32_16x16x32_bf16 v[110:113], v[78:81], v[142:145], v[110:113]
	v_mfma_f32_16x16x32_bf16 v[106:109], v[98:101], v[130:133], v[106:109]
	v_mfma_f32_16x16x32_bf16 v[94:97], v[78:81], v[150:153], v[94:97]
	v_mfma_f32_16x16x32_bf16 v[90:93], v[98:101], v[146:149], v[90:93]
	v_mfma_f32_16x16x32_bf16 v[86:89], v[78:81], v[166:169], v[86:89]
	v_mfma_f32_16x16x32_bf16 v[82:85], v[98:101], v[154:157], v[82:85]
	v_mfma_f32_16x16x32_bf16 v[78:81], v[78:81], v[174:177], v[26:29]
	v_mfma_f32_16x16x32_bf16 v[26:29], v[98:101], v[170:173], v[30:33]
	v_mfma_f32_16x16x32_bf16 v[106:109], v[102:105], v[142:145], v[106:109]
	v_mfma_f32_16x16x32_bf16 v[90:93], v[102:105], v[150:153], v[90:93]
	v_mfma_f32_16x16x32_bf16 v[82:85], v[102:105], v[166:169], v[82:85]
	v_mfma_f32_16x16x32_bf16 v[74:77], v[102:105], v[174:177], v[26:29]
	s_barrier
	s_add_u32 s4, s4, 0x100080
	s_addc_u32 s5, s5, 0
	s_add_i32 s14, s16, s21
	v_lshl_add_u64 v[26:27], s[4:5], 0, v[0:1]
	s_mov_b32 m0, s14
	s_nop 0
	global_load_lds_dwordx4 v[26:27], off
	v_lshl_add_u64 v[26:27], s[4:5], 0, v[188:189]
	s_add_i32 m0, s14, 0x2000
	s_nop 0
	global_load_lds_dwordx4 v[26:27], off
	s_waitcnt vmcnt(6)
	s_barrier
	v_mfma_f32_16x16x32_bf16 v[26:29], v[184:187], v[130:133], v[38:41]
	v_mfma_f32_16x16x32_bf16 v[38:41], v[200:203], v[142:145], v[26:29]
	v_mfma_f32_16x16x32_bf16 v[26:29], v[204:207], v[130:133], v[34:37]
	v_mfma_f32_16x16x32_bf16 v[22:25], v[184:187], v[146:149], v[22:25]
	v_mfma_f32_16x16x32_bf16 v[18:21], v[204:207], v[146:149], v[18:21]
	v_mfma_f32_16x16x32_bf16 v[14:17], v[184:187], v[154:157], v[14:17]
	v_mfma_f32_16x16x32_bf16 v[10:13], v[204:207], v[154:157], v[10:13]
	v_mfma_f32_16x16x32_bf16 v[6:9], v[184:187], v[170:173], v[6:9]
	v_mfma_f32_16x16x32_bf16 v[2:5], v[204:207], v[170:173], v[2:5]
	v_mfma_f32_16x16x32_bf16 v[34:37], v[208:211], v[142:145], v[26:29]
	v_mfma_f32_16x16x32_bf16 v[22:25], v[200:203], v[150:153], v[22:25]
	v_mfma_f32_16x16x32_bf16 v[18:21], v[208:211], v[150:153], v[18:21]
	v_mfma_f32_16x16x32_bf16 v[14:17], v[200:203], v[166:169], v[14:17]
	v_mfma_f32_16x16x32_bf16 v[10:13], v[208:211], v[166:169], v[10:13]
	v_mfma_f32_16x16x32_bf16 v[6:9], v[200:203], v[174:177], v[6:9]
	v_mfma_f32_16x16x32_bf16 v[2:5], v[208:211], v[174:177], v[2:5]
	s_add_i32 s57, s57, 2
	s_add_u32 s51, s51, 0x100
	s_addc_u32 s56, s56, 0
	s_add_u32 s8, s8, 0x208800
	s_addc_u32 s9, s9, 0
	s_cmp_gt_u32 s57, 61
	s_barrier
; __device__ __forceinline__ unsigned cvt_pk_bf16(float lo, float hi) { unsigned r; asm volatile("v_cvt_pk_bf16_f32 %0, %1, %2" : "=v"(r) : "v"(lo), "v"(hi)); return r; }
; __device__ __forceinline__ float bf_lo(unsigned w) { return __uint_as_float(w << 16); }
; __device__ __forceinline__ float bf_hi(unsigned w) { return __uint_as_float(w & 0xffff0000u); }
; #define PG8_BAR __builtin_amdgcn_s_barrier()
; template <class Epi>
; __device__ __forceinline__ void gemm_phase(LAS unsigned char* lds, const Gemm g, const StaticOrder& S, const Epi& E) {
;     ...
;             PG8_WAIT_V(6); PG8_BAR; PG8_MMA(1, 1, At, B1); PG8_BAR;
;         }
;     __device__ __forceinline__ void operator()(const f32x4 (&acc)[2][2][4][2], const Unit& u, int wr, int wc, int fr, int fq, const Pre&) const {
;         const int row0 = u.pm * BM + wr * 64 + fr, col0 = u.pn * BM + wc * 32 + 8 * fq;
;         f32x4 bs[2][2];
; #pragma unroll
;         for (int bj = 0; bj < 2; ++bj) { bs[bj][0] = *(const f32x4*)(bias + col0 + bj * HALF); bs[bj][1] = *(const f32x4*)(bias + col0 + bj * HALF + 4); }
; #pragma unroll
;         for (int bj = 0; bj < 2; ++bj) { const int c = col0 + bj * HALF;
; #pragma unroll
;             for (int ai = 0; ai < 2; ++ai) { u32x4 zv[4], gv[4];
; #pragma unroll
;                 for (int m = 0; m < 4; ++m) { const int r = row0 + ai * HALF + m * 16; zv[m] = *(const u32x4*)(Z + (size_t)r * DE2 + c); gv[m] = *(const u32x4*)(Gm + (size_t)(c >> 4) * GSTR + r * 16 + (c & 15)); }
; #pragma unroll
;                 for (int m = 0; m < 4; ++m) { const int r = row0 + ai * HALF + m * 16;
;                     const u32x4 zw = zv[m], gw = gv[m];
;                     const f32x4 a0 = acc[ai][bj][m][0] + bs[bj][0], a1 = acc[ai][bj][m][1] + bs[bj][1];
;                     u32x4 w;
;                     w.x = cvt_pk_bf16(glu_gate_f(bf_lo(gw.x), a0[0], bf_lo(zw.x)), glu_gate_f(bf_hi(gw.x), a0[1], bf_hi(zw.x)));
;                     w.y = cvt_pk_bf16(glu_gate_f(bf_lo(gw.y), a0[2], bf_lo(zw.y)), glu_gate_f(bf_hi(gw.y), a0[3], bf_hi(zw.y)));
;                     w.z = cvt_pk_bf16(glu_gate_f(bf_lo(gw.z), a1[0], bf_lo(zw.z)), glu_gate_f(bf_hi(gw.z), a1[1], bf_hi(zw.z)));
;                     w.w = cvt_pk_bf16(glu_gate_f(bf_lo(gw.w), a1[2], bf_lo(zw.w)), glu_gate_f(bf_hi(gw.w), a1[3], bf_hi(zw.w)));
;                     *(u32x4*)(O + (size_t)r * DE + c) = w; } } }
	s_cbranch_scc0 .LBB0_796
	s_setprio 0
	v_lshl_or_b32 v200, s36, 8, v246
	v_ashrrev_i32_e32 v201, 31, v200
	v_lshl_add_u32 v224, s35, 8, v244
	v_lshlrev_b64 v[204:205], 1, v[200:201]
	v_ashrrev_i32_e32 v225, 31, v224
	v_ashrrev_i32_e32 v130, 4, v200
	v_lshl_add_u64 v[222:223], s[46:47], 0, v[204:205]
	v_lshlrev_b64 v[202:203], 14, v[224:225]
	v_lshl_add_u64 v[30:31], v[200:201], 2, s[10:11]
	v_mad_i64_i32 v[220:221], s[4:5], v130, s94, v[194:195]
	v_lshl_add_u64 v[130:131], v[222:223], 0, v[202:203]
	global_load_dwordx4 v[98:101], v[30:31], off offset:16
	global_load_dwordx4 v[102:105], v[30:31], off
	global_load_dwordx4 v[26:29], v[30:31], off offset:528
	s_nop 0
	global_load_dwordx4 v[30:33], v[30:31], off offset:512
	v_or_b32_e32 v226, 48, v224
	global_load_dwordx4 v[170:173], v[130:131], off
	v_lshlrev_b32_e32 v142, 4, v226
	v_ashrrev_i32_e32 v143, 31, v142
	v_lshlrev_b64 v[218:219], 1, v[142:143]
	v_lshl_add_u64 v[142:143], v[220:221], 0, v[218:219]
	global_load_dwordx4 v[142:145], v[142:143], off
	v_lshlrev_b32_e32 v130, 4, v224
	v_ashrrev_i32_e32 v131, 31, v130
	v_lshlrev_b64 v[206:207], 1, v[130:131]
	v_lshl_add_u64 v[130:131], v[220:221], 0, v[206:207]
	global_load_dwordx4 v[174:177], v[130:131], off
	v_or_b32_e32 v230, 16, v224
	v_ashrrev_i32_e32 v231, 31, v230
	v_lshlrev_b64 v[210:211], 14, v[230:231]
	v_lshl_add_u64 v[130:131], v[222:223], 0, v[210:211]
	global_load_dwordx4 v[154:157], v[130:131], off
	v_lshlrev_b32_e32 v130, 4, v230
	v_ashrrev_i32_e32 v131, 31, v130
	v_or_b32_e32 v228, 32, v224
	v_lshlrev_b64 v[208:209], 1, v[130:131]
	v_ashrrev_i32_e32 v229, 31, v228
	v_lshl_add_u64 v[130:131], v[220:221], 0, v[208:209]
	v_lshlrev_b64 v[214:215], 14, v[228:229]
	global_load_dwordx4 v[166:169], v[130:131], off
	v_lshl_add_u64 v[130:131], v[222:223], 0, v[214:215]
	global_load_dwordx4 v[146:149], v[130:131], off
	v_lshlrev_b32_e32 v130, 4, v228
	v_ashrrev_i32_e32 v131, 31, v130
	v_lshlrev_b64 v[212:213], 1, v[130:131]
	v_ashrrev_i32_e32 v227, 31, v226
	v_lshl_add_u64 v[130:131], v[220:221], 0, v[212:213]
	v_lshlrev_b64 v[216:217], 14, v[226:227]
	global_load_dwordx4 v[150:153], v[130:131], off
	v_lshl_add_u64 v[130:131], v[222:223], 0, v[216:217]
	global_load_dwordx4 v[130:133], v[130:131], off
	s_and_b64 vcc, exec, s[40:41]
	s_mov_b32 s35, s50
	s_mov_b32 s36, s48
	s_mov_b64 s[8:9], s[54:55]
	s_mov_b64 s[14:15], s[52:53]
	s_waitcnt vmcnt(0)
	v_pk_add_f32 v[134:135], v[134:135], v[98:99]
	v_pk_add_f32 v[184:185], v[162:163], v[102:103]
	v_pk_add_f32 v[162:163], v[160:161], v[100:101]
	v_pk_add_f32 v[160:161], v[158:159], v[98:99]
	v_mul_f32_e32 v158, 0xbfb8aa3b, v184
	v_lshlrev_b32_e32 v186, 16, v170
	v_mul_f32_e32 v159, 0xbfb8aa3b, v186
	v_exp_f32_e32 v158, v158
	v_exp_f32_e32 v159, v159
	v_and_b32_e32 v170, 0xffff0000, v170
	v_pk_add_f32 v[164:165], v[164:165], v[104:105]
	v_mul_f32_e32 v160, 0xbfb8aa3b, v160
	v_pk_add_f32 v[158:159], v[158:159], 1.0 op_sel_hi:[1,0]
	v_mul_f32_e32 v164, 0xbfb8aa3b, v164
	v_mul_f32_e32 v158, v158, v159
	v_rcp_f32_e32 v158, v158
	v_lshlrev_b32_e32 v187, 16, v174
	v_mul_f32_e32 v184, v187, v186
	v_mul_f32_e32 v159, 0xbfb8aa3b, v170
	v_mul_f32_e32 v184, v184, v158
	v_mul_f32_e32 v158, 0xbfb8aa3b, v185
	v_exp_f32_e32 v158, v158
	v_exp_f32_e32 v159, v159
	v_and_b32_e32 v174, 0xffff0000, v174
	v_mul_f32_e32 v170, v174, v170
	v_mul_f32_e32 v162, 0xbfb8aa3b, v162
	v_pk_add_f32 v[158:159], v[158:159], 1.0 op_sel_hi:[1,0]
	v_pk_add_f32 v[138:139], v[138:139], v[102:103]
	v_mul_f32_e32 v158, v158, v159
	v_rcp_f32_e32 v158, v158
	v_lshlrev_b32_e32 v159, 16, v171
	v_and_b32_e32 v171, 0xffff0000, v171
	v_mul_f32_e32 v138, 0xbfb8aa3b, v138
	v_mul_f32_e32 v158, v170, v158
	v_cvt_pk_bf16_f32 v158, v184, v158
	v_exp_f32_e32 v184, v164
	v_mul_f32_e32 v164, 0xbfb8aa3b, v159
	v_exp_f32_e32 v185, v164
	v_lshlrev_b32_e32 v170, 16, v175
	v_mul_f32_e32 v159, v170, v159
	v_and_b32_e32 v170, 0xffff0000, v175
	v_pk_add_f32 v[184:185], v[184:185], 1.0 op_sel_hi:[1,0]
	v_mul_f32_e32 v170, v170, v171
	v_mul_f32_e32 v164, v184, v185
	v_rcp_f32_e32 v164, v164
	v_pk_add_f32 v[140:141], v[140:141], v[104:105]
	v_mul_f32_e32 v134, 0xbfb8aa3b, v134
	v_mul_f32_e32 v140, 0xbfb8aa3b, v140
	v_mul_f32_e32 v159, v159, v164
	v_mul_f32_e32 v164, 0xbfb8aa3b, v165
	v_mul_f32_e32 v165, 0xbfb8aa3b, v171
	v_exp_f32_e32 v164, v164
	v_exp_f32_e32 v165, v165
	v_lshlrev_b32_e32 v171, 16, v176
	v_pk_add_f32 v[136:137], v[136:137], v[100:101]
	v_pk_add_f32 v[126:127], v[126:127], v[102:103]
	v_pk_add_f32 v[164:165], v[164:165], 1.0 op_sel_hi:[1,0]
	v_mul_f32_e32 v126, 0xbfb8aa3b, v126
	v_mul_f32_e32 v164, v164, v165
	v_rcp_f32_e32 v164, v164
	v_pk_add_f32 v[128:129], v[128:129], v[104:105]
	v_pk_add_f32 v[122:123], v[122:123], v[98:99]
	v_mul_f32_e32 v128, 0xbfb8aa3b, v128
	v_mul_f32_e32 v164, v170, v164
	v_lshlrev_b32_e32 v170, 16, v172
	v_cvt_pk_bf16_f32 v159, v159, v164
	v_exp_f32_e32 v164, v160
	v_mul_f32_e32 v160, 0xbfb8aa3b, v170
	v_exp_f32_e32 v165, v160
	v_mul_f32_e32 v160, v171, v170
	v_and_b32_e32 v170, 0xffff0000, v172
	v_mul_f32_e32 v122, 0xbfb8aa3b, v122
	v_pk_add_f32 v[164:165], v[164:165], 1.0 op_sel_hi:[1,0]
	v_pk_add_f32 v[124:125], v[124:125], v[100:101]
	v_mul_f32_e32 v164, v164, v165
	v_rcp_f32_e32 v164, v164
	v_and_b32_e32 v165, 0xffff0000, v176
	v_mul_f32_e32 v165, v165, v170
	v_pk_add_f32 v[118:119], v[118:119], v[102:103]
	v_mul_f32_e32 v164, v160, v164
	v_mul_f32_e32 v160, 0xbfb8aa3b, v161
	v_mul_f32_e32 v161, 0xbfb8aa3b, v170
	v_exp_f32_e32 v160, v160
	v_exp_f32_e32 v161, v161
	v_lshlrev_b32_e32 v170, 16, v177
	v_mul_f32_e32 v118, 0xbfb8aa3b, v118
	v_pk_add_f32 v[120:121], v[120:121], v[104:105]
; __device__ __forceinline__ unsigned cvt_pk_bf16(float lo, float hi) { unsigned r; asm volatile("v_cvt_pk_bf16_f32 %0, %1, %2" : "=v"(r) : "v"(lo), "v"(hi)); return r; }
; __device__ __forceinline__ float bf_lo(unsigned w) { return __uint_as_float(w << 16); }
; __device__ __forceinline__ float bf_hi(unsigned w) { return __uint_as_float(w & 0xffff0000u); }
;     __device__ __forceinline__ void operator()(const f32x4 (&acc)[2][2][4][2], const Unit& u, int wr, int wc, int fr, int fq, const Pre&) const {
;     ...
;             for (int ai = 0; ai < 2; ++ai) { u32x4 zv[4], gv[4];
; #pragma unroll
;                 for (int m = 0; m < 4; ++m) { const int r = row0 + ai * HALF + m * 16; zv[m] = *(const u32x4*)(Z + (size_t)r * DE2 + c); gv[m] = *(const u32x4*)(Gm + (size_t)(c >> 4) * GSTR + r * 16 + (c & 15)); }
; #pragma unroll
;                 for (int m = 0; m < 4; ++m) { const int r = row0 + ai * HALF + m * 16;
;                     const u32x4 zw = zv[m], gw = gv[m];
;                     const f32x4 a0 = acc[ai][bj][m][0] + bs[bj][0], a1 = acc[ai][bj][m][1] + bs[bj][1];
;                     u32x4 w;
;                     w.x = cvt_pk_bf16(glu_gate_f(bf_lo(gw.x), a0[0], bf_lo(zw.x)), glu_gate_f(bf_hi(gw.x), a0[1], bf_hi(zw.x)));
;                     w.y = cvt_pk_bf16(glu_gate_f(bf_lo(gw.y), a0[2], bf_lo(zw.y)), glu_gate_f(bf_hi(gw.y), a0[3], bf_hi(zw.y)));
;                     w.z = cvt_pk_bf16(glu_gate_f(bf_lo(gw.z), a1[0], bf_lo(zw.z)), glu_gate_f(bf_hi(gw.z), a1[1], bf_hi(zw.z)));
;                     w.w = cvt_pk_bf16(glu_gate_f(bf_lo(gw.w), a1[2], bf_lo(zw.w)), glu_gate_f(bf_hi(gw.w), a1[3], bf_hi(zw.w)));
;                     *(u32x4*)(O + (size_t)r * DE + c) = w; } } }
	v_pk_add_f32 v[160:161], v[160:161], 1.0 op_sel_hi:[1,0]
	v_mul_f32_e32 v120, 0xbfb8aa3b, v120
	v_mul_f32_e32 v160, v160, v161
	v_rcp_f32_e32 v160, v160
	v_lshlrev_b32_e32 v161, 16, v173
	v_pk_add_f32 v[114:115], v[114:115], v[98:99]
	v_pk_add_f32 v[116:117], v[116:117], v[100:101]
	v_mul_f32_e32 v160, v165, v160
	v_cvt_pk_bf16_f32 v160, v164, v160
	v_exp_f32_e32 v164, v162
	v_mul_f32_e32 v162, 0xbfb8aa3b, v161
	v_exp_f32_e32 v165, v162
	v_mul_f32_e32 v161, v170, v161
	v_mul_f32_e32 v114, 0xbfb8aa3b, v114
	v_add_u32_e32 v176, 0x80, v224
	v_pk_add_f32 v[164:165], v[164:165], 1.0 op_sel_hi:[1,0]
	v_add_u32_e32 v170, 0xb0, v224
	v_mul_f32_e32 v162, v164, v165
	v_rcp_f32_e32 v162, v162
	v_and_b32_e32 v165, 0xffff0000, v173
	v_and_b32_e32 v164, 0xffff0000, v177
	v_mul_f32_e32 v164, v164, v165
	v_mul_f32_e32 v161, v161, v162
	v_mul_f32_e32 v162, 0xbfb8aa3b, v163
	v_mul_f32_e32 v163, 0xbfb8aa3b, v165
	v_exp_f32_e32 v162, v162
	v_exp_f32_e32 v163, v163
	v_ashrrev_i32_e32 v177, 31, v176
	v_pk_add_f32 v[110:111], v[110:111], v[102:103]
	v_add_u32_e32 v174, 0x90, v224
	v_pk_add_f32 v[162:163], v[162:163], 1.0 op_sel_hi:[1,0]
	v_mul_f32_e32 v110, 0xbfb8aa3b, v110
	v_mul_f32_e32 v162, v162, v163
	v_rcp_f32_e32 v162, v162
	v_exp_f32_e32 v184, v110
	v_ashrrev_i32_e32 v175, 31, v174
	v_add_u32_e32 v172, 0xa0, v224
	v_mul_f32_e32 v162, v164, v162
	v_cvt_pk_bf16_f32 v161, v161, v162
	v_lshlrev_b64 v[162:163], 13, v[224:225]
	v_lshl_add_u64 v[162:163], s[44:45], 0, v[162:163]
	v_lshl_add_u64 v[162:163], v[162:163], 0, v[204:205]
	global_store_dwordx4 v[162:163], v[158:161], off
	v_ashrrev_i32_e32 v173, 31, v172
	v_ashrrev_i32_e32 v171, 31, v170
	v_lshlrev_b32_e32 v160, 16, v154
	v_exp_f32_e32 v158, v138
	v_mul_f32_e32 v138, 0xbfb8aa3b, v160
	v_exp_f32_e32 v159, v138
	v_lshlrev_b32_e32 v161, 16, v166
	v_mul_f32_e32 v138, v161, v160
	v_and_b32_e32 v154, 0xffff0000, v154
	v_pk_add_f32 v[158:159], v[158:159], 1.0 op_sel_hi:[1,0]
	v_lshlrev_b64 v[160:161], 14, v[172:173]
	v_mul_f32_e32 v158, v158, v159
	v_rcp_f32_e32 v158, v158
	v_and_b32_e32 v159, 0xffff0000, v166
	v_pk_add_f32 v[112:113], v[112:113], v[104:105]
	v_pk_add_f32 v[106:107], v[106:107], v[98:99]
	v_mul_f32_e32 v158, v138, v158
	v_mul_f32_e32 v138, 0xbfb8aa3b, v139
	v_mul_f32_e32 v139, 0xbfb8aa3b, v154
	v_exp_f32_e32 v138, v138
	v_exp_f32_e32 v139, v139
	v_mul_f32_e32 v154, v159, v154
	v_mul_f32_e32 v112, 0xbfb8aa3b, v112
	v_mul_f32_e32 v106, 0xbfb8aa3b, v106
	v_pk_add_f32 v[138:139], v[138:139], 1.0 op_sel_hi:[1,0]
	v_pk_add_f32 v[108:109], v[108:109], v[100:101]
	v_mul_f32_e32 v138, v138, v139
	v_rcp_f32_e32 v138, v138
	v_lshlrev_b32_e32 v139, 16, v155
	v_and_b32_e32 v155, 0xffff0000, v155
	v_pk_add_f32 v[94:95], v[94:95], v[102:103]
	v_mul_f32_e32 v138, v154, v138
	v_cvt_pk_bf16_f32 v138, v158, v138
	v_exp_f32_e32 v158, v140
	v_mul_f32_e32 v140, 0xbfb8aa3b, v139
	v_exp_f32_e32 v159, v140
	v_lshlrev_b32_e32 v154, 16, v167
	v_mul_f32_e32 v139, v154, v139
	v_and_b32_e32 v154, 0xffff0000, v167
	v_pk_add_f32 v[158:159], v[158:159], 1.0 op_sel_hi:[1,0]
	v_mul_f32_e32 v154, v154, v155
	v_mul_f32_e32 v140, v158, v159
	v_rcp_f32_e32 v140, v140
	v_lshlrev_b64 v[166:167], 14, v[170:171]
	v_mul_f32_e32 v94, 0xbfb8aa3b, v94
	v_pk_add_f32 v[96:97], v[96:97], v[104:105]
	v_mul_f32_e32 v139, v139, v140
	v_mul_f32_e32 v140, 0xbfb8aa3b, v141
	v_mul_f32_e32 v141, 0xbfb8aa3b, v155
	v_exp_f32_e32 v140, v140
	v_exp_f32_e32 v141, v141
	v_lshlrev_b32_e32 v155, 16, v168
	v_mul_f32_e32 v96, 0xbfb8aa3b, v96
	v_pk_add_f32 v[90:91], v[90:91], v[98:99]
	v_pk_add_f32 v[140:141], v[140:141], 1.0 op_sel_hi:[1,0]
	v_mul_f32_e32 v90, 0xbfb8aa3b, v90
	v_mul_f32_e32 v140, v140, v141
	v_rcp_f32_e32 v140, v140
	v_pk_add_f32 v[92:93], v[92:93], v[100:101]
	v_pk_add_f32 v[86:87], v[86:87], v[102:103]
	v_pk_add_f32 v[88:89], v[88:89], v[104:105]
	v_mul_f32_e32 v140, v154, v140
	v_lshlrev_b32_e32 v154, 16, v156
	v_cvt_pk_bf16_f32 v139, v139, v140
	v_exp_f32_e32 v140, v134
	v_mul_f32_e32 v134, 0xbfb8aa3b, v154
	v_exp_f32_e32 v141, v134
	v_mul_f32_e32 v134, v155, v154
	v_and_b32_e32 v154, 0xffff0000, v156
	v_mul_f32_e32 v86, 0xbfb8aa3b, v86
	v_pk_add_f32 v[140:141], v[140:141], 1.0 op_sel_hi:[1,0]
	v_mul_f32_e32 v88, 0xbfb8aa3b, v88
	v_mul_f32_e32 v140, v140, v141
	v_rcp_f32_e32 v140, v140
	v_and_b32_e32 v141, 0xffff0000, v168
	v_mul_f32_e32 v141, v141, v154
	v_pk_add_f32 v[82:83], v[82:83], v[98:99]
	v_mul_f32_e32 v140, v134, v140
	v_mul_f32_e32 v134, 0xbfb8aa3b, v135
	v_mul_f32_e32 v135, 0xbfb8aa3b, v154
	v_exp_f32_e32 v134, v134
	v_exp_f32_e32 v135, v135
	v_lshlrev_b32_e32 v154, 16, v169
	v_mul_f32_e32 v82, 0xbfb8aa3b, v82
	v_pk_add_f32 v[84:85], v[84:85], v[100:101]
	v_pk_add_f32 v[134:135], v[134:135], 1.0 op_sel_hi:[1,0]
	v_pk_add_f32 v[78:79], v[78:79], v[102:103]
	v_mul_f32_e32 v134, v134, v135
	v_rcp_f32_e32 v134, v134
	v_mul_f32_e32 v78, 0xbfb8aa3b, v78
	v_pk_add_f32 v[80:81], v[80:81], v[104:105]
	v_pk_add_f32 v[74:75], v[74:75], v[98:99]
	v_mul_f32_e32 v134, v141, v134
	v_lshlrev_b32_e32 v141, 16, v157
	v_cvt_pk_bf16_f32 v140, v140, v134
	v_mul_f32_e32 v134, 0xbfb8aa3b, v136
	v_mul_f32_e32 v135, 0xbfb8aa3b, v141
	v_exp_f32_e32 v134, v134
	v_exp_f32_e32 v135, v135
	v_mul_f32_e32 v136, v154, v141
	v_and_b32_e32 v154, 0xffff0000, v157
	v_and_b32_e32 v141, 0xffff0000, v169
	v_pk_add_f32 v[134:135], v[134:135], 1.0 op_sel_hi:[1,0]
	v_lshlrev_b64 v[156:157], 14, v[174:175]
	v_mul_f32_e32 v134, v134, v135
	v_rcp_f32_e32 v134, v134
	v_mul_f32_e32 v135, 0xbfb8aa3b, v154
	v_exp_f32_e32 v135, v135
	v_mul_f32_e32 v80, 0xbfb8aa3b, v80
	v_mul_f32_e32 v136, v136, v134
	v_mul_f32_e32 v134, 0xbfb8aa3b, v137
	v_exp_f32_e32 v134, v134
; __device__ __forceinline__ unsigned cvt_pk_bf16(float lo, float hi) { unsigned r; asm volatile("v_cvt_pk_bf16_f32 %0, %1, %2" : "=v"(r) : "v"(lo), "v"(hi)); return r; }
; __device__ __forceinline__ float bf_lo(unsigned w) { return __uint_as_float(w << 16); }
; __device__ __forceinline__ float bf_hi(unsigned w) { return __uint_as_float(w & 0xffff0000u); }
;     __device__ __forceinline__ void operator()(const f32x4 (&acc)[2][2][4][2], const Unit& u, int wr, int wc, int fr, int fq, const Pre&) const {
;     ...
;             for (int ai = 0; ai < 2; ++ai) { u32x4 zv[4], gv[4];
; #pragma unroll
;                 for (int m = 0; m < 4; ++m) { const int r = row0 + ai * HALF + m * 16; zv[m] = *(const u32x4*)(Z + (size_t)r * DE2 + c); gv[m] = *(const u32x4*)(Gm + (size_t)(c >> 4) * GSTR + r * 16 + (c & 15)); }
; #pragma unroll
;                 for (int m = 0; m < 4; ++m) { const int r = row0 + ai * HALF + m * 16;
;                     const u32x4 zw = zv[m], gw = gv[m];
;                     const f32x4 a0 = acc[ai][bj][m][0] + bs[bj][0], a1 = acc[ai][bj][m][1] + bs[bj][1];
;                     u32x4 w;
;                     w.x = cvt_pk_bf16(glu_gate_f(bf_lo(gw.x), a0[0], bf_lo(zw.x)), glu_gate_f(bf_hi(gw.x), a0[1], bf_hi(zw.x)));
;                     w.y = cvt_pk_bf16(glu_gate_f(bf_lo(gw.y), a0[2], bf_lo(zw.y)), glu_gate_f(bf_hi(gw.y), a0[3], bf_hi(zw.y)));
;                     w.z = cvt_pk_bf16(glu_gate_f(bf_lo(gw.z), a1[0], bf_lo(zw.z)), glu_gate_f(bf_hi(gw.z), a1[1], bf_hi(zw.z)));
;                     w.w = cvt_pk_bf16(glu_gate_f(bf_lo(gw.w), a1[2], bf_lo(zw.w)), glu_gate_f(bf_hi(gw.w), a1[3], bf_hi(zw.w)));
;                     *(u32x4*)(O + (size_t)r * DE + c) = w; } } }
	v_mul_f32_e32 v137, v141, v154
	v_mul_f32_e32 v74, 0xbfb8aa3b, v74
	v_pk_add_f32 v[76:77], v[76:77], v[100:101]
	v_pk_add_f32 v[134:135], v[134:135], 1.0 op_sel_hi:[1,0]
	v_pk_add_f32 v[70:71], v[70:71], v[30:31]
	v_mul_f32_e32 v134, v134, v135
	v_rcp_f32_e32 v134, v134
	v_mul_f32_e32 v70, 0xbfb8aa3b, v70
	v_pk_add_f32 v[72:73], v[72:73], v[32:33]
	v_pk_add_f32 v[66:67], v[66:67], v[26:27]
	v_mul_f32_e32 v134, v137, v134
	v_cvt_pk_bf16_f32 v141, v136, v134
	v_lshlrev_b64 v[134:135], 13, v[230:231]
	v_lshl_add_u64 v[134:135], s[44:45], 0, v[134:135]
	v_lshlrev_b32_e32 v136, 16, v146
	v_lshl_add_u64 v[154:155], v[134:135], 0, v[204:205]
	v_exp_f32_e32 v134, v126
	v_mul_f32_e32 v126, 0xbfb8aa3b, v136
	v_exp_f32_e32 v135, v126
	v_lshlrev_b32_e32 v137, 16, v150
	v_mul_f32_e32 v126, v137, v136
	v_and_b32_e32 v136, 0xffff0000, v146
	v_pk_add_f32 v[134:135], v[134:135], 1.0 op_sel_hi:[1,0]
	global_store_dwordx4 v[154:155], v[138:141], off
	v_mul_f32_e32 v134, v134, v135
	v_rcp_f32_e32 v134, v134
	v_and_b32_e32 v135, 0xffff0000, v150
	v_mul_f32_e32 v135, v135, v136
	v_mul_f32_e32 v72, 0xbfb8aa3b, v72
	v_mul_f32_e32 v134, v126, v134
	v_mul_f32_e32 v126, 0xbfb8aa3b, v127
	v_mul_f32_e32 v127, 0xbfb8aa3b, v136
	v_exp_f32_e32 v126, v126
	v_exp_f32_e32 v127, v127
	v_lshlrev_b32_e32 v136, 16, v151
	v_mul_f32_e32 v66, 0xbfb8aa3b, v66
	v_pk_add_f32 v[68:69], v[68:69], v[28:29]
	v_pk_add_f32 v[126:127], v[126:127], 1.0 op_sel_hi:[1,0]
	v_pk_add_f32 v[62:63], v[62:63], v[30:31]
	v_mul_f32_e32 v126, v126, v127
	v_rcp_f32_e32 v126, v126
	v_lshlrev_b32_e32 v127, 16, v147
	v_mul_f32_e32 v62, 0xbfb8aa3b, v62
	v_pk_add_f32 v[64:65], v[64:65], v[32:33]
	v_mul_f32_e32 v126, v135, v126
	v_cvt_pk_bf16_f32 v126, v134, v126
	v_exp_f32_e32 v134, v128
	v_mul_f32_e32 v128, 0xbfb8aa3b, v127
	v_exp_f32_e32 v135, v128
	v_mul_f32_e32 v127, v136, v127
	v_mul_f32_e32 v64, 0xbfb8aa3b, v64
	v_pk_add_f32 v[58:59], v[58:59], v[26:27]
	v_pk_add_f32 v[134:135], v[134:135], 1.0 op_sel_hi:[1,0]
	v_mul_f32_e32 v58, 0xbfb8aa3b, v58
	v_mul_f32_e32 v128, v134, v135
	v_rcp_f32_e32 v128, v128
	v_and_b32_e32 v135, 0xffff0000, v147
	v_and_b32_e32 v134, 0xffff0000, v151
	v_mul_f32_e32 v134, v134, v135
	v_mul_f32_e32 v127, v127, v128
	v_mul_f32_e32 v128, 0xbfb8aa3b, v129
	v_mul_f32_e32 v129, 0xbfb8aa3b, v135
	v_exp_f32_e32 v128, v128
	v_exp_f32_e32 v129, v129
	v_lshlrev_b32_e32 v135, 16, v152
	v_lshlrev_b64 v[150:151], 14, v[176:177]
	v_pk_add_f32 v[60:61], v[60:61], v[28:29]
	v_pk_add_f32 v[128:129], v[128:129], 1.0 op_sel_hi:[1,0]
	v_pk_add_f32 v[54:55], v[54:55], v[30:31]
	v_mul_f32_e32 v128, v128, v129
	v_rcp_f32_e32 v128, v128
	v_mul_f32_e32 v54, 0xbfb8aa3b, v54
	v_pk_add_f32 v[56:57], v[56:57], v[32:33]
	v_pk_add_f32 v[50:51], v[50:51], v[26:27]
	v_mul_f32_e32 v128, v134, v128
	v_lshlrev_b32_e32 v134, 16, v148
	v_cvt_pk_bf16_f32 v127, v127, v128
	v_exp_f32_e32 v128, v122
	v_mul_f32_e32 v122, 0xbfb8aa3b, v134
	v_exp_f32_e32 v129, v122
	v_mul_f32_e32 v122, v135, v134
	v_and_b32_e32 v134, 0xffff0000, v148
	v_mul_f32_e32 v56, 0xbfb8aa3b, v56
	v_pk_add_f32 v[128:129], v[128:129], 1.0 op_sel_hi:[1,0]
	v_mul_f32_e32 v50, 0xbfb8aa3b, v50
	v_mul_f32_e32 v128, v128, v129
	v_rcp_f32_e32 v128, v128
	v_and_b32_e32 v129, 0xffff0000, v152
	v_mul_f32_e32 v129, v129, v134
	v_pk_add_f32 v[52:53], v[52:53], v[28:29]
	v_mul_f32_e32 v128, v122, v128
	v_mul_f32_e32 v122, 0xbfb8aa3b, v123
	v_mul_f32_e32 v123, 0xbfb8aa3b, v134
	v_exp_f32_e32 v122, v122
	v_exp_f32_e32 v123, v123
	v_lshlrev_b32_e32 v134, 16, v153
	v_pk_add_f32 v[46:47], v[46:47], v[30:31]
	v_pk_add_f32 v[48:49], v[48:49], v[32:33]
	v_pk_add_f32 v[122:123], v[122:123], 1.0 op_sel_hi:[1,0]
	v_mul_f32_e32 v46, 0xbfb8aa3b, v46
	v_mul_f32_e32 v122, v122, v123
	v_rcp_f32_e32 v122, v122
	v_mul_f32_e32 v48, 0xbfb8aa3b, v48
	v_pk_add_f32 v[42:43], v[42:43], v[26:27]
	v_pk_add_f32 v[44:45], v[44:45], v[28:29]
	v_mul_f32_e32 v122, v129, v122
	v_lshlrev_b32_e32 v129, 16, v149
	v_cvt_pk_bf16_f32 v128, v128, v122
	v_mul_f32_e32 v122, 0xbfb8aa3b, v124
	v_mul_f32_e32 v123, 0xbfb8aa3b, v129
	v_exp_f32_e32 v122, v122
	v_exp_f32_e32 v123, v123
	v_mul_f32_e32 v124, v134, v129
	v_and_b32_e32 v134, 0xffff0000, v149
	v_and_b32_e32 v129, 0xffff0000, v153
	v_pk_add_f32 v[122:123], v[122:123], 1.0 op_sel_hi:[1,0]
	v_mul_f32_e32 v42, 0xbfb8aa3b, v42
	v_mul_f32_e32 v122, v122, v123
	v_rcp_f32_e32 v122, v122
	v_mul_f32_e32 v123, 0xbfb8aa3b, v134
	v_exp_f32_e32 v123, v123
	v_pk_add_f32 v[38:39], v[38:39], v[30:31]
	v_mul_f32_e32 v124, v124, v122
	v_mul_f32_e32 v122, 0xbfb8aa3b, v125
	v_exp_f32_e32 v122, v122
	v_mul_f32_e32 v125, v129, v134
	v_mul_f32_e32 v38, 0xbfb8aa3b, v38
	v_pk_add_f32 v[40:41], v[40:41], v[32:33]
	v_pk_add_f32 v[122:123], v[122:123], 1.0 op_sel_hi:[1,0]
	v_mul_f32_e32 v40, 0xbfb8aa3b, v40
	v_mul_f32_e32 v122, v122, v123
	v_rcp_f32_e32 v122, v122
	v_pk_add_f32 v[34:35], v[34:35], v[26:27]
	v_pk_add_f32 v[36:37], v[36:37], v[28:29]
	v_mul_f32_e32 v34, 0xbfb8aa3b, v34
	v_mul_f32_e32 v122, v125, v122
	v_cvt_pk_bf16_f32 v129, v124, v122
	v_lshlrev_b64 v[122:123], 13, v[228:229]
	v_lshl_add_u64 v[122:123], s[44:45], 0, v[122:123]
	v_lshlrev_b32_e32 v124, 16, v130
	v_lshl_add_u64 v[146:147], v[122:123], 0, v[204:205]
	v_exp_f32_e32 v122, v118
	v_mul_f32_e32 v118, 0xbfb8aa3b, v124
	v_exp_f32_e32 v123, v118
	v_lshlrev_b32_e32 v125, 16, v142
	v_mul_f32_e32 v118, v125, v124
	v_and_b32_e32 v124, 0xffff0000, v130
	v_pk_add_f32 v[122:123], v[122:123], 1.0 op_sel_hi:[1,0]
	global_store_dwordx4 v[146:147], v[126:129], off
	v_mul_f32_e32 v122, v122, v123
	v_rcp_f32_e32 v122, v122
	v_and_b32_e32 v123, 0xffff0000, v142
	v_mul_f32_e32 v123, v123, v124
; __device__ __forceinline__ unsigned cvt_pk_bf16(float lo, float hi) { unsigned r; asm volatile("v_cvt_pk_bf16_f32 %0, %1, %2" : "=v"(r) : "v"(lo), "v"(hi)); return r; }
; __device__ __forceinline__ float bf_lo(unsigned w) { return __uint_as_float(w << 16); }
; __device__ __forceinline__ float bf_hi(unsigned w) { return __uint_as_float(w & 0xffff0000u); }
;     __device__ __forceinline__ void operator()(const f32x4 (&acc)[2][2][4][2], const Unit& u, int wr, int wc, int fr, int fq, const Pre&) const {
;     ...
;             for (int ai = 0; ai < 2; ++ai) { u32x4 zv[4], gv[4];
; #pragma unroll
;                 for (int m = 0; m < 4; ++m) { const int r = row0 + ai * HALF + m * 16; zv[m] = *(const u32x4*)(Z + (size_t)r * DE2 + c); gv[m] = *(const u32x4*)(Gm + (size_t)(c >> 4) * GSTR + r * 16 + (c & 15)); }
; #pragma unroll
;                 for (int m = 0; m < 4; ++m) { const int r = row0 + ai * HALF + m * 16;
;                     const u32x4 zw = zv[m], gw = gv[m];
;                     const f32x4 a0 = acc[ai][bj][m][0] + bs[bj][0], a1 = acc[ai][bj][m][1] + bs[bj][1];
;                     u32x4 w;
;                     w.x = cvt_pk_bf16(glu_gate_f(bf_lo(gw.x), a0[0], bf_lo(zw.x)), glu_gate_f(bf_hi(gw.x), a0[1], bf_hi(zw.x)));
;                     w.y = cvt_pk_bf16(glu_gate_f(bf_lo(gw.y), a0[2], bf_lo(zw.y)), glu_gate_f(bf_hi(gw.y), a0[3], bf_hi(zw.y)));
;                     w.z = cvt_pk_bf16(glu_gate_f(bf_lo(gw.z), a1[0], bf_lo(zw.z)), glu_gate_f(bf_hi(gw.z), a1[1], bf_hi(zw.z)));
;                     w.w = cvt_pk_bf16(glu_gate_f(bf_lo(gw.w), a1[2], bf_lo(zw.w)), glu_gate_f(bf_hi(gw.w), a1[3], bf_hi(zw.w)));
;                     *(u32x4*)(O + (size_t)r * DE + c) = w; } } }
	v_pk_add_f32 v[22:23], v[22:23], v[30:31]
	v_mul_f32_e32 v122, v118, v122
	v_mul_f32_e32 v118, 0xbfb8aa3b, v119
	v_mul_f32_e32 v119, 0xbfb8aa3b, v124
	v_exp_f32_e32 v118, v118
	v_exp_f32_e32 v119, v119
	v_lshlrev_b32_e32 v124, 16, v143
	v_mul_f32_e32 v22, 0xbfb8aa3b, v22
	v_pk_add_f32 v[24:25], v[24:25], v[32:33]
	v_pk_add_f32 v[118:119], v[118:119], 1.0 op_sel_hi:[1,0]
	v_mul_f32_e32 v24, 0xbfb8aa3b, v24
	v_mul_f32_e32 v118, v118, v119
	v_rcp_f32_e32 v118, v118
	v_lshlrev_b32_e32 v119, 16, v131
	v_pk_add_f32 v[18:19], v[18:19], v[26:27]
	v_pk_add_f32 v[20:21], v[20:21], v[28:29]
	v_mul_f32_e32 v118, v123, v118
	v_cvt_pk_bf16_f32 v118, v122, v118
	v_exp_f32_e32 v122, v120
	v_mul_f32_e32 v120, 0xbfb8aa3b, v119
	v_exp_f32_e32 v123, v120
	v_mul_f32_e32 v119, v124, v119
	v_mul_f32_e32 v18, 0xbfb8aa3b, v18
	v_pk_add_f32 v[14:15], v[14:15], v[30:31]
	v_pk_add_f32 v[122:123], v[122:123], 1.0 op_sel_hi:[1,0]
	v_mul_f32_e32 v14, 0xbfb8aa3b, v14
	v_mul_f32_e32 v120, v122, v123
	v_rcp_f32_e32 v120, v120
	v_and_b32_e32 v123, 0xffff0000, v131
	v_and_b32_e32 v122, 0xffff0000, v143
	v_mul_f32_e32 v122, v122, v123
	v_mul_f32_e32 v119, v119, v120
	v_mul_f32_e32 v120, 0xbfb8aa3b, v121
	v_mul_f32_e32 v121, 0xbfb8aa3b, v123
	v_exp_f32_e32 v120, v120
	v_exp_f32_e32 v121, v121
	v_lshlrev_b32_e32 v123, 16, v144
	v_pk_add_f32 v[16:17], v[16:17], v[32:33]
	v_pk_add_f32 v[10:11], v[10:11], v[26:27]
	v_pk_add_f32 v[120:121], v[120:121], 1.0 op_sel_hi:[1,0]
	v_mul_f32_e32 v16, 0xbfb8aa3b, v16
	v_mul_f32_e32 v120, v120, v121
	v_rcp_f32_e32 v120, v120
	v_mul_f32_e32 v10, 0xbfb8aa3b, v10
	v_pk_add_f32 v[12:13], v[12:13], v[28:29]
	v_pk_add_f32 v[6:7], v[6:7], v[30:31]
	v_mul_f32_e32 v120, v122, v120
	v_lshlrev_b32_e32 v122, 16, v132
	v_cvt_pk_bf16_f32 v119, v119, v120
	v_exp_f32_e32 v120, v114
	v_mul_f32_e32 v114, 0xbfb8aa3b, v122
	v_exp_f32_e32 v121, v114
	v_mul_f32_e32 v114, v123, v122
	v_and_b32_e32 v122, 0xffff0000, v132
	v_mul_f32_e32 v6, 0xbfb8aa3b, v6
	v_pk_add_f32 v[120:121], v[120:121], 1.0 op_sel_hi:[1,0]
	v_pk_add_f32 v[8:9], v[8:9], v[32:33]
	v_mul_f32_e32 v120, v120, v121
	v_rcp_f32_e32 v120, v120
	v_and_b32_e32 v121, 0xffff0000, v144
	v_mul_f32_e32 v121, v121, v122
	v_mul_f32_e32 v8, 0xbfb8aa3b, v8
	v_mul_f32_e32 v120, v114, v120
	v_mul_f32_e32 v114, 0xbfb8aa3b, v115
	v_mul_f32_e32 v115, 0xbfb8aa3b, v122
	v_exp_f32_e32 v114, v114
	v_exp_f32_e32 v115, v115
	v_lshlrev_b32_e32 v122, 16, v145
	v_pk_add_f32 v[2:3], v[2:3], v[26:27]
	v_pk_add_f32 v[4:5], v[4:5], v[28:29]
	v_pk_add_f32 v[114:115], v[114:115], 1.0 op_sel_hi:[1,0]
	v_mul_f32_e32 v2, 0xbfb8aa3b, v2
	v_mul_f32_e32 v114, v114, v115
	v_rcp_f32_e32 v114, v114
	s_nop 0
	v_mul_f32_e32 v114, v121, v114
	v_lshlrev_b32_e32 v121, 16, v133
	v_cvt_pk_bf16_f32 v120, v120, v114
	v_mul_f32_e32 v114, 0xbfb8aa3b, v116
	v_mul_f32_e32 v115, 0xbfb8aa3b, v121
	v_exp_f32_e32 v114, v114
	v_exp_f32_e32 v115, v115
	v_mul_f32_e32 v116, v122, v121
	v_and_b32_e32 v122, 0xffff0000, v133
	v_and_b32_e32 v121, 0xffff0000, v145
	v_pk_add_f32 v[114:115], v[114:115], 1.0 op_sel_hi:[1,0]
	s_nop 0
	v_mul_f32_e32 v114, v114, v115
	v_rcp_f32_e32 v114, v114
	v_mul_f32_e32 v115, 0xbfb8aa3b, v122
	v_exp_f32_e32 v115, v115
	v_mul_f32_e32 v116, v116, v114
	v_mul_f32_e32 v114, 0xbfb8aa3b, v117
	v_exp_f32_e32 v114, v114
	v_mul_f32_e32 v117, v121, v122
	v_pk_add_f32 v[114:115], v[114:115], 1.0 op_sel_hi:[1,0]
	s_nop 0
	v_mul_f32_e32 v114, v114, v115
	v_rcp_f32_e32 v114, v114
	s_nop 0
	v_mul_f32_e32 v114, v117, v114
	v_cvt_pk_bf16_f32 v121, v116, v114
	v_lshlrev_b64 v[114:115], 13, v[226:227]
	v_lshl_add_u64 v[114:115], s[44:45], 0, v[114:115]
	v_lshl_add_u64 v[148:149], v[114:115], 0, v[204:205]
	global_store_dwordx4 v[148:149], v[118:121], off
	v_lshl_add_u64 v[114:115], v[222:223], 0, v[150:151]
	global_load_dwordx4 v[138:141], v[114:115], off
	v_lshlrev_b32_e32 v118, 4, v170
	v_ashrrev_i32_e32 v119, 31, v118
	v_lshlrev_b64 v[168:169], 1, v[118:119]
	v_lshl_add_u64 v[118:119], v[220:221], 0, v[168:169]
	global_load_dwordx4 v[118:121], v[118:119], off
	v_lshlrev_b32_e32 v114, 4, v176
	v_ashrrev_i32_e32 v115, 31, v114
	v_lshlrev_b64 v[152:153], 1, v[114:115]
	v_lshl_add_u64 v[114:115], v[220:221], 0, v[152:153]
	global_load_dwordx4 v[142:145], v[114:115], off
	v_lshl_add_u64 v[114:115], v[222:223], 0, v[156:157]
	global_load_dwordx4 v[130:133], v[114:115], off
	v_lshlrev_b32_e32 v114, 4, v174
	v_ashrrev_i32_e32 v115, 31, v114
	v_lshlrev_b64 v[158:159], 1, v[114:115]
	v_lshl_add_u64 v[114:115], v[220:221], 0, v[158:159]
	global_load_dwordx4 v[134:137], v[114:115], off
	v_lshl_add_u64 v[114:115], v[222:223], 0, v[160:161]
	global_load_dwordx4 v[122:125], v[114:115], off
	v_lshlrev_b32_e32 v114, 4, v172
	v_ashrrev_i32_e32 v115, 31, v114
	v_lshlrev_b64 v[164:165], 1, v[114:115]
	v_lshl_add_u64 v[114:115], v[220:221], 0, v[164:165]
	global_load_dwordx4 v[126:129], v[114:115], off
	v_lshl_add_u64 v[114:115], v[222:223], 0, v[166:167]
	global_load_dwordx4 v[114:117], v[114:115], off
	s_waitcnt vmcnt(0)
; __device__ __forceinline__ unsigned cvt_pk_bf16(float lo, float hi) { unsigned r; asm volatile("v_cvt_pk_bf16_f32 %0, %1, %2" : "=v"(r) : "v"(lo), "v"(hi)); return r; }
; __device__ __forceinline__ float bf_lo(unsigned w) { return __uint_as_float(w << 16); }
; __device__ __forceinline__ float bf_hi(unsigned w) { return __uint_as_float(w & 0xffff0000u); }
;     __device__ __forceinline__ void operator()(const f32x4 (&acc)[2][2][4][2], const Unit& u, int wr, int wc, int fr, int fq, const Pre&) const {
;     ...
;                 for (int m = 0; m < 4; ++m) { const int r = row0 + ai * HALF + m * 16;
;                     const u32x4 zw = zv[m], gw = gv[m];
;                     const f32x4 a0 = acc[ai][bj][m][0] + bs[bj][0], a1 = acc[ai][bj][m][1] + bs[bj][1];
;                     u32x4 w;
;                     w.x = cvt_pk_bf16(glu_gate_f(bf_lo(gw.x), a0[0], bf_lo(zw.x)), glu_gate_f(bf_hi(gw.x), a0[1], bf_hi(zw.x)));
;                     w.y = cvt_pk_bf16(glu_gate_f(bf_lo(gw.y), a0[2], bf_lo(zw.y)), glu_gate_f(bf_hi(gw.y), a0[3], bf_hi(zw.y)));
;                     w.z = cvt_pk_bf16(glu_gate_f(bf_lo(gw.z), a1[0], bf_lo(zw.z)), glu_gate_f(bf_hi(gw.z), a1[1], bf_hi(zw.z)));
;                     w.w = cvt_pk_bf16(glu_gate_f(bf_lo(gw.w), a1[2], bf_lo(zw.w)), glu_gate_f(bf_hi(gw.w), a1[3], bf_hi(zw.w)));
;                     *(u32x4*)(O + (size_t)r * DE + c) = w; } } }
	v_lshlrev_b32_e32 v186, 16, v138
	v_mul_f32_e32 v110, 0xbfb8aa3b, v186
	v_exp_f32_e32 v185, v110
	v_and_b32_e32 v138, 0xffff0000, v138
	v_pk_add_f32 v[184:185], v[184:185], 1.0 op_sel_hi:[1,0]
	s_nop 0
	v_mul_f32_e32 v184, v184, v185
	v_rcp_f32_e32 v184, v184
	v_lshlrev_b32_e32 v187, 16, v142
	v_mul_f32_e32 v110, v187, v186
	v_mul_f32_e32 v184, v110, v184
	v_mul_f32_e32 v110, 0xbfb8aa3b, v111
	v_mul_f32_e32 v111, 0xbfb8aa3b, v138
	v_exp_f32_e32 v110, v110
	v_exp_f32_e32 v111, v111
	v_and_b32_e32 v142, 0xffff0000, v142
	v_mul_f32_e32 v138, v142, v138
	v_pk_add_f32 v[110:111], v[110:111], 1.0 op_sel_hi:[1,0]
	s_nop 0
	v_mul_f32_e32 v110, v110, v111
	v_rcp_f32_e32 v110, v110
	v_lshlrev_b32_e32 v111, 16, v139
	v_and_b32_e32 v139, 0xffff0000, v139
	v_mul_f32_e32 v110, v138, v110
	v_cvt_pk_bf16_f32 v110, v184, v110
	v_exp_f32_e32 v184, v112
	v_mul_f32_e32 v112, 0xbfb8aa3b, v111
	v_exp_f32_e32 v185, v112
	v_lshlrev_b32_e32 v138, 16, v143
	v_mul_f32_e32 v111, v138, v111
	v_and_b32_e32 v138, 0xffff0000, v143
	v_pk_add_f32 v[184:185], v[184:185], 1.0 op_sel_hi:[1,0]
	v_mul_f32_e32 v138, v138, v139
	v_mul_f32_e32 v112, v184, v185
	v_rcp_f32_e32 v112, v112
	s_nop 0
	v_mul_f32_e32 v111, v111, v112
	v_mul_f32_e32 v112, 0xbfb8aa3b, v113
	v_mul_f32_e32 v113, 0xbfb8aa3b, v139
	v_exp_f32_e32 v112, v112
	v_exp_f32_e32 v113, v113
	v_lshlrev_b32_e32 v139, 16, v144
	v_pk_add_f32 v[112:113], v[112:113], 1.0 op_sel_hi:[1,0]
	s_nop 0
	v_mul_f32_e32 v112, v112, v113
	v_rcp_f32_e32 v112, v112
	s_nop 0
	v_mul_f32_e32 v112, v138, v112
	v_lshlrev_b32_e32 v138, 16, v140
	v_cvt_pk_bf16_f32 v111, v111, v112
	v_exp_f32_e32 v112, v106
	v_mul_f32_e32 v106, 0xbfb8aa3b, v138
	v_exp_f32_e32 v113, v106
	v_mul_f32_e32 v106, v139, v138
	v_and_b32_e32 v138, 0xffff0000, v140
	v_pk_add_f32 v[112:113], v[112:113], 1.0 op_sel_hi:[1,0]
	s_nop 0
	v_mul_f32_e32 v112, v112, v113
	v_rcp_f32_e32 v112, v112
	v_and_b32_e32 v113, 0xffff0000, v144
	v_mul_f32_e32 v113, v113, v138
	v_mul_f32_e32 v112, v106, v112
	v_mul_f32_e32 v106, 0xbfb8aa3b, v107
	v_mul_f32_e32 v107, 0xbfb8aa3b, v138
	v_exp_f32_e32 v106, v106
	v_exp_f32_e32 v107, v107
	v_lshlrev_b32_e32 v138, 16, v145
	v_pk_add_f32 v[106:107], v[106:107], 1.0 op_sel_hi:[1,0]
	s_nop 0
	v_mul_f32_e32 v106, v106, v107
	v_rcp_f32_e32 v106, v106
	s_nop 0
	v_mul_f32_e32 v106, v113, v106
	v_lshlrev_b32_e32 v113, 16, v141
	v_cvt_pk_bf16_f32 v112, v112, v106
	v_mul_f32_e32 v106, 0xbfb8aa3b, v108
	v_mul_f32_e32 v107, 0xbfb8aa3b, v113
	v_exp_f32_e32 v106, v106
	v_exp_f32_e32 v107, v107
	v_mul_f32_e32 v108, v138, v113
	v_and_b32_e32 v138, 0xffff0000, v141
	v_and_b32_e32 v113, 0xffff0000, v145
	v_pk_add_f32 v[106:107], v[106:107], 1.0 op_sel_hi:[1,0]
	s_nop 0
	v_mul_f32_e32 v106, v106, v107
	v_rcp_f32_e32 v106, v106
	v_mul_f32_e32 v107, 0xbfb8aa3b, v138
	v_exp_f32_e32 v107, v107
	v_mul_f32_e32 v108, v108, v106
	v_mul_f32_e32 v106, 0xbfb8aa3b, v109
	v_exp_f32_e32 v106, v106
	v_mul_f32_e32 v109, v113, v138
	v_pk_add_f32 v[106:107], v[106:107], 1.0 op_sel_hi:[1,0]
	s_nop 0
	v_mul_f32_e32 v106, v106, v107
	v_rcp_f32_e32 v106, v106
	s_nop 0
	v_mul_f32_e32 v106, v109, v106
	v_cvt_pk_bf16_f32 v113, v108, v106
	v_lshlrev_b64 v[106:107], 13, v[176:177]
	v_lshl_add_u64 v[106:107], s[44:45], 0, v[106:107]
	v_lshl_add_u64 v[106:107], v[106:107], 0, v[204:205]
	global_store_dwordx4 v[106:107], v[110:113], off
	v_exp_f32_e32 v108, v94
	s_nop 0
	v_lshlrev_b32_e32 v110, 16, v130
	v_mul_f32_e32 v94, 0xbfb8aa3b, v110
	v_exp_f32_e32 v109, v94
	v_lshlrev_b32_e32 v111, 16, v134
	v_mul_f32_e32 v94, v111, v110
	v_and_b32_e32 v110, 0xffff0000, v130
	v_pk_add_f32 v[108:109], v[108:109], 1.0 op_sel_hi:[1,0]
	s_nop 0
	v_mul_f32_e32 v108, v108, v109
	v_rcp_f32_e32 v108, v108
	v_and_b32_e32 v109, 0xffff0000, v134
	v_mul_f32_e32 v109, v109, v110
	v_mul_f32_e32 v108, v94, v108
	v_mul_f32_e32 v94, 0xbfb8aa3b, v95
	v_mul_f32_e32 v95, 0xbfb8aa3b, v110
	v_exp_f32_e32 v94, v94
	v_exp_f32_e32 v95, v95
	v_lshlrev_b32_e32 v110, 16, v135
	v_pk_add_f32 v[94:95], v[94:95], 1.0 op_sel_hi:[1,0]
	s_nop 0
	v_mul_f32_e32 v94, v94, v95
	v_rcp_f32_e32 v94, v94
	v_lshlrev_b32_e32 v95, 16, v131
	v_mul_f32_e32 v94, v109, v94
	v_cvt_pk_bf16_f32 v94, v108, v94
	v_exp_f32_e32 v108, v96
	v_mul_f32_e32 v96, 0xbfb8aa3b, v95
	v_exp_f32_e32 v109, v96
	v_mul_f32_e32 v95, v110, v95
	v_pk_add_f32 v[108:109], v[108:109], 1.0 op_sel_hi:[1,0]
	s_nop 0
	v_mul_f32_e32 v96, v108, v109
	v_rcp_f32_e32 v96, v96
	v_and_b32_e32 v109, 0xffff0000, v131
	v_and_b32_e32 v108, 0xffff0000, v135
	v_mul_f32_e32 v108, v108, v109
	v_mul_f32_e32 v95, v95, v96
	v_mul_f32_e32 v96, 0xbfb8aa3b, v97
	v_mul_f32_e32 v97, 0xbfb8aa3b, v109
	v_exp_f32_e32 v96, v96
	v_exp_f32_e32 v97, v97
	v_lshlrev_b32_e32 v109, 16, v136
	v_pk_add_f32 v[96:97], v[96:97], 1.0 op_sel_hi:[1,0]
	s_nop 0
	v_mul_f32_e32 v96, v96, v97
	v_rcp_f32_e32 v96, v96
	s_nop 0
	v_mul_f32_e32 v96, v108, v96
	v_lshlrev_b32_e32 v108, 16, v132
	v_cvt_pk_bf16_f32 v95, v95, v96
	v_exp_f32_e32 v96, v90
	v_mul_f32_e32 v90, 0xbfb8aa3b, v108
	v_exp_f32_e32 v97, v90
	v_mul_f32_e32 v90, v109, v108
	v_and_b32_e32 v108, 0xffff0000, v132
	v_pk_add_f32 v[96:97], v[96:97], 1.0 op_sel_hi:[1,0]
	s_nop 0
	v_mul_f32_e32 v96, v96, v97
	v_rcp_f32_e32 v96, v96
	v_and_b32_e32 v97, 0xffff0000, v136
	v_mul_f32_e32 v97, v97, v108
	v_mul_f32_e32 v96, v90, v96
	v_mul_f32_e32 v90, 0xbfb8aa3b, v91
	v_mul_f32_e32 v91, 0xbfb8aa3b, v108
	v_exp_f32_e32 v90, v90
	v_exp_f32_e32 v91, v91
	v_lshlrev_b32_e32 v108, 16, v137
	v_pk_add_f32 v[90:91], v[90:91], 1.0 op_sel_hi:[1,0]
	s_nop 0
	v_mul_f32_e32 v90, v90, v91
	v_rcp_f32_e32 v90, v90
	s_nop 0
	v_mul_f32_e32 v90, v97, v90
	v_lshlrev_b32_e32 v97, 16, v133
; __device__ __forceinline__ unsigned cvt_pk_bf16(float lo, float hi) { unsigned r; asm volatile("v_cvt_pk_bf16_f32 %0, %1, %2" : "=v"(r) : "v"(lo), "v"(hi)); return r; }
; __device__ __forceinline__ float bf_lo(unsigned w) { return __uint_as_float(w << 16); }
; __device__ __forceinline__ float bf_hi(unsigned w) { return __uint_as_float(w & 0xffff0000u); }
;     __device__ __forceinline__ void operator()(const f32x4 (&acc)[2][2][4][2], const Unit& u, int wr, int wc, int fr, int fq, const Pre&) const {
;     ...
;                 for (int m = 0; m < 4; ++m) { const int r = row0 + ai * HALF + m * 16;
;                     const u32x4 zw = zv[m], gw = gv[m];
;                     const f32x4 a0 = acc[ai][bj][m][0] + bs[bj][0], a1 = acc[ai][bj][m][1] + bs[bj][1];
;                     u32x4 w;
;                     w.x = cvt_pk_bf16(glu_gate_f(bf_lo(gw.x), a0[0], bf_lo(zw.x)), glu_gate_f(bf_hi(gw.x), a0[1], bf_hi(zw.x)));
;                     w.y = cvt_pk_bf16(glu_gate_f(bf_lo(gw.y), a0[2], bf_lo(zw.y)), glu_gate_f(bf_hi(gw.y), a0[3], bf_hi(zw.y)));
;                     w.z = cvt_pk_bf16(glu_gate_f(bf_lo(gw.z), a1[0], bf_lo(zw.z)), glu_gate_f(bf_hi(gw.z), a1[1], bf_hi(zw.z)));
;                     w.w = cvt_pk_bf16(glu_gate_f(bf_lo(gw.w), a1[2], bf_lo(zw.w)), glu_gate_f(bf_hi(gw.w), a1[3], bf_hi(zw.w)));
;                     *(u32x4*)(O + (size_t)r * DE + c) = w; } } }
	v_cvt_pk_bf16_f32 v96, v96, v90
	v_mul_f32_e32 v90, 0xbfb8aa3b, v92
	v_mul_f32_e32 v91, 0xbfb8aa3b, v97
	v_exp_f32_e32 v90, v90
	v_exp_f32_e32 v91, v91
	v_mul_f32_e32 v92, v108, v97
	v_and_b32_e32 v108, 0xffff0000, v133
	v_and_b32_e32 v97, 0xffff0000, v137
	v_pk_add_f32 v[90:91], v[90:91], 1.0 op_sel_hi:[1,0]
	s_nop 0
	v_mul_f32_e32 v90, v90, v91
	v_rcp_f32_e32 v90, v90
	v_mul_f32_e32 v91, 0xbfb8aa3b, v108
	v_exp_f32_e32 v91, v91
	v_mul_f32_e32 v92, v92, v90
	v_mul_f32_e32 v90, 0xbfb8aa3b, v93
	v_exp_f32_e32 v90, v90
	v_mul_f32_e32 v93, v97, v108
	v_pk_add_f32 v[90:91], v[90:91], 1.0 op_sel_hi:[1,0]
	s_nop 0
	v_mul_f32_e32 v90, v90, v91
	v_rcp_f32_e32 v90, v90
	s_nop 0
	v_mul_f32_e32 v90, v93, v90
	v_cvt_pk_bf16_f32 v97, v92, v90
	v_lshlrev_b64 v[90:91], 13, v[174:175]
	v_lshl_add_u64 v[90:91], s[44:45], 0, v[90:91]
	v_lshlrev_b32_e32 v92, 16, v122
	v_lshl_add_u64 v[108:109], v[90:91], 0, v[204:205]
	v_exp_f32_e32 v90, v86
	v_mul_f32_e32 v86, 0xbfb8aa3b, v92
	v_exp_f32_e32 v91, v86
	v_lshlrev_b32_e32 v93, 16, v126
	v_mul_f32_e32 v86, v93, v92
	v_and_b32_e32 v92, 0xffff0000, v122
	v_pk_add_f32 v[90:91], v[90:91], 1.0 op_sel_hi:[1,0]
	global_store_dwordx4 v[108:109], v[94:97], off
	v_mul_f32_e32 v90, v90, v91
	v_rcp_f32_e32 v90, v90
	v_and_b32_e32 v91, 0xffff0000, v126
	v_mul_f32_e32 v91, v91, v92
	v_mul_f32_e32 v90, v86, v90
	v_mul_f32_e32 v86, 0xbfb8aa3b, v87
	v_mul_f32_e32 v87, 0xbfb8aa3b, v92
	v_exp_f32_e32 v86, v86
	v_exp_f32_e32 v87, v87
	v_lshlrev_b32_e32 v92, 16, v127
	v_pk_add_f32 v[86:87], v[86:87], 1.0 op_sel_hi:[1,0]
	s_nop 0
	v_mul_f32_e32 v86, v86, v87
	v_rcp_f32_e32 v86, v86
	v_lshlrev_b32_e32 v87, 16, v123
	v_mul_f32_e32 v86, v91, v86
	v_cvt_pk_bf16_f32 v86, v90, v86
	v_exp_f32_e32 v90, v88
	v_mul_f32_e32 v88, 0xbfb8aa3b, v87
	v_exp_f32_e32 v91, v88
	v_mul_f32_e32 v87, v92, v87
	v_pk_add_f32 v[90:91], v[90:91], 1.0 op_sel_hi:[1,0]
	s_nop 0
	v_mul_f32_e32 v88, v90, v91
	v_rcp_f32_e32 v88, v88
	v_and_b32_e32 v91, 0xffff0000, v123
	v_and_b32_e32 v90, 0xffff0000, v127
	v_mul_f32_e32 v90, v90, v91
	v_mul_f32_e32 v87, v87, v88
	v_mul_f32_e32 v88, 0xbfb8aa3b, v89
	v_mul_f32_e32 v89, 0xbfb8aa3b, v91
	v_exp_f32_e32 v88, v88
	v_exp_f32_e32 v89, v89
	v_lshlrev_b32_e32 v91, 16, v128
	v_pk_add_f32 v[88:89], v[88:89], 1.0 op_sel_hi:[1,0]
	s_nop 0
	v_mul_f32_e32 v88, v88, v89
	v_rcp_f32_e32 v88, v88
	s_nop 0
	v_mul_f32_e32 v88, v90, v88
	v_lshlrev_b32_e32 v90, 16, v124
	v_cvt_pk_bf16_f32 v87, v87, v88
	v_exp_f32_e32 v88, v82
	v_mul_f32_e32 v82, 0xbfb8aa3b, v90
	v_exp_f32_e32 v89, v82
	v_mul_f32_e32 v82, v91, v90
	v_and_b32_e32 v90, 0xffff0000, v124
	v_pk_add_f32 v[88:89], v[88:89], 1.0 op_sel_hi:[1,0]
	s_nop 0
	v_mul_f32_e32 v88, v88, v89
	v_rcp_f32_e32 v88, v88
	v_and_b32_e32 v89, 0xffff0000, v128
	v_mul_f32_e32 v89, v89, v90
	v_mul_f32_e32 v88, v82, v88
	v_mul_f32_e32 v82, 0xbfb8aa3b, v83
	v_mul_f32_e32 v83, 0xbfb8aa3b, v90
	v_exp_f32_e32 v82, v82
	v_exp_f32_e32 v83, v83
	v_lshlrev_b32_e32 v90, 16, v129
	v_pk_add_f32 v[82:83], v[82:83], 1.0 op_sel_hi:[1,0]
	s_nop 0
	v_mul_f32_e32 v82, v82, v83
	v_rcp_f32_e32 v82, v82
	s_nop 0
	v_mul_f32_e32 v82, v89, v82
	v_lshlrev_b32_e32 v89, 16, v125
	v_cvt_pk_bf16_f32 v88, v88, v82
	v_mul_f32_e32 v82, 0xbfb8aa3b, v84
	v_mul_f32_e32 v83, 0xbfb8aa3b, v89
	v_exp_f32_e32 v82, v82
	v_exp_f32_e32 v83, v83
	v_mul_f32_e32 v84, v90, v89
	v_and_b32_e32 v90, 0xffff0000, v125
	v_and_b32_e32 v89, 0xffff0000, v129
	v_pk_add_f32 v[82:83], v[82:83], 1.0 op_sel_hi:[1,0]
	s_nop 0
	v_mul_f32_e32 v82, v82, v83
	v_rcp_f32_e32 v82, v82
	v_mul_f32_e32 v83, 0xbfb8aa3b, v90
	v_exp_f32_e32 v83, v83
	v_mul_f32_e32 v84, v84, v82
	v_mul_f32_e32 v82, 0xbfb8aa3b, v85
	v_exp_f32_e32 v82, v82
	v_mul_f32_e32 v85, v89, v90
	v_pk_add_f32 v[82:83], v[82:83], 1.0 op_sel_hi:[1,0]
	s_nop 0
	v_mul_f32_e32 v82, v82, v83
	v_rcp_f32_e32 v82, v82
	s_nop 0
	v_mul_f32_e32 v82, v85, v82
	v_cvt_pk_bf16_f32 v89, v84, v82
	v_lshlrev_b64 v[82:83], 13, v[172:173]
	v_lshl_add_u64 v[82:83], s[44:45], 0, v[82:83]
	v_lshlrev_b32_e32 v84, 16, v114
	v_lshl_add_u64 v[110:111], v[82:83], 0, v[204:205]
	v_exp_f32_e32 v82, v78
	v_mul_f32_e32 v78, 0xbfb8aa3b, v84
	v_exp_f32_e32 v83, v78
	v_lshlrev_b32_e32 v85, 16, v118
	v_mul_f32_e32 v78, v85, v84
	v_and_b32_e32 v84, 0xffff0000, v114
	v_pk_add_f32 v[82:83], v[82:83], 1.0 op_sel_hi:[1,0]
	global_store_dwordx4 v[110:111], v[86:89], off
	v_mul_f32_e32 v82, v82, v83
	v_rcp_f32_e32 v82, v82
	v_and_b32_e32 v83, 0xffff0000, v118
	v_mul_f32_e32 v83, v83, v84
	v_exp_f32_e32 v118, v70
	v_mul_f32_e32 v82, v78, v82
	v_mul_f32_e32 v78, 0xbfb8aa3b, v79
	v_mul_f32_e32 v79, 0xbfb8aa3b, v84
	v_exp_f32_e32 v78, v78
	v_exp_f32_e32 v79, v79
	v_lshlrev_b32_e32 v84, 16, v119
	v_pk_add_f32 v[78:79], v[78:79], 1.0 op_sel_hi:[1,0]
	s_nop 0
	v_mul_f32_e32 v78, v78, v79
	v_rcp_f32_e32 v78, v78
	v_lshlrev_b32_e32 v79, 16, v115
	v_mul_f32_e32 v78, v83, v78
	v_cvt_pk_bf16_f32 v78, v82, v78
	v_exp_f32_e32 v82, v80
	v_mul_f32_e32 v80, 0xbfb8aa3b, v79
	v_exp_f32_e32 v83, v80
	v_mul_f32_e32 v79, v84, v79
	v_pk_add_f32 v[82:83], v[82:83], 1.0 op_sel_hi:[1,0]
	s_nop 0
	v_mul_f32_e32 v80, v82, v83
	v_rcp_f32_e32 v80, v80
	v_and_b32_e32 v83, 0xffff0000, v115
	v_and_b32_e32 v82, 0xffff0000, v119
	v_mul_f32_e32 v82, v82, v83
	v_mul_f32_e32 v79, v79, v80
	v_mul_f32_e32 v80, 0xbfb8aa3b, v81
	v_mul_f32_e32 v81, 0xbfb8aa3b, v83
	v_exp_f32_e32 v80, v80
	v_exp_f32_e32 v81, v81
	v_lshlrev_b32_e32 v83, 16, v120
	v_pk_add_f32 v[80:81], v[80:81], 1.0 op_sel_hi:[1,0]
	s_nop 0
	v_mul_f32_e32 v80, v80, v81
	v_rcp_f32_e32 v80, v80
	s_nop 0
	v_mul_f32_e32 v80, v82, v80
	v_lshlrev_b32_e32 v82, 16, v116
	v_cvt_pk_bf16_f32 v79, v79, v80
	v_exp_f32_e32 v80, v74
; __device__ __forceinline__ unsigned cvt_pk_bf16(float lo, float hi) { unsigned r; asm volatile("v_cvt_pk_bf16_f32 %0, %1, %2" : "=v"(r) : "v"(lo), "v"(hi)); return r; }
; __device__ __forceinline__ float bf_lo(unsigned w) { return __uint_as_float(w << 16); }
; __device__ __forceinline__ float bf_hi(unsigned w) { return __uint_as_float(w & 0xffff0000u); }
;     __device__ __forceinline__ void operator()(const f32x4 (&acc)[2][2][4][2], const Unit& u, int wr, int wc, int fr, int fq, const Pre&) const {
;     ...
;         for (int bj = 0; bj < 2; ++bj) { const int c = col0 + bj * HALF;
; #pragma unroll
;             for (int ai = 0; ai < 2; ++ai) { u32x4 zv[4], gv[4];
; #pragma unroll
;                 for (int m = 0; m < 4; ++m) { const int r = row0 + ai * HALF + m * 16; zv[m] = *(const u32x4*)(Z + (size_t)r * DE2 + c); gv[m] = *(const u32x4*)(Gm + (size_t)(c >> 4) * GSTR + r * 16 + (c & 15)); }
; #pragma unroll
;                 for (int m = 0; m < 4; ++m) { const int r = row0 + ai * HALF + m * 16;
;                     const u32x4 zw = zv[m], gw = gv[m];
;                     const f32x4 a0 = acc[ai][bj][m][0] + bs[bj][0], a1 = acc[ai][bj][m][1] + bs[bj][1];
;                     u32x4 w;
;                     w.x = cvt_pk_bf16(glu_gate_f(bf_lo(gw.x), a0[0], bf_lo(zw.x)), glu_gate_f(bf_hi(gw.x), a0[1], bf_hi(zw.x)));
;                     w.y = cvt_pk_bf16(glu_gate_f(bf_lo(gw.y), a0[2], bf_lo(zw.y)), glu_gate_f(bf_hi(gw.y), a0[3], bf_hi(zw.y)));
;                     w.z = cvt_pk_bf16(glu_gate_f(bf_lo(gw.z), a1[0], bf_lo(zw.z)), glu_gate_f(bf_hi(gw.z), a1[1], bf_hi(zw.z)));
;                     w.w = cvt_pk_bf16(glu_gate_f(bf_lo(gw.w), a1[2], bf_lo(zw.w)), glu_gate_f(bf_hi(gw.w), a1[3], bf_hi(zw.w)));
;                     *(u32x4*)(O + (size_t)r * DE + c) = w; } } }
	v_mul_f32_e32 v74, 0xbfb8aa3b, v82
	v_exp_f32_e32 v81, v74
	v_mul_f32_e32 v74, v83, v82
	v_and_b32_e32 v82, 0xffff0000, v116
	v_pk_add_f32 v[80:81], v[80:81], 1.0 op_sel_hi:[1,0]
	s_nop 0
	v_mul_f32_e32 v80, v80, v81
	v_rcp_f32_e32 v80, v80
	v_and_b32_e32 v81, 0xffff0000, v120
	v_mul_f32_e32 v81, v81, v82
	v_mul_f32_e32 v80, v74, v80
	v_mul_f32_e32 v74, 0xbfb8aa3b, v75
	v_mul_f32_e32 v75, 0xbfb8aa3b, v82
	v_exp_f32_e32 v74, v74
	v_exp_f32_e32 v75, v75
	v_lshlrev_b32_e32 v82, 16, v121
	v_pk_add_f32 v[74:75], v[74:75], 1.0 op_sel_hi:[1,0]
	s_nop 0
	v_mul_f32_e32 v74, v74, v75
	v_rcp_f32_e32 v74, v74
	s_nop 0
	v_mul_f32_e32 v74, v81, v74
	v_lshlrev_b32_e32 v81, 16, v117
	v_cvt_pk_bf16_f32 v80, v80, v74
	v_mul_f32_e32 v74, 0xbfb8aa3b, v76
	v_mul_f32_e32 v75, 0xbfb8aa3b, v81
	v_exp_f32_e32 v74, v74
	v_exp_f32_e32 v75, v75
	v_mul_f32_e32 v76, v82, v81
	v_and_b32_e32 v82, 0xffff0000, v117
	v_and_b32_e32 v81, 0xffff0000, v121
	v_pk_add_f32 v[74:75], v[74:75], 1.0 op_sel_hi:[1,0]
	s_nop 0
	v_mul_f32_e32 v74, v74, v75
	v_rcp_f32_e32 v74, v74
	v_mul_f32_e32 v75, 0xbfb8aa3b, v82
	v_exp_f32_e32 v75, v75
	v_mul_f32_e32 v76, v76, v74
	v_mul_f32_e32 v74, 0xbfb8aa3b, v77
	v_exp_f32_e32 v74, v74
	v_mul_f32_e32 v77, v81, v82
	v_pk_add_f32 v[74:75], v[74:75], 1.0 op_sel_hi:[1,0]
	s_nop 0
	v_mul_f32_e32 v74, v74, v75
	v_rcp_f32_e32 v74, v74
	s_nop 0
	v_mul_f32_e32 v74, v77, v74
	v_cvt_pk_bf16_f32 v81, v76, v74
	v_lshlrev_b64 v[74:75], 13, v[170:171]
	v_lshl_add_u64 v[74:75], s[44:45], 0, v[74:75]
	v_lshl_add_u64 v[112:113], v[74:75], 0, v[204:205]
	v_or_b32_e32 v74, 0x80, v200
	v_ashrrev_i32_e32 v75, 31, v74
	v_ashrrev_i32_e32 v76, 4, v74
	v_mad_i64_i32 v[114:115], s[4:5], v76, s94, v[194:195]
	v_lshl_add_u64 v[76:77], s[46:47], 0, v[202:203]
	v_lshlrev_b64 v[116:117], 1, v[74:75]
	v_lshl_add_u64 v[74:75], v[76:77], 0, v[116:117]
	global_load_dwordx4 v[98:101], v[74:75], off
	s_nop 0
	global_store_dwordx4 v[112:113], v[78:81], off
	s_nop 1
	v_lshl_add_u64 v[78:79], v[114:115], 0, v[218:219]
	global_load_dwordx4 v[78:81], v[78:79], off
	v_lshl_add_u64 v[74:75], v[114:115], 0, v[206:207]
	global_load_dwordx4 v[102:105], v[74:75], off
	v_lshl_add_u64 v[74:75], s[46:47], 0, v[210:211]
	v_lshl_add_u64 v[74:75], v[74:75], 0, v[116:117]
	global_load_dwordx4 v[90:93], v[74:75], off
	v_lshl_add_u64 v[74:75], v[114:115], 0, v[208:209]
	global_load_dwordx4 v[94:97], v[74:75], off
	v_lshl_add_u64 v[74:75], s[46:47], 0, v[214:215]
	v_lshl_add_u64 v[74:75], v[74:75], 0, v[116:117]
	global_load_dwordx4 v[82:85], v[74:75], off
	v_lshl_add_u64 v[74:75], v[114:115], 0, v[212:213]
	global_load_dwordx4 v[86:89], v[74:75], off
	v_lshl_add_u64 v[74:75], s[46:47], 0, v[216:217]
	v_lshl_add_u64 v[74:75], v[74:75], 0, v[116:117]
	global_load_dwordx4 v[74:77], v[74:75], off
	s_waitcnt vmcnt(0)
	v_lshlrev_b32_e32 v120, 16, v98
	v_mul_f32_e32 v70, 0xbfb8aa3b, v120
	v_exp_f32_e32 v119, v70
	v_and_b32_e32 v98, 0xffff0000, v98
	v_pk_add_f32 v[118:119], v[118:119], 1.0 op_sel_hi:[1,0]
	s_nop 0
	v_mul_f32_e32 v118, v118, v119
	v_rcp_f32_e32 v118, v118
	v_lshlrev_b32_e32 v121, 16, v102
	v_mul_f32_e32 v70, v121, v120
	v_and_b32_e32 v102, 0xffff0000, v102
	v_mul_f32_e32 v118, v70, v118
	v_mul_f32_e32 v70, 0xbfb8aa3b, v71
	v_mul_f32_e32 v71, 0xbfb8aa3b, v98
	v_exp_f32_e32 v70, v70
	v_exp_f32_e32 v71, v71
	v_mul_f32_e32 v98, v102, v98
	v_pk_add_f32 v[70:71], v[70:71], 1.0 op_sel_hi:[1,0]
	s_nop 0
	v_mul_f32_e32 v70, v70, v71
	v_rcp_f32_e32 v70, v70
	v_lshlrev_b32_e32 v71, 16, v99
	v_and_b32_e32 v99, 0xffff0000, v99
	v_mul_f32_e32 v70, v98, v70
	v_cvt_pk_bf16_f32 v70, v118, v70
	v_exp_f32_e32 v118, v72
	v_mul_f32_e32 v72, 0xbfb8aa3b, v71
	v_exp_f32_e32 v119, v72
	v_lshlrev_b32_e32 v98, 16, v103
	v_mul_f32_e32 v71, v98, v71
	v_and_b32_e32 v98, 0xffff0000, v103
	v_pk_add_f32 v[118:119], v[118:119], 1.0 op_sel_hi:[1,0]
	v_mul_f32_e32 v98, v98, v99
	v_mul_f32_e32 v72, v118, v119
	v_rcp_f32_e32 v72, v72
	s_nop 0
	v_mul_f32_e32 v71, v71, v72
	v_mul_f32_e32 v72, 0xbfb8aa3b, v73
	v_mul_f32_e32 v73, 0xbfb8aa3b, v99
	v_exp_f32_e32 v72, v72
	v_exp_f32_e32 v73, v73
	v_lshlrev_b32_e32 v99, 16, v104
	v_pk_add_f32 v[72:73], v[72:73], 1.0 op_sel_hi:[1,0]
	s_nop 0
	v_mul_f32_e32 v72, v72, v73
	v_rcp_f32_e32 v72, v72
	s_nop 0
	v_mul_f32_e32 v72, v98, v72
	v_lshlrev_b32_e32 v98, 16, v100
	v_cvt_pk_bf16_f32 v71, v71, v72
	v_exp_f32_e32 v72, v66
	v_mul_f32_e32 v66, 0xbfb8aa3b, v98
	v_exp_f32_e32 v73, v66
	v_mul_f32_e32 v66, v99, v98
	v_and_b32_e32 v98, 0xffff0000, v100
	v_pk_add_f32 v[72:73], v[72:73], 1.0 op_sel_hi:[1,0]
	s_nop 0
	v_mul_f32_e32 v72, v72, v73
	v_rcp_f32_e32 v72, v72
	v_and_b32_e32 v73, 0xffff0000, v104
	v_mul_f32_e32 v73, v73, v98
	v_mul_f32_e32 v72, v66, v72
	v_mul_f32_e32 v66, 0xbfb8aa3b, v67
	v_mul_f32_e32 v67, 0xbfb8aa3b, v98
	v_exp_f32_e32 v66, v66
	v_exp_f32_e32 v67, v67
	v_lshlrev_b32_e32 v98, 16, v105
	v_pk_add_f32 v[66:67], v[66:67], 1.0 op_sel_hi:[1,0]
	s_nop 0
	v_mul_f32_e32 v66, v66, v67
	v_rcp_f32_e32 v66, v66
	s_nop 0
	v_mul_f32_e32 v66, v73, v66
	v_lshlrev_b32_e32 v73, 16, v101
	v_cvt_pk_bf16_f32 v72, v72, v66
	v_mul_f32_e32 v66, 0xbfb8aa3b, v68
	v_mul_f32_e32 v67, 0xbfb8aa3b, v73
	v_exp_f32_e32 v66, v66
	v_exp_f32_e32 v67, v67
	v_mul_f32_e32 v68, v98, v73
	v_and_b32_e32 v98, 0xffff0000, v101
	v_and_b32_e32 v73, 0xffff0000, v105
	v_pk_add_f32 v[66:67], v[66:67], 1.0 op_sel_hi:[1,0]
	s_nop 0
	v_mul_f32_e32 v66, v66, v67
	v_rcp_f32_e32 v66, v66
	v_mul_f32_e32 v67, 0xbfb8aa3b, v98
	v_exp_f32_e32 v67, v67
	v_mul_f32_e32 v68, v68, v66
	v_mul_f32_e32 v66, 0xbfb8aa3b, v69
	v_exp_f32_e32 v66, v66
	v_mul_f32_e32 v69, v73, v98
	v_pk_add_f32 v[66:67], v[66:67], 1.0 op_sel_hi:[1,0]
	s_nop 0
; __device__ __forceinline__ unsigned cvt_pk_bf16(float lo, float hi) { unsigned r; asm volatile("v_cvt_pk_bf16_f32 %0, %1, %2" : "=v"(r) : "v"(lo), "v"(hi)); return r; }
; __device__ __forceinline__ float bf_lo(unsigned w) { return __uint_as_float(w << 16); }
; __device__ __forceinline__ float bf_hi(unsigned w) { return __uint_as_float(w & 0xffff0000u); }
;     __device__ __forceinline__ void operator()(const f32x4 (&acc)[2][2][4][2], const Unit& u, int wr, int wc, int fr, int fq, const Pre&) const {
;     ...
;                 for (int m = 0; m < 4; ++m) { const int r = row0 + ai * HALF + m * 16;
;                     const u32x4 zw = zv[m], gw = gv[m];
;                     const f32x4 a0 = acc[ai][bj][m][0] + bs[bj][0], a1 = acc[ai][bj][m][1] + bs[bj][1];
;                     u32x4 w;
;                     w.x = cvt_pk_bf16(glu_gate_f(bf_lo(gw.x), a0[0], bf_lo(zw.x)), glu_gate_f(bf_hi(gw.x), a0[1], bf_hi(zw.x)));
;                     w.y = cvt_pk_bf16(glu_gate_f(bf_lo(gw.y), a0[2], bf_lo(zw.y)), glu_gate_f(bf_hi(gw.y), a0[3], bf_hi(zw.y)));
;                     w.z = cvt_pk_bf16(glu_gate_f(bf_lo(gw.z), a1[0], bf_lo(zw.z)), glu_gate_f(bf_hi(gw.z), a1[1], bf_hi(zw.z)));
;                     w.w = cvt_pk_bf16(glu_gate_f(bf_lo(gw.w), a1[2], bf_lo(zw.w)), glu_gate_f(bf_hi(gw.w), a1[3], bf_hi(zw.w)));
;                     *(u32x4*)(O + (size_t)r * DE + c) = w; } } }
	v_mul_f32_e32 v66, v66, v67
	v_rcp_f32_e32 v66, v66
	s_nop 0
	v_mul_f32_e32 v66, v69, v66
	v_cvt_pk_bf16_f32 v73, v68, v66
	v_lshlrev_b32_e32 v68, 16, v90
	v_exp_f32_e32 v66, v62
	v_mul_f32_e32 v62, 0xbfb8aa3b, v68
	v_exp_f32_e32 v67, v62
	v_lshlrev_b32_e32 v69, 16, v94
	v_mul_f32_e32 v62, v69, v68
	v_and_b32_e32 v68, 0xffff0000, v90
	v_pk_add_f32 v[66:67], v[66:67], 1.0 op_sel_hi:[1,0]
	global_store_dwordx4 v[162:163], v[70:73], off offset:256
	v_mul_f32_e32 v66, v66, v67
	v_rcp_f32_e32 v66, v66
	v_and_b32_e32 v67, 0xffff0000, v94
	v_mul_f32_e32 v67, v67, v68
	v_mul_f32_e32 v66, v62, v66
	v_mul_f32_e32 v62, 0xbfb8aa3b, v63
	v_mul_f32_e32 v63, 0xbfb8aa3b, v68
	v_exp_f32_e32 v62, v62
	v_exp_f32_e32 v63, v63
	v_lshlrev_b32_e32 v68, 16, v95
	v_pk_add_f32 v[62:63], v[62:63], 1.0 op_sel_hi:[1,0]
	s_nop 0
	v_mul_f32_e32 v62, v62, v63
	v_rcp_f32_e32 v62, v62
	v_lshlrev_b32_e32 v63, 16, v91
	v_mul_f32_e32 v62, v67, v62
	v_cvt_pk_bf16_f32 v62, v66, v62
	v_exp_f32_e32 v66, v64
	v_mul_f32_e32 v64, 0xbfb8aa3b, v63
	v_exp_f32_e32 v67, v64
	v_mul_f32_e32 v63, v68, v63
	v_pk_add_f32 v[66:67], v[66:67], 1.0 op_sel_hi:[1,0]
	s_nop 0
	v_mul_f32_e32 v64, v66, v67
	v_rcp_f32_e32 v64, v64
	v_and_b32_e32 v67, 0xffff0000, v91
	v_and_b32_e32 v66, 0xffff0000, v95
	v_mul_f32_e32 v66, v66, v67
	v_mul_f32_e32 v63, v63, v64
	v_mul_f32_e32 v64, 0xbfb8aa3b, v65
	v_mul_f32_e32 v65, 0xbfb8aa3b, v67
	v_exp_f32_e32 v64, v64
	v_exp_f32_e32 v65, v65
	v_lshlrev_b32_e32 v67, 16, v96
	v_pk_add_f32 v[64:65], v[64:65], 1.0 op_sel_hi:[1,0]
	s_nop 0
	v_mul_f32_e32 v64, v64, v65
	v_rcp_f32_e32 v64, v64
	s_nop 0
	v_mul_f32_e32 v64, v66, v64
	v_lshlrev_b32_e32 v66, 16, v92
	v_cvt_pk_bf16_f32 v63, v63, v64
	v_exp_f32_e32 v64, v58
	v_mul_f32_e32 v58, 0xbfb8aa3b, v66
	v_exp_f32_e32 v65, v58
	v_mul_f32_e32 v58, v67, v66
	v_and_b32_e32 v66, 0xffff0000, v92
	v_pk_add_f32 v[64:65], v[64:65], 1.0 op_sel_hi:[1,0]
	s_nop 0
	v_mul_f32_e32 v64, v64, v65
	v_rcp_f32_e32 v64, v64
	v_and_b32_e32 v65, 0xffff0000, v96
	v_mul_f32_e32 v65, v65, v66
	v_mul_f32_e32 v64, v58, v64
	v_mul_f32_e32 v58, 0xbfb8aa3b, v59
	v_mul_f32_e32 v59, 0xbfb8aa3b, v66
	v_exp_f32_e32 v58, v58
	v_exp_f32_e32 v59, v59
	v_lshlrev_b32_e32 v66, 16, v97
	v_pk_add_f32 v[58:59], v[58:59], 1.0 op_sel_hi:[1,0]
	s_nop 0
	v_mul_f32_e32 v58, v58, v59
	v_rcp_f32_e32 v58, v58
	s_nop 0
	v_mul_f32_e32 v58, v65, v58
	v_lshlrev_b32_e32 v65, 16, v93
	v_cvt_pk_bf16_f32 v64, v64, v58
	v_mul_f32_e32 v58, 0xbfb8aa3b, v60
	v_mul_f32_e32 v59, 0xbfb8aa3b, v65
	v_exp_f32_e32 v58, v58
	v_exp_f32_e32 v59, v59
	v_mul_f32_e32 v60, v66, v65
	v_and_b32_e32 v66, 0xffff0000, v93
	v_and_b32_e32 v65, 0xffff0000, v97
	v_pk_add_f32 v[58:59], v[58:59], 1.0 op_sel_hi:[1,0]
	s_nop 0
	v_mul_f32_e32 v58, v58, v59
	v_rcp_f32_e32 v58, v58
	v_mul_f32_e32 v59, 0xbfb8aa3b, v66
	v_exp_f32_e32 v59, v59
	v_mul_f32_e32 v60, v60, v58
	v_mul_f32_e32 v58, 0xbfb8aa3b, v61
	v_exp_f32_e32 v58, v58
	v_mul_f32_e32 v61, v65, v66
	v_pk_add_f32 v[58:59], v[58:59], 1.0 op_sel_hi:[1,0]
	s_nop 0
	v_mul_f32_e32 v58, v58, v59
	v_rcp_f32_e32 v58, v58
	s_nop 0
	v_mul_f32_e32 v58, v61, v58
	v_cvt_pk_bf16_f32 v65, v60, v58
	v_lshlrev_b32_e32 v60, 16, v82
	v_exp_f32_e32 v58, v54
	v_mul_f32_e32 v54, 0xbfb8aa3b, v60
	v_exp_f32_e32 v59, v54
	v_lshlrev_b32_e32 v61, 16, v86
	v_mul_f32_e32 v54, v61, v60
	v_and_b32_e32 v60, 0xffff0000, v82
	v_pk_add_f32 v[58:59], v[58:59], 1.0 op_sel_hi:[1,0]
	global_store_dwordx4 v[154:155], v[62:65], off offset:256
	v_mul_f32_e32 v58, v58, v59
	v_rcp_f32_e32 v58, v58
	v_and_b32_e32 v59, 0xffff0000, v86
	v_mul_f32_e32 v59, v59, v60
	v_mul_f32_e32 v58, v54, v58
	v_mul_f32_e32 v54, 0xbfb8aa3b, v55
	v_mul_f32_e32 v55, 0xbfb8aa3b, v60
	v_exp_f32_e32 v54, v54
	v_exp_f32_e32 v55, v55
	v_lshlrev_b32_e32 v60, 16, v87
	v_pk_add_f32 v[54:55], v[54:55], 1.0 op_sel_hi:[1,0]
	s_nop 0
	v_mul_f32_e32 v54, v54, v55
	v_rcp_f32_e32 v54, v54
	v_lshlrev_b32_e32 v55, 16, v83
	v_mul_f32_e32 v54, v59, v54
	v_cvt_pk_bf16_f32 v54, v58, v54
	v_exp_f32_e32 v58, v56
	v_mul_f32_e32 v56, 0xbfb8aa3b, v55
	v_exp_f32_e32 v59, v56
	v_mul_f32_e32 v55, v60, v55
	v_pk_add_f32 v[58:59], v[58:59], 1.0 op_sel_hi:[1,0]
	s_nop 0
	v_mul_f32_e32 v56, v58, v59
	v_rcp_f32_e32 v56, v56
	v_and_b32_e32 v59, 0xffff0000, v83
	v_and_b32_e32 v58, 0xffff0000, v87
	v_mul_f32_e32 v58, v58, v59
	v_mul_f32_e32 v55, v55, v56
	v_mul_f32_e32 v56, 0xbfb8aa3b, v57
	v_mul_f32_e32 v57, 0xbfb8aa3b, v59
	v_exp_f32_e32 v56, v56
	v_exp_f32_e32 v57, v57
	v_lshlrev_b32_e32 v59, 16, v88
	v_pk_add_f32 v[56:57], v[56:57], 1.0 op_sel_hi:[1,0]
	s_nop 0
	v_mul_f32_e32 v56, v56, v57
	v_rcp_f32_e32 v56, v56
	s_nop 0
	v_mul_f32_e32 v56, v58, v56
	v_lshlrev_b32_e32 v58, 16, v84
	v_cvt_pk_bf16_f32 v55, v55, v56
	v_exp_f32_e32 v56, v50
	v_mul_f32_e32 v50, 0xbfb8aa3b, v58
	v_exp_f32_e32 v57, v50
	v_mul_f32_e32 v50, v59, v58
	v_and_b32_e32 v58, 0xffff0000, v84
	v_pk_add_f32 v[56:57], v[56:57], 1.0 op_sel_hi:[1,0]
	s_nop 0
	v_mul_f32_e32 v56, v56, v57
	v_rcp_f32_e32 v56, v56
	v_and_b32_e32 v57, 0xffff0000, v88
	v_mul_f32_e32 v57, v57, v58
	v_mul_f32_e32 v56, v50, v56
	v_mul_f32_e32 v50, 0xbfb8aa3b, v51
	v_mul_f32_e32 v51, 0xbfb8aa3b, v58
	v_exp_f32_e32 v50, v50
	v_exp_f32_e32 v51, v51
	v_lshlrev_b32_e32 v58, 16, v89
	v_pk_add_f32 v[50:51], v[50:51], 1.0 op_sel_hi:[1,0]
	s_nop 0
	v_mul_f32_e32 v50, v50, v51
	v_rcp_f32_e32 v50, v50
	s_nop 0
	v_mul_f32_e32 v50, v57, v50
	v_lshlrev_b32_e32 v57, 16, v85
	v_cvt_pk_bf16_f32 v56, v56, v50
	v_mul_f32_e32 v50, 0xbfb8aa3b, v52
	v_mul_f32_e32 v51, 0xbfb8aa3b, v57
	v_exp_f32_e32 v50, v50
	v_exp_f32_e32 v51, v51
	v_mul_f32_e32 v52, v58, v57
	v_and_b32_e32 v58, 0xffff0000, v85
	v_and_b32_e32 v57, 0xffff0000, v89
; __device__ __forceinline__ unsigned cvt_pk_bf16(float lo, float hi) { unsigned r; asm volatile("v_cvt_pk_bf16_f32 %0, %1, %2" : "=v"(r) : "v"(lo), "v"(hi)); return r; }
; __device__ __forceinline__ float bf_lo(unsigned w) { return __uint_as_float(w << 16); }
; __device__ __forceinline__ float bf_hi(unsigned w) { return __uint_as_float(w & 0xffff0000u); }
;     __device__ __forceinline__ void operator()(const f32x4 (&acc)[2][2][4][2], const Unit& u, int wr, int wc, int fr, int fq, const Pre&) const {
;     ...
;             for (int ai = 0; ai < 2; ++ai) { u32x4 zv[4], gv[4];
; #pragma unroll
;                 for (int m = 0; m < 4; ++m) { const int r = row0 + ai * HALF + m * 16; zv[m] = *(const u32x4*)(Z + (size_t)r * DE2 + c); gv[m] = *(const u32x4*)(Gm + (size_t)(c >> 4) * GSTR + r * 16 + (c & 15)); }
; #pragma unroll
;                 for (int m = 0; m < 4; ++m) { const int r = row0 + ai * HALF + m * 16;
;                     const u32x4 zw = zv[m], gw = gv[m];
;                     const f32x4 a0 = acc[ai][bj][m][0] + bs[bj][0], a1 = acc[ai][bj][m][1] + bs[bj][1];
;                     u32x4 w;
;                     w.x = cvt_pk_bf16(glu_gate_f(bf_lo(gw.x), a0[0], bf_lo(zw.x)), glu_gate_f(bf_hi(gw.x), a0[1], bf_hi(zw.x)));
;                     w.y = cvt_pk_bf16(glu_gate_f(bf_lo(gw.y), a0[2], bf_lo(zw.y)), glu_gate_f(bf_hi(gw.y), a0[3], bf_hi(zw.y)));
;                     w.z = cvt_pk_bf16(glu_gate_f(bf_lo(gw.z), a1[0], bf_lo(zw.z)), glu_gate_f(bf_hi(gw.z), a1[1], bf_hi(zw.z)));
;                     w.w = cvt_pk_bf16(glu_gate_f(bf_lo(gw.w), a1[2], bf_lo(zw.w)), glu_gate_f(bf_hi(gw.w), a1[3], bf_hi(zw.w)));
;                     *(u32x4*)(O + (size_t)r * DE + c) = w; } } }
	v_pk_add_f32 v[50:51], v[50:51], 1.0 op_sel_hi:[1,0]
	s_nop 0
	v_mul_f32_e32 v50, v50, v51
	v_rcp_f32_e32 v50, v50
	v_mul_f32_e32 v51, 0xbfb8aa3b, v58
	v_exp_f32_e32 v51, v51
	v_mul_f32_e32 v52, v52, v50
	v_mul_f32_e32 v50, 0xbfb8aa3b, v53
	v_exp_f32_e32 v50, v50
	v_mul_f32_e32 v53, v57, v58
	v_pk_add_f32 v[50:51], v[50:51], 1.0 op_sel_hi:[1,0]
	s_nop 0
	v_mul_f32_e32 v50, v50, v51
	v_rcp_f32_e32 v50, v50
	s_nop 0
	v_mul_f32_e32 v50, v53, v50
	v_cvt_pk_bf16_f32 v57, v52, v50
	v_lshlrev_b32_e32 v52, 16, v74
	v_exp_f32_e32 v50, v46
	v_mul_f32_e32 v46, 0xbfb8aa3b, v52
	v_exp_f32_e32 v51, v46
	v_lshlrev_b32_e32 v53, 16, v78
	v_mul_f32_e32 v46, v53, v52
	v_and_b32_e32 v52, 0xffff0000, v74
	v_pk_add_f32 v[50:51], v[50:51], 1.0 op_sel_hi:[1,0]
	global_store_dwordx4 v[146:147], v[54:57], off offset:256
	v_mul_f32_e32 v50, v50, v51
	v_rcp_f32_e32 v50, v50
	v_and_b32_e32 v51, 0xffff0000, v78
	v_mul_f32_e32 v51, v51, v52
	v_exp_f32_e32 v74, v38
	v_mul_f32_e32 v50, v46, v50
	v_mul_f32_e32 v46, 0xbfb8aa3b, v47
	v_mul_f32_e32 v47, 0xbfb8aa3b, v52
	v_exp_f32_e32 v46, v46
	v_exp_f32_e32 v47, v47
	v_lshlrev_b32_e32 v52, 16, v79
	v_pk_add_f32 v[46:47], v[46:47], 1.0 op_sel_hi:[1,0]
	s_nop 0
	v_mul_f32_e32 v46, v46, v47
	v_rcp_f32_e32 v46, v46
	v_lshlrev_b32_e32 v47, 16, v75
	v_mul_f32_e32 v46, v51, v46
	v_cvt_pk_bf16_f32 v46, v50, v46
	v_exp_f32_e32 v50, v48
	v_mul_f32_e32 v48, 0xbfb8aa3b, v47
	v_exp_f32_e32 v51, v48
	v_mul_f32_e32 v47, v52, v47
	v_pk_add_f32 v[50:51], v[50:51], 1.0 op_sel_hi:[1,0]
	s_nop 0
	v_mul_f32_e32 v48, v50, v51
	v_rcp_f32_e32 v48, v48
	v_and_b32_e32 v51, 0xffff0000, v75
	v_and_b32_e32 v50, 0xffff0000, v79
	v_mul_f32_e32 v50, v50, v51
	v_mul_f32_e32 v47, v47, v48
	v_mul_f32_e32 v48, 0xbfb8aa3b, v49
	v_mul_f32_e32 v49, 0xbfb8aa3b, v51
	v_exp_f32_e32 v48, v48
	v_exp_f32_e32 v49, v49
	v_lshlrev_b32_e32 v51, 16, v80
	v_pk_add_f32 v[48:49], v[48:49], 1.0 op_sel_hi:[1,0]
	s_nop 0
	v_mul_f32_e32 v48, v48, v49
	v_rcp_f32_e32 v48, v48
	s_nop 0
	v_mul_f32_e32 v48, v50, v48
	v_lshlrev_b32_e32 v50, 16, v76
	v_cvt_pk_bf16_f32 v47, v47, v48
	v_exp_f32_e32 v48, v42
	v_mul_f32_e32 v42, 0xbfb8aa3b, v50
	v_exp_f32_e32 v49, v42
	v_mul_f32_e32 v42, v51, v50
	v_and_b32_e32 v50, 0xffff0000, v76
	v_pk_add_f32 v[48:49], v[48:49], 1.0 op_sel_hi:[1,0]
	s_nop 0
	v_mul_f32_e32 v48, v48, v49
	v_rcp_f32_e32 v48, v48
	v_and_b32_e32 v49, 0xffff0000, v80
	v_mul_f32_e32 v49, v49, v50
	v_mul_f32_e32 v48, v42, v48
	v_mul_f32_e32 v42, 0xbfb8aa3b, v43
	v_mul_f32_e32 v43, 0xbfb8aa3b, v50
	v_exp_f32_e32 v42, v42
	v_exp_f32_e32 v43, v43
	v_lshlrev_b32_e32 v50, 16, v81
	v_pk_add_f32 v[42:43], v[42:43], 1.0 op_sel_hi:[1,0]
	s_nop 0
	v_mul_f32_e32 v42, v42, v43
	v_rcp_f32_e32 v42, v42
	s_nop 0
	v_mul_f32_e32 v42, v49, v42
	v_lshlrev_b32_e32 v49, 16, v77
	v_cvt_pk_bf16_f32 v48, v48, v42
	v_mul_f32_e32 v42, 0xbfb8aa3b, v44
	v_mul_f32_e32 v43, 0xbfb8aa3b, v49
	v_exp_f32_e32 v42, v42
	v_exp_f32_e32 v43, v43
	v_mul_f32_e32 v44, v50, v49
	v_and_b32_e32 v50, 0xffff0000, v77
	v_and_b32_e32 v49, 0xffff0000, v81
	v_pk_add_f32 v[42:43], v[42:43], 1.0 op_sel_hi:[1,0]
	s_nop 0
	v_mul_f32_e32 v42, v42, v43
	v_rcp_f32_e32 v42, v42
	v_mul_f32_e32 v43, 0xbfb8aa3b, v50
	v_exp_f32_e32 v43, v43
	v_mul_f32_e32 v44, v44, v42
	v_mul_f32_e32 v42, 0xbfb8aa3b, v45
	v_exp_f32_e32 v42, v42
	v_mul_f32_e32 v45, v49, v50
	v_pk_add_f32 v[42:43], v[42:43], 1.0 op_sel_hi:[1,0]
	s_nop 0
	v_mul_f32_e32 v42, v42, v43
	v_rcp_f32_e32 v42, v42
	s_nop 0
	v_mul_f32_e32 v42, v45, v42
	v_cvt_pk_bf16_f32 v49, v44, v42
	v_lshl_add_u64 v[42:43], s[46:47], 0, v[150:151]
	global_store_dwordx4 v[148:149], v[46:49], off offset:256
	v_lshl_add_u64 v[42:43], v[42:43], 0, v[116:117]
	global_load_dwordx4 v[66:69], v[42:43], off
	v_lshl_add_u64 v[46:47], v[114:115], 0, v[168:169]
	global_load_dwordx4 v[46:49], v[46:47], off
	v_lshl_add_u64 v[42:43], v[114:115], 0, v[152:153]
	global_load_dwordx4 v[70:73], v[42:43], off
	v_lshl_add_u64 v[42:43], s[46:47], 0, v[156:157]
	v_lshl_add_u64 v[42:43], v[42:43], 0, v[116:117]
	global_load_dwordx4 v[58:61], v[42:43], off
	v_lshl_add_u64 v[42:43], v[114:115], 0, v[158:159]
	global_load_dwordx4 v[62:65], v[42:43], off
	v_lshl_add_u64 v[42:43], s[46:47], 0, v[160:161]
	v_lshl_add_u64 v[42:43], v[42:43], 0, v[116:117]
	global_load_dwordx4 v[50:53], v[42:43], off
	v_lshl_add_u64 v[42:43], v[114:115], 0, v[164:165]
	global_load_dwordx4 v[54:57], v[42:43], off
	v_lshl_add_u64 v[42:43], s[46:47], 0, v[166:167]
	v_lshl_add_u64 v[42:43], v[42:43], 0, v[116:117]
	global_load_dwordx4 v[42:45], v[42:43], off
	s_waitcnt vmcnt(0)
; __device__ __forceinline__ unsigned cvt_pk_bf16(float lo, float hi) { unsigned r; asm volatile("v_cvt_pk_bf16_f32 %0, %1, %2" : "=v"(r) : "v"(lo), "v"(hi)); return r; }
; __device__ __forceinline__ float bf_lo(unsigned w) { return __uint_as_float(w << 16); }
; __device__ __forceinline__ float bf_hi(unsigned w) { return __uint_as_float(w & 0xffff0000u); }
;     __device__ __forceinline__ void operator()(const f32x4 (&acc)[2][2][4][2], const Unit& u, int wr, int wc, int fr, int fq, const Pre&) const {
;     ...
;                 for (int m = 0; m < 4; ++m) { const int r = row0 + ai * HALF + m * 16;
;                     const u32x4 zw = zv[m], gw = gv[m];
;                     const f32x4 a0 = acc[ai][bj][m][0] + bs[bj][0], a1 = acc[ai][bj][m][1] + bs[bj][1];
;                     u32x4 w;
;                     w.x = cvt_pk_bf16(glu_gate_f(bf_lo(gw.x), a0[0], bf_lo(zw.x)), glu_gate_f(bf_hi(gw.x), a0[1], bf_hi(zw.x)));
;                     w.y = cvt_pk_bf16(glu_gate_f(bf_lo(gw.y), a0[2], bf_lo(zw.y)), glu_gate_f(bf_hi(gw.y), a0[3], bf_hi(zw.y)));
;                     w.z = cvt_pk_bf16(glu_gate_f(bf_lo(gw.z), a1[0], bf_lo(zw.z)), glu_gate_f(bf_hi(gw.z), a1[1], bf_hi(zw.z)));
;                     w.w = cvt_pk_bf16(glu_gate_f(bf_lo(gw.w), a1[2], bf_lo(zw.w)), glu_gate_f(bf_hi(gw.w), a1[3], bf_hi(zw.w)));
;                     *(u32x4*)(O + (size_t)r * DE + c) = w; } } }
	v_lshlrev_b32_e32 v76, 16, v66
	v_mul_f32_e32 v38, 0xbfb8aa3b, v76
	v_exp_f32_e32 v75, v38
	v_and_b32_e32 v66, 0xffff0000, v66
	v_lshlrev_b32_e32 v77, 16, v70
	v_mul_f32_e32 v38, v77, v76
	v_pk_add_f32 v[74:75], v[74:75], 1.0 op_sel_hi:[1,0]
	v_and_b32_e32 v70, 0xffff0000, v70
	v_mul_f32_e32 v74, v74, v75
	v_rcp_f32_e32 v74, v74
	s_nop 0
	v_mul_f32_e32 v74, v38, v74
	v_mul_f32_e32 v38, 0xbfb8aa3b, v39
	v_mul_f32_e32 v39, 0xbfb8aa3b, v66
	v_exp_f32_e32 v38, v38
	v_exp_f32_e32 v39, v39
	v_mul_f32_e32 v66, v70, v66
	v_pk_add_f32 v[38:39], v[38:39], 1.0 op_sel_hi:[1,0]
	s_nop 0
	v_mul_f32_e32 v38, v38, v39
	v_rcp_f32_e32 v38, v38
	v_lshlrev_b32_e32 v39, 16, v67
	v_and_b32_e32 v67, 0xffff0000, v67
	v_mul_f32_e32 v38, v66, v38
	v_cvt_pk_bf16_f32 v38, v74, v38
	v_exp_f32_e32 v74, v40
	v_mul_f32_e32 v40, 0xbfb8aa3b, v39
	v_exp_f32_e32 v75, v40
	v_lshlrev_b32_e32 v66, 16, v71
	v_mul_f32_e32 v39, v66, v39
	v_and_b32_e32 v66, 0xffff0000, v71
	v_pk_add_f32 v[74:75], v[74:75], 1.0 op_sel_hi:[1,0]
	v_mul_f32_e32 v66, v66, v67
	v_mul_f32_e32 v40, v74, v75
	v_rcp_f32_e32 v40, v40
	s_nop 0
	v_mul_f32_e32 v39, v39, v40
	v_mul_f32_e32 v40, 0xbfb8aa3b, v41
	v_mul_f32_e32 v41, 0xbfb8aa3b, v67
	v_exp_f32_e32 v40, v40
	v_exp_f32_e32 v41, v41
	v_lshlrev_b32_e32 v67, 16, v72
	v_pk_add_f32 v[40:41], v[40:41], 1.0 op_sel_hi:[1,0]
	s_nop 0
	v_mul_f32_e32 v40, v40, v41
	v_rcp_f32_e32 v40, v40
	s_nop 0
	v_mul_f32_e32 v40, v66, v40
	v_lshlrev_b32_e32 v66, 16, v68
	v_cvt_pk_bf16_f32 v39, v39, v40
	v_exp_f32_e32 v40, v34
	v_mul_f32_e32 v34, 0xbfb8aa3b, v66
	v_exp_f32_e32 v41, v34
	v_mul_f32_e32 v34, v67, v66
	v_and_b32_e32 v66, 0xffff0000, v68
	v_pk_add_f32 v[40:41], v[40:41], 1.0 op_sel_hi:[1,0]
	s_nop 0
	v_mul_f32_e32 v40, v40, v41
	v_rcp_f32_e32 v40, v40
	v_and_b32_e32 v41, 0xffff0000, v72
	v_mul_f32_e32 v41, v41, v66
	v_mul_f32_e32 v40, v34, v40
	v_mul_f32_e32 v34, 0xbfb8aa3b, v35
	v_mul_f32_e32 v35, 0xbfb8aa3b, v66
	v_exp_f32_e32 v34, v34
	v_exp_f32_e32 v35, v35
	v_lshlrev_b32_e32 v66, 16, v73
	v_pk_add_f32 v[34:35], v[34:35], 1.0 op_sel_hi:[1,0]
	s_nop 0
	v_mul_f32_e32 v34, v34, v35
	v_rcp_f32_e32 v34, v34
	s_nop 0
	v_mul_f32_e32 v34, v41, v34
	v_lshlrev_b32_e32 v41, 16, v69
	v_cvt_pk_bf16_f32 v40, v40, v34
	v_mul_f32_e32 v34, 0xbfb8aa3b, v36
	v_mul_f32_e32 v35, 0xbfb8aa3b, v41
	v_exp_f32_e32 v34, v34
	v_exp_f32_e32 v35, v35
	v_mul_f32_e32 v36, v66, v41
	v_and_b32_e32 v66, 0xffff0000, v69
	v_and_b32_e32 v41, 0xffff0000, v73
	v_pk_add_f32 v[34:35], v[34:35], 1.0 op_sel_hi:[1,0]
	s_nop 0
	v_mul_f32_e32 v34, v34, v35
	v_rcp_f32_e32 v34, v34
	v_mul_f32_e32 v35, 0xbfb8aa3b, v66
	v_exp_f32_e32 v35, v35
	v_mul_f32_e32 v36, v36, v34
	v_mul_f32_e32 v34, 0xbfb8aa3b, v37
	v_exp_f32_e32 v34, v34
	v_mul_f32_e32 v37, v41, v66
	v_pk_add_f32 v[34:35], v[34:35], 1.0 op_sel_hi:[1,0]
	s_nop 0
	v_mul_f32_e32 v34, v34, v35
	v_rcp_f32_e32 v34, v34
	s_nop 0
	v_mul_f32_e32 v34, v37, v34
	v_cvt_pk_bf16_f32 v41, v36, v34
	v_lshlrev_b32_e32 v36, 16, v58
	v_exp_f32_e32 v34, v22
	v_mul_f32_e32 v22, 0xbfb8aa3b, v36
	v_exp_f32_e32 v35, v22
	v_lshlrev_b32_e32 v37, 16, v62
	v_mul_f32_e32 v22, v37, v36
	v_and_b32_e32 v36, 0xffff0000, v58
	v_pk_add_f32 v[34:35], v[34:35], 1.0 op_sel_hi:[1,0]
	global_store_dwordx4 v[106:107], v[38:41], off offset:256
	v_mul_f32_e32 v34, v34, v35
	v_rcp_f32_e32 v34, v34
	v_and_b32_e32 v35, 0xffff0000, v62
	v_mul_f32_e32 v35, v35, v36
	v_mul_f32_e32 v34, v22, v34
	v_mul_f32_e32 v22, 0xbfb8aa3b, v23
	v_mul_f32_e32 v23, 0xbfb8aa3b, v36
	v_exp_f32_e32 v22, v22
	v_exp_f32_e32 v23, v23
	v_lshlrev_b32_e32 v36, 16, v63
	v_pk_add_f32 v[22:23], v[22:23], 1.0 op_sel_hi:[1,0]
	s_nop 0
	v_mul_f32_e32 v22, v22, v23
	v_rcp_f32_e32 v22, v22
	v_lshlrev_b32_e32 v23, 16, v59
	v_mul_f32_e32 v22, v35, v22
	v_cvt_pk_bf16_f32 v22, v34, v22
	v_exp_f32_e32 v34, v24
	v_mul_f32_e32 v24, 0xbfb8aa3b, v23
	v_exp_f32_e32 v35, v24
	v_mul_f32_e32 v23, v36, v23
	v_pk_add_f32 v[34:35], v[34:35], 1.0 op_sel_hi:[1,0]
	s_nop 0
	v_mul_f32_e32 v24, v34, v35
	v_rcp_f32_e32 v24, v24
	v_and_b32_e32 v35, 0xffff0000, v59
	v_and_b32_e32 v34, 0xffff0000, v63
	v_mul_f32_e32 v34, v34, v35
	v_mul_f32_e32 v23, v23, v24
	v_mul_f32_e32 v24, 0xbfb8aa3b, v25
	v_mul_f32_e32 v25, 0xbfb8aa3b, v35
	v_exp_f32_e32 v24, v24
	v_exp_f32_e32 v25, v25
	v_lshlrev_b32_e32 v35, 16, v64
	v_pk_add_f32 v[24:25], v[24:25], 1.0 op_sel_hi:[1,0]
	s_nop 0
	v_mul_f32_e32 v24, v24, v25
	v_rcp_f32_e32 v24, v24
	s_nop 0
	v_mul_f32_e32 v24, v34, v24
	v_lshlrev_b32_e32 v34, 16, v60
	v_cvt_pk_bf16_f32 v23, v23, v24
	v_exp_f32_e32 v24, v18
	v_mul_f32_e32 v18, 0xbfb8aa3b, v34
	v_exp_f32_e32 v25, v18
	v_mul_f32_e32 v18, v35, v34
	v_and_b32_e32 v34, 0xffff0000, v60
	v_pk_add_f32 v[24:25], v[24:25], 1.0 op_sel_hi:[1,0]
	s_nop 0
	v_mul_f32_e32 v24, v24, v25
	v_rcp_f32_e32 v24, v24
	v_and_b32_e32 v25, 0xffff0000, v64
	v_mul_f32_e32 v25, v25, v34
	v_mul_f32_e32 v24, v18, v24
	v_mul_f32_e32 v18, 0xbfb8aa3b, v19
	v_mul_f32_e32 v19, 0xbfb8aa3b, v34
	v_exp_f32_e32 v18, v18
	v_exp_f32_e32 v19, v19
	v_lshlrev_b32_e32 v34, 16, v65
	v_pk_add_f32 v[18:19], v[18:19], 1.0 op_sel_hi:[1,0]
	s_nop 0
	v_mul_f32_e32 v18, v18, v19
	v_rcp_f32_e32 v18, v18
	s_nop 0
	v_mul_f32_e32 v18, v25, v18
	v_lshlrev_b32_e32 v25, 16, v61
	v_cvt_pk_bf16_f32 v24, v24, v18
	v_mul_f32_e32 v18, 0xbfb8aa3b, v20
	v_mul_f32_e32 v19, 0xbfb8aa3b, v25
	v_exp_f32_e32 v18, v18
	v_exp_f32_e32 v19, v19
	v_mul_f32_e32 v20, v34, v25
	v_and_b32_e32 v34, 0xffff0000, v61
	v_and_b32_e32 v25, 0xffff0000, v65
	v_pk_add_f32 v[18:19], v[18:19], 1.0 op_sel_hi:[1,0]
	s_nop 0
	v_mul_f32_e32 v18, v18, v19
	v_rcp_f32_e32 v18, v18
	v_mul_f32_e32 v19, 0xbfb8aa3b, v34
	v_exp_f32_e32 v19, v19
	v_mul_f32_e32 v20, v20, v18
; __device__ __forceinline__ unsigned cvt_pk_bf16(float lo, float hi) { unsigned r; asm volatile("v_cvt_pk_bf16_f32 %0, %1, %2" : "=v"(r) : "v"(lo), "v"(hi)); return r; }
; __device__ __forceinline__ float bf_lo(unsigned w) { return __uint_as_float(w << 16); }
; __device__ __forceinline__ float bf_hi(unsigned w) { return __uint_as_float(w & 0xffff0000u); }
; #define PG8_WAIT_V(n) asm volatile("s_waitcnt vmcnt(" #n ")" ::: "memory")
; #define PG8_BAR __builtin_amdgcn_s_barrier()
; template <class Epi>
; __device__ __forceinline__ void gemm_phase(LAS unsigned char* lds, const Gemm g, const StaticOrder& S, const Epi& E) {
;     ...
;         if (!has_next) break;
; #pragma unroll
;         for (int a = 0; a < 2; ++a)
; #pragma unroll
;             for (int b = 0; b < 2; ++b)
; #pragma unroll
;                 for (int m = 0; m < 4; ++m)
; #pragma unroll
;                     for (int n = 0; n < 2; ++n) acc[a][b][m][n] = (f32x4){0.f, 0.f, 0.f, 0.f};
;         cur = nxt; cA = nA; cB = nB; ++ui;
;         pre = E.pre(cur, wr, fr);
;     }
;     PG8_WAIT_V(0);
;     if (wr == 0) PG8_BAR;
;     __device__ __forceinline__ void operator()(const f32x4 (&acc)[2][2][4][2], const Unit& u, int wr, int wc, int fr, int fq, const Pre&) const {
;     ...
;                 for (int m = 0; m < 4; ++m) { const int r = row0 + ai * HALF + m * 16;
;                     const u32x4 zw = zv[m], gw = gv[m];
;                     const f32x4 a0 = acc[ai][bj][m][0] + bs[bj][0], a1 = acc[ai][bj][m][1] + bs[bj][1];
;                     u32x4 w;
;                     w.x = cvt_pk_bf16(glu_gate_f(bf_lo(gw.x), a0[0], bf_lo(zw.x)), glu_gate_f(bf_hi(gw.x), a0[1], bf_hi(zw.x)));
;                     w.y = cvt_pk_bf16(glu_gate_f(bf_lo(gw.y), a0[2], bf_lo(zw.y)), glu_gate_f(bf_hi(gw.y), a0[3], bf_hi(zw.y)));
;                     w.z = cvt_pk_bf16(glu_gate_f(bf_lo(gw.z), a1[0], bf_lo(zw.z)), glu_gate_f(bf_hi(gw.z), a1[1], bf_hi(zw.z)));
;                     w.w = cvt_pk_bf16(glu_gate_f(bf_lo(gw.w), a1[2], bf_lo(zw.w)), glu_gate_f(bf_hi(gw.w), a1[3], bf_hi(zw.w)));
;                     *(u32x4*)(O + (size_t)r * DE + c) = w; } } }
	v_mul_f32_e32 v18, 0xbfb8aa3b, v21
	v_exp_f32_e32 v18, v18
	v_mul_f32_e32 v21, v25, v34
	v_pk_add_f32 v[18:19], v[18:19], 1.0 op_sel_hi:[1,0]
	s_nop 0
	v_mul_f32_e32 v18, v18, v19
	v_rcp_f32_e32 v18, v18
	s_nop 0
	v_mul_f32_e32 v18, v21, v18
	v_cvt_pk_bf16_f32 v25, v20, v18
	v_lshlrev_b32_e32 v20, 16, v50
	v_exp_f32_e32 v18, v14
	v_mul_f32_e32 v14, 0xbfb8aa3b, v20
	v_exp_f32_e32 v19, v14
	v_lshlrev_b32_e32 v21, 16, v54
	v_mul_f32_e32 v14, v21, v20
	v_and_b32_e32 v20, 0xffff0000, v50
	v_pk_add_f32 v[18:19], v[18:19], 1.0 op_sel_hi:[1,0]
	global_store_dwordx4 v[108:109], v[22:25], off offset:256
	v_mul_f32_e32 v18, v18, v19
	v_rcp_f32_e32 v18, v18
	v_and_b32_e32 v19, 0xffff0000, v54
	v_mul_f32_e32 v19, v19, v20
	v_mul_f32_e32 v18, v14, v18
	v_mul_f32_e32 v14, 0xbfb8aa3b, v15
	v_mul_f32_e32 v15, 0xbfb8aa3b, v20
	v_exp_f32_e32 v14, v14
	v_exp_f32_e32 v15, v15
	v_lshlrev_b32_e32 v20, 16, v55
	v_pk_add_f32 v[14:15], v[14:15], 1.0 op_sel_hi:[1,0]
	s_nop 0
	v_mul_f32_e32 v14, v14, v15
	v_rcp_f32_e32 v14, v14
	v_lshlrev_b32_e32 v15, 16, v51
	v_mul_f32_e32 v14, v19, v14
	v_cvt_pk_bf16_f32 v14, v18, v14
	v_exp_f32_e32 v18, v16
	v_mul_f32_e32 v16, 0xbfb8aa3b, v15
	v_exp_f32_e32 v19, v16
	v_mul_f32_e32 v15, v20, v15
	v_pk_add_f32 v[18:19], v[18:19], 1.0 op_sel_hi:[1,0]
	s_nop 0
	v_mul_f32_e32 v16, v18, v19
	v_rcp_f32_e32 v16, v16
	v_and_b32_e32 v19, 0xffff0000, v51
	v_and_b32_e32 v18, 0xffff0000, v55
	v_mul_f32_e32 v18, v18, v19
	v_mul_f32_e32 v15, v15, v16
	v_mul_f32_e32 v16, 0xbfb8aa3b, v17
	v_mul_f32_e32 v17, 0xbfb8aa3b, v19
	v_exp_f32_e32 v16, v16
	v_exp_f32_e32 v17, v17
	v_lshlrev_b32_e32 v19, 16, v56
	v_pk_add_f32 v[16:17], v[16:17], 1.0 op_sel_hi:[1,0]
	s_nop 0
	v_mul_f32_e32 v16, v16, v17
	v_rcp_f32_e32 v16, v16
	s_nop 0
	v_mul_f32_e32 v16, v18, v16
	v_lshlrev_b32_e32 v18, 16, v52
	v_cvt_pk_bf16_f32 v15, v15, v16
	v_exp_f32_e32 v16, v10
	v_mul_f32_e32 v10, 0xbfb8aa3b, v18
	v_exp_f32_e32 v17, v10
	v_mul_f32_e32 v10, v19, v18
	v_and_b32_e32 v18, 0xffff0000, v52
	v_pk_add_f32 v[16:17], v[16:17], 1.0 op_sel_hi:[1,0]
	s_nop 0
	v_mul_f32_e32 v16, v16, v17
	v_rcp_f32_e32 v16, v16
	v_and_b32_e32 v17, 0xffff0000, v56
	v_mul_f32_e32 v17, v17, v18
	v_mul_f32_e32 v16, v10, v16
	v_mul_f32_e32 v10, 0xbfb8aa3b, v11
	v_mul_f32_e32 v11, 0xbfb8aa3b, v18
	v_exp_f32_e32 v10, v10
	v_exp_f32_e32 v11, v11
	v_lshlrev_b32_e32 v18, 16, v57
	v_pk_add_f32 v[10:11], v[10:11], 1.0 op_sel_hi:[1,0]
	s_nop 0
	v_mul_f32_e32 v10, v10, v11
	v_rcp_f32_e32 v10, v10
	s_nop 0
	v_mul_f32_e32 v10, v17, v10
	v_lshlrev_b32_e32 v17, 16, v53
	v_cvt_pk_bf16_f32 v16, v16, v10
	v_mul_f32_e32 v10, 0xbfb8aa3b, v12
	v_mul_f32_e32 v11, 0xbfb8aa3b, v17
	v_exp_f32_e32 v10, v10
	v_exp_f32_e32 v11, v11
	v_mul_f32_e32 v12, v18, v17
	v_and_b32_e32 v18, 0xffff0000, v53
	v_and_b32_e32 v17, 0xffff0000, v57
	v_pk_add_f32 v[10:11], v[10:11], 1.0 op_sel_hi:[1,0]
	s_nop 0
	v_mul_f32_e32 v10, v10, v11
	v_rcp_f32_e32 v10, v10
	v_mul_f32_e32 v11, 0xbfb8aa3b, v18
	v_exp_f32_e32 v11, v11
	v_mul_f32_e32 v12, v12, v10
	v_mul_f32_e32 v10, 0xbfb8aa3b, v13
	v_exp_f32_e32 v10, v10
	v_mul_f32_e32 v13, v17, v18
	v_pk_add_f32 v[10:11], v[10:11], 1.0 op_sel_hi:[1,0]
	s_nop 0
	v_mul_f32_e32 v10, v10, v11
	v_rcp_f32_e32 v10, v10
	s_nop 0
	v_mul_f32_e32 v10, v13, v10
	v_cvt_pk_bf16_f32 v17, v12, v10
	v_lshlrev_b32_e32 v12, 16, v42
	v_exp_f32_e32 v10, v6
	v_mul_f32_e32 v6, 0xbfb8aa3b, v12
	v_exp_f32_e32 v11, v6
	v_lshlrev_b32_e32 v13, 16, v46
	v_mul_f32_e32 v6, v13, v12
	v_and_b32_e32 v12, 0xffff0000, v42
	v_pk_add_f32 v[10:11], v[10:11], 1.0 op_sel_hi:[1,0]
	global_store_dwordx4 v[110:111], v[14:17], off offset:256
	v_mul_f32_e32 v10, v10, v11
	v_rcp_f32_e32 v10, v10
	v_and_b32_e32 v11, 0xffff0000, v46
	v_mul_f32_e32 v11, v11, v12
	v_mul_f32_e32 v10, v6, v10
	v_mul_f32_e32 v6, 0xbfb8aa3b, v7
	v_mul_f32_e32 v7, 0xbfb8aa3b, v12
	v_exp_f32_e32 v6, v6
	v_exp_f32_e32 v7, v7
	v_lshlrev_b32_e32 v12, 16, v47
	v_pk_add_f32 v[6:7], v[6:7], 1.0 op_sel_hi:[1,0]
	s_nop 0
	v_mul_f32_e32 v6, v6, v7
	v_rcp_f32_e32 v6, v6
	v_lshlrev_b32_e32 v7, 16, v43
	v_mul_f32_e32 v6, v11, v6
	v_cvt_pk_bf16_f32 v6, v10, v6
	v_exp_f32_e32 v10, v8
	v_mul_f32_e32 v8, 0xbfb8aa3b, v7
	v_exp_f32_e32 v11, v8
	v_mul_f32_e32 v7, v12, v7
	v_pk_add_f32 v[10:11], v[10:11], 1.0 op_sel_hi:[1,0]
	s_nop 0
	v_mul_f32_e32 v8, v10, v11
	v_rcp_f32_e32 v8, v8
	v_and_b32_e32 v11, 0xffff0000, v43
	v_and_b32_e32 v10, 0xffff0000, v47
	v_mul_f32_e32 v10, v10, v11
	v_mul_f32_e32 v7, v7, v8
	v_mul_f32_e32 v8, 0xbfb8aa3b, v9
	v_mul_f32_e32 v9, 0xbfb8aa3b, v11
	v_exp_f32_e32 v8, v8
	v_exp_f32_e32 v9, v9
	v_lshlrev_b32_e32 v11, 16, v48
	v_pk_add_f32 v[8:9], v[8:9], 1.0 op_sel_hi:[1,0]
	s_nop 0
	v_mul_f32_e32 v8, v8, v9
	v_rcp_f32_e32 v8, v8
	s_nop 0
	v_mul_f32_e32 v8, v10, v8
	v_lshlrev_b32_e32 v10, 16, v44
	v_cvt_pk_bf16_f32 v7, v7, v8
	v_exp_f32_e32 v8, v2
	v_mul_f32_e32 v2, 0xbfb8aa3b, v10
	v_exp_f32_e32 v9, v2
	v_mul_f32_e32 v2, v11, v10
	v_and_b32_e32 v10, 0xffff0000, v44
	v_pk_add_f32 v[8:9], v[8:9], 1.0 op_sel_hi:[1,0]
	s_nop 0
	v_mul_f32_e32 v8, v8, v9
	v_rcp_f32_e32 v8, v8
	v_and_b32_e32 v9, 0xffff0000, v48
	v_mul_f32_e32 v9, v9, v10
	v_mul_f32_e32 v8, v2, v8
	v_mul_f32_e32 v2, 0xbfb8aa3b, v3
	v_mul_f32_e32 v3, 0xbfb8aa3b, v10
	v_exp_f32_e32 v2, v2
	v_exp_f32_e32 v3, v3
	v_lshlrev_b32_e32 v10, 16, v49
	v_pk_add_f32 v[2:3], v[2:3], 1.0 op_sel_hi:[1,0]
	s_nop 0
	v_mul_f32_e32 v2, v2, v3
	v_rcp_f32_e32 v2, v2
	s_nop 0
	v_mul_f32_e32 v2, v9, v2
	v_lshlrev_b32_e32 v9, 16, v45
	v_cvt_pk_bf16_f32 v8, v8, v2
	v_mul_f32_e32 v2, 0xbfb8aa3b, v4
	v_mul_f32_e32 v3, 0xbfb8aa3b, v9
	v_exp_f32_e32 v2, v2
	v_exp_f32_e32 v3, v3
	v_mul_f32_e32 v4, v10, v9
	v_and_b32_e32 v10, 0xffff0000, v45
	v_and_b32_e32 v9, 0xffff0000, v49
	v_pk_add_f32 v[2:3], v[2:3], 1.0 op_sel_hi:[1,0]
	s_nop 0
	v_mul_f32_e32 v2, v2, v3
	v_rcp_f32_e32 v2, v2
	v_mul_f32_e32 v3, 0xbfb8aa3b, v10
	v_exp_f32_e32 v3, v3
	v_mul_f32_e32 v4, v4, v2
	v_mul_f32_e32 v2, 0xbfb8aa3b, v5
	v_exp_f32_e32 v2, v2
	v_mul_f32_e32 v5, v9, v10
	v_pk_add_f32 v[2:3], v[2:3], 1.0 op_sel_hi:[1,0]
	s_nop 0
	v_mul_f32_e32 v2, v2, v3
	v_rcp_f32_e32 v2, v2
	s_nop 0
	v_mul_f32_e32 v2, v5, v2
	v_cvt_pk_bf16_f32 v9, v4, v2
	global_store_dwordx4 v[112:113], v[6:9], off offset:256
	s_cbranch_vccz .LBB0_789
	s_waitcnt vmcnt(0)
	v_readlane_b32 s36, v254, 56
	s_cmpk_gt_u32 s18, 0xff
	v_readlane_b32 s37, v254, 57
	s_cbranch_scc1 .LBB0_800
	s_barrier
